# v69 plus: the priority flip between the two 16-MFMA blocks of a GEMM segment removed (the MFMA segment is now MFMAs only)
# speedup vs baseline: 1.0167x; 1.0034x over previous
; #define PG8_KSETUP() const bool last = (t == nt - 2); const char* a1 = cA + (size_t)(t + 1) * kstep; \
;             const char* a2 = last ? nA : cA + (size_t)(t + 2) * kstep; const char* b2 = last ? nB : cB + (size_t)(t + 2) * kstep; const char* a3 = a2 + kstep; const char* b3 = b2 + kstep; \
;             if (last && has_next) S.a_ready(nxt)
; template <class Epi, class Sched, bool ALIGN_EPI = false, bool SP2 = false>
; __device__ __forceinline__ void gemm_phase(PG8_LAS unsigned char* lds, const Gemm g, const Sched& S, const Epi& E) {
;     ...
;         int t0 = 0;
;         if constexpr (SP2 && Epi::NVM == 16) { if (ui > 0) { const int t = 0; PG8_KSETUP(); PG8_KITER_SP2(24, 24); t0 = 2; } }
;         if constexpr (SP2 && Epi::NVM == 8) { if (ui > 0) { const int t = 0; PG8_KSETUP(); PG8_KITER_SP2(16, 16); t0 = 2; } }
;         for (int t = t0; t < nt; t += 2) {
;             PG8_KSETUP();
;             if constexpr (SP2) {
;             PG8_KITER_SP2(8, 8);
.LBB0_185:
	ds_read_b128 v[136:139], v149
	ds_read_b128 v[154:157], v149 offset:1024
	ds_read_b128 v[158:161], v149 offset:2048
	ds_read_b128 v[162:165], v149 offset:3072
	ds_read_b128 v[166:169], v150
	ds_read_b128 v[170:173], v150 offset:1024
	ds_read_b128 v[174:177], v150 offset:2048
	ds_read_b128 v[178:181], v150 offset:3072
	s_cmp_eq_u32 s86, 28
	s_cselect_b32 s54, s80, s84
	s_cselect_b32 s55, s25, s85
	s_cselect_b32 s46, s81, s82
	s_cselect_b32 s47, s19, s83
	s_add_u32 s44, s54, 0x80
	s_addc_u32 s45, s55, 0
	ds_read_b128 v[182:185], v151
	ds_read_b128 v[186:189], v151 offset:1024
	ds_read_b128 v[190:193], v151 offset:2048
	ds_read_b128 v[194:197], v151 offset:3072
	ds_read_b128 v[198:201], v151 offset:4096
	ds_read_b128 v[202:205], v151 offset:5120
	ds_read_b128 v[206:209], v151 offset:6144
	ds_read_b128 v[210:213], v151 offset:7168
	s_mov_b32 m0, s75
	s_nop 0
	global_load_lds_dwordx4 v1, s[40:41] offset:0
	s_nop 0
	s_mov_b32 m0, s76
	s_nop 0
	global_load_lds_dwordx4 v143, s[40:41] offset:0
	s_waitcnt vmcnt(8)
	s_waitcnt lgkmcnt(0)
	s_barrier
	s_setprio 1
	v_mfma_f32_16x16x32_bf16 v[126:129], v[136:139], v[182:185], v[126:129]
	v_mfma_f32_16x16x32_bf16 v[126:129], v[154:157], v[186:189], v[126:129]
	v_mfma_f32_16x16x32_bf16 v[122:125], v[158:161], v[182:185], v[122:125]
	v_mfma_f32_16x16x32_bf16 v[122:125], v[162:165], v[186:189], v[122:125]
	v_mfma_f32_16x16x32_bf16 v[114:117], v[136:139], v[190:193], v[114:117]
	v_mfma_f32_16x16x32_bf16 v[114:117], v[154:157], v[194:197], v[114:117]
	v_mfma_f32_16x16x32_bf16 v[106:109], v[158:161], v[190:193], v[106:109]
	v_mfma_f32_16x16x32_bf16 v[106:109], v[162:165], v[194:197], v[106:109]
	v_mfma_f32_16x16x32_bf16 v[98:101], v[136:139], v[198:201], v[98:101]
	v_mfma_f32_16x16x32_bf16 v[98:101], v[154:157], v[202:205], v[98:101]
	v_mfma_f32_16x16x32_bf16 v[90:93], v[158:161], v[198:201], v[90:93]
	v_mfma_f32_16x16x32_bf16 v[90:93], v[162:165], v[202:205], v[90:93]
	v_mfma_f32_16x16x32_bf16 v[82:85], v[136:139], v[206:209], v[82:85]
	v_mfma_f32_16x16x32_bf16 v[82:85], v[154:157], v[210:213], v[82:85]
	v_mfma_f32_16x16x32_bf16 v[74:77], v[158:161], v[206:209], v[74:77]
	v_mfma_f32_16x16x32_bf16 v[74:77], v[162:165], v[210:213], v[74:77]
	v_mfma_f32_16x16x32_bf16 v[118:121], v[166:169], v[182:185], v[118:121]
	v_mfma_f32_16x16x32_bf16 v[118:121], v[170:173], v[186:189], v[118:121]
	v_mfma_f32_16x16x32_bf16 v[110:113], v[174:177], v[182:185], v[110:113]
	v_mfma_f32_16x16x32_bf16 v[110:113], v[178:181], v[186:189], v[110:113]
	v_mfma_f32_16x16x32_bf16 v[102:105], v[166:169], v[190:193], v[102:105]
	v_mfma_f32_16x16x32_bf16 v[102:105], v[170:173], v[194:197], v[102:105]
	v_mfma_f32_16x16x32_bf16 v[94:97], v[174:177], v[190:193], v[94:97]
	v_mfma_f32_16x16x32_bf16 v[94:97], v[178:181], v[194:197], v[94:97]
	v_mfma_f32_16x16x32_bf16 v[86:89], v[166:169], v[198:201], v[86:89]
	v_mfma_f32_16x16x32_bf16 v[86:89], v[170:173], v[202:205], v[86:89]
	v_mfma_f32_16x16x32_bf16 v[78:81], v[174:177], v[198:201], v[78:81]
	v_mfma_f32_16x16x32_bf16 v[78:81], v[178:181], v[202:205], v[78:81]
	v_mfma_f32_16x16x32_bf16 v[70:73], v[166:169], v[206:209], v[70:73]
	v_mfma_f32_16x16x32_bf16 v[70:73], v[170:173], v[210:213], v[70:73]
	v_mfma_f32_16x16x32_bf16 v[66:69], v[174:177], v[206:209], v[66:69]
	v_mfma_f32_16x16x32_bf16 v[66:69], v[178:181], v[210:213], v[66:69]
	s_barrier
	s_setprio 0
	ds_read_b128 v[182:185], v151 offset:16384
	ds_read_b128 v[186:189], v151 offset:17408
	ds_read_b128 v[190:193], v151 offset:18432
	ds_read_b128 v[194:197], v151 offset:19456
	ds_read_b128 v[198:201], v151 offset:20480
	ds_read_b128 v[202:205], v151 offset:21504
	ds_read_b128 v[206:209], v151 offset:22528
	ds_read_b128 v[210:213], v151 offset:23552
	s_mov_b32 m0, s39
	s_nop 0
	global_load_lds_dwordx4 v135, s[46:47] offset:0
	s_add_u32 s30, s46, 0x80000
	s_mov_b32 m0, s58
	s_nop 0
	global_load_lds_dwordx4 v145, s[46:47] offset:0
	s_addc_u32 s31, s47, 0
	s_mov_b32 m0, s59
	s_nop 0
	global_load_lds_dwordx4 v135, s[30:31] offset:0
	s_nop 0
	s_mov_b32 m0, s64
	s_nop 0
	global_load_lds_dwordx4 v145, s[30:31] offset:0
	s_nop 0
	s_mov_b32 m0, s53
	s_nop 0
	global_load_lds_dwordx4 v1, s[54:55] offset:0
	s_nop 0
	s_mov_b32 m0, s65
	s_nop 0
	global_load_lds_dwordx4 v143, s[54:55] offset:0
	s_waitcnt vmcnt(8)
	s_waitcnt lgkmcnt(0)
	s_barrier
	s_setprio 1
	v_mfma_f32_16x16x32_bf16 v[62:65], v[136:139], v[182:185], v[62:65]
	v_mfma_f32_16x16x32_bf16 v[62:65], v[154:157], v[186:189], v[62:65]
	v_mfma_f32_16x16x32_bf16 v[58:61], v[158:161], v[182:185], v[58:61]
	v_mfma_f32_16x16x32_bf16 v[58:61], v[162:165], v[186:189], v[58:61]
	v_mfma_f32_16x16x32_bf16 v[50:53], v[136:139], v[190:193], v[50:53]
	v_mfma_f32_16x16x32_bf16 v[50:53], v[154:157], v[194:197], v[50:53]
	v_mfma_f32_16x16x32_bf16 v[42:45], v[158:161], v[190:193], v[42:45]
	v_mfma_f32_16x16x32_bf16 v[42:45], v[162:165], v[194:197], v[42:45]
	v_mfma_f32_16x16x32_bf16 v[34:37], v[136:139], v[198:201], v[34:37]
	v_mfma_f32_16x16x32_bf16 v[34:37], v[154:157], v[202:205], v[34:37]
	v_mfma_f32_16x16x32_bf16 v[26:29], v[158:161], v[198:201], v[26:29]
	v_mfma_f32_16x16x32_bf16 v[26:29], v[162:165], v[202:205], v[26:29]
	v_mfma_f32_16x16x32_bf16 v[18:21], v[136:139], v[206:209], v[18:21]
	v_mfma_f32_16x16x32_bf16 v[18:21], v[154:157], v[210:213], v[18:21]
	v_mfma_f32_16x16x32_bf16 v[10:13], v[158:161], v[206:209], v[10:13]
	v_mfma_f32_16x16x32_bf16 v[10:13], v[162:165], v[210:213], v[10:13]
	v_mfma_f32_16x16x32_bf16 v[54:57], v[166:169], v[182:185], v[54:57]
	v_mfma_f32_16x16x32_bf16 v[54:57], v[170:173], v[186:189], v[54:57]
	v_mfma_f32_16x16x32_bf16 v[46:49], v[174:177], v[182:185], v[46:49]
	v_mfma_f32_16x16x32_bf16 v[46:49], v[178:181], v[186:189], v[46:49]
	v_mfma_f32_16x16x32_bf16 v[38:41], v[166:169], v[190:193], v[38:41]
	v_mfma_f32_16x16x32_bf16 v[38:41], v[170:173], v[194:197], v[38:41]
	v_mfma_f32_16x16x32_bf16 v[30:33], v[174:177], v[190:193], v[30:33]
	v_mfma_f32_16x16x32_bf16 v[30:33], v[178:181], v[194:197], v[30:33]
	v_mfma_f32_16x16x32_bf16 v[22:25], v[166:169], v[198:201], v[22:25]
	v_mfma_f32_16x16x32_bf16 v[22:25], v[170:173], v[202:205], v[22:25]
	v_mfma_f32_16x16x32_bf16 v[14:17], v[174:177], v[198:201], v[14:17]
	v_mfma_f32_16x16x32_bf16 v[14:17], v[178:181], v[202:205], v[14:17]
	v_mfma_f32_16x16x32_bf16 v[6:9], v[166:169], v[206:209], v[6:9]
	v_mfma_f32_16x16x32_bf16 v[6:9], v[170:173], v[210:213], v[6:9]
	v_mfma_f32_16x16x32_bf16 v[2:5], v[174:177], v[206:209], v[2:5]
	v_mfma_f32_16x16x32_bf16 v[2:5], v[178:181], v[210:213], v[2:5]
	s_barrier
; #define PG8_STAGE(bufoff, gbase, voff) PG8_STAGEI(bufoff, gbase, 0, voff)
; #define PG8_LDA(dst, b, h) do { _Pragma("unroll") for (int m = 0; m < 4; ++m) _Pragma("unroll") for (int k = 0; k < 2; ++k) dst[m][k] = *(const PG8_LAS bf16x8*)(lds + PG8_SA(b, h) + aoff + m * 2048 + k * 1024); } while (0)
; #define PG8_WAIT_V(n) asm volatile("s_waitcnt vmcnt(" #n ")" ::: "memory")
; #define PG8_BAR __builtin_amdgcn_s_barrier()
; template <class Epi, class Sched, bool ALIGN_EPI = false, bool SP2 = false>
; __device__ __forceinline__ void gemm_phase(PG8_LAS unsigned char* lds, const Gemm g, const Sched& S, const Epi& E) {
;     ...
;         int t0 = 0;
;         if constexpr (SP2 && Epi::NVM == 16) { if (ui > 0) { const int t = 0; PG8_KSETUP(); PG8_KITER_SP2(24, 24); t0 = 2; } }
;         if constexpr (SP2 && Epi::NVM == 8) { if (ui > 0) { const int t = 0; PG8_KSETUP(); PG8_KITER_SP2(16, 16); t0 = 2; } }
;         for (int t = t0; t < nt; t += 2) {
;             PG8_KSETUP();
;             if constexpr (SP2) {
;             PG8_KITER_SP2(8, 8);
;             } else {
;             PG8_LDB(B0, 0, 0); PG8_SCHED; PG8_LDA(At, 0, 0); PG8_STAGE(PG8_SA(1, 1), a1 + hstep, voffA);
;             PG8_WAIT_L(8); PG8_BAR; PG8_WAIT_L(0); PG8_MMA(0, 0, At, B0); PG8_BAR; PG8_SCHED;
;             PG8_LDB(B1, 0, 1); PG8_STAGE(PG8_SB(0, 0), b2, voffB);
;             PG8_BAR; PG8_WAIT_L(0); PG8_MMA(0, 1, At, B1); PG8_BAR;
;             PG8_LDA(At, 0, 1); PG8_STAGE(PG8_SA(0, 0), a2, voffA);
;             PG8_BAR; PG8_WAIT_L(0); PG8_MMA(1, 0, At, B0); PG8_BAR; PG8_SCHED;
;             PG8_STAGE(PG8_SB(0, 1), b2 + hstep, voffB);
;             PG8_WAIT_V(6); PG8_BAR; PG8_MMA(1, 1, At, B1); PG8_BAR;
;             PG8_LDB(B0, 1, 0); PG8_SCHED; PG8_LDA(At, 1, 0); PG8_STAGE(PG8_SA(0, 1), a2 + hstep, voffA);
;             PG8_WAIT_L(8); PG8_BAR; PG8_WAIT_L(0); PG8_MMA(0, 0, At, B0); PG8_BAR; PG8_SCHED;
;             PG8_LDB(B1, 1, 1); PG8_STAGE(PG8_SB(1, 0), b3, voffB);
;             PG8_BAR; PG8_WAIT_L(0); PG8_MMA(0, 1, At, B1); PG8_BAR;
;             PG8_LDA(At, 1, 1); PG8_STAGE(PG8_SA(1, 0), a3, voffA);
;             PG8_BAR; PG8_WAIT_L(0); PG8_MMA(1, 0, At, B0); PG8_BAR; PG8_SCHED;
;             PG8_STAGE(PG8_SB(1, 1), b3 + hstep, voffB);
;             PG8_WAIT_V(6); PG8_BAR; PG8_MMA(1, 1, At, B1); PG8_BAR;
;             }
;         }
;     ...
;         if constexpr (ALIGN_EPI) { if (wr == 0) PG8_BAR; }
	s_setprio 0
	ds_read_b128 v[136:139], v152
	ds_read_b128 v[154:157], v152 offset:1024
	ds_read_b128 v[158:161], v152 offset:2048
	ds_read_b128 v[162:165], v152 offset:3072
	ds_read_b128 v[166:169], v153
	ds_read_b128 v[170:173], v153 offset:1024
	ds_read_b128 v[174:177], v153 offset:2048
	ds_read_b128 v[178:181], v153 offset:3072
	ds_read_b128 v[182:185], v151 offset:32768
	ds_read_b128 v[186:189], v151 offset:33792
	ds_read_b128 v[190:193], v151 offset:34816
	ds_read_b128 v[194:197], v151 offset:35840
	ds_read_b128 v[198:201], v151 offset:36864
	ds_read_b128 v[202:205], v151 offset:37888
	ds_read_b128 v[206:209], v151 offset:38912
	ds_read_b128 v[210:213], v151 offset:39936
	s_add_u32 s30, s54, 0x80000
	s_addc_u32 s31, s55, 0
	s_mov_b32 m0, s66
	s_nop 0
	global_load_lds_dwordx4 v1, s[30:31] offset:0
	s_nop 0
	s_mov_b32 m0, s67
	s_nop 0
	global_load_lds_dwordx4 v143, s[30:31] offset:0
	s_waitcnt vmcnt(8)
	s_waitcnt lgkmcnt(0)
	s_barrier
	s_setprio 1
	v_mfma_f32_16x16x32_bf16 v[126:129], v[136:139], v[182:185], v[126:129]
	v_mfma_f32_16x16x32_bf16 v[126:129], v[154:157], v[186:189], v[126:129]
	v_mfma_f32_16x16x32_bf16 v[122:125], v[158:161], v[182:185], v[122:125]
	v_mfma_f32_16x16x32_bf16 v[122:125], v[162:165], v[186:189], v[122:125]
	v_mfma_f32_16x16x32_bf16 v[114:117], v[136:139], v[190:193], v[114:117]
	v_mfma_f32_16x16x32_bf16 v[114:117], v[154:157], v[194:197], v[114:117]
	v_mfma_f32_16x16x32_bf16 v[106:109], v[158:161], v[190:193], v[106:109]
	v_mfma_f32_16x16x32_bf16 v[106:109], v[162:165], v[194:197], v[106:109]
	v_mfma_f32_16x16x32_bf16 v[98:101], v[136:139], v[198:201], v[98:101]
	v_mfma_f32_16x16x32_bf16 v[98:101], v[154:157], v[202:205], v[98:101]
	v_mfma_f32_16x16x32_bf16 v[90:93], v[158:161], v[198:201], v[90:93]
	v_mfma_f32_16x16x32_bf16 v[90:93], v[162:165], v[202:205], v[90:93]
	v_mfma_f32_16x16x32_bf16 v[82:85], v[136:139], v[206:209], v[82:85]
	v_mfma_f32_16x16x32_bf16 v[82:85], v[154:157], v[210:213], v[82:85]
	v_mfma_f32_16x16x32_bf16 v[74:77], v[158:161], v[206:209], v[74:77]
	v_mfma_f32_16x16x32_bf16 v[74:77], v[162:165], v[210:213], v[74:77]
	v_mfma_f32_16x16x32_bf16 v[118:121], v[166:169], v[182:185], v[118:121]
	v_mfma_f32_16x16x32_bf16 v[118:121], v[170:173], v[186:189], v[118:121]
	v_mfma_f32_16x16x32_bf16 v[110:113], v[174:177], v[182:185], v[110:113]
	v_mfma_f32_16x16x32_bf16 v[110:113], v[178:181], v[186:189], v[110:113]
	v_mfma_f32_16x16x32_bf16 v[102:105], v[166:169], v[190:193], v[102:105]
	v_mfma_f32_16x16x32_bf16 v[102:105], v[170:173], v[194:197], v[102:105]
	v_mfma_f32_16x16x32_bf16 v[94:97], v[174:177], v[190:193], v[94:97]
	v_mfma_f32_16x16x32_bf16 v[94:97], v[178:181], v[194:197], v[94:97]
	v_mfma_f32_16x16x32_bf16 v[86:89], v[166:169], v[198:201], v[86:89]
	v_mfma_f32_16x16x32_bf16 v[86:89], v[170:173], v[202:205], v[86:89]
	v_mfma_f32_16x16x32_bf16 v[78:81], v[174:177], v[198:201], v[78:81]
	v_mfma_f32_16x16x32_bf16 v[78:81], v[178:181], v[202:205], v[78:81]
	v_mfma_f32_16x16x32_bf16 v[70:73], v[166:169], v[206:209], v[70:73]
	v_mfma_f32_16x16x32_bf16 v[70:73], v[170:173], v[210:213], v[70:73]
	v_mfma_f32_16x16x32_bf16 v[66:69], v[174:177], v[206:209], v[66:69]
	v_mfma_f32_16x16x32_bf16 v[66:69], v[178:181], v[210:213], v[66:69]
	s_barrier
	s_setprio 0
	ds_read_b128 v[182:185], v151 offset:49152
	ds_read_b128 v[186:189], v151 offset:50176
	ds_read_b128 v[190:193], v151 offset:51200
	ds_read_b128 v[194:197], v151 offset:52224
	ds_read_b128 v[198:201], v151 offset:53248
	ds_read_b128 v[202:205], v151 offset:54272
	ds_read_b128 v[206:209], v151 offset:55296
	ds_read_b128 v[210:213], v151 offset:56320
	s_add_u32 s30, s46, 0x80
	s_addc_u32 s31, s47, 0
	s_mov_b32 m0, s69
	s_nop 0
	global_load_lds_dwordx4 v135, s[30:31] offset:0
	s_nop 0
	s_mov_b32 m0, s70
	s_nop 0
	global_load_lds_dwordx4 v145, s[30:31] offset:0
	s_add_u32 s30, s46, 0x80080
	s_addc_u32 s31, s47, 0
	s_mov_b32 m0, s73
	s_nop 0
	global_load_lds_dwordx4 v135, s[30:31] offset:0
	s_nop 0
	s_mov_b32 m0, s74
	s_nop 0
	global_load_lds_dwordx4 v145, s[30:31] offset:0
	s_nop 0
	s_mov_b32 m0, s71
	s_nop 0
	global_load_lds_dwordx4 v1, s[44:45] offset:0
	s_nop 0
	s_mov_b32 m0, s72
	s_nop 0
	global_load_lds_dwordx4 v143, s[44:45] offset:0
	s_waitcnt vmcnt(8)
	s_waitcnt lgkmcnt(0)
	s_barrier
	s_setprio 1
	v_mfma_f32_16x16x32_bf16 v[62:65], v[136:139], v[182:185], v[62:65]
	v_mfma_f32_16x16x32_bf16 v[62:65], v[154:157], v[186:189], v[62:65]
	v_mfma_f32_16x16x32_bf16 v[58:61], v[158:161], v[182:185], v[58:61]
	v_mfma_f32_16x16x32_bf16 v[58:61], v[162:165], v[186:189], v[58:61]
	v_mfma_f32_16x16x32_bf16 v[50:53], v[136:139], v[190:193], v[50:53]
	v_mfma_f32_16x16x32_bf16 v[50:53], v[154:157], v[194:197], v[50:53]
	v_mfma_f32_16x16x32_bf16 v[42:45], v[158:161], v[190:193], v[42:45]
	v_mfma_f32_16x16x32_bf16 v[42:45], v[162:165], v[194:197], v[42:45]
	v_mfma_f32_16x16x32_bf16 v[34:37], v[136:139], v[198:201], v[34:37]
	v_mfma_f32_16x16x32_bf16 v[34:37], v[154:157], v[202:205], v[34:37]
	v_mfma_f32_16x16x32_bf16 v[26:29], v[158:161], v[198:201], v[26:29]
	v_mfma_f32_16x16x32_bf16 v[26:29], v[162:165], v[202:205], v[26:29]
	v_mfma_f32_16x16x32_bf16 v[18:21], v[136:139], v[206:209], v[18:21]
	v_mfma_f32_16x16x32_bf16 v[18:21], v[154:157], v[210:213], v[18:21]
	v_mfma_f32_16x16x32_bf16 v[10:13], v[158:161], v[206:209], v[10:13]
	v_mfma_f32_16x16x32_bf16 v[10:13], v[162:165], v[210:213], v[10:13]
	v_mfma_f32_16x16x32_bf16 v[54:57], v[166:169], v[182:185], v[54:57]
	v_mfma_f32_16x16x32_bf16 v[54:57], v[170:173], v[186:189], v[54:57]
	v_mfma_f32_16x16x32_bf16 v[46:49], v[174:177], v[182:185], v[46:49]
	v_mfma_f32_16x16x32_bf16 v[46:49], v[178:181], v[186:189], v[46:49]
	v_mfma_f32_16x16x32_bf16 v[38:41], v[166:169], v[190:193], v[38:41]
	v_mfma_f32_16x16x32_bf16 v[38:41], v[170:173], v[194:197], v[38:41]
	v_mfma_f32_16x16x32_bf16 v[30:33], v[174:177], v[190:193], v[30:33]
	v_mfma_f32_16x16x32_bf16 v[30:33], v[178:181], v[194:197], v[30:33]
	v_mfma_f32_16x16x32_bf16 v[22:25], v[166:169], v[198:201], v[22:25]
	v_mfma_f32_16x16x32_bf16 v[22:25], v[170:173], v[202:205], v[22:25]
	v_mfma_f32_16x16x32_bf16 v[14:17], v[174:177], v[198:201], v[14:17]
	v_mfma_f32_16x16x32_bf16 v[14:17], v[178:181], v[202:205], v[14:17]
	v_mfma_f32_16x16x32_bf16 v[6:9], v[166:169], v[206:209], v[6:9]
	v_mfma_f32_16x16x32_bf16 v[6:9], v[170:173], v[210:213], v[6:9]
	v_mfma_f32_16x16x32_bf16 v[2:5], v[174:177], v[206:209], v[2:5]
	v_mfma_f32_16x16x32_bf16 v[2:5], v[178:181], v[210:213], v[2:5]
	s_barrier
	s_setprio 0
	s_add_i32 s86, s86, 2
	s_add_u32 s82, s82, 0x100
	s_addc_u32 s83, s83, 0
	s_add_u32 s84, s84, 0x100
	s_addc_u32 s85, s85, 0
	s_add_u32 s40, s40, 0x100
	s_addc_u32 s41, s41, 0
	s_cmp_gt_u32 s86, 29
	s_cbranch_scc0 .LBB0_185
	s_and_b64 vcc, exec, s[16:17]
	s_cbranch_vccz .LBB0_188
	s_barrier

; #define PG8_KSETUP() const bool last = (t == nt - 2); const char* a1 = cA + (size_t)(t + 1) * kstep; \
;             const char* a2 = last ? nA : cA + (size_t)(t + 2) * kstep; const char* b2 = last ? nB : cB + (size_t)(t + 2) * kstep; const char* a3 = a2 + kstep; const char* b3 = b2 + kstep; \
;             if (last && has_next) S.a_ready(nxt)
; template <class Epi, class Sched, bool ALIGN_EPI = false, bool SP2 = false>
; __device__ __forceinline__ void gemm_phase(PG8_LAS unsigned char* lds, const Gemm g, const Sched& S, const Epi& E) {
;     ...
;         int t0 = 0;
;         if constexpr (SP2 && Epi::NVM == 16) { if (ui > 0) { const int t = 0; PG8_KSETUP(); PG8_KITER_SP2(24, 24); t0 = 2; } }
.LBB0_624:
	s_cmp_eq_u32 s37, 0
	s_mov_b32 s64, 0
	s_cbranch_scc1 .LBB0_626
	ds_read_b128 v[4:7], v147
	ds_read_b128 v[8:11], v147 offset:1024
	ds_read_b128 v[12:15], v147 offset:2048
	ds_read_b128 v[16:19], v147 offset:3072
	ds_read_b128 v[20:23], v148
	ds_read_b128 v[24:27], v148 offset:1024
	ds_read_b128 v[28:31], v148 offset:2048
	ds_read_b128 v[32:35], v148 offset:3072
	s_add_u32 s44, s56, 0x100
	s_addc_u32 s45, s57, 0
	s_add_u32 s30, s58, 0x100
	s_addc_u32 s31, s59, 0
	s_add_u32 s40, s56, 0x180
	s_addc_u32 s41, s57, 0
	ds_read_b128 v[36:39], v149
	ds_read_b128 v[40:43], v149 offset:1024
	ds_read_b128 v[44:47], v149 offset:2048
	ds_read_b128 v[48:51], v149 offset:3072
	ds_read_b128 v[52:55], v149 offset:4096
	ds_read_b128 v[56:59], v149 offset:5120
	ds_read_b128 v[60:63], v149 offset:6144
	ds_read_b128 v[64:67], v149 offset:7168
	s_add_u32 s42, s56, 0x80080
	s_addc_u32 s43, s57, 0
	s_mov_b32 m0, s81
	s_nop 0
	global_load_lds_dwordx4 v1, s[42:43] offset:0
	s_nop 0
	s_mov_b32 m0, s82
	s_nop 0
	global_load_lds_dwordx4 v143, s[42:43] offset:0
	s_waitcnt vmcnt(24)
	s_waitcnt lgkmcnt(0)
	s_barrier
	s_setprio 1
	v_mfma_f32_16x16x32_bf16 v[92:95], v[4:7], v[60:63], 0
	v_mfma_f32_16x16x32_bf16 v[68:71], v[4:7], v[36:39], 0
	v_mfma_f32_16x16x32_bf16 v[72:75], v[12:15], v[36:39], 0
	v_mfma_f32_16x16x32_bf16 v[76:79], v[4:7], v[44:47], 0
	v_mfma_f32_16x16x32_bf16 v[80:83], v[12:15], v[44:47], 0
	v_mfma_f32_16x16x32_bf16 v[84:87], v[4:7], v[52:55], 0
	v_mfma_f32_16x16x32_bf16 v[88:91], v[12:15], v[52:55], 0
	v_mfma_f32_16x16x32_bf16 v[102:105], v[8:11], v[64:67], v[92:95]
	v_mfma_f32_16x16x32_bf16 v[92:95], v[12:15], v[60:63], 0
	v_mfma_f32_16x16x32_bf16 v[68:71], v[8:11], v[40:43], v[68:71]
	v_mfma_f32_16x16x32_bf16 v[72:75], v[16:19], v[40:43], v[72:75]
	v_mfma_f32_16x16x32_bf16 v[76:79], v[8:11], v[48:51], v[76:79]
	v_mfma_f32_16x16x32_bf16 v[80:83], v[16:19], v[48:51], v[80:83]
	v_mfma_f32_16x16x32_bf16 v[84:87], v[8:11], v[56:59], v[84:87]
	v_mfma_f32_16x16x32_bf16 v[88:91], v[16:19], v[56:59], v[88:91]
	v_mfma_f32_16x16x32_bf16 v[106:109], v[16:19], v[64:67], v[92:95]
	v_mfma_f32_16x16x32_bf16 v[92:95], v[20:23], v[36:39], 0
	v_mfma_f32_16x16x32_bf16 v[36:39], v[28:31], v[36:39], 0
	v_mfma_f32_16x16x32_bf16 v[118:121], v[24:27], v[40:43], v[92:95]
	v_mfma_f32_16x16x32_bf16 v[36:39], v[32:35], v[40:43], v[36:39]
	v_mfma_f32_16x16x32_bf16 v[40:43], v[20:23], v[44:47], 0
	v_mfma_f32_16x16x32_bf16 v[44:47], v[28:31], v[44:47], 0
	v_mfma_f32_16x16x32_bf16 v[40:43], v[24:27], v[48:51], v[40:43]
	v_mfma_f32_16x16x32_bf16 v[44:47], v[32:35], v[48:51], v[44:47]
	v_mfma_f32_16x16x32_bf16 v[48:51], v[20:23], v[52:55], 0
	v_mfma_f32_16x16x32_bf16 v[52:55], v[28:31], v[52:55], 0
	v_mfma_f32_16x16x32_bf16 v[48:51], v[24:27], v[56:59], v[48:51]
	v_mfma_f32_16x16x32_bf16 v[52:55], v[32:35], v[56:59], v[52:55]
	v_mfma_f32_16x16x32_bf16 v[56:59], v[20:23], v[60:63], 0
	v_mfma_f32_16x16x32_bf16 v[60:63], v[28:31], v[60:63], 0
	v_mfma_f32_16x16x32_bf16 v[56:59], v[24:27], v[64:67], v[56:59]
	v_mfma_f32_16x16x32_bf16 v[60:63], v[32:35], v[64:67], v[60:63]
	s_barrier
	s_setprio 0
	ds_read_b128 v[64:67], v149 offset:16384
	ds_read_b128 v[92:95], v149 offset:17408
	ds_read_b128 v[96:99], v149 offset:18432
	ds_read_b128 v[110:113], v149 offset:19456
	ds_read_b128 v[114:117], v149 offset:20480
	ds_read_b128 v[122:125], v149 offset:21504
	ds_read_b128 v[126:129], v149 offset:22528
	ds_read_b128 v[130:133], v149 offset:23552
	s_mov_b32 m0, s52
	s_nop 0
	global_load_lds_dwordx4 v142, s[30:31] offset:0
	s_nop 0
	s_mov_b32 m0, s53
	s_nop 0
	global_load_lds_dwordx4 v144, s[30:31] offset:0
	s_add_u32 s30, s58, 0x80100
	s_addc_u32 s31, s59, 0
	s_mov_b32 m0, s55
	s_nop 0
	global_load_lds_dwordx4 v142, s[30:31] offset:0
	s_nop 0
	s_mov_b32 m0, s68
	s_nop 0
	global_load_lds_dwordx4 v144, s[30:31] offset:0
	s_nop 0
	s_mov_b32 m0, s33
	s_nop 0
	global_load_lds_dwordx4 v1, s[44:45] offset:0
	s_nop 0
	s_mov_b32 m0, s69
	s_nop 0
	global_load_lds_dwordx4 v143, s[44:45] offset:0
	s_waitcnt vmcnt(24)
	s_waitcnt lgkmcnt(0)
	s_barrier
	s_setprio 1
	v_mfma_f32_16x16x32_bf16 v[138:141], v[4:7], v[64:67], 0
	v_mfma_f32_16x16x32_bf16 v[156:159], v[4:7], v[96:99], 0
	v_mfma_f32_16x16x32_bf16 v[164:167], v[4:7], v[114:117], 0
	v_mfma_f32_16x16x32_bf16 v[4:7], v[4:7], v[126:129], 0
	v_mfma_f32_16x16x32_bf16 v[138:141], v[8:11], v[92:95], v[138:141]
	v_mfma_f32_16x16x32_bf16 v[156:159], v[8:11], v[110:113], v[156:159]
	v_mfma_f32_16x16x32_bf16 v[164:167], v[8:11], v[122:125], v[164:167]
	v_mfma_f32_16x16x32_bf16 v[4:7], v[8:11], v[130:133], v[4:7]
	v_mfma_f32_16x16x32_bf16 v[8:11], v[12:15], v[126:129], 0
	v_mfma_f32_16x16x32_bf16 v[152:155], v[12:15], v[64:67], 0
	v_mfma_f32_16x16x32_bf16 v[160:163], v[12:15], v[96:99], 0
	v_mfma_f32_16x16x32_bf16 v[168:171], v[12:15], v[114:117], 0
	v_mfma_f32_16x16x32_bf16 v[8:11], v[16:19], v[130:133], v[8:11]
	v_mfma_f32_16x16x32_bf16 v[152:155], v[16:19], v[92:95], v[152:155]
	v_mfma_f32_16x16x32_bf16 v[160:163], v[16:19], v[110:113], v[160:163]
	v_mfma_f32_16x16x32_bf16 v[168:171], v[16:19], v[122:125], v[168:171]
	v_mfma_f32_16x16x32_bf16 v[12:15], v[20:23], v[64:67], 0
	v_mfma_f32_16x16x32_bf16 v[172:175], v[24:27], v[92:95], v[12:15]
	v_mfma_f32_16x16x32_bf16 v[12:15], v[28:31], v[64:67], 0
	v_mfma_f32_16x16x32_bf16 v[176:179], v[32:35], v[92:95], v[12:15]
	v_mfma_f32_16x16x32_bf16 v[12:15], v[20:23], v[96:99], 0
	v_mfma_f32_16x16x32_bf16 v[180:183], v[24:27], v[110:113], v[12:15]
	v_mfma_f32_16x16x32_bf16 v[12:15], v[28:31], v[96:99], 0
	v_mfma_f32_16x16x32_bf16 v[184:187], v[32:35], v[110:113], v[12:15]
	v_mfma_f32_16x16x32_bf16 v[12:15], v[20:23], v[114:117], 0
	v_mfma_f32_16x16x32_bf16 v[188:191], v[24:27], v[122:125], v[12:15]
	v_mfma_f32_16x16x32_bf16 v[12:15], v[28:31], v[114:117], 0
	v_mfma_f32_16x16x32_bf16 v[192:195], v[32:35], v[122:125], v[12:15]
	v_mfma_f32_16x16x32_bf16 v[12:15], v[20:23], v[126:129], 0
	v_mfma_f32_16x16x32_bf16 v[196:199], v[24:27], v[130:133], v[12:15]
	v_mfma_f32_16x16x32_bf16 v[12:15], v[28:31], v[126:129], 0
	v_mfma_f32_16x16x32_bf16 v[200:203], v[32:35], v[130:133], v[12:15]
	s_barrier
; #define PG8_KSETUP() const bool last = (t == nt - 2); const char* a1 = cA + (size_t)(t + 1) * kstep; \
;             const char* a2 = last ? nA : cA + (size_t)(t + 2) * kstep; const char* b2 = last ? nB : cB + (size_t)(t + 2) * kstep; const char* a3 = a2 + kstep; const char* b3 = b2 + kstep; \
;             if (last && has_next) S.a_ready(nxt)
; template <class Epi, class Sched, bool ALIGN_EPI = false, bool SP2 = false>
; __device__ __forceinline__ void gemm_phase(PG8_LAS unsigned char* lds, const Gemm g, const Sched& S, const Epi& E) {
;     ...
;         int t0 = 0;
;         if constexpr (SP2 && Epi::NVM == 16) { if (ui > 0) { const int t = 0; PG8_KSETUP(); PG8_KITER_SP2(24, 24); t0 = 2; } }
	s_setprio 0
	s_nop 4
	ds_read_b128 v[12:15], v150
	ds_read_b128 v[16:19], v150 offset:1024
	ds_read_b128 v[22:25], v150 offset:2048
	ds_read_b128 v[26:29], v150 offset:3072
	ds_read_b128 v[204:207], v151
	ds_read_b128 v[208:211], v151 offset:1024
	ds_read_b128 v[212:215], v151 offset:2048
	ds_read_b128 v[216:219], v151 offset:3072
	ds_read_b128 v[30:33], v149 offset:32768
	ds_read_b128 v[64:67], v149 offset:33792
	ds_read_b128 v[220:223], v149 offset:34816
	ds_read_b128 v[224:227], v149 offset:35840
	ds_read_b128 v[228:231], v149 offset:36864
	ds_read_b128 v[232:235], v149 offset:37888
	ds_read_b128 v[236:239], v149 offset:38912
	ds_read_b128 v[240:243], v149 offset:39936
	s_add_u32 s30, s56, 0x80100
	s_addc_u32 s31, s57, 0
	s_mov_b32 m0, s70
	s_nop 0
	global_load_lds_dwordx4 v1, s[30:31] offset:0
	s_nop 0
	s_mov_b32 m0, s71
	s_nop 0
	global_load_lds_dwordx4 v143, s[30:31] offset:0
	s_waitcnt vmcnt(8)
	s_waitcnt lgkmcnt(0)
	s_barrier
	s_setprio 1
	v_mfma_f32_16x16x32_bf16 v[68:71], v[12:15], v[30:33], v[68:71]
	v_mfma_f32_16x16x32_bf16 v[130:133], v[16:19], v[64:67], v[68:71]
	v_mfma_f32_16x16x32_bf16 v[68:71], v[22:25], v[30:33], v[72:75]
	v_mfma_f32_16x16x32_bf16 v[126:129], v[26:29], v[64:67], v[68:71]
	v_mfma_f32_16x16x32_bf16 v[68:71], v[12:15], v[220:223], v[76:79]
	v_mfma_f32_16x16x32_bf16 v[114:117], v[16:19], v[224:227], v[68:71]
	v_mfma_f32_16x16x32_bf16 v[68:71], v[22:25], v[220:223], v[80:83]
	v_mfma_f32_16x16x32_bf16 v[110:113], v[26:29], v[224:227], v[68:71]
	v_mfma_f32_16x16x32_bf16 v[68:71], v[12:15], v[228:231], v[84:87]
	v_mfma_f32_16x16x32_bf16 v[98:101], v[16:19], v[232:235], v[68:71]
	v_mfma_f32_16x16x32_bf16 v[68:71], v[22:25], v[228:231], v[88:91]
	v_mfma_f32_16x16x32_bf16 v[94:97], v[26:29], v[232:235], v[68:71]
	v_mfma_f32_16x16x32_bf16 v[68:71], v[12:15], v[236:239], v[102:105]
	v_mfma_f32_16x16x32_bf16 v[82:85], v[16:19], v[240:243], v[68:71]
	v_mfma_f32_16x16x32_bf16 v[68:71], v[22:25], v[236:239], v[106:109]
	v_mfma_f32_16x16x32_bf16 v[78:81], v[26:29], v[240:243], v[68:71]
	v_mfma_f32_16x16x32_bf16 v[68:71], v[204:207], v[30:33], v[118:121]
	v_mfma_f32_16x16x32_bf16 v[30:33], v[212:215], v[30:33], v[36:39]
	v_mfma_f32_16x16x32_bf16 v[118:121], v[216:219], v[64:67], v[30:33]
	v_mfma_f32_16x16x32_bf16 v[30:33], v[204:207], v[220:223], v[40:43]
	v_mfma_f32_16x16x32_bf16 v[106:109], v[208:211], v[224:227], v[30:33]
	v_mfma_f32_16x16x32_bf16 v[30:33], v[212:215], v[220:223], v[44:47]
	v_mfma_f32_16x16x32_bf16 v[102:105], v[216:219], v[224:227], v[30:33]
	v_mfma_f32_16x16x32_bf16 v[30:33], v[204:207], v[228:231], v[48:51]
	v_mfma_f32_16x16x32_bf16 v[90:93], v[208:211], v[232:235], v[30:33]
	v_mfma_f32_16x16x32_bf16 v[30:33], v[212:215], v[228:231], v[52:55]
	v_mfma_f32_16x16x32_bf16 v[86:89], v[216:219], v[232:235], v[30:33]
	v_mfma_f32_16x16x32_bf16 v[30:33], v[204:207], v[236:239], v[56:59]
	v_mfma_f32_16x16x32_bf16 v[74:77], v[208:211], v[240:243], v[30:33]
	v_mfma_f32_16x16x32_bf16 v[30:33], v[212:215], v[236:239], v[60:63]
	v_mfma_f32_16x16x32_bf16 v[122:125], v[208:211], v[64:67], v[68:71]
	v_mfma_f32_16x16x32_bf16 v[70:73], v[216:219], v[240:243], v[30:33]
	s_barrier
	s_setprio 0
	ds_read_b128 v[38:41], v149 offset:49152
	ds_read_b128 v[42:45], v149 offset:50176
	ds_read_b128 v[220:223], v149 offset:51200
	ds_read_b128 v[224:227], v149 offset:52224
	ds_read_b128 v[228:231], v149 offset:53248
	ds_read_b128 v[232:235], v149 offset:54272
	ds_read_b128 v[236:239], v149 offset:55296
	ds_read_b128 v[240:243], v149 offset:56320
	s_add_u32 s30, s58, 0x180
	s_addc_u32 s31, s59, 0
	s_mov_b32 m0, s75
	s_nop 0
	global_load_lds_dwordx4 v142, s[30:31] offset:0
	s_nop 0
	s_mov_b32 m0, s76
	s_nop 0
	global_load_lds_dwordx4 v144, s[30:31] offset:0
	s_add_u32 s30, s58, 0x80180
	s_addc_u32 s31, s59, 0
	s_mov_b32 m0, s79
	s_nop 0
	global_load_lds_dwordx4 v142, s[30:31] offset:0
	s_nop 0
	s_mov_b32 m0, s80
	s_nop 0
	global_load_lds_dwordx4 v144, s[30:31] offset:0
	s_nop 0
	s_mov_b32 m0, s77
	s_nop 0
	global_load_lds_dwordx4 v1, s[40:41] offset:0
	s_nop 0
	s_mov_b32 m0, s78
	s_nop 0
	global_load_lds_dwordx4 v143, s[40:41] offset:0
	s_waitcnt vmcnt(8)
	s_waitcnt lgkmcnt(0)
	s_barrier
	s_setprio 1
	v_mfma_f32_16x16x32_bf16 v[30:33], v[12:15], v[38:41], v[138:141]
	v_mfma_f32_16x16x32_bf16 v[66:69], v[16:19], v[42:45], v[30:33]
	v_mfma_f32_16x16x32_bf16 v[30:33], v[22:25], v[38:41], v[152:155]
	v_mfma_f32_16x16x32_bf16 v[62:65], v[26:29], v[42:45], v[30:33]
	v_mfma_f32_16x16x32_bf16 v[30:33], v[12:15], v[220:223], v[156:159]
	v_mfma_f32_16x16x32_bf16 v[50:53], v[16:19], v[224:227], v[30:33]
	v_mfma_f32_16x16x32_bf16 v[30:33], v[22:25], v[220:223], v[160:163]
	v_mfma_f32_16x16x32_bf16 v[46:49], v[26:29], v[224:227], v[30:33]
	v_mfma_f32_16x16x32_bf16 v[30:33], v[12:15], v[228:231], v[164:167]
	v_mfma_f32_16x16x32_bf16 v[4:7], v[12:15], v[236:239], v[4:7]
	v_mfma_f32_16x16x32_bf16 v[34:37], v[16:19], v[232:235], v[30:33]
	v_mfma_f32_16x16x32_bf16 v[30:33], v[22:25], v[228:231], v[168:171]
	v_mfma_f32_16x16x32_bf16 v[18:21], v[16:19], v[240:243], v[4:7]
	v_mfma_f32_16x16x32_bf16 v[4:7], v[22:25], v[236:239], v[8:11]
	v_mfma_f32_16x16x32_bf16 v[30:33], v[26:29], v[232:235], v[30:33]
	v_mfma_f32_16x16x32_bf16 v[14:17], v[26:29], v[240:243], v[4:7]
	v_mfma_f32_16x16x32_bf16 v[4:7], v[204:207], v[38:41], v[172:175]
	v_mfma_f32_16x16x32_bf16 v[58:61], v[208:211], v[42:45], v[4:7]
	v_mfma_f32_16x16x32_bf16 v[4:7], v[212:215], v[38:41], v[176:179]
	v_mfma_f32_16x16x32_bf16 v[54:57], v[216:219], v[42:45], v[4:7]
	v_mfma_f32_16x16x32_bf16 v[4:7], v[204:207], v[220:223], v[180:183]
	v_mfma_f32_16x16x32_bf16 v[42:45], v[208:211], v[224:227], v[4:7]
	v_mfma_f32_16x16x32_bf16 v[4:7], v[212:215], v[220:223], v[184:187]
	v_mfma_f32_16x16x32_bf16 v[38:41], v[216:219], v[224:227], v[4:7]
	v_mfma_f32_16x16x32_bf16 v[4:7], v[204:207], v[228:231], v[188:191]
	v_mfma_f32_16x16x32_bf16 v[26:29], v[208:211], v[232:235], v[4:7]
	v_mfma_f32_16x16x32_bf16 v[4:7], v[212:215], v[228:231], v[192:195]
	v_mfma_f32_16x16x32_bf16 v[22:25], v[216:219], v[232:235], v[4:7]
	v_mfma_f32_16x16x32_bf16 v[4:7], v[204:207], v[236:239], v[196:199]
	v_mfma_f32_16x16x32_bf16 v[10:13], v[208:211], v[240:243], v[4:7]
	v_mfma_f32_16x16x32_bf16 v[4:7], v[212:215], v[236:239], v[200:203]
	v_mfma_f32_16x16x32_bf16 v[6:9], v[216:219], v[240:243], v[4:7]
	s_barrier
	s_setprio 0
	s_mov_b32 s64, 2
	s_branch .LBB0_627

; #define PG8_KSETUP() const bool last = (t == nt - 2); const char* a1 = cA + (size_t)(t + 1) * kstep; \
;             const char* a2 = last ? nA : cA + (size_t)(t + 2) * kstep; const char* b2 = last ? nB : cB + (size_t)(t + 2) * kstep; const char* a3 = a2 + kstep; const char* b3 = b2 + kstep; \
;             if (last && has_next) S.a_ready(nxt)
; template <class Epi, class Sched, bool ALIGN_EPI = false, bool SP2 = false>
; __device__ __forceinline__ void gemm_phase(PG8_LAS unsigned char* lds, const Gemm g, const Sched& S, const Epi& E) {
;     ...
;         int t0 = 0;
;         if constexpr (SP2 && Epi::NVM == 16) { if (ui > 0) { const int t = 0; PG8_KSETUP(); PG8_KITER_SP2(24, 24); t0 = 2; } }
;         if constexpr (SP2 && Epi::NVM == 8) { if (ui > 0) { const int t = 0; PG8_KSETUP(); PG8_KITER_SP2(16, 16); t0 = 2; } }
;         for (int t = t0; t < nt; t += 2) {
;             PG8_KSETUP();
;             if constexpr (SP2) {
;             PG8_KITER_SP2(8, 8);
.LBB0_628:
	ds_read_b128 v[138:141], v147
	ds_read_b128 v[152:155], v147 offset:1024
	ds_read_b128 v[156:159], v147 offset:2048
	ds_read_b128 v[160:163], v147 offset:3072
	ds_read_b128 v[164:167], v148
	ds_read_b128 v[168:171], v148 offset:1024
	ds_read_b128 v[172:175], v148 offset:2048
	ds_read_b128 v[176:179], v148 offset:3072
	s_cmp_eq_u32 s88, 28
	s_cselect_b32 s66, s47, s91
	s_cselect_b32 s67, s39, s92
	s_cselect_b32 s64, s87, s89
	s_cselect_b32 s65, s37, s90
	s_add_u32 s58, s66, 0x80
	s_addc_u32 s59, s67, 0
	ds_read_b128 v[180:183], v149
	ds_read_b128 v[184:187], v149 offset:1024
	ds_read_b128 v[188:191], v149 offset:2048
	ds_read_b128 v[192:195], v149 offset:3072
	ds_read_b128 v[196:199], v149 offset:4096
	ds_read_b128 v[200:203], v149 offset:5120
	ds_read_b128 v[204:207], v149 offset:6144
	ds_read_b128 v[208:211], v149 offset:7168
	s_mov_b32 m0, s81
	s_nop 0
	global_load_lds_dwordx4 v1, s[56:57] offset:0
	s_nop 0
	s_mov_b32 m0, s82
	s_nop 0
	global_load_lds_dwordx4 v143, s[56:57] offset:0
	s_waitcnt vmcnt(8)
	s_waitcnt lgkmcnt(0)
	s_barrier
	s_setprio 1
	v_mfma_f32_16x16x32_bf16 v[130:133], v[138:141], v[180:183], v[130:133]
	v_mfma_f32_16x16x32_bf16 v[130:133], v[152:155], v[184:187], v[130:133]
	v_mfma_f32_16x16x32_bf16 v[126:129], v[156:159], v[180:183], v[126:129]
	v_mfma_f32_16x16x32_bf16 v[126:129], v[160:163], v[184:187], v[126:129]
	v_mfma_f32_16x16x32_bf16 v[114:117], v[138:141], v[188:191], v[114:117]
	v_mfma_f32_16x16x32_bf16 v[114:117], v[152:155], v[192:195], v[114:117]
	v_mfma_f32_16x16x32_bf16 v[110:113], v[156:159], v[188:191], v[110:113]
	v_mfma_f32_16x16x32_bf16 v[110:113], v[160:163], v[192:195], v[110:113]
	v_mfma_f32_16x16x32_bf16 v[98:101], v[138:141], v[196:199], v[98:101]
	v_mfma_f32_16x16x32_bf16 v[98:101], v[152:155], v[200:203], v[98:101]
	v_mfma_f32_16x16x32_bf16 v[94:97], v[156:159], v[196:199], v[94:97]
	v_mfma_f32_16x16x32_bf16 v[94:97], v[160:163], v[200:203], v[94:97]
	v_mfma_f32_16x16x32_bf16 v[82:85], v[138:141], v[204:207], v[82:85]
	v_mfma_f32_16x16x32_bf16 v[82:85], v[152:155], v[208:211], v[82:85]
	v_mfma_f32_16x16x32_bf16 v[78:81], v[156:159], v[204:207], v[78:81]
	v_mfma_f32_16x16x32_bf16 v[78:81], v[160:163], v[208:211], v[78:81]
	v_mfma_f32_16x16x32_bf16 v[122:125], v[164:167], v[180:183], v[122:125]
	v_mfma_f32_16x16x32_bf16 v[122:125], v[168:171], v[184:187], v[122:125]
	v_mfma_f32_16x16x32_bf16 v[118:121], v[172:175], v[180:183], v[118:121]
	v_mfma_f32_16x16x32_bf16 v[118:121], v[176:179], v[184:187], v[118:121]
	v_mfma_f32_16x16x32_bf16 v[106:109], v[164:167], v[188:191], v[106:109]
	v_mfma_f32_16x16x32_bf16 v[106:109], v[168:171], v[192:195], v[106:109]
	v_mfma_f32_16x16x32_bf16 v[102:105], v[172:175], v[188:191], v[102:105]
	v_mfma_f32_16x16x32_bf16 v[102:105], v[176:179], v[192:195], v[102:105]
	v_mfma_f32_16x16x32_bf16 v[90:93], v[164:167], v[196:199], v[90:93]
	v_mfma_f32_16x16x32_bf16 v[90:93], v[168:171], v[200:203], v[90:93]
	v_mfma_f32_16x16x32_bf16 v[86:89], v[172:175], v[196:199], v[86:89]
	v_mfma_f32_16x16x32_bf16 v[86:89], v[176:179], v[200:203], v[86:89]
	v_mfma_f32_16x16x32_bf16 v[74:77], v[164:167], v[204:207], v[74:77]
	v_mfma_f32_16x16x32_bf16 v[74:77], v[168:171], v[208:211], v[74:77]
	v_mfma_f32_16x16x32_bf16 v[70:73], v[172:175], v[204:207], v[70:73]
	v_mfma_f32_16x16x32_bf16 v[70:73], v[176:179], v[208:211], v[70:73]
	s_barrier
	s_setprio 0
	ds_read_b128 v[180:183], v149 offset:16384
	ds_read_b128 v[184:187], v149 offset:17408
	ds_read_b128 v[188:191], v149 offset:18432
	ds_read_b128 v[192:195], v149 offset:19456
	ds_read_b128 v[196:199], v149 offset:20480
	ds_read_b128 v[200:203], v149 offset:21504
	ds_read_b128 v[204:207], v149 offset:22528
	ds_read_b128 v[208:211], v149 offset:23552
	s_mov_b32 m0, s52
	s_nop 0
	global_load_lds_dwordx4 v142, s[64:65] offset:0
	s_add_u32 s30, s64, 0x80000
	s_mov_b32 m0, s53
	s_nop 0
	global_load_lds_dwordx4 v144, s[64:65] offset:0
	s_addc_u32 s31, s65, 0
	s_mov_b32 m0, s55
	s_nop 0
	global_load_lds_dwordx4 v142, s[30:31] offset:0
	s_nop 0
	s_mov_b32 m0, s68
	s_nop 0
	global_load_lds_dwordx4 v144, s[30:31] offset:0
	s_nop 0
	s_mov_b32 m0, s33
	s_nop 0
	global_load_lds_dwordx4 v1, s[66:67] offset:0
	s_nop 0
	s_mov_b32 m0, s69
	s_nop 0
	global_load_lds_dwordx4 v143, s[66:67] offset:0
	s_waitcnt vmcnt(8)
	s_waitcnt lgkmcnt(0)
	s_barrier
	s_setprio 1
	v_mfma_f32_16x16x32_bf16 v[66:69], v[138:141], v[180:183], v[66:69]
	v_mfma_f32_16x16x32_bf16 v[66:69], v[152:155], v[184:187], v[66:69]
	v_mfma_f32_16x16x32_bf16 v[62:65], v[156:159], v[180:183], v[62:65]
	v_mfma_f32_16x16x32_bf16 v[62:65], v[160:163], v[184:187], v[62:65]
	v_mfma_f32_16x16x32_bf16 v[50:53], v[138:141], v[188:191], v[50:53]
	v_mfma_f32_16x16x32_bf16 v[50:53], v[152:155], v[192:195], v[50:53]
	v_mfma_f32_16x16x32_bf16 v[46:49], v[156:159], v[188:191], v[46:49]
	v_mfma_f32_16x16x32_bf16 v[46:49], v[160:163], v[192:195], v[46:49]
	v_mfma_f32_16x16x32_bf16 v[34:37], v[138:141], v[196:199], v[34:37]
	v_mfma_f32_16x16x32_bf16 v[34:37], v[152:155], v[200:203], v[34:37]
	v_mfma_f32_16x16x32_bf16 v[30:33], v[156:159], v[196:199], v[30:33]
	v_mfma_f32_16x16x32_bf16 v[30:33], v[160:163], v[200:203], v[30:33]
	v_mfma_f32_16x16x32_bf16 v[18:21], v[138:141], v[204:207], v[18:21]
	v_mfma_f32_16x16x32_bf16 v[18:21], v[152:155], v[208:211], v[18:21]
	v_mfma_f32_16x16x32_bf16 v[14:17], v[156:159], v[204:207], v[14:17]
	v_mfma_f32_16x16x32_bf16 v[14:17], v[160:163], v[208:211], v[14:17]
	v_mfma_f32_16x16x32_bf16 v[58:61], v[164:167], v[180:183], v[58:61]
	v_mfma_f32_16x16x32_bf16 v[54:57], v[172:175], v[180:183], v[54:57]
	v_mfma_f32_16x16x32_bf16 v[42:45], v[164:167], v[188:191], v[42:45]
	v_mfma_f32_16x16x32_bf16 v[38:41], v[172:175], v[188:191], v[38:41]
	v_mfma_f32_16x16x32_bf16 v[26:29], v[164:167], v[196:199], v[26:29]
	v_mfma_f32_16x16x32_bf16 v[22:25], v[172:175], v[196:199], v[22:25]
	v_mfma_f32_16x16x32_bf16 v[10:13], v[164:167], v[204:207], v[10:13]
	v_mfma_f32_16x16x32_bf16 v[4:7], v[172:175], v[204:207], v[6:9]
	v_mfma_f32_16x16x32_bf16 v[58:61], v[168:171], v[184:187], v[58:61]
	v_mfma_f32_16x16x32_bf16 v[54:57], v[176:179], v[184:187], v[54:57]
	v_mfma_f32_16x16x32_bf16 v[42:45], v[168:171], v[192:195], v[42:45]
	v_mfma_f32_16x16x32_bf16 v[38:41], v[176:179], v[192:195], v[38:41]
	v_mfma_f32_16x16x32_bf16 v[26:29], v[168:171], v[200:203], v[26:29]
	v_mfma_f32_16x16x32_bf16 v[22:25], v[176:179], v[200:203], v[22:25]
	v_mfma_f32_16x16x32_bf16 v[10:13], v[168:171], v[208:211], v[10:13]
	v_mfma_f32_16x16x32_bf16 v[4:7], v[176:179], v[208:211], v[4:7]
	s_barrier
; #define PG8_STAGE(bufoff, gbase, voff) PG8_STAGEI(bufoff, gbase, 0, voff)
; #define PG8_LDA(dst, b, h) do { _Pragma("unroll") for (int m = 0; m < 4; ++m) _Pragma("unroll") for (int k = 0; k < 2; ++k) dst[m][k] = *(const PG8_LAS bf16x8*)(lds + PG8_SA(b, h) + aoff + m * 2048 + k * 1024); } while (0)
; #define PG8_WAIT_V(n) asm volatile("s_waitcnt vmcnt(" #n ")" ::: "memory")
; #define PG8_BAR __builtin_amdgcn_s_barrier()
; template <class Epi, class Sched, bool ALIGN_EPI = false, bool SP2 = false>
; __device__ __forceinline__ void gemm_phase(PG8_LAS unsigned char* lds, const Gemm g, const Sched& S, const Epi& E) {
;     ...
;         int t0 = 0;
;         if constexpr (SP2 && Epi::NVM == 16) { if (ui > 0) { const int t = 0; PG8_KSETUP(); PG8_KITER_SP2(24, 24); t0 = 2; } }
;         if constexpr (SP2 && Epi::NVM == 8) { if (ui > 0) { const int t = 0; PG8_KSETUP(); PG8_KITER_SP2(16, 16); t0 = 2; } }
;         for (int t = t0; t < nt; t += 2) {
;             PG8_KSETUP();
;             if constexpr (SP2) {
;             PG8_KITER_SP2(8, 8);
;             } else {
;             PG8_LDB(B0, 0, 0); PG8_SCHED; PG8_LDA(At, 0, 0); PG8_STAGE(PG8_SA(1, 1), a1 + hstep, voffA);
;             PG8_WAIT_L(8); PG8_BAR; PG8_WAIT_L(0); PG8_MMA(0, 0, At, B0); PG8_BAR; PG8_SCHED;
;             PG8_LDB(B1, 0, 1); PG8_STAGE(PG8_SB(0, 0), b2, voffB);
;             PG8_BAR; PG8_WAIT_L(0); PG8_MMA(0, 1, At, B1); PG8_BAR;
;             PG8_LDA(At, 0, 1); PG8_STAGE(PG8_SA(0, 0), a2, voffA);
;             PG8_BAR; PG8_WAIT_L(0); PG8_MMA(1, 0, At, B0); PG8_BAR; PG8_SCHED;
;             PG8_STAGE(PG8_SB(0, 1), b2 + hstep, voffB);
;             PG8_WAIT_V(6); PG8_BAR; PG8_MMA(1, 1, At, B1); PG8_BAR;
;             PG8_LDB(B0, 1, 0); PG8_SCHED; PG8_LDA(At, 1, 0); PG8_STAGE(PG8_SA(0, 1), a2 + hstep, voffA);
;             PG8_WAIT_L(8); PG8_BAR; PG8_WAIT_L(0); PG8_MMA(0, 0, At, B0); PG8_BAR; PG8_SCHED;
;             PG8_LDB(B1, 1, 1); PG8_STAGE(PG8_SB(1, 0), b3, voffB);
;             PG8_BAR; PG8_WAIT_L(0); PG8_MMA(0, 1, At, B1); PG8_BAR;
;             PG8_LDA(At, 1, 1); PG8_STAGE(PG8_SA(1, 0), a3, voffA);
;             PG8_BAR; PG8_WAIT_L(0); PG8_MMA(1, 0, At, B0); PG8_BAR; PG8_SCHED;
;             PG8_STAGE(PG8_SB(1, 1), b3 + hstep, voffB);
;             PG8_WAIT_V(6); PG8_BAR; PG8_MMA(1, 1, At, B1); PG8_BAR;
;             }
;         }
;     ...
;         if constexpr (ALIGN_EPI) { if (wr == 0) PG8_BAR; }
	s_setprio 0
	ds_read_b128 v[138:141], v150
	ds_read_b128 v[152:155], v150 offset:1024
	ds_read_b128 v[156:159], v150 offset:2048
	ds_read_b128 v[160:163], v150 offset:3072
	ds_read_b128 v[164:167], v151
	ds_read_b128 v[168:171], v151 offset:1024
	ds_read_b128 v[172:175], v151 offset:2048
	ds_read_b128 v[176:179], v151 offset:3072
	ds_read_b128 v[180:183], v149 offset:32768
	ds_read_b128 v[184:187], v149 offset:33792
	ds_read_b128 v[188:191], v149 offset:34816
	ds_read_b128 v[192:195], v149 offset:35840
	ds_read_b128 v[196:199], v149 offset:36864
	ds_read_b128 v[200:203], v149 offset:37888
	ds_read_b128 v[204:207], v149 offset:38912
	ds_read_b128 v[208:211], v149 offset:39936
	s_add_u32 s30, s66, 0x80000
	s_addc_u32 s31, s67, 0
	s_mov_b32 m0, s70
	s_nop 0
	global_load_lds_dwordx4 v1, s[30:31] offset:0
	s_nop 0
	s_mov_b32 m0, s71
	s_nop 0
	global_load_lds_dwordx4 v143, s[30:31] offset:0
	s_waitcnt vmcnt(8)
	s_waitcnt lgkmcnt(0)
	s_barrier
	s_setprio 1
	v_mfma_f32_16x16x32_bf16 v[130:133], v[138:141], v[180:183], v[130:133]
	v_mfma_f32_16x16x32_bf16 v[130:133], v[152:155], v[184:187], v[130:133]
	v_mfma_f32_16x16x32_bf16 v[126:129], v[156:159], v[180:183], v[126:129]
	v_mfma_f32_16x16x32_bf16 v[126:129], v[160:163], v[184:187], v[126:129]
	v_mfma_f32_16x16x32_bf16 v[114:117], v[138:141], v[188:191], v[114:117]
	v_mfma_f32_16x16x32_bf16 v[114:117], v[152:155], v[192:195], v[114:117]
	v_mfma_f32_16x16x32_bf16 v[110:113], v[156:159], v[188:191], v[110:113]
	v_mfma_f32_16x16x32_bf16 v[110:113], v[160:163], v[192:195], v[110:113]
	v_mfma_f32_16x16x32_bf16 v[98:101], v[138:141], v[196:199], v[98:101]
	v_mfma_f32_16x16x32_bf16 v[98:101], v[152:155], v[200:203], v[98:101]
	v_mfma_f32_16x16x32_bf16 v[94:97], v[156:159], v[196:199], v[94:97]
	v_mfma_f32_16x16x32_bf16 v[94:97], v[160:163], v[200:203], v[94:97]
	v_mfma_f32_16x16x32_bf16 v[82:85], v[138:141], v[204:207], v[82:85]
	v_mfma_f32_16x16x32_bf16 v[82:85], v[152:155], v[208:211], v[82:85]
	v_mfma_f32_16x16x32_bf16 v[78:81], v[156:159], v[204:207], v[78:81]
	v_mfma_f32_16x16x32_bf16 v[78:81], v[160:163], v[208:211], v[78:81]
	v_mfma_f32_16x16x32_bf16 v[122:125], v[164:167], v[180:183], v[122:125]
	v_mfma_f32_16x16x32_bf16 v[122:125], v[168:171], v[184:187], v[122:125]
	v_mfma_f32_16x16x32_bf16 v[118:121], v[172:175], v[180:183], v[118:121]
	v_mfma_f32_16x16x32_bf16 v[118:121], v[176:179], v[184:187], v[118:121]
	v_mfma_f32_16x16x32_bf16 v[106:109], v[164:167], v[188:191], v[106:109]
	v_mfma_f32_16x16x32_bf16 v[106:109], v[168:171], v[192:195], v[106:109]
	v_mfma_f32_16x16x32_bf16 v[102:105], v[172:175], v[188:191], v[102:105]
	v_mfma_f32_16x16x32_bf16 v[102:105], v[176:179], v[192:195], v[102:105]
	v_mfma_f32_16x16x32_bf16 v[90:93], v[164:167], v[196:199], v[90:93]
	v_mfma_f32_16x16x32_bf16 v[90:93], v[168:171], v[200:203], v[90:93]
	v_mfma_f32_16x16x32_bf16 v[86:89], v[172:175], v[196:199], v[86:89]
	v_mfma_f32_16x16x32_bf16 v[86:89], v[176:179], v[200:203], v[86:89]
	v_mfma_f32_16x16x32_bf16 v[74:77], v[164:167], v[204:207], v[74:77]
	v_mfma_f32_16x16x32_bf16 v[74:77], v[168:171], v[208:211], v[74:77]
	v_mfma_f32_16x16x32_bf16 v[70:73], v[172:175], v[204:207], v[70:73]
	v_mfma_f32_16x16x32_bf16 v[70:73], v[176:179], v[208:211], v[70:73]
	s_barrier
	s_setprio 0
	ds_read_b128 v[180:183], v149 offset:49152
	ds_read_b128 v[184:187], v149 offset:50176
	ds_read_b128 v[188:191], v149 offset:51200
	ds_read_b128 v[192:195], v149 offset:52224
	ds_read_b128 v[196:199], v149 offset:53248
	ds_read_b128 v[200:203], v149 offset:54272
	ds_read_b128 v[204:207], v149 offset:55296
	ds_read_b128 v[208:211], v149 offset:56320
	s_add_u32 s30, s64, 0x80
	s_addc_u32 s31, s65, 0
	s_mov_b32 m0, s75
	s_nop 0
	global_load_lds_dwordx4 v142, s[30:31] offset:0
	s_nop 0
	s_mov_b32 m0, s76
	s_nop 0
	global_load_lds_dwordx4 v144, s[30:31] offset:0
	s_add_u32 s30, s64, 0x80080
	s_addc_u32 s31, s65, 0
	s_mov_b32 m0, s79
	s_nop 0
	global_load_lds_dwordx4 v142, s[30:31] offset:0
	s_nop 0
	s_mov_b32 m0, s80
	s_nop 0
	global_load_lds_dwordx4 v144, s[30:31] offset:0
	s_nop 0
	s_mov_b32 m0, s77
	s_nop 0
	global_load_lds_dwordx4 v1, s[58:59] offset:0
	s_nop 0
	s_mov_b32 m0, s78
	s_nop 0
	global_load_lds_dwordx4 v143, s[58:59] offset:0
	s_waitcnt vmcnt(8)
	s_waitcnt lgkmcnt(0)
	s_barrier
	s_setprio 1
	v_mfma_f32_16x16x32_bf16 v[66:69], v[138:141], v[180:183], v[66:69]
	v_mfma_f32_16x16x32_bf16 v[66:69], v[152:155], v[184:187], v[66:69]
	v_mfma_f32_16x16x32_bf16 v[62:65], v[156:159], v[180:183], v[62:65]
	v_mfma_f32_16x16x32_bf16 v[62:65], v[160:163], v[184:187], v[62:65]
	v_mfma_f32_16x16x32_bf16 v[50:53], v[138:141], v[188:191], v[50:53]
	v_mfma_f32_16x16x32_bf16 v[50:53], v[152:155], v[192:195], v[50:53]
	v_mfma_f32_16x16x32_bf16 v[46:49], v[156:159], v[188:191], v[46:49]
	v_mfma_f32_16x16x32_bf16 v[46:49], v[160:163], v[192:195], v[46:49]
	v_mfma_f32_16x16x32_bf16 v[34:37], v[138:141], v[196:199], v[34:37]
	v_mfma_f32_16x16x32_bf16 v[34:37], v[152:155], v[200:203], v[34:37]
	v_mfma_f32_16x16x32_bf16 v[30:33], v[156:159], v[196:199], v[30:33]
	v_mfma_f32_16x16x32_bf16 v[30:33], v[160:163], v[200:203], v[30:33]
	v_mfma_f32_16x16x32_bf16 v[18:21], v[138:141], v[204:207], v[18:21]
	v_mfma_f32_16x16x32_bf16 v[18:21], v[152:155], v[208:211], v[18:21]
	v_mfma_f32_16x16x32_bf16 v[14:17], v[156:159], v[204:207], v[14:17]
	v_mfma_f32_16x16x32_bf16 v[14:17], v[160:163], v[208:211], v[14:17]
	v_mfma_f32_16x16x32_bf16 v[58:61], v[164:167], v[180:183], v[58:61]
	v_mfma_f32_16x16x32_bf16 v[54:57], v[172:175], v[180:183], v[54:57]
	v_mfma_f32_16x16x32_bf16 v[42:45], v[164:167], v[188:191], v[42:45]
	v_mfma_f32_16x16x32_bf16 v[38:41], v[172:175], v[188:191], v[38:41]
	v_mfma_f32_16x16x32_bf16 v[26:29], v[164:167], v[196:199], v[26:29]
	v_mfma_f32_16x16x32_bf16 v[22:25], v[172:175], v[196:199], v[22:25]
	v_mfma_f32_16x16x32_bf16 v[8:11], v[164:167], v[204:207], v[10:13]
	v_mfma_f32_16x16x32_bf16 v[4:7], v[172:175], v[204:207], v[4:7]
	v_mfma_f32_16x16x32_bf16 v[58:61], v[168:171], v[184:187], v[58:61]
	v_mfma_f32_16x16x32_bf16 v[54:57], v[176:179], v[184:187], v[54:57]
	v_mfma_f32_16x16x32_bf16 v[42:45], v[168:171], v[192:195], v[42:45]
	v_mfma_f32_16x16x32_bf16 v[38:41], v[176:179], v[192:195], v[38:41]
	v_mfma_f32_16x16x32_bf16 v[26:29], v[168:171], v[200:203], v[26:29]
	v_mfma_f32_16x16x32_bf16 v[22:25], v[176:179], v[200:203], v[22:25]
	v_mfma_f32_16x16x32_bf16 v[10:13], v[168:171], v[208:211], v[8:11]
	v_mfma_f32_16x16x32_bf16 v[6:9], v[176:179], v[208:211], v[4:7]
	s_barrier
	s_setprio 0
	s_add_i32 s88, s88, 2
	s_add_u32 s89, s89, 0x100
	s_addc_u32 s90, s90, 0
	s_add_u32 s91, s91, 0x100
	s_addc_u32 s92, s92, 0
	s_add_u32 s56, s56, 0x100
	s_addc_u32 s57, s57, 0
	s_cmp_gt_u32 s88, 29
	s_cbranch_scc0 .LBB0_628
	s_and_b64 vcc, exec, s[20:21]
	s_cbranch_vccz .LBB0_631
	s_barrier

; #define PG8_KSETUP() const bool last = (t == nt - 2); const char* a1 = cA + (size_t)(t + 1) * kstep; \
;             const char* a2 = last ? nA : cA + (size_t)(t + 2) * kstep; const char* b2 = last ? nB : cB + (size_t)(t + 2) * kstep; const char* a3 = a2 + kstep; const char* b3 = b2 + kstep; \
;             if (last && has_next) S.a_ready(nxt)
; template <class Epi, class Sched, bool ALIGN_EPI = false, bool SP2 = false>
; __device__ __forceinline__ void gemm_phase(PG8_LAS unsigned char* lds, const Gemm g, const Sched& S, const Epi& E) {
;     ...
;         int t0 = 0;
;         if constexpr (SP2 && Epi::NVM == 16) { if (ui > 0) { const int t = 0; PG8_KSETUP(); PG8_KITER_SP2(24, 24); t0 = 2; } }
;         if constexpr (SP2 && Epi::NVM == 8) { if (ui > 0) { const int t = 0; PG8_KSETUP(); PG8_KITER_SP2(16, 16); t0 = 2; } }
.LBB0_783:
	s_cmp_lg_u32 s77, 0
	s_mov_b32 s44, 0
	s_cbranch_scc0 .LBB0_785
	ds_read_b128 v[4:7], v152
	ds_read_b128 v[8:11], v152 offset:1024
	ds_read_b128 v[12:15], v152 offset:2048
	ds_read_b128 v[16:19], v152 offset:3072
	ds_read_b128 v[20:23], v153
	ds_read_b128 v[24:27], v153 offset:1024
	ds_read_b128 v[28:31], v153 offset:2048
	ds_read_b128 v[32:35], v153 offset:3072
	s_add_u32 s28, s38, 0x100
	s_addc_u32 s29, s39, 0
	s_add_u32 s30, s40, 0x100
	s_addc_u32 s31, s41, 0
	s_add_u32 s24, s38, 0x180
	s_addc_u32 s25, s39, 0
	ds_read_b128 v[36:39], v154
	ds_read_b128 v[40:43], v154 offset:1024
	ds_read_b128 v[44:47], v154 offset:2048
	ds_read_b128 v[48:51], v154 offset:3072
	ds_read_b128 v[52:55], v154 offset:4096
	ds_read_b128 v[56:59], v154 offset:5120
	ds_read_b128 v[60:63], v154 offset:6144
	ds_read_b128 v[64:67], v154 offset:7168
	s_add_u32 s42, s38, 0x80080
	s_addc_u32 s43, s39, 0
	s_mov_b32 m0, s68
	s_nop 0
	global_load_lds_dwordx4 v1, s[42:43] offset:0
	s_nop 0
	s_mov_b32 m0, s69
	s_nop 0
	global_load_lds_dwordx4 v147, s[42:43] offset:0
	s_waitcnt vmcnt(16)
	s_waitcnt lgkmcnt(0)
	s_barrier
	s_setprio 1
	v_mfma_f32_16x16x32_bf16 v[92:95], v[4:7], v[60:63], 0
	v_mfma_f32_16x16x32_bf16 v[68:71], v[4:7], v[36:39], 0
	v_mfma_f32_16x16x32_bf16 v[72:75], v[12:15], v[36:39], 0
	v_mfma_f32_16x16x32_bf16 v[76:79], v[4:7], v[44:47], 0
	v_mfma_f32_16x16x32_bf16 v[80:83], v[12:15], v[44:47], 0
	v_mfma_f32_16x16x32_bf16 v[84:87], v[4:7], v[52:55], 0
	v_mfma_f32_16x16x32_bf16 v[88:91], v[12:15], v[52:55], 0
	v_mfma_f32_16x16x32_bf16 v[102:105], v[8:11], v[64:67], v[92:95]
	v_mfma_f32_16x16x32_bf16 v[92:95], v[12:15], v[60:63], 0
	v_mfma_f32_16x16x32_bf16 v[68:71], v[8:11], v[40:43], v[68:71]
	v_mfma_f32_16x16x32_bf16 v[72:75], v[16:19], v[40:43], v[72:75]
	v_mfma_f32_16x16x32_bf16 v[76:79], v[8:11], v[48:51], v[76:79]
	v_mfma_f32_16x16x32_bf16 v[80:83], v[16:19], v[48:51], v[80:83]
	v_mfma_f32_16x16x32_bf16 v[84:87], v[8:11], v[56:59], v[84:87]
	v_mfma_f32_16x16x32_bf16 v[88:91], v[16:19], v[56:59], v[88:91]
	v_mfma_f32_16x16x32_bf16 v[106:109], v[16:19], v[64:67], v[92:95]
	v_mfma_f32_16x16x32_bf16 v[92:95], v[20:23], v[36:39], 0
	v_mfma_f32_16x16x32_bf16 v[36:39], v[28:31], v[36:39], 0
	v_mfma_f32_16x16x32_bf16 v[118:121], v[24:27], v[40:43], v[92:95]
	v_mfma_f32_16x16x32_bf16 v[36:39], v[32:35], v[40:43], v[36:39]
	v_mfma_f32_16x16x32_bf16 v[40:43], v[20:23], v[44:47], 0
	v_mfma_f32_16x16x32_bf16 v[44:47], v[28:31], v[44:47], 0
	v_mfma_f32_16x16x32_bf16 v[40:43], v[24:27], v[48:51], v[40:43]
	v_mfma_f32_16x16x32_bf16 v[44:47], v[32:35], v[48:51], v[44:47]
	v_mfma_f32_16x16x32_bf16 v[48:51], v[20:23], v[52:55], 0
	v_mfma_f32_16x16x32_bf16 v[52:55], v[28:31], v[52:55], 0
	v_mfma_f32_16x16x32_bf16 v[48:51], v[24:27], v[56:59], v[48:51]
	v_mfma_f32_16x16x32_bf16 v[52:55], v[32:35], v[56:59], v[52:55]
	v_mfma_f32_16x16x32_bf16 v[56:59], v[20:23], v[60:63], 0
	v_mfma_f32_16x16x32_bf16 v[60:63], v[28:31], v[60:63], 0
	v_mfma_f32_16x16x32_bf16 v[56:59], v[24:27], v[64:67], v[56:59]
	v_mfma_f32_16x16x32_bf16 v[60:63], v[32:35], v[64:67], v[60:63]
	s_barrier
	s_setprio 0
	ds_read_b128 v[64:67], v154 offset:16384
	ds_read_b128 v[92:95], v154 offset:17408
	ds_read_b128 v[96:99], v154 offset:18432
	ds_read_b128 v[110:113], v154 offset:19456
	ds_read_b128 v[114:117], v154 offset:20480
	ds_read_b128 v[122:125], v154 offset:21504
	ds_read_b128 v[126:129], v154 offset:22528
	ds_read_b128 v[130:133], v154 offset:23552
	s_mov_b32 m0, s37
	s_nop 0
	global_load_lds_dwordx4 v146, s[30:31] offset:0
	s_nop 0
	s_mov_b32 m0, s52
	s_nop 0
	global_load_lds_dwordx4 v148, s[30:31] offset:0
	s_add_u32 s30, s40, 0x80100
	s_addc_u32 s31, s41, 0
	s_mov_b32 m0, s53
	s_nop 0
	global_load_lds_dwordx4 v146, s[30:31] offset:0
	s_nop 0
	s_mov_b32 m0, s54
	s_nop 0
	global_load_lds_dwordx4 v148, s[30:31] offset:0
	s_nop 0
	s_mov_b32 m0, s23
	s_nop 0
	global_load_lds_dwordx4 v1, s[28:29] offset:0
	s_nop 0
	s_mov_b32 m0, s55
	s_nop 0
	global_load_lds_dwordx4 v147, s[28:29] offset:0
	s_waitcnt vmcnt(16)
	s_waitcnt lgkmcnt(0)
	s_barrier
	s_setprio 1
	v_mfma_f32_16x16x32_bf16 v[138:141], v[4:7], v[64:67], 0
	v_mfma_f32_16x16x32_bf16 v[158:161], v[4:7], v[96:99], 0
	v_mfma_f32_16x16x32_bf16 v[166:169], v[4:7], v[114:117], 0
	v_mfma_f32_16x16x32_bf16 v[4:7], v[4:7], v[126:129], 0
	v_mfma_f32_16x16x32_bf16 v[138:141], v[8:11], v[92:95], v[138:141]
	v_mfma_f32_16x16x32_bf16 v[158:161], v[8:11], v[110:113], v[158:161]
	v_mfma_f32_16x16x32_bf16 v[166:169], v[8:11], v[122:125], v[166:169]
	v_mfma_f32_16x16x32_bf16 v[4:7], v[8:11], v[130:133], v[4:7]
	v_mfma_f32_16x16x32_bf16 v[8:11], v[12:15], v[126:129], 0
	v_mfma_f32_16x16x32_bf16 v[142:145], v[12:15], v[64:67], 0
	v_mfma_f32_16x16x32_bf16 v[162:165], v[12:15], v[96:99], 0
	v_mfma_f32_16x16x32_bf16 v[170:173], v[12:15], v[114:117], 0
	v_mfma_f32_16x16x32_bf16 v[8:11], v[16:19], v[130:133], v[8:11]
	v_mfma_f32_16x16x32_bf16 v[142:145], v[16:19], v[92:95], v[142:145]
	v_mfma_f32_16x16x32_bf16 v[162:165], v[16:19], v[110:113], v[162:165]
	v_mfma_f32_16x16x32_bf16 v[170:173], v[16:19], v[122:125], v[170:173]
	v_mfma_f32_16x16x32_bf16 v[12:15], v[20:23], v[64:67], 0
	v_mfma_f32_16x16x32_bf16 v[174:177], v[24:27], v[92:95], v[12:15]
	v_mfma_f32_16x16x32_bf16 v[12:15], v[28:31], v[64:67], 0
	v_mfma_f32_16x16x32_bf16 v[178:181], v[32:35], v[92:95], v[12:15]
	v_mfma_f32_16x16x32_bf16 v[12:15], v[20:23], v[96:99], 0
	v_mfma_f32_16x16x32_bf16 v[182:185], v[24:27], v[110:113], v[12:15]
	v_mfma_f32_16x16x32_bf16 v[12:15], v[28:31], v[96:99], 0
	v_mfma_f32_16x16x32_bf16 v[186:189], v[32:35], v[110:113], v[12:15]
	v_mfma_f32_16x16x32_bf16 v[12:15], v[20:23], v[114:117], 0
	v_mfma_f32_16x16x32_bf16 v[190:193], v[24:27], v[122:125], v[12:15]
	v_mfma_f32_16x16x32_bf16 v[12:15], v[28:31], v[114:117], 0
	v_mfma_f32_16x16x32_bf16 v[194:197], v[32:35], v[122:125], v[12:15]
	v_mfma_f32_16x16x32_bf16 v[12:15], v[20:23], v[126:129], 0
	v_mfma_f32_16x16x32_bf16 v[198:201], v[24:27], v[130:133], v[12:15]
	v_mfma_f32_16x16x32_bf16 v[12:15], v[28:31], v[126:129], 0
	v_mfma_f32_16x16x32_bf16 v[202:205], v[32:35], v[130:133], v[12:15]
	s_barrier
; #define PG8_KSETUP() const bool last = (t == nt - 2); const char* a1 = cA + (size_t)(t + 1) * kstep; \
;             const char* a2 = last ? nA : cA + (size_t)(t + 2) * kstep; const char* b2 = last ? nB : cB + (size_t)(t + 2) * kstep; const char* a3 = a2 + kstep; const char* b3 = b2 + kstep; \
;             if (last && has_next) S.a_ready(nxt)
; template <class Epi, class Sched, bool ALIGN_EPI = false, bool SP2 = false>
; __device__ __forceinline__ void gemm_phase(PG8_LAS unsigned char* lds, const Gemm g, const Sched& S, const Epi& E) {
;     ...
;         int t0 = 0;
;         if constexpr (SP2 && Epi::NVM == 16) { if (ui > 0) { const int t = 0; PG8_KSETUP(); PG8_KITER_SP2(24, 24); t0 = 2; } }
;         if constexpr (SP2 && Epi::NVM == 8) { if (ui > 0) { const int t = 0; PG8_KSETUP(); PG8_KITER_SP2(16, 16); t0 = 2; } }
	s_setprio 0
	s_nop 4
	ds_read_b128 v[12:15], v155
	ds_read_b128 v[16:19], v155 offset:1024
	ds_read_b128 v[22:25], v155 offset:2048
	ds_read_b128 v[26:29], v155 offset:3072
	ds_read_b128 v[206:209], v156
	ds_read_b128 v[210:213], v156 offset:1024
	ds_read_b128 v[214:217], v156 offset:2048
	ds_read_b128 v[218:221], v156 offset:3072
	ds_read_b128 v[30:33], v154 offset:32768
	ds_read_b128 v[64:67], v154 offset:33792
	ds_read_b128 v[222:225], v154 offset:34816
	ds_read_b128 v[226:229], v154 offset:35840
	ds_read_b128 v[230:233], v154 offset:36864
	ds_read_b128 v[234:237], v154 offset:37888
	ds_read_b128 v[238:241], v154 offset:38912
	ds_read_b128 v[242:245], v154 offset:39936
	s_add_u32 s28, s38, 0x80100
	s_addc_u32 s29, s39, 0
	s_mov_b32 m0, s56
	s_nop 0
	global_load_lds_dwordx4 v1, s[28:29] offset:0
	s_nop 0
	s_mov_b32 m0, s57
	s_nop 0
	global_load_lds_dwordx4 v147, s[28:29] offset:0
	s_waitcnt vmcnt(8)
	s_waitcnt lgkmcnt(0)
	s_barrier
	s_setprio 1
	v_mfma_f32_16x16x32_bf16 v[68:71], v[12:15], v[30:33], v[68:71]
	v_mfma_f32_16x16x32_bf16 v[130:133], v[16:19], v[64:67], v[68:71]
	v_mfma_f32_16x16x32_bf16 v[68:71], v[22:25], v[30:33], v[72:75]
	v_mfma_f32_16x16x32_bf16 v[126:129], v[26:29], v[64:67], v[68:71]
	v_mfma_f32_16x16x32_bf16 v[68:71], v[12:15], v[222:225], v[76:79]
	v_mfma_f32_16x16x32_bf16 v[114:117], v[16:19], v[226:229], v[68:71]
	v_mfma_f32_16x16x32_bf16 v[68:71], v[22:25], v[222:225], v[80:83]
	v_mfma_f32_16x16x32_bf16 v[110:113], v[26:29], v[226:229], v[68:71]
	v_mfma_f32_16x16x32_bf16 v[68:71], v[12:15], v[230:233], v[84:87]
	v_mfma_f32_16x16x32_bf16 v[98:101], v[16:19], v[234:237], v[68:71]
	v_mfma_f32_16x16x32_bf16 v[68:71], v[22:25], v[230:233], v[88:91]
	v_mfma_f32_16x16x32_bf16 v[94:97], v[26:29], v[234:237], v[68:71]
	v_mfma_f32_16x16x32_bf16 v[68:71], v[12:15], v[238:241], v[102:105]
	v_mfma_f32_16x16x32_bf16 v[82:85], v[16:19], v[242:245], v[68:71]
	v_mfma_f32_16x16x32_bf16 v[68:71], v[22:25], v[238:241], v[106:109]
	v_mfma_f32_16x16x32_bf16 v[78:81], v[26:29], v[242:245], v[68:71]
	v_mfma_f32_16x16x32_bf16 v[68:71], v[206:209], v[30:33], v[118:121]
	v_mfma_f32_16x16x32_bf16 v[30:33], v[214:217], v[30:33], v[36:39]
	v_mfma_f32_16x16x32_bf16 v[118:121], v[218:221], v[64:67], v[30:33]
	v_mfma_f32_16x16x32_bf16 v[30:33], v[206:209], v[222:225], v[40:43]
	v_mfma_f32_16x16x32_bf16 v[106:109], v[210:213], v[226:229], v[30:33]
	v_mfma_f32_16x16x32_bf16 v[30:33], v[214:217], v[222:225], v[44:47]
	v_mfma_f32_16x16x32_bf16 v[102:105], v[218:221], v[226:229], v[30:33]
	v_mfma_f32_16x16x32_bf16 v[30:33], v[206:209], v[230:233], v[48:51]
	v_mfma_f32_16x16x32_bf16 v[90:93], v[210:213], v[234:237], v[30:33]
	v_mfma_f32_16x16x32_bf16 v[30:33], v[214:217], v[230:233], v[52:55]
	v_mfma_f32_16x16x32_bf16 v[86:89], v[218:221], v[234:237], v[30:33]
	v_mfma_f32_16x16x32_bf16 v[30:33], v[206:209], v[238:241], v[56:59]
	v_mfma_f32_16x16x32_bf16 v[74:77], v[210:213], v[242:245], v[30:33]
	v_mfma_f32_16x16x32_bf16 v[30:33], v[214:217], v[238:241], v[60:63]
	v_mfma_f32_16x16x32_bf16 v[122:125], v[210:213], v[64:67], v[68:71]
	v_mfma_f32_16x16x32_bf16 v[66:69], v[218:221], v[242:245], v[30:33]
	s_barrier
	s_setprio 0
	ds_read_b128 v[38:41], v154 offset:49152
	ds_read_b128 v[42:45], v154 offset:50176
	ds_read_b128 v[222:225], v154 offset:51200
	ds_read_b128 v[226:229], v154 offset:52224
	ds_read_b128 v[230:233], v154 offset:53248
	ds_read_b128 v[234:237], v154 offset:54272
	ds_read_b128 v[238:241], v154 offset:55296
	ds_read_b128 v[242:245], v154 offset:56320
	s_add_u32 s28, s40, 0x180
	s_addc_u32 s29, s41, 0
	s_mov_b32 m0, s58
	s_nop 0
	global_load_lds_dwordx4 v146, s[28:29] offset:0
	s_nop 0
	s_mov_b32 m0, s59
	s_nop 0
	global_load_lds_dwordx4 v148, s[28:29] offset:0
	s_add_u32 s28, s40, 0x80180
	s_addc_u32 s29, s41, 0
	s_mov_b32 m0, s66
	s_nop 0
	global_load_lds_dwordx4 v146, s[28:29] offset:0
	s_nop 0
	s_mov_b32 m0, s67
	s_nop 0
	global_load_lds_dwordx4 v148, s[28:29] offset:0
	s_nop 0
	s_mov_b32 m0, s64
	s_nop 0
	global_load_lds_dwordx4 v1, s[24:25] offset:0
	s_nop 0
	s_mov_b32 m0, s65
	s_nop 0
	global_load_lds_dwordx4 v147, s[24:25] offset:0
	s_waitcnt vmcnt(8)
	s_waitcnt lgkmcnt(0)
	s_barrier
	s_setprio 1
	v_mfma_f32_16x16x32_bf16 v[30:33], v[12:15], v[38:41], v[138:141]
	v_mfma_f32_16x16x32_bf16 v[70:73], v[16:19], v[42:45], v[30:33]
	v_mfma_f32_16x16x32_bf16 v[30:33], v[22:25], v[38:41], v[142:145]
	v_mfma_f32_16x16x32_bf16 v[62:65], v[26:29], v[42:45], v[30:33]
	v_mfma_f32_16x16x32_bf16 v[30:33], v[12:15], v[222:225], v[158:161]
	v_mfma_f32_16x16x32_bf16 v[50:53], v[16:19], v[226:229], v[30:33]
	v_mfma_f32_16x16x32_bf16 v[30:33], v[22:25], v[222:225], v[162:165]
	v_mfma_f32_16x16x32_bf16 v[46:49], v[26:29], v[226:229], v[30:33]
	v_mfma_f32_16x16x32_bf16 v[30:33], v[12:15], v[230:233], v[166:169]
	v_mfma_f32_16x16x32_bf16 v[4:7], v[12:15], v[238:241], v[4:7]
	v_mfma_f32_16x16x32_bf16 v[34:37], v[16:19], v[234:237], v[30:33]
	v_mfma_f32_16x16x32_bf16 v[30:33], v[22:25], v[230:233], v[170:173]
	v_mfma_f32_16x16x32_bf16 v[18:21], v[16:19], v[242:245], v[4:7]
	v_mfma_f32_16x16x32_bf16 v[4:7], v[22:25], v[238:241], v[8:11]
	v_mfma_f32_16x16x32_bf16 v[30:33], v[26:29], v[234:237], v[30:33]
	v_mfma_f32_16x16x32_bf16 v[14:17], v[26:29], v[242:245], v[4:7]
	v_mfma_f32_16x16x32_bf16 v[4:7], v[206:209], v[38:41], v[174:177]
	v_mfma_f32_16x16x32_bf16 v[58:61], v[210:213], v[42:45], v[4:7]
	v_mfma_f32_16x16x32_bf16 v[4:7], v[214:217], v[38:41], v[178:181]
	v_mfma_f32_16x16x32_bf16 v[54:57], v[218:221], v[42:45], v[4:7]
	v_mfma_f32_16x16x32_bf16 v[4:7], v[206:209], v[222:225], v[182:185]
	v_mfma_f32_16x16x32_bf16 v[42:45], v[210:213], v[226:229], v[4:7]
	v_mfma_f32_16x16x32_bf16 v[4:7], v[214:217], v[222:225], v[186:189]
	v_mfma_f32_16x16x32_bf16 v[38:41], v[218:221], v[226:229], v[4:7]
	v_mfma_f32_16x16x32_bf16 v[4:7], v[206:209], v[230:233], v[190:193]
	v_mfma_f32_16x16x32_bf16 v[26:29], v[210:213], v[234:237], v[4:7]
	v_mfma_f32_16x16x32_bf16 v[4:7], v[214:217], v[230:233], v[194:197]
	v_mfma_f32_16x16x32_bf16 v[22:25], v[218:221], v[234:237], v[4:7]
	v_mfma_f32_16x16x32_bf16 v[4:7], v[206:209], v[238:241], v[198:201]
	v_mfma_f32_16x16x32_bf16 v[10:13], v[210:213], v[242:245], v[4:7]
	v_mfma_f32_16x16x32_bf16 v[4:7], v[214:217], v[238:241], v[202:205]
	v_mfma_f32_16x16x32_bf16 v[6:9], v[218:221], v[242:245], v[4:7]
	s_barrier
	s_setprio 0
	s_mov_b32 s44, 2
	s_branch .LBB0_786

; #define PG8_KSETUP() const bool last = (t == nt - 2); const char* a1 = cA + (size_t)(t + 1) * kstep; \
;             const char* a2 = last ? nA : cA + (size_t)(t + 2) * kstep; const char* b2 = last ? nB : cB + (size_t)(t + 2) * kstep; const char* a3 = a2 + kstep; const char* b3 = b2 + kstep; \
;             if (last && has_next) S.a_ready(nxt)
; template <class Epi, class Sched, bool ALIGN_EPI = false, bool SP2 = false>
; __device__ __forceinline__ void gemm_phase(PG8_LAS unsigned char* lds, const Gemm g, const Sched& S, const Epi& E) {
;     ...
;         int t0 = 0;
;         if constexpr (SP2 && Epi::NVM == 16) { if (ui > 0) { const int t = 0; PG8_KSETUP(); PG8_KITER_SP2(24, 24); t0 = 2; } }
;         if constexpr (SP2 && Epi::NVM == 8) { if (ui > 0) { const int t = 0; PG8_KSETUP(); PG8_KITER_SP2(16, 16); t0 = 2; } }
;         for (int t = t0; t < nt; t += 2) {
;             PG8_KSETUP();
;             if constexpr (SP2) {
;             PG8_KITER_SP2(8, 8);
.LBB0_787:
	ds_read_b128 v[138:141], v152
	ds_read_b128 v[142:145], v152 offset:1024
	ds_read_b128 v[158:161], v152 offset:2048
	ds_read_b128 v[162:165], v152 offset:3072
	ds_read_b128 v[166:169], v153
	ds_read_b128 v[170:173], v153 offset:1024
	ds_read_b128 v[174:177], v153 offset:2048
	ds_read_b128 v[178:181], v153 offset:3072
	s_cmp_eq_u32 s80, 28
	s_cselect_b32 s44, s78, s83
	s_cselect_b32 s45, s21, s84
	s_cselect_b32 s40, s79, s81
	s_cselect_b32 s41, s19, s82
	s_add_u32 s38, s44, 0x80
	s_addc_u32 s39, s45, 0
	ds_read_b128 v[182:185], v154
	ds_read_b128 v[186:189], v154 offset:1024
	ds_read_b128 v[190:193], v154 offset:2048
	ds_read_b128 v[194:197], v154 offset:3072
	ds_read_b128 v[198:201], v154 offset:4096
	ds_read_b128 v[202:205], v154 offset:5120
	ds_read_b128 v[206:209], v154 offset:6144
	ds_read_b128 v[210:213], v154 offset:7168
	s_add_u32 s30, s83, 0x7ff80
	s_addc_u32 s31, s84, 0
	s_mov_b32 m0, s68
	s_nop 0
	global_load_lds_dwordx4 v1, s[30:31] offset:0
	s_nop 0
	s_mov_b32 m0, s69
	s_nop 0
	global_load_lds_dwordx4 v147, s[30:31] offset:0
	s_waitcnt vmcnt(8)
	s_waitcnt lgkmcnt(0)
	s_barrier
	s_setprio 1
	v_mfma_f32_16x16x32_bf16 v[130:133], v[138:141], v[182:185], v[130:133]
	v_mfma_f32_16x16x32_bf16 v[130:133], v[142:145], v[186:189], v[130:133]
	v_mfma_f32_16x16x32_bf16 v[126:129], v[158:161], v[182:185], v[126:129]
	v_mfma_f32_16x16x32_bf16 v[126:129], v[162:165], v[186:189], v[126:129]
	v_mfma_f32_16x16x32_bf16 v[114:117], v[138:141], v[190:193], v[114:117]
	v_mfma_f32_16x16x32_bf16 v[114:117], v[142:145], v[194:197], v[114:117]
	v_mfma_f32_16x16x32_bf16 v[110:113], v[158:161], v[190:193], v[110:113]
	v_mfma_f32_16x16x32_bf16 v[110:113], v[162:165], v[194:197], v[110:113]
	v_mfma_f32_16x16x32_bf16 v[98:101], v[138:141], v[198:201], v[98:101]
	v_mfma_f32_16x16x32_bf16 v[98:101], v[142:145], v[202:205], v[98:101]
	v_mfma_f32_16x16x32_bf16 v[94:97], v[158:161], v[198:201], v[94:97]
	v_mfma_f32_16x16x32_bf16 v[94:97], v[162:165], v[202:205], v[94:97]
	v_mfma_f32_16x16x32_bf16 v[82:85], v[138:141], v[206:209], v[82:85]
	v_mfma_f32_16x16x32_bf16 v[82:85], v[142:145], v[210:213], v[82:85]
	v_mfma_f32_16x16x32_bf16 v[78:81], v[158:161], v[206:209], v[78:81]
	v_mfma_f32_16x16x32_bf16 v[78:81], v[162:165], v[210:213], v[78:81]
	v_mfma_f32_16x16x32_bf16 v[122:125], v[166:169], v[182:185], v[122:125]
	v_mfma_f32_16x16x32_bf16 v[122:125], v[170:173], v[186:189], v[122:125]
	v_mfma_f32_16x16x32_bf16 v[118:121], v[174:177], v[182:185], v[118:121]
	v_mfma_f32_16x16x32_bf16 v[118:121], v[178:181], v[186:189], v[118:121]
	v_mfma_f32_16x16x32_bf16 v[106:109], v[166:169], v[190:193], v[106:109]
	v_mfma_f32_16x16x32_bf16 v[106:109], v[170:173], v[194:197], v[106:109]
	v_mfma_f32_16x16x32_bf16 v[102:105], v[174:177], v[190:193], v[102:105]
	v_mfma_f32_16x16x32_bf16 v[102:105], v[178:181], v[194:197], v[102:105]
	v_mfma_f32_16x16x32_bf16 v[90:93], v[166:169], v[198:201], v[90:93]
	v_mfma_f32_16x16x32_bf16 v[90:93], v[170:173], v[202:205], v[90:93]
	v_mfma_f32_16x16x32_bf16 v[86:89], v[174:177], v[198:201], v[86:89]
	v_mfma_f32_16x16x32_bf16 v[86:89], v[178:181], v[202:205], v[86:89]
	v_mfma_f32_16x16x32_bf16 v[74:77], v[166:169], v[206:209], v[74:77]
	v_mfma_f32_16x16x32_bf16 v[74:77], v[170:173], v[210:213], v[74:77]
	v_mfma_f32_16x16x32_bf16 v[66:69], v[174:177], v[206:209], v[66:69]
	v_mfma_f32_16x16x32_bf16 v[66:69], v[178:181], v[210:213], v[66:69]
	s_barrier
	s_setprio 0
	ds_read_b128 v[182:185], v154 offset:16384
	ds_read_b128 v[186:189], v154 offset:17408
	ds_read_b128 v[190:193], v154 offset:18432
	ds_read_b128 v[194:197], v154 offset:19456
	ds_read_b128 v[198:201], v154 offset:20480
	ds_read_b128 v[202:205], v154 offset:21504
	ds_read_b128 v[206:209], v154 offset:22528
	ds_read_b128 v[210:213], v154 offset:23552
	s_mov_b32 m0, s37
	s_nop 0
	global_load_lds_dwordx4 v146, s[40:41] offset:0
	s_add_u32 s30, s40, 0x80000
	s_mov_b32 m0, s52
	s_nop 0
	global_load_lds_dwordx4 v148, s[40:41] offset:0
	s_addc_u32 s31, s41, 0
	s_mov_b32 m0, s53
	s_nop 0
	global_load_lds_dwordx4 v146, s[30:31] offset:0
	s_nop 0
	s_mov_b32 m0, s54
	s_nop 0
	global_load_lds_dwordx4 v148, s[30:31] offset:0
	s_nop 0
	s_mov_b32 m0, s23
	s_nop 0
	global_load_lds_dwordx4 v1, s[44:45] offset:0
	s_nop 0
	s_mov_b32 m0, s55
	s_nop 0
	global_load_lds_dwordx4 v147, s[44:45] offset:0
	s_waitcnt vmcnt(8)
	s_waitcnt lgkmcnt(0)
	s_barrier
	s_setprio 1
	v_mfma_f32_16x16x32_bf16 v[70:73], v[138:141], v[182:185], v[70:73]
	v_mfma_f32_16x16x32_bf16 v[70:73], v[142:145], v[186:189], v[70:73]
	v_mfma_f32_16x16x32_bf16 v[62:65], v[158:161], v[182:185], v[62:65]
	v_mfma_f32_16x16x32_bf16 v[62:65], v[162:165], v[186:189], v[62:65]
	v_mfma_f32_16x16x32_bf16 v[50:53], v[138:141], v[190:193], v[50:53]
	v_mfma_f32_16x16x32_bf16 v[50:53], v[142:145], v[194:197], v[50:53]
	v_mfma_f32_16x16x32_bf16 v[46:49], v[158:161], v[190:193], v[46:49]
	v_mfma_f32_16x16x32_bf16 v[46:49], v[162:165], v[194:197], v[46:49]
	v_mfma_f32_16x16x32_bf16 v[34:37], v[138:141], v[198:201], v[34:37]
	v_mfma_f32_16x16x32_bf16 v[34:37], v[142:145], v[202:205], v[34:37]
	v_mfma_f32_16x16x32_bf16 v[30:33], v[158:161], v[198:201], v[30:33]
	v_mfma_f32_16x16x32_bf16 v[30:33], v[162:165], v[202:205], v[30:33]
	v_mfma_f32_16x16x32_bf16 v[18:21], v[138:141], v[206:209], v[18:21]
	v_mfma_f32_16x16x32_bf16 v[18:21], v[142:145], v[210:213], v[18:21]
	v_mfma_f32_16x16x32_bf16 v[14:17], v[158:161], v[206:209], v[14:17]
	v_mfma_f32_16x16x32_bf16 v[14:17], v[162:165], v[210:213], v[14:17]
	v_mfma_f32_16x16x32_bf16 v[58:61], v[166:169], v[182:185], v[58:61]
	v_mfma_f32_16x16x32_bf16 v[54:57], v[174:177], v[182:185], v[54:57]
	v_mfma_f32_16x16x32_bf16 v[42:45], v[166:169], v[190:193], v[42:45]
	v_mfma_f32_16x16x32_bf16 v[38:41], v[174:177], v[190:193], v[38:41]
	v_mfma_f32_16x16x32_bf16 v[26:29], v[166:169], v[198:201], v[26:29]
	v_mfma_f32_16x16x32_bf16 v[22:25], v[174:177], v[198:201], v[22:25]
	v_mfma_f32_16x16x32_bf16 v[10:13], v[166:169], v[206:209], v[10:13]
	v_mfma_f32_16x16x32_bf16 v[4:7], v[174:177], v[206:209], v[6:9]
	v_mfma_f32_16x16x32_bf16 v[58:61], v[170:173], v[186:189], v[58:61]
	v_mfma_f32_16x16x32_bf16 v[54:57], v[178:181], v[186:189], v[54:57]
	v_mfma_f32_16x16x32_bf16 v[42:45], v[170:173], v[194:197], v[42:45]
	v_mfma_f32_16x16x32_bf16 v[38:41], v[178:181], v[194:197], v[38:41]
	v_mfma_f32_16x16x32_bf16 v[26:29], v[170:173], v[202:205], v[26:29]
	v_mfma_f32_16x16x32_bf16 v[22:25], v[178:181], v[202:205], v[22:25]
	v_mfma_f32_16x16x32_bf16 v[10:13], v[170:173], v[210:213], v[10:13]
	v_mfma_f32_16x16x32_bf16 v[4:7], v[178:181], v[210:213], v[4:7]
	s_barrier
; #define PG8_STAGE(bufoff, gbase, voff) PG8_STAGEI(bufoff, gbase, 0, voff)
; #define PG8_LDA(dst, b, h) do { _Pragma("unroll") for (int m = 0; m < 4; ++m) _Pragma("unroll") for (int k = 0; k < 2; ++k) dst[m][k] = *(const PG8_LAS bf16x8*)(lds + PG8_SA(b, h) + aoff + m * 2048 + k * 1024); } while (0)
; #define PG8_WAIT_V(n) asm volatile("s_waitcnt vmcnt(" #n ")" ::: "memory")
; #define PG8_BAR __builtin_amdgcn_s_barrier()
; template <class Epi, class Sched, bool ALIGN_EPI = false, bool SP2 = false>
; __device__ __forceinline__ void gemm_phase(PG8_LAS unsigned char* lds, const Gemm g, const Sched& S, const Epi& E) {
;     ...
;         int t0 = 0;
;         if constexpr (SP2 && Epi::NVM == 16) { if (ui > 0) { const int t = 0; PG8_KSETUP(); PG8_KITER_SP2(24, 24); t0 = 2; } }
;         if constexpr (SP2 && Epi::NVM == 8) { if (ui > 0) { const int t = 0; PG8_KSETUP(); PG8_KITER_SP2(16, 16); t0 = 2; } }
;         for (int t = t0; t < nt; t += 2) {
;             PG8_KSETUP();
;             if constexpr (SP2) {
;             PG8_KITER_SP2(8, 8);
;             } else {
;             PG8_LDB(B0, 0, 0); PG8_SCHED; PG8_LDA(At, 0, 0); PG8_STAGE(PG8_SA(1, 1), a1 + hstep, voffA);
;             PG8_WAIT_L(8); PG8_BAR; PG8_WAIT_L(0); PG8_MMA(0, 0, At, B0); PG8_BAR; PG8_SCHED;
;             PG8_LDB(B1, 0, 1); PG8_STAGE(PG8_SB(0, 0), b2, voffB);
;             PG8_BAR; PG8_WAIT_L(0); PG8_MMA(0, 1, At, B1); PG8_BAR;
;             PG8_LDA(At, 0, 1); PG8_STAGE(PG8_SA(0, 0), a2, voffA);
;             PG8_BAR; PG8_WAIT_L(0); PG8_MMA(1, 0, At, B0); PG8_BAR; PG8_SCHED;
;             PG8_STAGE(PG8_SB(0, 1), b2 + hstep, voffB);
;             PG8_WAIT_V(6); PG8_BAR; PG8_MMA(1, 1, At, B1); PG8_BAR;
;             PG8_LDB(B0, 1, 0); PG8_SCHED; PG8_LDA(At, 1, 0); PG8_STAGE(PG8_SA(0, 1), a2 + hstep, voffA);
;             PG8_WAIT_L(8); PG8_BAR; PG8_WAIT_L(0); PG8_MMA(0, 0, At, B0); PG8_BAR; PG8_SCHED;
;             PG8_LDB(B1, 1, 1); PG8_STAGE(PG8_SB(1, 0), b3, voffB);
;             PG8_BAR; PG8_WAIT_L(0); PG8_MMA(0, 1, At, B1); PG8_BAR;
;             PG8_LDA(At, 1, 1); PG8_STAGE(PG8_SA(1, 0), a3, voffA);
;             PG8_BAR; PG8_WAIT_L(0); PG8_MMA(1, 0, At, B0); PG8_BAR; PG8_SCHED;
;             PG8_STAGE(PG8_SB(1, 1), b3 + hstep, voffB);
;             PG8_WAIT_V(6); PG8_BAR; PG8_MMA(1, 1, At, B1); PG8_BAR;
;             }
;         }
;     ...
;         if constexpr (ALIGN_EPI) { if (wr == 0) PG8_BAR; }
	s_setprio 0
	ds_read_b128 v[138:141], v155
	ds_read_b128 v[142:145], v155 offset:1024
	ds_read_b128 v[158:161], v155 offset:2048
	ds_read_b128 v[162:165], v155 offset:3072
	ds_read_b128 v[166:169], v156
	ds_read_b128 v[170:173], v156 offset:1024
	ds_read_b128 v[174:177], v156 offset:2048
	ds_read_b128 v[178:181], v156 offset:3072
	ds_read_b128 v[182:185], v154 offset:32768
	ds_read_b128 v[186:189], v154 offset:33792
	ds_read_b128 v[190:193], v154 offset:34816
	ds_read_b128 v[194:197], v154 offset:35840
	ds_read_b128 v[198:201], v154 offset:36864
	ds_read_b128 v[202:205], v154 offset:37888
	ds_read_b128 v[206:209], v154 offset:38912
	ds_read_b128 v[210:213], v154 offset:39936
	s_add_u32 s30, s44, 0x80000
	s_addc_u32 s31, s45, 0
	s_mov_b32 m0, s56
	s_nop 0
	global_load_lds_dwordx4 v1, s[30:31] offset:0
	s_nop 0
	s_mov_b32 m0, s57
	s_nop 0
	global_load_lds_dwordx4 v147, s[30:31] offset:0
	s_waitcnt vmcnt(8)
	s_waitcnt lgkmcnt(0)
	s_barrier
	s_setprio 1
	v_mfma_f32_16x16x32_bf16 v[130:133], v[138:141], v[182:185], v[130:133]
	v_mfma_f32_16x16x32_bf16 v[130:133], v[142:145], v[186:189], v[130:133]
	v_mfma_f32_16x16x32_bf16 v[126:129], v[158:161], v[182:185], v[126:129]
	v_mfma_f32_16x16x32_bf16 v[126:129], v[162:165], v[186:189], v[126:129]
	v_mfma_f32_16x16x32_bf16 v[114:117], v[138:141], v[190:193], v[114:117]
	v_mfma_f32_16x16x32_bf16 v[114:117], v[142:145], v[194:197], v[114:117]
	v_mfma_f32_16x16x32_bf16 v[110:113], v[158:161], v[190:193], v[110:113]
	v_mfma_f32_16x16x32_bf16 v[110:113], v[162:165], v[194:197], v[110:113]
	v_mfma_f32_16x16x32_bf16 v[98:101], v[138:141], v[198:201], v[98:101]
	v_mfma_f32_16x16x32_bf16 v[98:101], v[142:145], v[202:205], v[98:101]
	v_mfma_f32_16x16x32_bf16 v[94:97], v[158:161], v[198:201], v[94:97]
	v_mfma_f32_16x16x32_bf16 v[94:97], v[162:165], v[202:205], v[94:97]
	v_mfma_f32_16x16x32_bf16 v[82:85], v[138:141], v[206:209], v[82:85]
	v_mfma_f32_16x16x32_bf16 v[82:85], v[142:145], v[210:213], v[82:85]
	v_mfma_f32_16x16x32_bf16 v[78:81], v[158:161], v[206:209], v[78:81]
	v_mfma_f32_16x16x32_bf16 v[78:81], v[162:165], v[210:213], v[78:81]
	v_mfma_f32_16x16x32_bf16 v[122:125], v[166:169], v[182:185], v[122:125]
	v_mfma_f32_16x16x32_bf16 v[122:125], v[170:173], v[186:189], v[122:125]
	v_mfma_f32_16x16x32_bf16 v[118:121], v[174:177], v[182:185], v[118:121]
	v_mfma_f32_16x16x32_bf16 v[118:121], v[178:181], v[186:189], v[118:121]
	v_mfma_f32_16x16x32_bf16 v[106:109], v[166:169], v[190:193], v[106:109]
	v_mfma_f32_16x16x32_bf16 v[106:109], v[170:173], v[194:197], v[106:109]
	v_mfma_f32_16x16x32_bf16 v[102:105], v[174:177], v[190:193], v[102:105]
	v_mfma_f32_16x16x32_bf16 v[102:105], v[178:181], v[194:197], v[102:105]
	v_mfma_f32_16x16x32_bf16 v[90:93], v[166:169], v[198:201], v[90:93]
	v_mfma_f32_16x16x32_bf16 v[90:93], v[170:173], v[202:205], v[90:93]
	v_mfma_f32_16x16x32_bf16 v[86:89], v[174:177], v[198:201], v[86:89]
	v_mfma_f32_16x16x32_bf16 v[86:89], v[178:181], v[202:205], v[86:89]
	v_mfma_f32_16x16x32_bf16 v[74:77], v[166:169], v[206:209], v[74:77]
	v_mfma_f32_16x16x32_bf16 v[74:77], v[170:173], v[210:213], v[74:77]
	v_mfma_f32_16x16x32_bf16 v[66:69], v[174:177], v[206:209], v[66:69]
	v_mfma_f32_16x16x32_bf16 v[66:69], v[178:181], v[210:213], v[66:69]
	s_barrier
	s_setprio 0
	ds_read_b128 v[182:185], v154 offset:49152
	ds_read_b128 v[186:189], v154 offset:50176
	ds_read_b128 v[190:193], v154 offset:51200
	ds_read_b128 v[194:197], v154 offset:52224
	ds_read_b128 v[198:201], v154 offset:53248
	ds_read_b128 v[202:205], v154 offset:54272
	ds_read_b128 v[206:209], v154 offset:55296
	ds_read_b128 v[210:213], v154 offset:56320
	s_add_u32 s30, s40, 0x80
	s_addc_u32 s31, s41, 0
	s_mov_b32 m0, s58
	s_nop 0
	global_load_lds_dwordx4 v146, s[30:31] offset:0
	s_nop 0
	s_mov_b32 m0, s59
	s_nop 0
	global_load_lds_dwordx4 v148, s[30:31] offset:0
	s_add_u32 s30, s40, 0x80080
	s_addc_u32 s31, s41, 0
	s_mov_b32 m0, s66
	s_nop 0
	global_load_lds_dwordx4 v146, s[30:31] offset:0
	s_nop 0
	s_mov_b32 m0, s67
	s_nop 0
	global_load_lds_dwordx4 v148, s[30:31] offset:0
	s_nop 0
	s_mov_b32 m0, s64
	s_nop 0
	global_load_lds_dwordx4 v1, s[38:39] offset:0
	s_nop 0
	s_mov_b32 m0, s65
	s_nop 0
	global_load_lds_dwordx4 v147, s[38:39] offset:0
	s_waitcnt vmcnt(8)
	s_waitcnt lgkmcnt(0)
	s_barrier
	s_setprio 1
	v_mfma_f32_16x16x32_bf16 v[70:73], v[138:141], v[182:185], v[70:73]
	v_mfma_f32_16x16x32_bf16 v[70:73], v[142:145], v[186:189], v[70:73]
	v_mfma_f32_16x16x32_bf16 v[62:65], v[158:161], v[182:185], v[62:65]
	v_mfma_f32_16x16x32_bf16 v[62:65], v[162:165], v[186:189], v[62:65]
	v_mfma_f32_16x16x32_bf16 v[50:53], v[138:141], v[190:193], v[50:53]
	v_mfma_f32_16x16x32_bf16 v[50:53], v[142:145], v[194:197], v[50:53]
	v_mfma_f32_16x16x32_bf16 v[46:49], v[158:161], v[190:193], v[46:49]
	v_mfma_f32_16x16x32_bf16 v[46:49], v[162:165], v[194:197], v[46:49]
	v_mfma_f32_16x16x32_bf16 v[34:37], v[138:141], v[198:201], v[34:37]
	v_mfma_f32_16x16x32_bf16 v[34:37], v[142:145], v[202:205], v[34:37]
	v_mfma_f32_16x16x32_bf16 v[30:33], v[158:161], v[198:201], v[30:33]
	v_mfma_f32_16x16x32_bf16 v[30:33], v[162:165], v[202:205], v[30:33]
	v_mfma_f32_16x16x32_bf16 v[18:21], v[138:141], v[206:209], v[18:21]
	v_mfma_f32_16x16x32_bf16 v[18:21], v[142:145], v[210:213], v[18:21]
	v_mfma_f32_16x16x32_bf16 v[14:17], v[158:161], v[206:209], v[14:17]
	v_mfma_f32_16x16x32_bf16 v[14:17], v[162:165], v[210:213], v[14:17]
	v_mfma_f32_16x16x32_bf16 v[58:61], v[166:169], v[182:185], v[58:61]
	v_mfma_f32_16x16x32_bf16 v[54:57], v[174:177], v[182:185], v[54:57]
	v_mfma_f32_16x16x32_bf16 v[42:45], v[166:169], v[190:193], v[42:45]
	v_mfma_f32_16x16x32_bf16 v[38:41], v[174:177], v[190:193], v[38:41]
	v_mfma_f32_16x16x32_bf16 v[26:29], v[166:169], v[198:201], v[26:29]
	v_mfma_f32_16x16x32_bf16 v[22:25], v[174:177], v[198:201], v[22:25]
	v_mfma_f32_16x16x32_bf16 v[8:11], v[166:169], v[206:209], v[10:13]
	v_mfma_f32_16x16x32_bf16 v[4:7], v[174:177], v[206:209], v[4:7]
	v_mfma_f32_16x16x32_bf16 v[58:61], v[170:173], v[186:189], v[58:61]
	v_mfma_f32_16x16x32_bf16 v[54:57], v[178:181], v[186:189], v[54:57]
	v_mfma_f32_16x16x32_bf16 v[42:45], v[170:173], v[194:197], v[42:45]
	v_mfma_f32_16x16x32_bf16 v[38:41], v[178:181], v[194:197], v[38:41]
	v_mfma_f32_16x16x32_bf16 v[26:29], v[170:173], v[202:205], v[26:29]
	v_mfma_f32_16x16x32_bf16 v[22:25], v[178:181], v[202:205], v[22:25]
	v_mfma_f32_16x16x32_bf16 v[10:13], v[170:173], v[210:213], v[8:11]
	v_mfma_f32_16x16x32_bf16 v[6:9], v[178:181], v[210:213], v[4:7]
	s_barrier
	s_setprio 0
	s_add_i32 s80, s80, 2
	s_add_u32 s81, s81, 0x100
	s_addc_u32 s82, s82, 0
	s_add_u32 s83, s83, 0x100
	s_addc_u32 s84, s84, 0
	s_cmp_gt_u32 s80, 29
	s_cbranch_scc0 .LBB0_787
	s_and_b64 vcc, exec, s[16:17]
	s_cbranch_vccz .LBB0_790
	s_barrier

; #define PG8_KSETUP() const bool last = (t == nt - 2); const char* a1 = cA + (size_t)(t + 1) * kstep; \
;             const char* a2 = last ? nA : cA + (size_t)(t + 2) * kstep; const char* b2 = last ? nB : cB + (size_t)(t + 2) * kstep; const char* a3 = a2 + kstep; const char* b3 = b2 + kstep; \
;             if (last && has_next) S.a_ready(nxt)
; template <class Epi, class Sched, bool ALIGN_EPI = false, bool SP2 = false>
; __device__ __forceinline__ void gemm_phase(PG8_LAS unsigned char* lds, const Gemm g, const Sched& S, const Epi& E) {
;     ...
;         int t0 = 0;
;         if constexpr (SP2 && Epi::NVM == 16) { if (ui > 0) { const int t = 0; PG8_KSETUP(); PG8_KITER_SP2(24, 24); t0 = 2; } }
.LBB0_867:
	ds_read_b128 v[4:7], v143
	ds_read_b128 v[8:11], v143 offset:1024
	ds_read_b128 v[12:15], v143 offset:2048
	ds_read_b128 v[16:19], v143 offset:3072
	ds_read_b128 v[20:23], v144
	ds_read_b128 v[24:27], v144 offset:1024
	ds_read_b128 v[28:31], v144 offset:2048
	ds_read_b128 v[32:35], v144 offset:3072
	s_add_u32 s44, s36, 0x100
	s_addc_u32 s45, s37, 0
	s_add_u32 s30, s38, 0x100
	s_addc_u32 s31, s39, 0
	s_add_u32 s40, s36, 0x180
	s_addc_u32 s41, s37, 0
	ds_read_b128 v[36:39], v145
	ds_read_b128 v[40:43], v145 offset:1024
	ds_read_b128 v[44:47], v145 offset:2048
	ds_read_b128 v[48:51], v145 offset:3072
	ds_read_b128 v[52:55], v145 offset:4096
	ds_read_b128 v[56:59], v145 offset:5120
	ds_read_b128 v[60:63], v145 offset:6144
	ds_read_b128 v[64:67], v145 offset:7168
	s_add_u32 s42, s36, 0x160080
	s_addc_u32 s43, s37, 0
	s_mov_b32 m0, s71
	s_nop 0
	global_load_lds_dwordx4 v1, s[42:43] offset:0
	s_nop 0
	s_mov_b32 m0, s72
	s_nop 0
	global_load_lds_dwordx4 v139, s[42:43] offset:0
	s_waitcnt vmcnt(24)
	s_waitcnt lgkmcnt(0)
	s_barrier
	s_setprio 1
	v_mfma_f32_16x16x32_bf16 v[92:95], v[4:7], v[60:63], 0
	v_mfma_f32_16x16x32_bf16 v[68:71], v[4:7], v[36:39], 0
	v_mfma_f32_16x16x32_bf16 v[72:75], v[12:15], v[36:39], 0
	v_mfma_f32_16x16x32_bf16 v[76:79], v[4:7], v[44:47], 0
	v_mfma_f32_16x16x32_bf16 v[80:83], v[12:15], v[44:47], 0
	v_mfma_f32_16x16x32_bf16 v[84:87], v[4:7], v[52:55], 0
	v_mfma_f32_16x16x32_bf16 v[88:91], v[12:15], v[52:55], 0
	v_mfma_f32_16x16x32_bf16 v[102:105], v[8:11], v[64:67], v[92:95]
	v_mfma_f32_16x16x32_bf16 v[92:95], v[12:15], v[60:63], 0
	v_mfma_f32_16x16x32_bf16 v[68:71], v[8:11], v[40:43], v[68:71]
	v_mfma_f32_16x16x32_bf16 v[72:75], v[16:19], v[40:43], v[72:75]
	v_mfma_f32_16x16x32_bf16 v[76:79], v[8:11], v[48:51], v[76:79]
	v_mfma_f32_16x16x32_bf16 v[80:83], v[16:19], v[48:51], v[80:83]
	v_mfma_f32_16x16x32_bf16 v[84:87], v[8:11], v[56:59], v[84:87]
	v_mfma_f32_16x16x32_bf16 v[88:91], v[16:19], v[56:59], v[88:91]
	v_mfma_f32_16x16x32_bf16 v[106:109], v[16:19], v[64:67], v[92:95]
	v_mfma_f32_16x16x32_bf16 v[92:95], v[20:23], v[36:39], 0
	v_mfma_f32_16x16x32_bf16 v[36:39], v[28:31], v[36:39], 0
	v_mfma_f32_16x16x32_bf16 v[118:121], v[24:27], v[40:43], v[92:95]
	v_mfma_f32_16x16x32_bf16 v[36:39], v[32:35], v[40:43], v[36:39]
	v_mfma_f32_16x16x32_bf16 v[40:43], v[20:23], v[44:47], 0
	v_mfma_f32_16x16x32_bf16 v[44:47], v[28:31], v[44:47], 0
	v_mfma_f32_16x16x32_bf16 v[40:43], v[24:27], v[48:51], v[40:43]
	v_mfma_f32_16x16x32_bf16 v[44:47], v[32:35], v[48:51], v[44:47]
	v_mfma_f32_16x16x32_bf16 v[48:51], v[20:23], v[52:55], 0
	v_mfma_f32_16x16x32_bf16 v[52:55], v[28:31], v[52:55], 0
	v_mfma_f32_16x16x32_bf16 v[48:51], v[24:27], v[56:59], v[48:51]
	v_mfma_f32_16x16x32_bf16 v[52:55], v[32:35], v[56:59], v[52:55]
	v_mfma_f32_16x16x32_bf16 v[56:59], v[20:23], v[60:63], 0
	v_mfma_f32_16x16x32_bf16 v[60:63], v[28:31], v[60:63], 0
	v_mfma_f32_16x16x32_bf16 v[56:59], v[24:27], v[64:67], v[56:59]
	v_mfma_f32_16x16x32_bf16 v[60:63], v[32:35], v[64:67], v[60:63]
	s_barrier
	s_setprio 0
	ds_read_b128 v[64:67], v145 offset:16384
	ds_read_b128 v[92:95], v145 offset:17408
	ds_read_b128 v[96:99], v145 offset:18432
	ds_read_b128 v[110:113], v145 offset:19456
	ds_read_b128 v[114:117], v145 offset:20480
	ds_read_b128 v[122:125], v145 offset:21504
	ds_read_b128 v[126:129], v145 offset:22528
	ds_read_b128 v[130:133], v145 offset:23552
	s_mov_b32 m0, s54
	s_nop 0
	global_load_lds_dwordx4 v138, s[30:31] offset:0
	s_nop 0
	s_mov_b32 m0, s55
	s_nop 0
	global_load_lds_dwordx4 v140, s[30:31] offset:0
	s_add_u32 s30, s38, 0x160100
	s_addc_u32 s31, s39, 0
	s_mov_b32 m0, s56
	s_nop 0
	global_load_lds_dwordx4 v138, s[30:31] offset:0
	s_nop 0
	s_mov_b32 m0, s57
	s_nop 0
	global_load_lds_dwordx4 v140, s[30:31] offset:0
	s_nop 0
	s_mov_b32 m0, s47
	s_nop 0
	global_load_lds_dwordx4 v1, s[44:45] offset:0
	s_nop 0
	s_mov_b32 m0, s58
	s_nop 0
	global_load_lds_dwordx4 v139, s[44:45] offset:0
	s_waitcnt vmcnt(24)
	s_waitcnt lgkmcnt(0)
	s_barrier
	s_setprio 1
	v_mfma_f32_16x16x32_bf16 v[148:151], v[4:7], v[64:67], 0
	v_mfma_f32_16x16x32_bf16 v[156:159], v[4:7], v[96:99], 0
	v_mfma_f32_16x16x32_bf16 v[164:167], v[4:7], v[114:117], 0
	v_mfma_f32_16x16x32_bf16 v[4:7], v[4:7], v[126:129], 0
	v_mfma_f32_16x16x32_bf16 v[148:151], v[8:11], v[92:95], v[148:151]
	v_mfma_f32_16x16x32_bf16 v[156:159], v[8:11], v[110:113], v[156:159]
	v_mfma_f32_16x16x32_bf16 v[164:167], v[8:11], v[122:125], v[164:167]
	v_mfma_f32_16x16x32_bf16 v[4:7], v[8:11], v[130:133], v[4:7]
	v_mfma_f32_16x16x32_bf16 v[8:11], v[12:15], v[126:129], 0
	v_mfma_f32_16x16x32_bf16 v[152:155], v[12:15], v[64:67], 0
	v_mfma_f32_16x16x32_bf16 v[160:163], v[12:15], v[96:99], 0
	v_mfma_f32_16x16x32_bf16 v[168:171], v[12:15], v[114:117], 0
	v_mfma_f32_16x16x32_bf16 v[8:11], v[16:19], v[130:133], v[8:11]
	v_mfma_f32_16x16x32_bf16 v[152:155], v[16:19], v[92:95], v[152:155]
	v_mfma_f32_16x16x32_bf16 v[160:163], v[16:19], v[110:113], v[160:163]
	v_mfma_f32_16x16x32_bf16 v[168:171], v[16:19], v[122:125], v[168:171]
	v_mfma_f32_16x16x32_bf16 v[12:15], v[20:23], v[64:67], 0
	v_mfma_f32_16x16x32_bf16 v[172:175], v[24:27], v[92:95], v[12:15]
	v_mfma_f32_16x16x32_bf16 v[12:15], v[28:31], v[64:67], 0
	v_mfma_f32_16x16x32_bf16 v[176:179], v[32:35], v[92:95], v[12:15]
	v_mfma_f32_16x16x32_bf16 v[12:15], v[20:23], v[96:99], 0
	v_mfma_f32_16x16x32_bf16 v[180:183], v[24:27], v[110:113], v[12:15]
	v_mfma_f32_16x16x32_bf16 v[12:15], v[28:31], v[96:99], 0
	v_mfma_f32_16x16x32_bf16 v[184:187], v[32:35], v[110:113], v[12:15]
	v_mfma_f32_16x16x32_bf16 v[12:15], v[20:23], v[114:117], 0
	v_mfma_f32_16x16x32_bf16 v[188:191], v[24:27], v[122:125], v[12:15]
	v_mfma_f32_16x16x32_bf16 v[12:15], v[28:31], v[114:117], 0
	v_mfma_f32_16x16x32_bf16 v[192:195], v[32:35], v[122:125], v[12:15]
	v_mfma_f32_16x16x32_bf16 v[12:15], v[20:23], v[126:129], 0
	v_mfma_f32_16x16x32_bf16 v[196:199], v[24:27], v[130:133], v[12:15]
	v_mfma_f32_16x16x32_bf16 v[12:15], v[28:31], v[126:129], 0
	v_mfma_f32_16x16x32_bf16 v[200:203], v[32:35], v[130:133], v[12:15]
	s_barrier
; #define PG8_KSETUP() const bool last = (t == nt - 2); const char* a1 = cA + (size_t)(t + 1) * kstep; \
;             const char* a2 = last ? nA : cA + (size_t)(t + 2) * kstep; const char* b2 = last ? nB : cB + (size_t)(t + 2) * kstep; const char* a3 = a2 + kstep; const char* b3 = b2 + kstep; \
;             if (last && has_next) S.a_ready(nxt)
; template <class Epi, class Sched, bool ALIGN_EPI = false, bool SP2 = false>
; __device__ __forceinline__ void gemm_phase(PG8_LAS unsigned char* lds, const Gemm g, const Sched& S, const Epi& E) {
;     ...
;         int t0 = 0;
;         if constexpr (SP2 && Epi::NVM == 16) { if (ui > 0) { const int t = 0; PG8_KSETUP(); PG8_KITER_SP2(24, 24); t0 = 2; } }
	s_setprio 0
	s_nop 4
	ds_read_b128 v[12:15], v146
	ds_read_b128 v[16:19], v146 offset:1024
	ds_read_b128 v[22:25], v146 offset:2048
	ds_read_b128 v[26:29], v146 offset:3072
	ds_read_b128 v[204:207], v147
	ds_read_b128 v[208:211], v147 offset:1024
	ds_read_b128 v[212:215], v147 offset:2048
	ds_read_b128 v[216:219], v147 offset:3072
	ds_read_b128 v[30:33], v145 offset:32768
	ds_read_b128 v[64:67], v145 offset:33792
	ds_read_b128 v[220:223], v145 offset:34816
	ds_read_b128 v[224:227], v145 offset:35840
	ds_read_b128 v[228:231], v145 offset:36864
	ds_read_b128 v[232:235], v145 offset:37888
	ds_read_b128 v[236:239], v145 offset:38912
	ds_read_b128 v[240:243], v145 offset:39936
	s_add_u32 s30, s36, 0x160100
	s_addc_u32 s31, s37, 0
	s_mov_b32 m0, s59
	s_nop 0
	global_load_lds_dwordx4 v1, s[30:31] offset:0
	s_nop 0
	s_mov_b32 m0, s64
	s_nop 0
	global_load_lds_dwordx4 v139, s[30:31] offset:0
	s_waitcnt vmcnt(8)
	s_waitcnt lgkmcnt(0)
	s_barrier
	s_setprio 1
	v_mfma_f32_16x16x32_bf16 v[68:71], v[12:15], v[30:33], v[68:71]
	v_mfma_f32_16x16x32_bf16 v[130:133], v[16:19], v[64:67], v[68:71]
	v_mfma_f32_16x16x32_bf16 v[68:71], v[22:25], v[30:33], v[72:75]
	v_mfma_f32_16x16x32_bf16 v[126:129], v[26:29], v[64:67], v[68:71]
	v_mfma_f32_16x16x32_bf16 v[68:71], v[12:15], v[220:223], v[76:79]
	v_mfma_f32_16x16x32_bf16 v[114:117], v[16:19], v[224:227], v[68:71]
	v_mfma_f32_16x16x32_bf16 v[68:71], v[22:25], v[220:223], v[80:83]
	v_mfma_f32_16x16x32_bf16 v[110:113], v[26:29], v[224:227], v[68:71]
	v_mfma_f32_16x16x32_bf16 v[68:71], v[12:15], v[228:231], v[84:87]
	v_mfma_f32_16x16x32_bf16 v[98:101], v[16:19], v[232:235], v[68:71]
	v_mfma_f32_16x16x32_bf16 v[68:71], v[22:25], v[228:231], v[88:91]
	v_mfma_f32_16x16x32_bf16 v[94:97], v[26:29], v[232:235], v[68:71]
	v_mfma_f32_16x16x32_bf16 v[68:71], v[12:15], v[236:239], v[102:105]
	v_mfma_f32_16x16x32_bf16 v[82:85], v[16:19], v[240:243], v[68:71]
	v_mfma_f32_16x16x32_bf16 v[68:71], v[22:25], v[236:239], v[106:109]
	v_mfma_f32_16x16x32_bf16 v[78:81], v[26:29], v[240:243], v[68:71]
	v_mfma_f32_16x16x32_bf16 v[68:71], v[204:207], v[30:33], v[118:121]
	v_mfma_f32_16x16x32_bf16 v[30:33], v[212:215], v[30:33], v[36:39]
	v_mfma_f32_16x16x32_bf16 v[118:121], v[216:219], v[64:67], v[30:33]
	v_mfma_f32_16x16x32_bf16 v[30:33], v[204:207], v[220:223], v[40:43]
	v_mfma_f32_16x16x32_bf16 v[106:109], v[208:211], v[224:227], v[30:33]
	v_mfma_f32_16x16x32_bf16 v[30:33], v[212:215], v[220:223], v[44:47]
	v_mfma_f32_16x16x32_bf16 v[102:105], v[216:219], v[224:227], v[30:33]
	v_mfma_f32_16x16x32_bf16 v[30:33], v[204:207], v[228:231], v[48:51]
	v_mfma_f32_16x16x32_bf16 v[90:93], v[208:211], v[232:235], v[30:33]
	v_mfma_f32_16x16x32_bf16 v[30:33], v[212:215], v[228:231], v[52:55]
	v_mfma_f32_16x16x32_bf16 v[86:89], v[216:219], v[232:235], v[30:33]
	v_mfma_f32_16x16x32_bf16 v[30:33], v[204:207], v[236:239], v[56:59]
	v_mfma_f32_16x16x32_bf16 v[122:125], v[208:211], v[64:67], v[68:71]
	v_mfma_f32_16x16x32_bf16 v[70:73], v[208:211], v[240:243], v[30:33]
	v_mfma_f32_16x16x32_bf16 v[30:33], v[212:215], v[236:239], v[60:63]
	v_mfma_f32_16x16x32_bf16 v[62:65], v[216:219], v[240:243], v[30:33]
	s_barrier
	s_setprio 0
	ds_read_b128 v[38:41], v145 offset:49152
	ds_read_b128 v[42:45], v145 offset:50176
	ds_read_b128 v[220:223], v145 offset:51200
	ds_read_b128 v[224:227], v145 offset:52224
	ds_read_b128 v[228:231], v145 offset:53248
	ds_read_b128 v[232:235], v145 offset:54272
	ds_read_b128 v[236:239], v145 offset:55296
	ds_read_b128 v[240:243], v145 offset:56320
	s_add_u32 s30, s38, 0x180
	s_addc_u32 s31, s39, 0
	s_mov_b32 m0, s65
	s_nop 0
	global_load_lds_dwordx4 v138, s[30:31] offset:0
	s_nop 0
	s_mov_b32 m0, s66
	s_nop 0
	global_load_lds_dwordx4 v140, s[30:31] offset:0
	s_add_u32 s30, s38, 0x160180
	s_addc_u32 s31, s39, 0
	s_mov_b32 m0, s69
	s_nop 0
	global_load_lds_dwordx4 v138, s[30:31] offset:0
	s_nop 0
	s_mov_b32 m0, s70
	s_nop 0
	global_load_lds_dwordx4 v140, s[30:31] offset:0
	s_nop 0
	s_mov_b32 m0, s67
	s_nop 0
	global_load_lds_dwordx4 v1, s[40:41] offset:0
	s_nop 0
	s_mov_b32 m0, s68
	s_nop 0
	global_load_lds_dwordx4 v139, s[40:41] offset:0
	s_waitcnt vmcnt(8)
	s_waitcnt lgkmcnt(0)
	s_barrier
	s_setprio 1
	v_mfma_f32_16x16x32_bf16 v[30:33], v[12:15], v[38:41], v[148:151]
	v_mfma_f32_16x16x32_bf16 v[74:77], v[16:19], v[42:45], v[30:33]
	v_mfma_f32_16x16x32_bf16 v[30:33], v[22:25], v[38:41], v[152:155]
	v_mfma_f32_16x16x32_bf16 v[66:69], v[26:29], v[42:45], v[30:33]
	v_mfma_f32_16x16x32_bf16 v[30:33], v[12:15], v[220:223], v[156:159]
	v_mfma_f32_16x16x32_bf16 v[50:53], v[16:19], v[224:227], v[30:33]
	v_mfma_f32_16x16x32_bf16 v[30:33], v[22:25], v[220:223], v[160:163]
	v_mfma_f32_16x16x32_bf16 v[46:49], v[26:29], v[224:227], v[30:33]
	v_mfma_f32_16x16x32_bf16 v[30:33], v[12:15], v[228:231], v[164:167]
	v_mfma_f32_16x16x32_bf16 v[4:7], v[12:15], v[236:239], v[4:7]
	v_mfma_f32_16x16x32_bf16 v[34:37], v[16:19], v[232:235], v[30:33]
	v_mfma_f32_16x16x32_bf16 v[30:33], v[22:25], v[228:231], v[168:171]
	v_mfma_f32_16x16x32_bf16 v[18:21], v[16:19], v[240:243], v[4:7]
	v_mfma_f32_16x16x32_bf16 v[4:7], v[22:25], v[236:239], v[8:11]
	v_mfma_f32_16x16x32_bf16 v[30:33], v[26:29], v[232:235], v[30:33]
	v_mfma_f32_16x16x32_bf16 v[14:17], v[26:29], v[240:243], v[4:7]
	v_mfma_f32_16x16x32_bf16 v[4:7], v[204:207], v[38:41], v[172:175]
	v_mfma_f32_16x16x32_bf16 v[58:61], v[208:211], v[42:45], v[4:7]
	v_mfma_f32_16x16x32_bf16 v[4:7], v[212:215], v[38:41], v[176:179]
	v_mfma_f32_16x16x32_bf16 v[54:57], v[216:219], v[42:45], v[4:7]
	v_mfma_f32_16x16x32_bf16 v[4:7], v[204:207], v[220:223], v[180:183]
	v_mfma_f32_16x16x32_bf16 v[42:45], v[208:211], v[224:227], v[4:7]
	v_mfma_f32_16x16x32_bf16 v[4:7], v[212:215], v[220:223], v[184:187]
	v_mfma_f32_16x16x32_bf16 v[38:41], v[216:219], v[224:227], v[4:7]
	v_mfma_f32_16x16x32_bf16 v[4:7], v[204:207], v[228:231], v[188:191]
	v_mfma_f32_16x16x32_bf16 v[26:29], v[208:211], v[232:235], v[4:7]
	v_mfma_f32_16x16x32_bf16 v[4:7], v[212:215], v[228:231], v[192:195]
	v_mfma_f32_16x16x32_bf16 v[22:25], v[216:219], v[232:235], v[4:7]
	v_mfma_f32_16x16x32_bf16 v[4:7], v[204:207], v[236:239], v[196:199]
	v_mfma_f32_16x16x32_bf16 v[10:13], v[208:211], v[240:243], v[4:7]
	v_mfma_f32_16x16x32_bf16 v[4:7], v[212:215], v[236:239], v[200:203]
	v_mfma_f32_16x16x32_bf16 v[6:9], v[216:219], v[240:243], v[4:7]
	s_barrier
	s_setprio 0
	s_mov_b32 s40, 2
	s_branch .LBB0_871

; #define PG8_KSETUP() const bool last = (t == nt - 2); const char* a1 = cA + (size_t)(t + 1) * kstep; \
;             const char* a2 = last ? nA : cA + (size_t)(t + 2) * kstep; const char* b2 = last ? nB : cB + (size_t)(t + 2) * kstep; const char* a3 = a2 + kstep; const char* b3 = b2 + kstep; \
;             if (last && has_next) S.a_ready(nxt)
; template <class Epi, class Sched, bool ALIGN_EPI = false, bool SP2 = false>
; __device__ __forceinline__ void gemm_phase(PG8_LAS unsigned char* lds, const Gemm g, const Sched& S, const Epi& E) {
;     ...
;         int t0 = 0;
;         if constexpr (SP2 && Epi::NVM == 16) { if (ui > 0) { const int t = 0; PG8_KSETUP(); PG8_KITER_SP2(24, 24); t0 = 2; } }
;         if constexpr (SP2 && Epi::NVM == 8) { if (ui > 0) { const int t = 0; PG8_KSETUP(); PG8_KITER_SP2(16, 16); t0 = 2; } }
;         for (int t = t0; t < nt; t += 2) {
;             PG8_KSETUP();
;             if constexpr (SP2) {
;             PG8_KITER_SP2(8, 8);
.LBB0_872:
	ds_read_b128 v[148:151], v143
	ds_read_b128 v[152:155], v143 offset:1024
	ds_read_b128 v[156:159], v143 offset:2048
	ds_read_b128 v[160:163], v143 offset:3072
	ds_read_b128 v[164:167], v144
	ds_read_b128 v[168:171], v144 offset:1024
	ds_read_b128 v[172:175], v144 offset:2048
	ds_read_b128 v[176:179], v144 offset:3072
	s_cmpk_eq_i32 s79, 0x54
	s_cselect_b32 s44, s6, s82
	s_cselect_b32 s45, s7, s83
	s_cselect_b32 s40, s28, s80
	s_cselect_b32 s41, s29, s81
	s_add_u32 s38, s44, 0x80
	s_addc_u32 s39, s45, 0
	ds_read_b128 v[180:183], v145
	ds_read_b128 v[184:187], v145 offset:1024
	ds_read_b128 v[188:191], v145 offset:2048
	ds_read_b128 v[192:195], v145 offset:3072
	ds_read_b128 v[196:199], v145 offset:4096
	ds_read_b128 v[200:203], v145 offset:5120
	ds_read_b128 v[204:207], v145 offset:6144
	ds_read_b128 v[208:211], v145 offset:7168
	s_mov_b32 m0, s71
	s_nop 0
	global_load_lds_dwordx4 v1, s[36:37] offset:0
	s_nop 0
	s_mov_b32 m0, s72
	s_nop 0
	global_load_lds_dwordx4 v139, s[36:37] offset:0
	s_waitcnt vmcnt(8)
	s_waitcnt lgkmcnt(0)
	s_barrier
	s_setprio 1
	v_mfma_f32_16x16x32_bf16 v[130:133], v[148:151], v[180:183], v[130:133]
	v_mfma_f32_16x16x32_bf16 v[130:133], v[152:155], v[184:187], v[130:133]
	v_mfma_f32_16x16x32_bf16 v[126:129], v[156:159], v[180:183], v[126:129]
	v_mfma_f32_16x16x32_bf16 v[126:129], v[160:163], v[184:187], v[126:129]
	v_mfma_f32_16x16x32_bf16 v[114:117], v[148:151], v[188:191], v[114:117]
	v_mfma_f32_16x16x32_bf16 v[114:117], v[152:155], v[192:195], v[114:117]
	v_mfma_f32_16x16x32_bf16 v[110:113], v[156:159], v[188:191], v[110:113]
	v_mfma_f32_16x16x32_bf16 v[110:113], v[160:163], v[192:195], v[110:113]
	v_mfma_f32_16x16x32_bf16 v[98:101], v[148:151], v[196:199], v[98:101]
	v_mfma_f32_16x16x32_bf16 v[98:101], v[152:155], v[200:203], v[98:101]
	v_mfma_f32_16x16x32_bf16 v[94:97], v[156:159], v[196:199], v[94:97]
	v_mfma_f32_16x16x32_bf16 v[94:97], v[160:163], v[200:203], v[94:97]
	v_mfma_f32_16x16x32_bf16 v[82:85], v[148:151], v[204:207], v[82:85]
	v_mfma_f32_16x16x32_bf16 v[82:85], v[152:155], v[208:211], v[82:85]
	v_mfma_f32_16x16x32_bf16 v[78:81], v[156:159], v[204:207], v[78:81]
	v_mfma_f32_16x16x32_bf16 v[78:81], v[160:163], v[208:211], v[78:81]
	v_mfma_f32_16x16x32_bf16 v[122:125], v[164:167], v[180:183], v[122:125]
	v_mfma_f32_16x16x32_bf16 v[122:125], v[168:171], v[184:187], v[122:125]
	v_mfma_f32_16x16x32_bf16 v[118:121], v[172:175], v[180:183], v[118:121]
	v_mfma_f32_16x16x32_bf16 v[118:121], v[176:179], v[184:187], v[118:121]
	v_mfma_f32_16x16x32_bf16 v[106:109], v[164:167], v[188:191], v[106:109]
	v_mfma_f32_16x16x32_bf16 v[106:109], v[168:171], v[192:195], v[106:109]
	v_mfma_f32_16x16x32_bf16 v[102:105], v[172:175], v[188:191], v[102:105]
	v_mfma_f32_16x16x32_bf16 v[102:105], v[176:179], v[192:195], v[102:105]
	v_mfma_f32_16x16x32_bf16 v[90:93], v[164:167], v[196:199], v[90:93]
	v_mfma_f32_16x16x32_bf16 v[90:93], v[168:171], v[200:203], v[90:93]
	v_mfma_f32_16x16x32_bf16 v[86:89], v[172:175], v[196:199], v[86:89]
	v_mfma_f32_16x16x32_bf16 v[86:89], v[176:179], v[200:203], v[86:89]
	v_mfma_f32_16x16x32_bf16 v[70:73], v[164:167], v[204:207], v[70:73]
	v_mfma_f32_16x16x32_bf16 v[70:73], v[168:171], v[208:211], v[70:73]
	v_mfma_f32_16x16x32_bf16 v[62:65], v[172:175], v[204:207], v[62:65]
	v_mfma_f32_16x16x32_bf16 v[62:65], v[176:179], v[208:211], v[62:65]
	s_barrier
	s_setprio 0
	ds_read_b128 v[180:183], v145 offset:16384
	ds_read_b128 v[184:187], v145 offset:17408
	ds_read_b128 v[188:191], v145 offset:18432
	ds_read_b128 v[192:195], v145 offset:19456
	ds_read_b128 v[196:199], v145 offset:20480
	ds_read_b128 v[200:203], v145 offset:21504
	ds_read_b128 v[204:207], v145 offset:22528
	ds_read_b128 v[208:211], v145 offset:23552
	s_mov_b32 m0, s54
	s_nop 0
	global_load_lds_dwordx4 v138, s[40:41] offset:0
	s_add_u32 s30, s40, 0x160000
	s_mov_b32 m0, s55
	s_nop 0
	global_load_lds_dwordx4 v140, s[40:41] offset:0
	s_addc_u32 s31, s41, 0
	s_mov_b32 m0, s56
	s_nop 0
	global_load_lds_dwordx4 v138, s[30:31] offset:0
	s_nop 0
	s_mov_b32 m0, s57
	s_nop 0
	global_load_lds_dwordx4 v140, s[30:31] offset:0
	s_nop 0
	s_mov_b32 m0, s47
	s_nop 0
	global_load_lds_dwordx4 v1, s[44:45] offset:0
	s_nop 0
	s_mov_b32 m0, s58
	s_nop 0
	global_load_lds_dwordx4 v139, s[44:45] offset:0
	s_waitcnt vmcnt(8)
	s_waitcnt lgkmcnt(0)
	s_barrier
	s_setprio 1
	v_mfma_f32_16x16x32_bf16 v[74:77], v[148:151], v[180:183], v[74:77]
	v_mfma_f32_16x16x32_bf16 v[74:77], v[152:155], v[184:187], v[74:77]
	v_mfma_f32_16x16x32_bf16 v[66:69], v[156:159], v[180:183], v[66:69]
	v_mfma_f32_16x16x32_bf16 v[66:69], v[160:163], v[184:187], v[66:69]
	v_mfma_f32_16x16x32_bf16 v[50:53], v[148:151], v[188:191], v[50:53]
	v_mfma_f32_16x16x32_bf16 v[50:53], v[152:155], v[192:195], v[50:53]
	v_mfma_f32_16x16x32_bf16 v[46:49], v[156:159], v[188:191], v[46:49]
	v_mfma_f32_16x16x32_bf16 v[46:49], v[160:163], v[192:195], v[46:49]
	v_mfma_f32_16x16x32_bf16 v[34:37], v[148:151], v[196:199], v[34:37]
	v_mfma_f32_16x16x32_bf16 v[34:37], v[152:155], v[200:203], v[34:37]
	v_mfma_f32_16x16x32_bf16 v[30:33], v[156:159], v[196:199], v[30:33]
	v_mfma_f32_16x16x32_bf16 v[30:33], v[160:163], v[200:203], v[30:33]
	v_mfma_f32_16x16x32_bf16 v[18:21], v[148:151], v[204:207], v[18:21]
	v_mfma_f32_16x16x32_bf16 v[18:21], v[152:155], v[208:211], v[18:21]
	v_mfma_f32_16x16x32_bf16 v[14:17], v[156:159], v[204:207], v[14:17]
	v_mfma_f32_16x16x32_bf16 v[14:17], v[160:163], v[208:211], v[14:17]
	v_mfma_f32_16x16x32_bf16 v[58:61], v[164:167], v[180:183], v[58:61]
	v_mfma_f32_16x16x32_bf16 v[54:57], v[172:175], v[180:183], v[54:57]
	v_mfma_f32_16x16x32_bf16 v[42:45], v[164:167], v[188:191], v[42:45]
	v_mfma_f32_16x16x32_bf16 v[38:41], v[172:175], v[188:191], v[38:41]
	v_mfma_f32_16x16x32_bf16 v[26:29], v[164:167], v[196:199], v[26:29]
	v_mfma_f32_16x16x32_bf16 v[22:25], v[172:175], v[196:199], v[22:25]
	v_mfma_f32_16x16x32_bf16 v[10:13], v[164:167], v[204:207], v[10:13]
	v_mfma_f32_16x16x32_bf16 v[4:7], v[172:175], v[204:207], v[6:9]
	v_mfma_f32_16x16x32_bf16 v[58:61], v[168:171], v[184:187], v[58:61]
	v_mfma_f32_16x16x32_bf16 v[54:57], v[176:179], v[184:187], v[54:57]
	v_mfma_f32_16x16x32_bf16 v[42:45], v[168:171], v[192:195], v[42:45]
	v_mfma_f32_16x16x32_bf16 v[38:41], v[176:179], v[192:195], v[38:41]
	v_mfma_f32_16x16x32_bf16 v[26:29], v[168:171], v[200:203], v[26:29]
	v_mfma_f32_16x16x32_bf16 v[22:25], v[176:179], v[200:203], v[22:25]
	v_mfma_f32_16x16x32_bf16 v[10:13], v[168:171], v[208:211], v[10:13]
	v_mfma_f32_16x16x32_bf16 v[4:7], v[176:179], v[208:211], v[4:7]
	s_barrier
; #define PG8_STAGE(bufoff, gbase, voff) PG8_STAGEI(bufoff, gbase, 0, voff)
; #define PG8_LDA(dst, b, h) do { _Pragma("unroll") for (int m = 0; m < 4; ++m) _Pragma("unroll") for (int k = 0; k < 2; ++k) dst[m][k] = *(const PG8_LAS bf16x8*)(lds + PG8_SA(b, h) + aoff + m * 2048 + k * 1024); } while (0)
; #define PG8_WAIT_V(n) asm volatile("s_waitcnt vmcnt(" #n ")" ::: "memory")
; #define PG8_BAR __builtin_amdgcn_s_barrier()
; template <class Epi, class Sched, bool ALIGN_EPI = false, bool SP2 = false>
; __device__ __forceinline__ void gemm_phase(PG8_LAS unsigned char* lds, const Gemm g, const Sched& S, const Epi& E) {
;     ...
;         int t0 = 0;
;         if constexpr (SP2 && Epi::NVM == 16) { if (ui > 0) { const int t = 0; PG8_KSETUP(); PG8_KITER_SP2(24, 24); t0 = 2; } }
;         if constexpr (SP2 && Epi::NVM == 8) { if (ui > 0) { const int t = 0; PG8_KSETUP(); PG8_KITER_SP2(16, 16); t0 = 2; } }
;         for (int t = t0; t < nt; t += 2) {
;             PG8_KSETUP();
;             if constexpr (SP2) {
;             PG8_KITER_SP2(8, 8);
;             } else {
;             PG8_LDB(B0, 0, 0); PG8_SCHED; PG8_LDA(At, 0, 0); PG8_STAGE(PG8_SA(1, 1), a1 + hstep, voffA);
;             PG8_WAIT_L(8); PG8_BAR; PG8_WAIT_L(0); PG8_MMA(0, 0, At, B0); PG8_BAR; PG8_SCHED;
;             PG8_LDB(B1, 0, 1); PG8_STAGE(PG8_SB(0, 0), b2, voffB);
;             PG8_BAR; PG8_WAIT_L(0); PG8_MMA(0, 1, At, B1); PG8_BAR;
;             PG8_LDA(At, 0, 1); PG8_STAGE(PG8_SA(0, 0), a2, voffA);
;             PG8_BAR; PG8_WAIT_L(0); PG8_MMA(1, 0, At, B0); PG8_BAR; PG8_SCHED;
;             PG8_STAGE(PG8_SB(0, 1), b2 + hstep, voffB);
;             PG8_WAIT_V(6); PG8_BAR; PG8_MMA(1, 1, At, B1); PG8_BAR;
;             PG8_LDB(B0, 1, 0); PG8_SCHED; PG8_LDA(At, 1, 0); PG8_STAGE(PG8_SA(0, 1), a2 + hstep, voffA);
;             PG8_WAIT_L(8); PG8_BAR; PG8_WAIT_L(0); PG8_MMA(0, 0, At, B0); PG8_BAR; PG8_SCHED;
;             PG8_LDB(B1, 1, 1); PG8_STAGE(PG8_SB(1, 0), b3, voffB);
;             PG8_BAR; PG8_WAIT_L(0); PG8_MMA(0, 1, At, B1); PG8_BAR;
;             PG8_LDA(At, 1, 1); PG8_STAGE(PG8_SA(1, 0), a3, voffA);
;             PG8_BAR; PG8_WAIT_L(0); PG8_MMA(1, 0, At, B0); PG8_BAR; PG8_SCHED;
;             PG8_STAGE(PG8_SB(1, 1), b3 + hstep, voffB);
;             PG8_WAIT_V(6); PG8_BAR; PG8_MMA(1, 1, At, B1); PG8_BAR;
;             }
;         }
;     ...
;         if constexpr (ALIGN_EPI) { if (wr == 0) PG8_BAR; }
	s_setprio 0
	ds_read_b128 v[148:151], v146
	ds_read_b128 v[152:155], v146 offset:1024
	ds_read_b128 v[156:159], v146 offset:2048
	ds_read_b128 v[160:163], v146 offset:3072
	ds_read_b128 v[164:167], v147
	ds_read_b128 v[168:171], v147 offset:1024
	ds_read_b128 v[172:175], v147 offset:2048
	ds_read_b128 v[176:179], v147 offset:3072
	ds_read_b128 v[180:183], v145 offset:32768
	ds_read_b128 v[184:187], v145 offset:33792
	ds_read_b128 v[188:191], v145 offset:34816
	ds_read_b128 v[192:195], v145 offset:35840
	ds_read_b128 v[196:199], v145 offset:36864
	ds_read_b128 v[200:203], v145 offset:37888
	ds_read_b128 v[204:207], v145 offset:38912
	ds_read_b128 v[208:211], v145 offset:39936
	s_add_u32 s30, s44, 0x160000
	s_addc_u32 s31, s45, 0
	s_mov_b32 m0, s59
	s_nop 0
	global_load_lds_dwordx4 v1, s[30:31] offset:0
	s_nop 0
	s_mov_b32 m0, s64
	s_nop 0
	global_load_lds_dwordx4 v139, s[30:31] offset:0
	s_waitcnt vmcnt(8)
	s_waitcnt lgkmcnt(0)
	s_barrier
	s_setprio 1
	v_mfma_f32_16x16x32_bf16 v[130:133], v[148:151], v[180:183], v[130:133]
	v_mfma_f32_16x16x32_bf16 v[130:133], v[152:155], v[184:187], v[130:133]
	v_mfma_f32_16x16x32_bf16 v[126:129], v[156:159], v[180:183], v[126:129]
	v_mfma_f32_16x16x32_bf16 v[126:129], v[160:163], v[184:187], v[126:129]
	v_mfma_f32_16x16x32_bf16 v[114:117], v[148:151], v[188:191], v[114:117]
	v_mfma_f32_16x16x32_bf16 v[114:117], v[152:155], v[192:195], v[114:117]
	v_mfma_f32_16x16x32_bf16 v[110:113], v[156:159], v[188:191], v[110:113]
	v_mfma_f32_16x16x32_bf16 v[110:113], v[160:163], v[192:195], v[110:113]
	v_mfma_f32_16x16x32_bf16 v[98:101], v[148:151], v[196:199], v[98:101]
	v_mfma_f32_16x16x32_bf16 v[98:101], v[152:155], v[200:203], v[98:101]
	v_mfma_f32_16x16x32_bf16 v[94:97], v[156:159], v[196:199], v[94:97]
	v_mfma_f32_16x16x32_bf16 v[94:97], v[160:163], v[200:203], v[94:97]
	v_mfma_f32_16x16x32_bf16 v[82:85], v[148:151], v[204:207], v[82:85]
	v_mfma_f32_16x16x32_bf16 v[82:85], v[152:155], v[208:211], v[82:85]
	v_mfma_f32_16x16x32_bf16 v[78:81], v[156:159], v[204:207], v[78:81]
	v_mfma_f32_16x16x32_bf16 v[78:81], v[160:163], v[208:211], v[78:81]
	v_mfma_f32_16x16x32_bf16 v[122:125], v[164:167], v[180:183], v[122:125]
	v_mfma_f32_16x16x32_bf16 v[122:125], v[168:171], v[184:187], v[122:125]
	v_mfma_f32_16x16x32_bf16 v[118:121], v[172:175], v[180:183], v[118:121]
	v_mfma_f32_16x16x32_bf16 v[118:121], v[176:179], v[184:187], v[118:121]
	v_mfma_f32_16x16x32_bf16 v[106:109], v[164:167], v[188:191], v[106:109]
	v_mfma_f32_16x16x32_bf16 v[106:109], v[168:171], v[192:195], v[106:109]
	v_mfma_f32_16x16x32_bf16 v[102:105], v[172:175], v[188:191], v[102:105]
	v_mfma_f32_16x16x32_bf16 v[102:105], v[176:179], v[192:195], v[102:105]
	v_mfma_f32_16x16x32_bf16 v[90:93], v[164:167], v[196:199], v[90:93]
	v_mfma_f32_16x16x32_bf16 v[90:93], v[168:171], v[200:203], v[90:93]
	v_mfma_f32_16x16x32_bf16 v[86:89], v[172:175], v[196:199], v[86:89]
	v_mfma_f32_16x16x32_bf16 v[86:89], v[176:179], v[200:203], v[86:89]
	v_mfma_f32_16x16x32_bf16 v[70:73], v[164:167], v[204:207], v[70:73]
	v_mfma_f32_16x16x32_bf16 v[70:73], v[168:171], v[208:211], v[70:73]
	v_mfma_f32_16x16x32_bf16 v[62:65], v[172:175], v[204:207], v[62:65]
	v_mfma_f32_16x16x32_bf16 v[62:65], v[176:179], v[208:211], v[62:65]
	s_barrier
	s_setprio 0
	ds_read_b128 v[180:183], v145 offset:49152
	ds_read_b128 v[184:187], v145 offset:50176
	ds_read_b128 v[188:191], v145 offset:51200
	ds_read_b128 v[192:195], v145 offset:52224
	ds_read_b128 v[196:199], v145 offset:53248
	ds_read_b128 v[200:203], v145 offset:54272
	ds_read_b128 v[204:207], v145 offset:55296
	ds_read_b128 v[208:211], v145 offset:56320
	s_add_u32 s30, s40, 0x80
	s_addc_u32 s31, s41, 0
	s_mov_b32 m0, s65
	s_nop 0
	global_load_lds_dwordx4 v138, s[30:31] offset:0
	s_nop 0
	s_mov_b32 m0, s66
	s_nop 0
	global_load_lds_dwordx4 v140, s[30:31] offset:0
	s_add_u32 s30, s40, 0x160080
	s_addc_u32 s31, s41, 0
	s_mov_b32 m0, s69
	s_nop 0
	global_load_lds_dwordx4 v138, s[30:31] offset:0
	s_nop 0
	s_mov_b32 m0, s70
	s_nop 0
	global_load_lds_dwordx4 v140, s[30:31] offset:0
	s_nop 0
	s_mov_b32 m0, s67
	s_nop 0
	global_load_lds_dwordx4 v1, s[38:39] offset:0
	s_nop 0
	s_mov_b32 m0, s68
	s_nop 0
	global_load_lds_dwordx4 v139, s[38:39] offset:0
	s_waitcnt vmcnt(8)
	s_waitcnt lgkmcnt(0)
	s_barrier
	s_setprio 1
	v_mfma_f32_16x16x32_bf16 v[74:77], v[148:151], v[180:183], v[74:77]
	v_mfma_f32_16x16x32_bf16 v[74:77], v[152:155], v[184:187], v[74:77]
	v_mfma_f32_16x16x32_bf16 v[66:69], v[156:159], v[180:183], v[66:69]
	v_mfma_f32_16x16x32_bf16 v[66:69], v[160:163], v[184:187], v[66:69]
	v_mfma_f32_16x16x32_bf16 v[50:53], v[148:151], v[188:191], v[50:53]
	v_mfma_f32_16x16x32_bf16 v[50:53], v[152:155], v[192:195], v[50:53]
	v_mfma_f32_16x16x32_bf16 v[46:49], v[156:159], v[188:191], v[46:49]
	v_mfma_f32_16x16x32_bf16 v[46:49], v[160:163], v[192:195], v[46:49]
	v_mfma_f32_16x16x32_bf16 v[34:37], v[148:151], v[196:199], v[34:37]
	v_mfma_f32_16x16x32_bf16 v[34:37], v[152:155], v[200:203], v[34:37]
	v_mfma_f32_16x16x32_bf16 v[30:33], v[156:159], v[196:199], v[30:33]
	v_mfma_f32_16x16x32_bf16 v[30:33], v[160:163], v[200:203], v[30:33]
	v_mfma_f32_16x16x32_bf16 v[18:21], v[148:151], v[204:207], v[18:21]
	v_mfma_f32_16x16x32_bf16 v[18:21], v[152:155], v[208:211], v[18:21]
	v_mfma_f32_16x16x32_bf16 v[14:17], v[156:159], v[204:207], v[14:17]
	v_mfma_f32_16x16x32_bf16 v[14:17], v[160:163], v[208:211], v[14:17]
	v_mfma_f32_16x16x32_bf16 v[58:61], v[164:167], v[180:183], v[58:61]
	v_mfma_f32_16x16x32_bf16 v[54:57], v[172:175], v[180:183], v[54:57]
	v_mfma_f32_16x16x32_bf16 v[42:45], v[164:167], v[188:191], v[42:45]
	v_mfma_f32_16x16x32_bf16 v[38:41], v[172:175], v[188:191], v[38:41]
	v_mfma_f32_16x16x32_bf16 v[26:29], v[164:167], v[196:199], v[26:29]
	v_mfma_f32_16x16x32_bf16 v[22:25], v[172:175], v[196:199], v[22:25]
	v_mfma_f32_16x16x32_bf16 v[8:11], v[164:167], v[204:207], v[10:13]
	v_mfma_f32_16x16x32_bf16 v[4:7], v[172:175], v[204:207], v[4:7]
	v_mfma_f32_16x16x32_bf16 v[58:61], v[168:171], v[184:187], v[58:61]
	v_mfma_f32_16x16x32_bf16 v[54:57], v[176:179], v[184:187], v[54:57]
	v_mfma_f32_16x16x32_bf16 v[42:45], v[168:171], v[192:195], v[42:45]
	v_mfma_f32_16x16x32_bf16 v[38:41], v[176:179], v[192:195], v[38:41]
	v_mfma_f32_16x16x32_bf16 v[26:29], v[168:171], v[200:203], v[26:29]
	v_mfma_f32_16x16x32_bf16 v[22:25], v[176:179], v[200:203], v[22:25]
	v_mfma_f32_16x16x32_bf16 v[10:13], v[168:171], v[208:211], v[8:11]
	v_mfma_f32_16x16x32_bf16 v[6:9], v[176:179], v[208:211], v[4:7]
	s_barrier
	s_setprio 0
	s_add_i32 s79, s79, 2
	s_add_u32 s80, s80, 0x100
	s_addc_u32 s81, s81, 0
	s_add_u32 s82, s82, 0x100
	s_addc_u32 s83, s83, 0
	s_add_u32 s36, s36, 0x100
	s_addc_u32 s37, s37, 0
	s_cmpk_gt_u32 s79, 0x55
	s_cbranch_scc0 .LBB0_872
	s_and_b64 vcc, exec, s[16:17]
	s_cbranch_vccz .LBB0_875
	s_barrier

; #define PG8_KSETUP() const bool last = (t == nt - 2); const char* a1 = cA + (size_t)(t + 1) * kstep; \
;             const char* a2 = last ? nA : cA + (size_t)(t + 2) * kstep; const char* b2 = last ? nB : cB + (size_t)(t + 2) * kstep; const char* a3 = a2 + kstep; const char* b3 = b2 + kstep; \
;             if (last && has_next) S.a_ready(nxt)
; template <class Epi, class Sched, bool ALIGN_EPI = false, bool SP2 = false>
; __device__ __forceinline__ void gemm_phase(PG8_LAS unsigned char* lds, const Gemm g, const Sched& S, const Epi& E) {
;     ...
;         int t0 = 0;
;         if constexpr (SP2 && Epi::NVM == 16) { if (ui > 0) { const int t = 0; PG8_KSETUP(); PG8_KITER_SP2(24, 24); t0 = 2; } }
;         if constexpr (SP2 && Epi::NVM == 8) { if (ui > 0) { const int t = 0; PG8_KSETUP(); PG8_KITER_SP2(16, 16); t0 = 2; } }
;         for (int t = t0; t < nt; t += 2) {
;             PG8_KSETUP();
;             if constexpr (SP2) {
;             PG8_KITER_SP2(8, 8);
.LBB0_1013:
	s_add_u32 s30, s40, s58
	s_addc_u32 s31, s41, 0
	s_add_u32 s42, s30, 0x100
	s_addc_u32 s43, s31, 0
	s_and_b64 s[30:31], s[54:55], exec
	s_cselect_b32 s67, s25, s43
	s_cselect_b32 s66, s94, s42
	s_add_u32 s30, s44, s58
	s_addc_u32 s31, s45, 0
	s_add_u32 s42, s30, 0x100
	s_addc_u32 s43, s31, 0
	s_add_u32 s56, s66, 0x80
	s_addc_u32 s57, s67, 0
	s_and_b64 s[30:31], s[54:55], exec
	s_cselect_b32 s69, s23, s43
	s_cselect_b32 s68, s95, s42
	s_add_u32 s30, s96, s58
	s_addc_u32 s31, s97, 0
	ds_read_b128 v[146:149], v141
	ds_read_b128 v[150:153], v141 offset:1024
	ds_read_b128 v[154:157], v141 offset:2048
	ds_read_b128 v[158:161], v141 offset:3072
	ds_read_b128 v[162:165], v142
	ds_read_b128 v[166:169], v142 offset:1024
	ds_read_b128 v[170:173], v142 offset:2048
	ds_read_b128 v[174:177], v142 offset:3072
	s_add_u32 s72, s30, 0x80
	s_addc_u32 s73, s31, 0
	s_add_u32 s70, s68, 0x10000
	s_addc_u32 s71, s69, 0
	s_add_u32 s64, s66, 0x10000
	s_addc_u32 s65, s67, 0
	s_add_u32 s58, s68, 0x80
	s_addc_u32 s59, s69, 0
	s_add_u32 s54, s68, 0x10080
	s_addc_u32 s55, s69, 0
	ds_read_b128 v[178:181], v143
	ds_read_b128 v[182:185], v143 offset:1024
	ds_read_b128 v[186:189], v143 offset:2048
	ds_read_b128 v[190:193], v143 offset:3072
	ds_read_b128 v[194:197], v143 offset:4096
	ds_read_b128 v[198:201], v143 offset:5120
	ds_read_b128 v[202:205], v143 offset:6144
	ds_read_b128 v[206:209], v143 offset:7168
	s_mov_b32 m0, s86
	s_nop 0
	global_load_lds_dwordx4 v1, s[72:73] offset:0
	s_nop 0
	s_mov_b32 m0, s87
	s_nop 0
	global_load_lds_dwordx4 v137, s[72:73] offset:0
	s_waitcnt vmcnt(8)
	s_waitcnt lgkmcnt(0)
	s_barrier
	s_setprio 1
	v_mfma_f32_16x16x32_bf16 v[126:129], v[146:149], v[178:181], v[126:129]
	v_mfma_f32_16x16x32_bf16 v[126:129], v[150:153], v[182:185], v[126:129]
	v_mfma_f32_16x16x32_bf16 v[122:125], v[154:157], v[178:181], v[122:125]
	v_mfma_f32_16x16x32_bf16 v[122:125], v[158:161], v[182:185], v[122:125]
	v_mfma_f32_16x16x32_bf16 v[118:121], v[146:149], v[186:189], v[118:121]
	v_mfma_f32_16x16x32_bf16 v[118:121], v[150:153], v[190:193], v[118:121]
	v_mfma_f32_16x16x32_bf16 v[110:113], v[154:157], v[186:189], v[110:113]
	v_mfma_f32_16x16x32_bf16 v[110:113], v[158:161], v[190:193], v[110:113]
	v_mfma_f32_16x16x32_bf16 v[102:105], v[146:149], v[194:197], v[102:105]
	v_mfma_f32_16x16x32_bf16 v[102:105], v[150:153], v[198:201], v[102:105]
	v_mfma_f32_16x16x32_bf16 v[94:97], v[154:157], v[194:197], v[94:97]
	v_mfma_f32_16x16x32_bf16 v[94:97], v[158:161], v[198:201], v[94:97]
	v_mfma_f32_16x16x32_bf16 v[86:89], v[146:149], v[202:205], v[86:89]
	v_mfma_f32_16x16x32_bf16 v[86:89], v[150:153], v[206:209], v[86:89]
	v_mfma_f32_16x16x32_bf16 v[78:81], v[154:157], v[202:205], v[78:81]
	v_mfma_f32_16x16x32_bf16 v[78:81], v[158:161], v[206:209], v[78:81]
	v_mfma_f32_16x16x32_bf16 v[114:117], v[162:165], v[178:181], v[114:117]
	v_mfma_f32_16x16x32_bf16 v[114:117], v[166:169], v[182:185], v[114:117]
	v_mfma_f32_16x16x32_bf16 v[106:109], v[170:173], v[178:181], v[106:109]
	v_mfma_f32_16x16x32_bf16 v[106:109], v[174:177], v[182:185], v[106:109]
	v_mfma_f32_16x16x32_bf16 v[98:101], v[162:165], v[186:189], v[98:101]
	v_mfma_f32_16x16x32_bf16 v[98:101], v[166:169], v[190:193], v[98:101]
	v_mfma_f32_16x16x32_bf16 v[90:93], v[170:173], v[186:189], v[90:93]
	v_mfma_f32_16x16x32_bf16 v[90:93], v[174:177], v[190:193], v[90:93]
	v_mfma_f32_16x16x32_bf16 v[82:85], v[162:165], v[194:197], v[82:85]
	v_mfma_f32_16x16x32_bf16 v[82:85], v[166:169], v[198:201], v[82:85]
	v_mfma_f32_16x16x32_bf16 v[74:77], v[170:173], v[194:197], v[74:77]
	v_mfma_f32_16x16x32_bf16 v[74:77], v[174:177], v[198:201], v[74:77]
	v_mfma_f32_16x16x32_bf16 v[70:73], v[162:165], v[202:205], v[70:73]
	v_mfma_f32_16x16x32_bf16 v[70:73], v[166:169], v[206:209], v[70:73]
	v_mfma_f32_16x16x32_bf16 v[66:69], v[170:173], v[202:205], v[66:69]
	v_mfma_f32_16x16x32_bf16 v[66:69], v[174:177], v[206:209], v[66:69]
	s_barrier
	s_setprio 0
	ds_read_b128 v[178:181], v143 offset:16384
	ds_read_b128 v[182:185], v143 offset:17408
	ds_read_b128 v[186:189], v143 offset:18432
	ds_read_b128 v[190:193], v143 offset:19456
	ds_read_b128 v[194:197], v143 offset:20480
	ds_read_b128 v[198:201], v143 offset:21504
	ds_read_b128 v[202:205], v143 offset:22528
	ds_read_b128 v[206:209], v143 offset:23552
	s_mov_b32 m0, s39
	s_nop 0
	global_load_lds_dwordx4 v136, s[68:69] offset:0
	s_nop 0
	s_mov_b32 m0, s74
	s_nop 0
	global_load_lds_dwordx4 v138, s[68:69] offset:0
	s_nop 0
	s_mov_b32 m0, s75
	s_nop 0
	global_load_lds_dwordx4 v136, s[70:71] offset:0
	s_nop 0
	s_mov_b32 m0, s76
	s_nop 0
	global_load_lds_dwordx4 v138, s[70:71] offset:0
	s_nop 0
	s_mov_b32 m0, s53
	s_nop 0
	global_load_lds_dwordx4 v1, s[66:67] offset:0
	s_nop 0
	s_mov_b32 m0, s77
	s_nop 0
	global_load_lds_dwordx4 v137, s[66:67] offset:0
	s_waitcnt vmcnt(8)
	s_waitcnt lgkmcnt(0)
	s_barrier
	s_setprio 1
	v_mfma_f32_16x16x32_bf16 v[62:65], v[146:149], v[178:181], v[62:65]
	v_mfma_f32_16x16x32_bf16 v[62:65], v[150:153], v[182:185], v[62:65]
	v_mfma_f32_16x16x32_bf16 v[58:61], v[154:157], v[178:181], v[58:61]
	v_mfma_f32_16x16x32_bf16 v[58:61], v[158:161], v[182:185], v[58:61]
	v_mfma_f32_16x16x32_bf16 v[54:57], v[146:149], v[186:189], v[54:57]
	v_mfma_f32_16x16x32_bf16 v[54:57], v[150:153], v[190:193], v[54:57]
	v_mfma_f32_16x16x32_bf16 v[46:49], v[154:157], v[186:189], v[46:49]
	v_mfma_f32_16x16x32_bf16 v[46:49], v[158:161], v[190:193], v[46:49]
	v_mfma_f32_16x16x32_bf16 v[38:41], v[146:149], v[194:197], v[38:41]
	v_mfma_f32_16x16x32_bf16 v[38:41], v[150:153], v[198:201], v[38:41]
	v_mfma_f32_16x16x32_bf16 v[30:33], v[154:157], v[194:197], v[30:33]
	v_mfma_f32_16x16x32_bf16 v[30:33], v[158:161], v[198:201], v[30:33]
	v_mfma_f32_16x16x32_bf16 v[22:25], v[146:149], v[202:205], v[22:25]
	v_mfma_f32_16x16x32_bf16 v[22:25], v[150:153], v[206:209], v[22:25]
	v_mfma_f32_16x16x32_bf16 v[14:17], v[154:157], v[202:205], v[14:17]
	v_mfma_f32_16x16x32_bf16 v[14:17], v[158:161], v[206:209], v[14:17]
	v_mfma_f32_16x16x32_bf16 v[50:53], v[162:165], v[178:181], v[50:53]
	v_mfma_f32_16x16x32_bf16 v[50:53], v[166:169], v[182:185], v[50:53]
	v_mfma_f32_16x16x32_bf16 v[42:45], v[170:173], v[178:181], v[42:45]
	v_mfma_f32_16x16x32_bf16 v[42:45], v[174:177], v[182:185], v[42:45]
	v_mfma_f32_16x16x32_bf16 v[34:37], v[162:165], v[186:189], v[34:37]
	v_mfma_f32_16x16x32_bf16 v[34:37], v[166:169], v[190:193], v[34:37]
	v_mfma_f32_16x16x32_bf16 v[26:29], v[170:173], v[186:189], v[26:29]
	v_mfma_f32_16x16x32_bf16 v[26:29], v[174:177], v[190:193], v[26:29]
	v_mfma_f32_16x16x32_bf16 v[18:21], v[162:165], v[194:197], v[18:21]
	v_mfma_f32_16x16x32_bf16 v[18:21], v[166:169], v[198:201], v[18:21]
	v_mfma_f32_16x16x32_bf16 v[10:13], v[170:173], v[194:197], v[10:13]
	v_mfma_f32_16x16x32_bf16 v[10:13], v[174:177], v[198:201], v[10:13]
	v_mfma_f32_16x16x32_bf16 v[6:9], v[162:165], v[202:205], v[6:9]
	v_mfma_f32_16x16x32_bf16 v[6:9], v[166:169], v[206:209], v[6:9]
	v_mfma_f32_16x16x32_bf16 v[2:5], v[170:173], v[202:205], v[2:5]
	v_mfma_f32_16x16x32_bf16 v[2:5], v[174:177], v[206:209], v[2:5]
	s_barrier
	s_setprio 0
	ds_read_b128 v[146:149], v144
	ds_read_b128 v[150:153], v144 offset:1024
	ds_read_b128 v[154:157], v144 offset:2048
	ds_read_b128 v[158:161], v144 offset:3072
	ds_read_b128 v[162:165], v145
	ds_read_b128 v[166:169], v145 offset:1024
	ds_read_b128 v[170:173], v145 offset:2048
	ds_read_b128 v[174:177], v145 offset:3072
	ds_read_b128 v[178:181], v143 offset:32768
	ds_read_b128 v[182:185], v143 offset:33792
	ds_read_b128 v[186:189], v143 offset:34816
	ds_read_b128 v[190:193], v143 offset:35840
	ds_read_b128 v[194:197], v143 offset:36864
	ds_read_b128 v[198:201], v143 offset:37888
	ds_read_b128 v[202:205], v143 offset:38912
	ds_read_b128 v[206:209], v143 offset:39936
	s_mov_b32 m0, s78
	s_nop 0
	global_load_lds_dwordx4 v1, s[64:65] offset:0
	s_nop 0
	s_mov_b32 m0, s79
	s_nop 0
	global_load_lds_dwordx4 v137, s[64:65] offset:0
	s_waitcnt vmcnt(8)
	s_waitcnt lgkmcnt(0)
	s_barrier
	s_setprio 1
	v_mfma_f32_16x16x32_bf16 v[126:129], v[146:149], v[178:181], v[126:129]
	v_mfma_f32_16x16x32_bf16 v[126:129], v[150:153], v[182:185], v[126:129]
	v_mfma_f32_16x16x32_bf16 v[122:125], v[154:157], v[178:181], v[122:125]
	v_mfma_f32_16x16x32_bf16 v[122:125], v[158:161], v[182:185], v[122:125]
	v_mfma_f32_16x16x32_bf16 v[118:121], v[146:149], v[186:189], v[118:121]
	v_mfma_f32_16x16x32_bf16 v[118:121], v[150:153], v[190:193], v[118:121]
	v_mfma_f32_16x16x32_bf16 v[110:113], v[154:157], v[186:189], v[110:113]
	v_mfma_f32_16x16x32_bf16 v[110:113], v[158:161], v[190:193], v[110:113]
	v_mfma_f32_16x16x32_bf16 v[102:105], v[146:149], v[194:197], v[102:105]
	v_mfma_f32_16x16x32_bf16 v[102:105], v[150:153], v[198:201], v[102:105]
	v_mfma_f32_16x16x32_bf16 v[94:97], v[154:157], v[194:197], v[94:97]
	v_mfma_f32_16x16x32_bf16 v[94:97], v[158:161], v[198:201], v[94:97]
	v_mfma_f32_16x16x32_bf16 v[86:89], v[146:149], v[202:205], v[86:89]
	v_mfma_f32_16x16x32_bf16 v[86:89], v[150:153], v[206:209], v[86:89]
	v_mfma_f32_16x16x32_bf16 v[78:81], v[154:157], v[202:205], v[78:81]
	v_mfma_f32_16x16x32_bf16 v[78:81], v[158:161], v[206:209], v[78:81]
	v_mfma_f32_16x16x32_bf16 v[114:117], v[162:165], v[178:181], v[114:117]
	v_mfma_f32_16x16x32_bf16 v[114:117], v[166:169], v[182:185], v[114:117]
	v_mfma_f32_16x16x32_bf16 v[106:109], v[170:173], v[178:181], v[106:109]
	v_mfma_f32_16x16x32_bf16 v[106:109], v[174:177], v[182:185], v[106:109]
	v_mfma_f32_16x16x32_bf16 v[98:101], v[162:165], v[186:189], v[98:101]
	v_mfma_f32_16x16x32_bf16 v[98:101], v[166:169], v[190:193], v[98:101]
	v_mfma_f32_16x16x32_bf16 v[90:93], v[170:173], v[186:189], v[90:93]
	v_mfma_f32_16x16x32_bf16 v[90:93], v[174:177], v[190:193], v[90:93]
	v_mfma_f32_16x16x32_bf16 v[82:85], v[162:165], v[194:197], v[82:85]
	v_mfma_f32_16x16x32_bf16 v[82:85], v[166:169], v[198:201], v[82:85]
	v_mfma_f32_16x16x32_bf16 v[74:77], v[170:173], v[194:197], v[74:77]
	v_mfma_f32_16x16x32_bf16 v[74:77], v[174:177], v[198:201], v[74:77]
	v_mfma_f32_16x16x32_bf16 v[70:73], v[162:165], v[202:205], v[70:73]
	v_mfma_f32_16x16x32_bf16 v[70:73], v[166:169], v[206:209], v[70:73]
	v_mfma_f32_16x16x32_bf16 v[66:69], v[170:173], v[202:205], v[66:69]
	v_mfma_f32_16x16x32_bf16 v[66:69], v[174:177], v[206:209], v[66:69]
	s_barrier
; #define PG8_STAGE(bufoff, gbase, voff) PG8_STAGEI(bufoff, gbase, 0, voff)
; #define PG8_LDA(dst, b, h) do { _Pragma("unroll") for (int m = 0; m < 4; ++m) _Pragma("unroll") for (int k = 0; k < 2; ++k) dst[m][k] = *(const PG8_LAS bf16x8*)(lds + PG8_SA(b, h) + aoff + m * 2048 + k * 1024); } while (0)
; #define PG8_WAIT_V(n) asm volatile("s_waitcnt vmcnt(" #n ")" ::: "memory")
; #define PG8_BAR __builtin_amdgcn_s_barrier()
; template <class Epi, class Sched, bool ALIGN_EPI = false, bool SP2 = false>
; __device__ __forceinline__ void gemm_phase(PG8_LAS unsigned char* lds, const Gemm g, const Sched& S, const Epi& E) {
;     ...
;         int t0 = 0;
;         if constexpr (SP2 && Epi::NVM == 16) { if (ui > 0) { const int t = 0; PG8_KSETUP(); PG8_KITER_SP2(24, 24); t0 = 2; } }
;         if constexpr (SP2 && Epi::NVM == 8) { if (ui > 0) { const int t = 0; PG8_KSETUP(); PG8_KITER_SP2(16, 16); t0 = 2; } }
;         for (int t = t0; t < nt; t += 2) {
;             PG8_KSETUP();
;             if constexpr (SP2) {
;             PG8_KITER_SP2(8, 8);
;             } else {
;             PG8_LDB(B0, 0, 0); PG8_SCHED; PG8_LDA(At, 0, 0); PG8_STAGE(PG8_SA(1, 1), a1 + hstep, voffA);
;             PG8_WAIT_L(8); PG8_BAR; PG8_WAIT_L(0); PG8_MMA(0, 0, At, B0); PG8_BAR; PG8_SCHED;
;             PG8_LDB(B1, 0, 1); PG8_STAGE(PG8_SB(0, 0), b2, voffB);
;             PG8_BAR; PG8_WAIT_L(0); PG8_MMA(0, 1, At, B1); PG8_BAR;
;             PG8_LDA(At, 0, 1); PG8_STAGE(PG8_SA(0, 0), a2, voffA);
;             PG8_BAR; PG8_WAIT_L(0); PG8_MMA(1, 0, At, B0); PG8_BAR; PG8_SCHED;
;             PG8_STAGE(PG8_SB(0, 1), b2 + hstep, voffB);
;             PG8_WAIT_V(6); PG8_BAR; PG8_MMA(1, 1, At, B1); PG8_BAR;
;             PG8_LDB(B0, 1, 0); PG8_SCHED; PG8_LDA(At, 1, 0); PG8_STAGE(PG8_SA(0, 1), a2 + hstep, voffA);
;             PG8_WAIT_L(8); PG8_BAR; PG8_WAIT_L(0); PG8_MMA(0, 0, At, B0); PG8_BAR; PG8_SCHED;
;             PG8_LDB(B1, 1, 1); PG8_STAGE(PG8_SB(1, 0), b3, voffB);
;             PG8_BAR; PG8_WAIT_L(0); PG8_MMA(0, 1, At, B1); PG8_BAR;
;             PG8_LDA(At, 1, 1); PG8_STAGE(PG8_SA(1, 0), a3, voffA);
;             PG8_BAR; PG8_WAIT_L(0); PG8_MMA(1, 0, At, B0); PG8_BAR; PG8_SCHED;
;             PG8_STAGE(PG8_SB(1, 1), b3 + hstep, voffB);
;             PG8_WAIT_V(6); PG8_BAR; PG8_MMA(1, 1, At, B1); PG8_BAR;
;             }
;         }
;     ...
;         if constexpr (ALIGN_EPI) { if (wr == 0) PG8_BAR; }
	s_setprio 0
	ds_read_b128 v[178:181], v143 offset:49152
	ds_read_b128 v[182:185], v143 offset:50176
	ds_read_b128 v[186:189], v143 offset:51200
	ds_read_b128 v[190:193], v143 offset:52224
	ds_read_b128 v[194:197], v143 offset:53248
	ds_read_b128 v[198:201], v143 offset:54272
	ds_read_b128 v[202:205], v143 offset:55296
	ds_read_b128 v[206:209], v143 offset:56320
	s_mov_b32 m0, s80
	s_nop 0
	global_load_lds_dwordx4 v136, s[58:59] offset:0
	s_nop 0
	s_mov_b32 m0, s81
	s_nop 0
	global_load_lds_dwordx4 v138, s[58:59] offset:0
	s_nop 0
	s_mov_b32 m0, s84
	s_nop 0
	global_load_lds_dwordx4 v136, s[54:55] offset:0
	s_nop 0
	s_mov_b32 m0, s85
	s_nop 0
	global_load_lds_dwordx4 v138, s[54:55] offset:0
	s_nop 0
	s_mov_b32 m0, s82
	s_nop 0
	global_load_lds_dwordx4 v1, s[56:57] offset:0
	s_nop 0
	s_mov_b32 m0, s83
	s_nop 0
	global_load_lds_dwordx4 v137, s[56:57] offset:0
	s_waitcnt vmcnt(8)
	s_waitcnt lgkmcnt(0)
	s_barrier
	s_setprio 1
	v_mfma_f32_16x16x32_bf16 v[62:65], v[146:149], v[178:181], v[62:65]
	v_mfma_f32_16x16x32_bf16 v[62:65], v[150:153], v[182:185], v[62:65]
	v_mfma_f32_16x16x32_bf16 v[58:61], v[154:157], v[178:181], v[58:61]
	v_mfma_f32_16x16x32_bf16 v[58:61], v[158:161], v[182:185], v[58:61]
	v_mfma_f32_16x16x32_bf16 v[54:57], v[146:149], v[186:189], v[54:57]
	v_mfma_f32_16x16x32_bf16 v[54:57], v[150:153], v[190:193], v[54:57]
	v_mfma_f32_16x16x32_bf16 v[46:49], v[154:157], v[186:189], v[46:49]
	v_mfma_f32_16x16x32_bf16 v[46:49], v[158:161], v[190:193], v[46:49]
	v_mfma_f32_16x16x32_bf16 v[38:41], v[146:149], v[194:197], v[38:41]
	v_mfma_f32_16x16x32_bf16 v[38:41], v[150:153], v[198:201], v[38:41]
	v_mfma_f32_16x16x32_bf16 v[30:33], v[154:157], v[194:197], v[30:33]
	v_mfma_f32_16x16x32_bf16 v[30:33], v[158:161], v[198:201], v[30:33]
	v_mfma_f32_16x16x32_bf16 v[22:25], v[146:149], v[202:205], v[22:25]
	v_mfma_f32_16x16x32_bf16 v[22:25], v[150:153], v[206:209], v[22:25]
	v_mfma_f32_16x16x32_bf16 v[14:17], v[154:157], v[202:205], v[14:17]
	v_mfma_f32_16x16x32_bf16 v[14:17], v[158:161], v[206:209], v[14:17]
	v_mfma_f32_16x16x32_bf16 v[50:53], v[162:165], v[178:181], v[50:53]
	v_mfma_f32_16x16x32_bf16 v[50:53], v[166:169], v[182:185], v[50:53]
	v_mfma_f32_16x16x32_bf16 v[42:45], v[170:173], v[178:181], v[42:45]
	v_mfma_f32_16x16x32_bf16 v[42:45], v[174:177], v[182:185], v[42:45]
	v_mfma_f32_16x16x32_bf16 v[34:37], v[162:165], v[186:189], v[34:37]
	v_mfma_f32_16x16x32_bf16 v[34:37], v[166:169], v[190:193], v[34:37]
	v_mfma_f32_16x16x32_bf16 v[26:29], v[170:173], v[186:189], v[26:29]
	v_mfma_f32_16x16x32_bf16 v[26:29], v[174:177], v[190:193], v[26:29]
	v_mfma_f32_16x16x32_bf16 v[18:21], v[162:165], v[194:197], v[18:21]
	v_mfma_f32_16x16x32_bf16 v[18:21], v[166:169], v[198:201], v[18:21]
	v_mfma_f32_16x16x32_bf16 v[10:13], v[170:173], v[194:197], v[10:13]
	v_mfma_f32_16x16x32_bf16 v[10:13], v[174:177], v[198:201], v[10:13]
	v_mfma_f32_16x16x32_bf16 v[6:9], v[162:165], v[202:205], v[6:9]
	v_mfma_f32_16x16x32_bf16 v[6:9], v[166:169], v[206:209], v[6:9]
	v_mfma_f32_16x16x32_bf16 v[2:5], v[170:173], v[202:205], v[2:5]
	v_mfma_f32_16x16x32_bf16 v[2:5], v[174:177], v[206:209], v[2:5]
	s_barrier
	s_setprio 0
	s_movk_i32 s58, 0x100
	s_andn2_b64 vcc, exec, s[46:47]
	s_mov_b64 s[54:55], -1
	s_mov_b64 s[46:47], 0
	s_cbranch_vccz .LBB0_1013
	s_and_b64 vcc, exec, s[14:15]
	s_cbranch_vccz .LBB0_1016
	s_barrier

; #define PG8_KSETUP() const bool last = (t == nt - 2); const char* a1 = cA + (size_t)(t + 1) * kstep; \
;             const char* a2 = last ? nA : cA + (size_t)(t + 2) * kstep; const char* b2 = last ? nB : cB + (size_t)(t + 2) * kstep; const char* a3 = a2 + kstep; const char* b3 = b2 + kstep; \
;             if (last && has_next) S.a_ready(nxt)
; template <class Epi, class Sched, bool ALIGN_EPI = false, bool SP2 = false>
; __device__ __forceinline__ void gemm_phase(PG8_LAS unsigned char* lds, const Gemm g, const Sched& S, const Epi& E) {
;     ...
;         int t0 = 0;
;         if constexpr (SP2 && Epi::NVM == 16) { if (ui > 0) { const int t = 0; PG8_KSETUP(); PG8_KITER_SP2(24, 24); t0 = 2; } }
.LBB0_2128:
	s_cmp_eq_u32 s29, 0
	s_mov_b32 s58, 0
	s_cbranch_scc1 .LBB0_2130
	ds_read_b128 v[4:7], v147
	ds_read_b128 v[8:11], v147 offset:1024
	ds_read_b128 v[12:15], v147 offset:2048
	ds_read_b128 v[16:19], v147 offset:3072
	ds_read_b128 v[20:23], v148
	ds_read_b128 v[24:27], v148 offset:1024
	ds_read_b128 v[28:31], v148 offset:2048
	ds_read_b128 v[32:35], v148 offset:3072
	s_add_u32 s40, s54, 0x100
	s_addc_u32 s41, s55, 0
	s_add_u32 s30, s56, 0x100
	s_addc_u32 s31, s57, 0
	s_add_u32 s38, s54, 0x180
	s_addc_u32 s39, s55, 0
	ds_read_b128 v[36:39], v149
	ds_read_b128 v[40:43], v149 offset:1024
	ds_read_b128 v[44:47], v149 offset:2048
	ds_read_b128 v[48:51], v149 offset:3072
	ds_read_b128 v[52:55], v149 offset:4096
	ds_read_b128 v[56:59], v149 offset:5120
	ds_read_b128 v[60:63], v149 offset:6144
	ds_read_b128 v[64:67], v149 offset:7168
	s_add_u32 s42, s54, 0x80080
	s_addc_u32 s43, s55, 0
	s_mov_b32 m0, s79
	s_nop 0
	global_load_lds_dwordx4 v1, s[42:43] offset:0
	s_nop 0
	s_mov_b32 m0, s80
	s_nop 0
	global_load_lds_dwordx4 v143, s[42:43] offset:0
	s_waitcnt vmcnt(24)
	s_waitcnt lgkmcnt(0)
	s_barrier
	s_setprio 1
	v_mfma_f32_16x16x32_bf16 v[92:95], v[4:7], v[60:63], 0
	v_mfma_f32_16x16x32_bf16 v[68:71], v[4:7], v[36:39], 0
	v_mfma_f32_16x16x32_bf16 v[72:75], v[12:15], v[36:39], 0
	v_mfma_f32_16x16x32_bf16 v[76:79], v[4:7], v[44:47], 0
	v_mfma_f32_16x16x32_bf16 v[80:83], v[12:15], v[44:47], 0
	v_mfma_f32_16x16x32_bf16 v[84:87], v[4:7], v[52:55], 0
	v_mfma_f32_16x16x32_bf16 v[88:91], v[12:15], v[52:55], 0
	v_mfma_f32_16x16x32_bf16 v[102:105], v[8:11], v[64:67], v[92:95]
	v_mfma_f32_16x16x32_bf16 v[92:95], v[12:15], v[60:63], 0
	v_mfma_f32_16x16x32_bf16 v[68:71], v[8:11], v[40:43], v[68:71]
	v_mfma_f32_16x16x32_bf16 v[72:75], v[16:19], v[40:43], v[72:75]
	v_mfma_f32_16x16x32_bf16 v[76:79], v[8:11], v[48:51], v[76:79]
	v_mfma_f32_16x16x32_bf16 v[80:83], v[16:19], v[48:51], v[80:83]
	v_mfma_f32_16x16x32_bf16 v[84:87], v[8:11], v[56:59], v[84:87]
	v_mfma_f32_16x16x32_bf16 v[88:91], v[16:19], v[56:59], v[88:91]
	v_mfma_f32_16x16x32_bf16 v[106:109], v[16:19], v[64:67], v[92:95]
	v_mfma_f32_16x16x32_bf16 v[92:95], v[20:23], v[36:39], 0
	v_mfma_f32_16x16x32_bf16 v[36:39], v[28:31], v[36:39], 0
	v_mfma_f32_16x16x32_bf16 v[118:121], v[24:27], v[40:43], v[92:95]
	v_mfma_f32_16x16x32_bf16 v[36:39], v[32:35], v[40:43], v[36:39]
	v_mfma_f32_16x16x32_bf16 v[40:43], v[20:23], v[44:47], 0
	v_mfma_f32_16x16x32_bf16 v[44:47], v[28:31], v[44:47], 0
	v_mfma_f32_16x16x32_bf16 v[40:43], v[24:27], v[48:51], v[40:43]
	v_mfma_f32_16x16x32_bf16 v[44:47], v[32:35], v[48:51], v[44:47]
	v_mfma_f32_16x16x32_bf16 v[48:51], v[20:23], v[52:55], 0
	v_mfma_f32_16x16x32_bf16 v[52:55], v[28:31], v[52:55], 0
	v_mfma_f32_16x16x32_bf16 v[48:51], v[24:27], v[56:59], v[48:51]
	v_mfma_f32_16x16x32_bf16 v[52:55], v[32:35], v[56:59], v[52:55]
	v_mfma_f32_16x16x32_bf16 v[56:59], v[20:23], v[60:63], 0
	v_mfma_f32_16x16x32_bf16 v[60:63], v[28:31], v[60:63], 0
	v_mfma_f32_16x16x32_bf16 v[56:59], v[24:27], v[64:67], v[56:59]
	v_mfma_f32_16x16x32_bf16 v[60:63], v[32:35], v[64:67], v[60:63]
	s_barrier
	s_setprio 0
	ds_read_b128 v[64:67], v149 offset:16384
	ds_read_b128 v[92:95], v149 offset:17408
	ds_read_b128 v[96:99], v149 offset:18432
	ds_read_b128 v[110:113], v149 offset:19456
	ds_read_b128 v[114:117], v149 offset:20480
	ds_read_b128 v[122:125], v149 offset:21504
	ds_read_b128 v[126:129], v149 offset:22528
	ds_read_b128 v[130:133], v149 offset:23552
	s_mov_b32 m0, s47
	s_nop 0
	global_load_lds_dwordx4 v142, s[30:31] offset:0
	s_nop 0
	s_mov_b32 m0, s52
	s_nop 0
	global_load_lds_dwordx4 v144, s[30:31] offset:0
	s_add_u32 s30, s56, 0x80100
	s_addc_u32 s31, s57, 0
	s_mov_b32 m0, s53
	s_nop 0
	global_load_lds_dwordx4 v142, s[30:31] offset:0
	s_nop 0
	s_mov_b32 m0, s66
	s_nop 0
	global_load_lds_dwordx4 v144, s[30:31] offset:0
	s_nop 0
	s_mov_b32 m0, s33
	s_nop 0
	global_load_lds_dwordx4 v1, s[40:41] offset:0
	s_nop 0
	s_mov_b32 m0, s67
	s_nop 0
	global_load_lds_dwordx4 v143, s[40:41] offset:0
	s_waitcnt vmcnt(24)
	s_waitcnt lgkmcnt(0)
	s_barrier
	s_setprio 1
	v_mfma_f32_16x16x32_bf16 v[138:141], v[4:7], v[64:67], 0
	v_mfma_f32_16x16x32_bf16 v[156:159], v[4:7], v[96:99], 0
	v_mfma_f32_16x16x32_bf16 v[164:167], v[4:7], v[114:117], 0
	v_mfma_f32_16x16x32_bf16 v[4:7], v[4:7], v[126:129], 0
	v_mfma_f32_16x16x32_bf16 v[138:141], v[8:11], v[92:95], v[138:141]
	v_mfma_f32_16x16x32_bf16 v[156:159], v[8:11], v[110:113], v[156:159]
	v_mfma_f32_16x16x32_bf16 v[164:167], v[8:11], v[122:125], v[164:167]
	v_mfma_f32_16x16x32_bf16 v[4:7], v[8:11], v[130:133], v[4:7]
	v_mfma_f32_16x16x32_bf16 v[8:11], v[12:15], v[126:129], 0
	v_mfma_f32_16x16x32_bf16 v[152:155], v[12:15], v[64:67], 0
	v_mfma_f32_16x16x32_bf16 v[160:163], v[12:15], v[96:99], 0
	v_mfma_f32_16x16x32_bf16 v[168:171], v[12:15], v[114:117], 0
	v_mfma_f32_16x16x32_bf16 v[8:11], v[16:19], v[130:133], v[8:11]
	v_mfma_f32_16x16x32_bf16 v[152:155], v[16:19], v[92:95], v[152:155]
	v_mfma_f32_16x16x32_bf16 v[160:163], v[16:19], v[110:113], v[160:163]
	v_mfma_f32_16x16x32_bf16 v[168:171], v[16:19], v[122:125], v[168:171]
	v_mfma_f32_16x16x32_bf16 v[12:15], v[20:23], v[64:67], 0
	v_mfma_f32_16x16x32_bf16 v[172:175], v[24:27], v[92:95], v[12:15]
	v_mfma_f32_16x16x32_bf16 v[12:15], v[28:31], v[64:67], 0
	v_mfma_f32_16x16x32_bf16 v[176:179], v[32:35], v[92:95], v[12:15]
	v_mfma_f32_16x16x32_bf16 v[12:15], v[20:23], v[96:99], 0
	v_mfma_f32_16x16x32_bf16 v[180:183], v[24:27], v[110:113], v[12:15]
	v_mfma_f32_16x16x32_bf16 v[12:15], v[28:31], v[96:99], 0
	v_mfma_f32_16x16x32_bf16 v[184:187], v[32:35], v[110:113], v[12:15]
	v_mfma_f32_16x16x32_bf16 v[12:15], v[20:23], v[114:117], 0
	v_mfma_f32_16x16x32_bf16 v[188:191], v[24:27], v[122:125], v[12:15]
	v_mfma_f32_16x16x32_bf16 v[12:15], v[28:31], v[114:117], 0
	v_mfma_f32_16x16x32_bf16 v[192:195], v[32:35], v[122:125], v[12:15]
	v_mfma_f32_16x16x32_bf16 v[12:15], v[20:23], v[126:129], 0
	v_mfma_f32_16x16x32_bf16 v[196:199], v[24:27], v[130:133], v[12:15]
	v_mfma_f32_16x16x32_bf16 v[12:15], v[28:31], v[126:129], 0
	v_mfma_f32_16x16x32_bf16 v[200:203], v[32:35], v[130:133], v[12:15]
	s_barrier
; #define PG8_KSETUP() const bool last = (t == nt - 2); const char* a1 = cA + (size_t)(t + 1) * kstep; \
;             const char* a2 = last ? nA : cA + (size_t)(t + 2) * kstep; const char* b2 = last ? nB : cB + (size_t)(t + 2) * kstep; const char* a3 = a2 + kstep; const char* b3 = b2 + kstep; \
;             if (last && has_next) S.a_ready(nxt)
; template <class Epi, class Sched, bool ALIGN_EPI = false, bool SP2 = false>
; __device__ __forceinline__ void gemm_phase(PG8_LAS unsigned char* lds, const Gemm g, const Sched& S, const Epi& E) {
;     ...
;         int t0 = 0;
;         if constexpr (SP2 && Epi::NVM == 16) { if (ui > 0) { const int t = 0; PG8_KSETUP(); PG8_KITER_SP2(24, 24); t0 = 2; } }
	s_setprio 0
	s_nop 4
	ds_read_b128 v[12:15], v150
	ds_read_b128 v[16:19], v150 offset:1024
	ds_read_b128 v[22:25], v150 offset:2048
	ds_read_b128 v[26:29], v150 offset:3072
	ds_read_b128 v[204:207], v151
	ds_read_b128 v[208:211], v151 offset:1024
	ds_read_b128 v[212:215], v151 offset:2048
	ds_read_b128 v[216:219], v151 offset:3072
	ds_read_b128 v[30:33], v149 offset:32768
	ds_read_b128 v[64:67], v149 offset:33792
	ds_read_b128 v[220:223], v149 offset:34816
	ds_read_b128 v[224:227], v149 offset:35840
	ds_read_b128 v[228:231], v149 offset:36864
	ds_read_b128 v[232:235], v149 offset:37888
	ds_read_b128 v[236:239], v149 offset:38912
	ds_read_b128 v[240:243], v149 offset:39936
	s_add_u32 s30, s54, 0x80100
	s_addc_u32 s31, s55, 0
	s_mov_b32 m0, s68
	s_nop 0
	global_load_lds_dwordx4 v1, s[30:31] offset:0
	s_nop 0
	s_mov_b32 m0, s69
	s_nop 0
	global_load_lds_dwordx4 v143, s[30:31] offset:0
	s_waitcnt vmcnt(8)
	s_waitcnt lgkmcnt(0)
	s_barrier
	s_setprio 1
	v_mfma_f32_16x16x32_bf16 v[68:71], v[12:15], v[30:33], v[68:71]
	v_mfma_f32_16x16x32_bf16 v[130:133], v[16:19], v[64:67], v[68:71]
	v_mfma_f32_16x16x32_bf16 v[68:71], v[22:25], v[30:33], v[72:75]
	v_mfma_f32_16x16x32_bf16 v[126:129], v[26:29], v[64:67], v[68:71]
	v_mfma_f32_16x16x32_bf16 v[68:71], v[12:15], v[220:223], v[76:79]
	v_mfma_f32_16x16x32_bf16 v[114:117], v[16:19], v[224:227], v[68:71]
	v_mfma_f32_16x16x32_bf16 v[68:71], v[22:25], v[220:223], v[80:83]
	v_mfma_f32_16x16x32_bf16 v[110:113], v[26:29], v[224:227], v[68:71]
	v_mfma_f32_16x16x32_bf16 v[68:71], v[12:15], v[228:231], v[84:87]
	v_mfma_f32_16x16x32_bf16 v[98:101], v[16:19], v[232:235], v[68:71]
	v_mfma_f32_16x16x32_bf16 v[68:71], v[22:25], v[228:231], v[88:91]
	v_mfma_f32_16x16x32_bf16 v[94:97], v[26:29], v[232:235], v[68:71]
	v_mfma_f32_16x16x32_bf16 v[68:71], v[12:15], v[236:239], v[102:105]
	v_mfma_f32_16x16x32_bf16 v[82:85], v[16:19], v[240:243], v[68:71]
	v_mfma_f32_16x16x32_bf16 v[68:71], v[22:25], v[236:239], v[106:109]
	v_mfma_f32_16x16x32_bf16 v[78:81], v[26:29], v[240:243], v[68:71]
	v_mfma_f32_16x16x32_bf16 v[68:71], v[204:207], v[30:33], v[118:121]
	v_mfma_f32_16x16x32_bf16 v[30:33], v[212:215], v[30:33], v[36:39]
	v_mfma_f32_16x16x32_bf16 v[118:121], v[216:219], v[64:67], v[30:33]
	v_mfma_f32_16x16x32_bf16 v[30:33], v[204:207], v[220:223], v[40:43]
	v_mfma_f32_16x16x32_bf16 v[106:109], v[208:211], v[224:227], v[30:33]
	v_mfma_f32_16x16x32_bf16 v[30:33], v[212:215], v[220:223], v[44:47]
	v_mfma_f32_16x16x32_bf16 v[102:105], v[216:219], v[224:227], v[30:33]
	v_mfma_f32_16x16x32_bf16 v[30:33], v[204:207], v[228:231], v[48:51]
	v_mfma_f32_16x16x32_bf16 v[90:93], v[208:211], v[232:235], v[30:33]
	v_mfma_f32_16x16x32_bf16 v[30:33], v[212:215], v[228:231], v[52:55]
	v_mfma_f32_16x16x32_bf16 v[86:89], v[216:219], v[232:235], v[30:33]
	v_mfma_f32_16x16x32_bf16 v[30:33], v[204:207], v[236:239], v[56:59]
	v_mfma_f32_16x16x32_bf16 v[74:77], v[208:211], v[240:243], v[30:33]
	v_mfma_f32_16x16x32_bf16 v[30:33], v[212:215], v[236:239], v[60:63]
	v_mfma_f32_16x16x32_bf16 v[122:125], v[208:211], v[64:67], v[68:71]
	v_mfma_f32_16x16x32_bf16 v[70:73], v[216:219], v[240:243], v[30:33]
	s_barrier
	s_setprio 0
	ds_read_b128 v[38:41], v149 offset:49152
	ds_read_b128 v[42:45], v149 offset:50176
	ds_read_b128 v[220:223], v149 offset:51200
	ds_read_b128 v[224:227], v149 offset:52224
	ds_read_b128 v[228:231], v149 offset:53248
	ds_read_b128 v[232:235], v149 offset:54272
	ds_read_b128 v[236:239], v149 offset:55296
	ds_read_b128 v[240:243], v149 offset:56320
	s_add_u32 s30, s56, 0x180
	s_addc_u32 s31, s57, 0
	s_mov_b32 m0, s73
	s_nop 0
	global_load_lds_dwordx4 v142, s[30:31] offset:0
	s_nop 0
	s_mov_b32 m0, s74
	s_nop 0
	global_load_lds_dwordx4 v144, s[30:31] offset:0
	s_add_u32 s30, s56, 0x80180
	s_addc_u32 s31, s57, 0
	s_mov_b32 m0, s77
	s_nop 0
	global_load_lds_dwordx4 v142, s[30:31] offset:0
	s_nop 0
	s_mov_b32 m0, s78
	s_nop 0
	global_load_lds_dwordx4 v144, s[30:31] offset:0
	s_nop 0
	s_mov_b32 m0, s75
	s_nop 0
	global_load_lds_dwordx4 v1, s[38:39] offset:0
	s_nop 0
	s_mov_b32 m0, s76
	s_nop 0
	global_load_lds_dwordx4 v143, s[38:39] offset:0
	s_waitcnt vmcnt(8)
	s_waitcnt lgkmcnt(0)
	s_barrier
	s_setprio 1
	v_mfma_f32_16x16x32_bf16 v[30:33], v[12:15], v[38:41], v[138:141]
	v_mfma_f32_16x16x32_bf16 v[66:69], v[16:19], v[42:45], v[30:33]
	v_mfma_f32_16x16x32_bf16 v[30:33], v[22:25], v[38:41], v[152:155]
	v_mfma_f32_16x16x32_bf16 v[62:65], v[26:29], v[42:45], v[30:33]
	v_mfma_f32_16x16x32_bf16 v[30:33], v[12:15], v[220:223], v[156:159]
	v_mfma_f32_16x16x32_bf16 v[50:53], v[16:19], v[224:227], v[30:33]
	v_mfma_f32_16x16x32_bf16 v[30:33], v[22:25], v[220:223], v[160:163]
	v_mfma_f32_16x16x32_bf16 v[46:49], v[26:29], v[224:227], v[30:33]
	v_mfma_f32_16x16x32_bf16 v[30:33], v[12:15], v[228:231], v[164:167]
	v_mfma_f32_16x16x32_bf16 v[4:7], v[12:15], v[236:239], v[4:7]
	v_mfma_f32_16x16x32_bf16 v[34:37], v[16:19], v[232:235], v[30:33]
	v_mfma_f32_16x16x32_bf16 v[30:33], v[22:25], v[228:231], v[168:171]
	v_mfma_f32_16x16x32_bf16 v[18:21], v[16:19], v[240:243], v[4:7]
	v_mfma_f32_16x16x32_bf16 v[4:7], v[22:25], v[236:239], v[8:11]
	v_mfma_f32_16x16x32_bf16 v[30:33], v[26:29], v[232:235], v[30:33]
	v_mfma_f32_16x16x32_bf16 v[14:17], v[26:29], v[240:243], v[4:7]
	v_mfma_f32_16x16x32_bf16 v[4:7], v[204:207], v[38:41], v[172:175]
	v_mfma_f32_16x16x32_bf16 v[58:61], v[208:211], v[42:45], v[4:7]
	v_mfma_f32_16x16x32_bf16 v[4:7], v[212:215], v[38:41], v[176:179]
	v_mfma_f32_16x16x32_bf16 v[54:57], v[216:219], v[42:45], v[4:7]
	v_mfma_f32_16x16x32_bf16 v[4:7], v[204:207], v[220:223], v[180:183]
	v_mfma_f32_16x16x32_bf16 v[42:45], v[208:211], v[224:227], v[4:7]
	v_mfma_f32_16x16x32_bf16 v[4:7], v[212:215], v[220:223], v[184:187]
	v_mfma_f32_16x16x32_bf16 v[38:41], v[216:219], v[224:227], v[4:7]
	v_mfma_f32_16x16x32_bf16 v[4:7], v[204:207], v[228:231], v[188:191]
	v_mfma_f32_16x16x32_bf16 v[26:29], v[208:211], v[232:235], v[4:7]
	v_mfma_f32_16x16x32_bf16 v[4:7], v[212:215], v[228:231], v[192:195]
	v_mfma_f32_16x16x32_bf16 v[22:25], v[216:219], v[232:235], v[4:7]
	v_mfma_f32_16x16x32_bf16 v[4:7], v[204:207], v[236:239], v[196:199]
	v_mfma_f32_16x16x32_bf16 v[10:13], v[208:211], v[240:243], v[4:7]
	v_mfma_f32_16x16x32_bf16 v[4:7], v[212:215], v[236:239], v[200:203]
	v_mfma_f32_16x16x32_bf16 v[6:9], v[216:219], v[240:243], v[4:7]
	s_barrier
	s_setprio 0
	s_mov_b32 s58, 2
	s_branch .LBB0_2131

; #define PG8_KSETUP() const bool last = (t == nt - 2); const char* a1 = cA + (size_t)(t + 1) * kstep; \
;             const char* a2 = last ? nA : cA + (size_t)(t + 2) * kstep; const char* b2 = last ? nB : cB + (size_t)(t + 2) * kstep; const char* a3 = a2 + kstep; const char* b3 = b2 + kstep; \
;             if (last && has_next) S.a_ready(nxt)
; template <class Epi, class Sched, bool ALIGN_EPI = false, bool SP2 = false>
; __device__ __forceinline__ void gemm_phase(PG8_LAS unsigned char* lds, const Gemm g, const Sched& S, const Epi& E) {
;     ...
;         int t0 = 0;
;         if constexpr (SP2 && Epi::NVM == 16) { if (ui > 0) { const int t = 0; PG8_KSETUP(); PG8_KITER_SP2(24, 24); t0 = 2; } }
;         if constexpr (SP2 && Epi::NVM == 8) { if (ui > 0) { const int t = 0; PG8_KSETUP(); PG8_KITER_SP2(16, 16); t0 = 2; } }
;         for (int t = t0; t < nt; t += 2) {
;             PG8_KSETUP();
;             if constexpr (SP2) {
;             PG8_KITER_SP2(8, 8);
.LBB0_2132:
	ds_read_b128 v[138:141], v147
	ds_read_b128 v[152:155], v147 offset:1024
	ds_read_b128 v[156:159], v147 offset:2048
	ds_read_b128 v[160:163], v147 offset:3072
	ds_read_b128 v[164:167], v148
	ds_read_b128 v[168:171], v148 offset:1024
	ds_read_b128 v[172:175], v148 offset:2048
	ds_read_b128 v[176:179], v148 offset:3072
	s_cmp_eq_u32 s86, 28
	s_cselect_b32 s64, s45, s89
	s_cselect_b32 s65, s37, s90
	s_cselect_b32 s58, s85, s87
	s_cselect_b32 s59, s29, s88
	s_add_u32 s56, s64, 0x80
	s_addc_u32 s57, s65, 0
	ds_read_b128 v[180:183], v149
	ds_read_b128 v[184:187], v149 offset:1024
	ds_read_b128 v[188:191], v149 offset:2048
	ds_read_b128 v[192:195], v149 offset:3072
	ds_read_b128 v[196:199], v149 offset:4096
	ds_read_b128 v[200:203], v149 offset:5120
	ds_read_b128 v[204:207], v149 offset:6144
	ds_read_b128 v[208:211], v149 offset:7168
	s_mov_b32 m0, s79
	s_nop 0
	global_load_lds_dwordx4 v1, s[54:55] offset:0
	s_nop 0
	s_mov_b32 m0, s80
	s_nop 0
	global_load_lds_dwordx4 v143, s[54:55] offset:0
	s_waitcnt vmcnt(8)
	s_waitcnt lgkmcnt(0)
	s_barrier
	s_setprio 1
	v_mfma_f32_16x16x32_bf16 v[130:133], v[138:141], v[180:183], v[130:133]
	v_mfma_f32_16x16x32_bf16 v[130:133], v[152:155], v[184:187], v[130:133]
	v_mfma_f32_16x16x32_bf16 v[126:129], v[156:159], v[180:183], v[126:129]
	v_mfma_f32_16x16x32_bf16 v[126:129], v[160:163], v[184:187], v[126:129]
	v_mfma_f32_16x16x32_bf16 v[114:117], v[138:141], v[188:191], v[114:117]
	v_mfma_f32_16x16x32_bf16 v[114:117], v[152:155], v[192:195], v[114:117]
	v_mfma_f32_16x16x32_bf16 v[110:113], v[156:159], v[188:191], v[110:113]
	v_mfma_f32_16x16x32_bf16 v[110:113], v[160:163], v[192:195], v[110:113]
	v_mfma_f32_16x16x32_bf16 v[98:101], v[138:141], v[196:199], v[98:101]
	v_mfma_f32_16x16x32_bf16 v[98:101], v[152:155], v[200:203], v[98:101]
	v_mfma_f32_16x16x32_bf16 v[94:97], v[156:159], v[196:199], v[94:97]
	v_mfma_f32_16x16x32_bf16 v[94:97], v[160:163], v[200:203], v[94:97]
	v_mfma_f32_16x16x32_bf16 v[82:85], v[138:141], v[204:207], v[82:85]
	v_mfma_f32_16x16x32_bf16 v[82:85], v[152:155], v[208:211], v[82:85]
	v_mfma_f32_16x16x32_bf16 v[78:81], v[156:159], v[204:207], v[78:81]
	v_mfma_f32_16x16x32_bf16 v[78:81], v[160:163], v[208:211], v[78:81]
	v_mfma_f32_16x16x32_bf16 v[122:125], v[164:167], v[180:183], v[122:125]
	v_mfma_f32_16x16x32_bf16 v[122:125], v[168:171], v[184:187], v[122:125]
	v_mfma_f32_16x16x32_bf16 v[118:121], v[172:175], v[180:183], v[118:121]
	v_mfma_f32_16x16x32_bf16 v[118:121], v[176:179], v[184:187], v[118:121]
	v_mfma_f32_16x16x32_bf16 v[106:109], v[164:167], v[188:191], v[106:109]
	v_mfma_f32_16x16x32_bf16 v[106:109], v[168:171], v[192:195], v[106:109]
	v_mfma_f32_16x16x32_bf16 v[102:105], v[172:175], v[188:191], v[102:105]
	v_mfma_f32_16x16x32_bf16 v[102:105], v[176:179], v[192:195], v[102:105]
	v_mfma_f32_16x16x32_bf16 v[90:93], v[164:167], v[196:199], v[90:93]
	v_mfma_f32_16x16x32_bf16 v[90:93], v[168:171], v[200:203], v[90:93]
	v_mfma_f32_16x16x32_bf16 v[86:89], v[172:175], v[196:199], v[86:89]
	v_mfma_f32_16x16x32_bf16 v[86:89], v[176:179], v[200:203], v[86:89]
	v_mfma_f32_16x16x32_bf16 v[74:77], v[164:167], v[204:207], v[74:77]
	v_mfma_f32_16x16x32_bf16 v[74:77], v[168:171], v[208:211], v[74:77]
	v_mfma_f32_16x16x32_bf16 v[70:73], v[172:175], v[204:207], v[70:73]
	v_mfma_f32_16x16x32_bf16 v[70:73], v[176:179], v[208:211], v[70:73]
	s_barrier
	s_setprio 0
	ds_read_b128 v[180:183], v149 offset:16384
	ds_read_b128 v[184:187], v149 offset:17408
	ds_read_b128 v[188:191], v149 offset:18432
	ds_read_b128 v[192:195], v149 offset:19456
	ds_read_b128 v[196:199], v149 offset:20480
	ds_read_b128 v[200:203], v149 offset:21504
	ds_read_b128 v[204:207], v149 offset:22528
	ds_read_b128 v[208:211], v149 offset:23552
	s_mov_b32 m0, s47
	s_nop 0
	global_load_lds_dwordx4 v142, s[58:59] offset:0
	s_add_u32 s30, s58, 0x80000
	s_mov_b32 m0, s52
	s_nop 0
	global_load_lds_dwordx4 v144, s[58:59] offset:0
	s_addc_u32 s31, s59, 0
	s_mov_b32 m0, s53
	s_nop 0
	global_load_lds_dwordx4 v142, s[30:31] offset:0
	s_nop 0
	s_mov_b32 m0, s66
	s_nop 0
	global_load_lds_dwordx4 v144, s[30:31] offset:0
	s_nop 0
	s_mov_b32 m0, s33
	s_nop 0
	global_load_lds_dwordx4 v1, s[64:65] offset:0
	s_nop 0
	s_mov_b32 m0, s67
	s_nop 0
	global_load_lds_dwordx4 v143, s[64:65] offset:0
	s_waitcnt vmcnt(8)
	s_waitcnt lgkmcnt(0)
	s_barrier
	s_setprio 1
	v_mfma_f32_16x16x32_bf16 v[66:69], v[138:141], v[180:183], v[66:69]
	v_mfma_f32_16x16x32_bf16 v[66:69], v[152:155], v[184:187], v[66:69]
	v_mfma_f32_16x16x32_bf16 v[62:65], v[156:159], v[180:183], v[62:65]
	v_mfma_f32_16x16x32_bf16 v[62:65], v[160:163], v[184:187], v[62:65]
	v_mfma_f32_16x16x32_bf16 v[50:53], v[138:141], v[188:191], v[50:53]
	v_mfma_f32_16x16x32_bf16 v[50:53], v[152:155], v[192:195], v[50:53]
	v_mfma_f32_16x16x32_bf16 v[46:49], v[156:159], v[188:191], v[46:49]
	v_mfma_f32_16x16x32_bf16 v[46:49], v[160:163], v[192:195], v[46:49]
	v_mfma_f32_16x16x32_bf16 v[34:37], v[138:141], v[196:199], v[34:37]
	v_mfma_f32_16x16x32_bf16 v[34:37], v[152:155], v[200:203], v[34:37]
	v_mfma_f32_16x16x32_bf16 v[30:33], v[156:159], v[196:199], v[30:33]
	v_mfma_f32_16x16x32_bf16 v[30:33], v[160:163], v[200:203], v[30:33]
	v_mfma_f32_16x16x32_bf16 v[18:21], v[138:141], v[204:207], v[18:21]
	v_mfma_f32_16x16x32_bf16 v[18:21], v[152:155], v[208:211], v[18:21]
	v_mfma_f32_16x16x32_bf16 v[14:17], v[156:159], v[204:207], v[14:17]
	v_mfma_f32_16x16x32_bf16 v[14:17], v[160:163], v[208:211], v[14:17]
	v_mfma_f32_16x16x32_bf16 v[58:61], v[164:167], v[180:183], v[58:61]
	v_mfma_f32_16x16x32_bf16 v[54:57], v[172:175], v[180:183], v[54:57]
	v_mfma_f32_16x16x32_bf16 v[42:45], v[164:167], v[188:191], v[42:45]
	v_mfma_f32_16x16x32_bf16 v[38:41], v[172:175], v[188:191], v[38:41]
	v_mfma_f32_16x16x32_bf16 v[26:29], v[164:167], v[196:199], v[26:29]
	v_mfma_f32_16x16x32_bf16 v[22:25], v[172:175], v[196:199], v[22:25]
	v_mfma_f32_16x16x32_bf16 v[10:13], v[164:167], v[204:207], v[10:13]
	v_mfma_f32_16x16x32_bf16 v[4:7], v[172:175], v[204:207], v[6:9]
	v_mfma_f32_16x16x32_bf16 v[58:61], v[168:171], v[184:187], v[58:61]
	v_mfma_f32_16x16x32_bf16 v[54:57], v[176:179], v[184:187], v[54:57]
	v_mfma_f32_16x16x32_bf16 v[42:45], v[168:171], v[192:195], v[42:45]
	v_mfma_f32_16x16x32_bf16 v[38:41], v[176:179], v[192:195], v[38:41]
	v_mfma_f32_16x16x32_bf16 v[26:29], v[168:171], v[200:203], v[26:29]
	v_mfma_f32_16x16x32_bf16 v[22:25], v[176:179], v[200:203], v[22:25]
	v_mfma_f32_16x16x32_bf16 v[10:13], v[168:171], v[208:211], v[10:13]
	v_mfma_f32_16x16x32_bf16 v[4:7], v[176:179], v[208:211], v[4:7]
	s_barrier
; #define PG8_KSETUP() const bool last = (t == nt - 2); const char* a1 = cA + (size_t)(t + 1) * kstep; \
;             const char* a2 = last ? nA : cA + (size_t)(t + 2) * kstep; const char* b2 = last ? nB : cB + (size_t)(t + 2) * kstep; const char* a3 = a2 + kstep; const char* b3 = b2 + kstep; \
;             if (last && has_next) S.a_ready(nxt)
; template <class Epi, class Sched, bool ALIGN_EPI = false, bool SP2 = false>
; __device__ __forceinline__ void gemm_phase(PG8_LAS unsigned char* lds, const Gemm g, const Sched& S, const Epi& E) {
;     ...
;         int t0 = 0;
;         if constexpr (SP2 && Epi::NVM == 16) { if (ui > 0) { const int t = 0; PG8_KSETUP(); PG8_KITER_SP2(24, 24); t0 = 2; } }
;         if constexpr (SP2 && Epi::NVM == 8) { if (ui > 0) { const int t = 0; PG8_KSETUP(); PG8_KITER_SP2(16, 16); t0 = 2; } }
;         for (int t = t0; t < nt; t += 2) {
;             PG8_KSETUP();
;             if constexpr (SP2) {
;             PG8_KITER_SP2(8, 8);
	s_setprio 0
	ds_read_b128 v[138:141], v150
	ds_read_b128 v[152:155], v150 offset:1024
	ds_read_b128 v[156:159], v150 offset:2048
	ds_read_b128 v[160:163], v150 offset:3072
	ds_read_b128 v[164:167], v151
	ds_read_b128 v[168:171], v151 offset:1024
	ds_read_b128 v[172:175], v151 offset:2048
	ds_read_b128 v[176:179], v151 offset:3072
	ds_read_b128 v[180:183], v149 offset:32768
	ds_read_b128 v[184:187], v149 offset:33792
	ds_read_b128 v[188:191], v149 offset:34816
	ds_read_b128 v[192:195], v149 offset:35840
	ds_read_b128 v[196:199], v149 offset:36864
	ds_read_b128 v[200:203], v149 offset:37888
	ds_read_b128 v[204:207], v149 offset:38912
	ds_read_b128 v[208:211], v149 offset:39936
	s_add_u32 s30, s64, 0x80000
	s_addc_u32 s31, s65, 0
	s_mov_b32 m0, s68
	s_nop 0
	global_load_lds_dwordx4 v1, s[30:31] offset:0
	s_nop 0
	s_mov_b32 m0, s69
	s_nop 0
	global_load_lds_dwordx4 v143, s[30:31] offset:0
	s_waitcnt vmcnt(8)
	s_waitcnt lgkmcnt(0)
	s_barrier
	s_setprio 1
	v_mfma_f32_16x16x32_bf16 v[130:133], v[138:141], v[180:183], v[130:133]
	v_mfma_f32_16x16x32_bf16 v[130:133], v[152:155], v[184:187], v[130:133]
	v_mfma_f32_16x16x32_bf16 v[126:129], v[156:159], v[180:183], v[126:129]
	v_mfma_f32_16x16x32_bf16 v[126:129], v[160:163], v[184:187], v[126:129]
	v_mfma_f32_16x16x32_bf16 v[114:117], v[138:141], v[188:191], v[114:117]
	v_mfma_f32_16x16x32_bf16 v[114:117], v[152:155], v[192:195], v[114:117]
	v_mfma_f32_16x16x32_bf16 v[110:113], v[156:159], v[188:191], v[110:113]
	v_mfma_f32_16x16x32_bf16 v[110:113], v[160:163], v[192:195], v[110:113]
	v_mfma_f32_16x16x32_bf16 v[98:101], v[138:141], v[196:199], v[98:101]
	v_mfma_f32_16x16x32_bf16 v[98:101], v[152:155], v[200:203], v[98:101]
	v_mfma_f32_16x16x32_bf16 v[94:97], v[156:159], v[196:199], v[94:97]
	v_mfma_f32_16x16x32_bf16 v[94:97], v[160:163], v[200:203], v[94:97]
	v_mfma_f32_16x16x32_bf16 v[82:85], v[138:141], v[204:207], v[82:85]
	v_mfma_f32_16x16x32_bf16 v[82:85], v[152:155], v[208:211], v[82:85]
	v_mfma_f32_16x16x32_bf16 v[78:81], v[156:159], v[204:207], v[78:81]
	v_mfma_f32_16x16x32_bf16 v[78:81], v[160:163], v[208:211], v[78:81]
	v_mfma_f32_16x16x32_bf16 v[122:125], v[164:167], v[180:183], v[122:125]
	v_mfma_f32_16x16x32_bf16 v[122:125], v[168:171], v[184:187], v[122:125]
	v_mfma_f32_16x16x32_bf16 v[118:121], v[172:175], v[180:183], v[118:121]
	v_mfma_f32_16x16x32_bf16 v[118:121], v[176:179], v[184:187], v[118:121]
	v_mfma_f32_16x16x32_bf16 v[106:109], v[164:167], v[188:191], v[106:109]
	v_mfma_f32_16x16x32_bf16 v[106:109], v[168:171], v[192:195], v[106:109]
	v_mfma_f32_16x16x32_bf16 v[102:105], v[172:175], v[188:191], v[102:105]
	v_mfma_f32_16x16x32_bf16 v[102:105], v[176:179], v[192:195], v[102:105]
	v_mfma_f32_16x16x32_bf16 v[90:93], v[164:167], v[196:199], v[90:93]
	v_mfma_f32_16x16x32_bf16 v[90:93], v[168:171], v[200:203], v[90:93]
	v_mfma_f32_16x16x32_bf16 v[86:89], v[172:175], v[196:199], v[86:89]
	v_mfma_f32_16x16x32_bf16 v[86:89], v[176:179], v[200:203], v[86:89]
	v_mfma_f32_16x16x32_bf16 v[74:77], v[164:167], v[204:207], v[74:77]
	v_mfma_f32_16x16x32_bf16 v[74:77], v[168:171], v[208:211], v[74:77]
	v_mfma_f32_16x16x32_bf16 v[70:73], v[172:175], v[204:207], v[70:73]
	v_mfma_f32_16x16x32_bf16 v[70:73], v[176:179], v[208:211], v[70:73]
	s_barrier
	s_setprio 0
	ds_read_b128 v[180:183], v149 offset:49152
	ds_read_b128 v[184:187], v149 offset:50176
	ds_read_b128 v[188:191], v149 offset:51200
	ds_read_b128 v[192:195], v149 offset:52224
	ds_read_b128 v[196:199], v149 offset:53248
	ds_read_b128 v[200:203], v149 offset:54272
	ds_read_b128 v[204:207], v149 offset:55296
	ds_read_b128 v[208:211], v149 offset:56320
	s_add_u32 s30, s58, 0x80
	s_addc_u32 s31, s59, 0
	s_mov_b32 m0, s73
	s_nop 0
	global_load_lds_dwordx4 v142, s[30:31] offset:0
	s_nop 0
	s_mov_b32 m0, s74
	s_nop 0
	global_load_lds_dwordx4 v144, s[30:31] offset:0
	s_add_u32 s30, s58, 0x80080
	s_addc_u32 s31, s59, 0
	s_mov_b32 m0, s77
	s_nop 0
	global_load_lds_dwordx4 v142, s[30:31] offset:0
	s_nop 0
	s_mov_b32 m0, s78
	s_nop 0
	global_load_lds_dwordx4 v144, s[30:31] offset:0
	s_nop 0
	s_mov_b32 m0, s75
	s_nop 0
	global_load_lds_dwordx4 v1, s[56:57] offset:0
	s_nop 0
	s_mov_b32 m0, s76
	s_nop 0
	global_load_lds_dwordx4 v143, s[56:57] offset:0
	s_waitcnt vmcnt(8)
	s_waitcnt lgkmcnt(0)
	s_barrier
	s_setprio 1
	v_mfma_f32_16x16x32_bf16 v[66:69], v[138:141], v[180:183], v[66:69]
	v_mfma_f32_16x16x32_bf16 v[66:69], v[152:155], v[184:187], v[66:69]
	v_mfma_f32_16x16x32_bf16 v[62:65], v[156:159], v[180:183], v[62:65]
	v_mfma_f32_16x16x32_bf16 v[62:65], v[160:163], v[184:187], v[62:65]
	v_mfma_f32_16x16x32_bf16 v[50:53], v[138:141], v[188:191], v[50:53]
	v_mfma_f32_16x16x32_bf16 v[50:53], v[152:155], v[192:195], v[50:53]
	v_mfma_f32_16x16x32_bf16 v[46:49], v[156:159], v[188:191], v[46:49]
	v_mfma_f32_16x16x32_bf16 v[46:49], v[160:163], v[192:195], v[46:49]
	v_mfma_f32_16x16x32_bf16 v[34:37], v[138:141], v[196:199], v[34:37]
	v_mfma_f32_16x16x32_bf16 v[34:37], v[152:155], v[200:203], v[34:37]
	v_mfma_f32_16x16x32_bf16 v[30:33], v[156:159], v[196:199], v[30:33]
	v_mfma_f32_16x16x32_bf16 v[30:33], v[160:163], v[200:203], v[30:33]
	v_mfma_f32_16x16x32_bf16 v[18:21], v[138:141], v[204:207], v[18:21]
	v_mfma_f32_16x16x32_bf16 v[18:21], v[152:155], v[208:211], v[18:21]
	v_mfma_f32_16x16x32_bf16 v[14:17], v[156:159], v[204:207], v[14:17]
	v_mfma_f32_16x16x32_bf16 v[14:17], v[160:163], v[208:211], v[14:17]
	v_mfma_f32_16x16x32_bf16 v[58:61], v[164:167], v[180:183], v[58:61]
	v_mfma_f32_16x16x32_bf16 v[54:57], v[172:175], v[180:183], v[54:57]
	v_mfma_f32_16x16x32_bf16 v[42:45], v[164:167], v[188:191], v[42:45]
	v_mfma_f32_16x16x32_bf16 v[38:41], v[172:175], v[188:191], v[38:41]
	v_mfma_f32_16x16x32_bf16 v[26:29], v[164:167], v[196:199], v[26:29]
	v_mfma_f32_16x16x32_bf16 v[22:25], v[172:175], v[196:199], v[22:25]
	v_mfma_f32_16x16x32_bf16 v[8:11], v[164:167], v[204:207], v[10:13]
	v_mfma_f32_16x16x32_bf16 v[4:7], v[172:175], v[204:207], v[4:7]
	v_mfma_f32_16x16x32_bf16 v[58:61], v[168:171], v[184:187], v[58:61]
	v_mfma_f32_16x16x32_bf16 v[54:57], v[176:179], v[184:187], v[54:57]
	v_mfma_f32_16x16x32_bf16 v[42:45], v[168:171], v[192:195], v[42:45]
	v_mfma_f32_16x16x32_bf16 v[38:41], v[176:179], v[192:195], v[38:41]
	v_mfma_f32_16x16x32_bf16 v[26:29], v[168:171], v[200:203], v[26:29]
	v_mfma_f32_16x16x32_bf16 v[22:25], v[176:179], v[200:203], v[22:25]
	v_mfma_f32_16x16x32_bf16 v[10:13], v[168:171], v[208:211], v[8:11]
	v_mfma_f32_16x16x32_bf16 v[6:9], v[176:179], v[208:211], v[4:7]
	s_barrier
	s_setprio 0
	s_add_i32 s86, s86, 2
	s_add_u32 s87, s87, 0x100
	s_addc_u32 s88, s88, 0
	s_add_u32 s89, s89, 0x100
	s_addc_u32 s90, s90, 0
	s_add_u32 s54, s54, 0x100
	s_addc_u32 s55, s55, 0
	s_cmp_gt_u32 s86, 29
	s_cbranch_scc0 .LBB0_2132
	s_and_b64 vcc, exec, s[18:19]
	s_cbranch_vccz .LBB0_2135
	s_barrier

; #define PG8_KSETUP() const bool last = (t == nt - 2); const char* a1 = cA + (size_t)(t + 1) * kstep; \
;             const char* a2 = last ? nA : cA + (size_t)(t + 2) * kstep; const char* b2 = last ? nB : cB + (size_t)(t + 2) * kstep; const char* a3 = a2 + kstep; const char* b3 = b2 + kstep; \
;             if (last && has_next) S.a_ready(nxt)
; template <class Epi, class Sched, bool ALIGN_EPI = false, bool SP2 = false>
; __device__ __forceinline__ void gemm_phase(PG8_LAS unsigned char* lds, const Gemm g, const Sched& S, const Epi& E) {
;     ...
;         int t0 = 0;
;         if constexpr (SP2 && Epi::NVM == 16) { if (ui > 0) { const int t = 0; PG8_KSETUP(); PG8_KITER_SP2(24, 24); t0 = 2; } }
;         if constexpr (SP2 && Epi::NVM == 8) { if (ui > 0) { const int t = 0; PG8_KSETUP(); PG8_KITER_SP2(16, 16); t0 = 2; } }
.LBB0_2287:
	s_cmp_lg_u32 s75, 0
	s_mov_b32 s40, 0
	s_cbranch_scc0 .LBB0_2289
	ds_read_b128 v[4:7], v152
	ds_read_b128 v[8:11], v152 offset:1024
	ds_read_b128 v[12:15], v152 offset:2048
	ds_read_b128 v[16:19], v152 offset:3072
	ds_read_b128 v[20:23], v153
	ds_read_b128 v[24:27], v153 offset:1024
	ds_read_b128 v[28:31], v153 offset:2048
	ds_read_b128 v[32:35], v153 offset:3072
	s_add_u32 s24, s36, 0x100
	s_addc_u32 s25, s37, 0
	s_add_u32 s30, s38, 0x100
	s_addc_u32 s31, s39, 0
	s_add_u32 s22, s36, 0x180
	s_addc_u32 s23, s37, 0
	ds_read_b128 v[36:39], v154
	ds_read_b128 v[40:43], v154 offset:1024
	ds_read_b128 v[44:47], v154 offset:2048
	ds_read_b128 v[48:51], v154 offset:3072
	ds_read_b128 v[52:55], v154 offset:4096
	ds_read_b128 v[56:59], v154 offset:5120
	ds_read_b128 v[60:63], v154 offset:6144
	ds_read_b128 v[64:67], v154 offset:7168
	s_add_u32 s40, s36, 0x80080
	s_addc_u32 s41, s37, 0
	s_mov_b32 m0, s66
	s_nop 0
	global_load_lds_dwordx4 v1, s[40:41] offset:0
	s_nop 0
	s_mov_b32 m0, s67
	s_nop 0
	global_load_lds_dwordx4 v147, s[40:41] offset:0
	s_waitcnt vmcnt(16)
	s_waitcnt lgkmcnt(0)
	s_barrier
	s_setprio 1
	v_mfma_f32_16x16x32_bf16 v[92:95], v[4:7], v[60:63], 0
	v_mfma_f32_16x16x32_bf16 v[68:71], v[4:7], v[36:39], 0
	v_mfma_f32_16x16x32_bf16 v[72:75], v[12:15], v[36:39], 0
	v_mfma_f32_16x16x32_bf16 v[76:79], v[4:7], v[44:47], 0
	v_mfma_f32_16x16x32_bf16 v[80:83], v[12:15], v[44:47], 0
	v_mfma_f32_16x16x32_bf16 v[84:87], v[4:7], v[52:55], 0
	v_mfma_f32_16x16x32_bf16 v[88:91], v[12:15], v[52:55], 0
	v_mfma_f32_16x16x32_bf16 v[102:105], v[8:11], v[64:67], v[92:95]
	v_mfma_f32_16x16x32_bf16 v[92:95], v[12:15], v[60:63], 0
	v_mfma_f32_16x16x32_bf16 v[68:71], v[8:11], v[40:43], v[68:71]
	v_mfma_f32_16x16x32_bf16 v[72:75], v[16:19], v[40:43], v[72:75]
	v_mfma_f32_16x16x32_bf16 v[76:79], v[8:11], v[48:51], v[76:79]
	v_mfma_f32_16x16x32_bf16 v[80:83], v[16:19], v[48:51], v[80:83]
	v_mfma_f32_16x16x32_bf16 v[84:87], v[8:11], v[56:59], v[84:87]
	v_mfma_f32_16x16x32_bf16 v[88:91], v[16:19], v[56:59], v[88:91]
	v_mfma_f32_16x16x32_bf16 v[106:109], v[16:19], v[64:67], v[92:95]
	v_mfma_f32_16x16x32_bf16 v[92:95], v[20:23], v[36:39], 0
	v_mfma_f32_16x16x32_bf16 v[36:39], v[28:31], v[36:39], 0
	v_mfma_f32_16x16x32_bf16 v[118:121], v[24:27], v[40:43], v[92:95]
	v_mfma_f32_16x16x32_bf16 v[36:39], v[32:35], v[40:43], v[36:39]
	v_mfma_f32_16x16x32_bf16 v[40:43], v[20:23], v[44:47], 0
	v_mfma_f32_16x16x32_bf16 v[44:47], v[28:31], v[44:47], 0
	v_mfma_f32_16x16x32_bf16 v[40:43], v[24:27], v[48:51], v[40:43]
	v_mfma_f32_16x16x32_bf16 v[44:47], v[32:35], v[48:51], v[44:47]
	v_mfma_f32_16x16x32_bf16 v[48:51], v[20:23], v[52:55], 0
	v_mfma_f32_16x16x32_bf16 v[52:55], v[28:31], v[52:55], 0
	v_mfma_f32_16x16x32_bf16 v[48:51], v[24:27], v[56:59], v[48:51]
	v_mfma_f32_16x16x32_bf16 v[52:55], v[32:35], v[56:59], v[52:55]
	v_mfma_f32_16x16x32_bf16 v[56:59], v[20:23], v[60:63], 0
	v_mfma_f32_16x16x32_bf16 v[60:63], v[28:31], v[60:63], 0
	v_mfma_f32_16x16x32_bf16 v[56:59], v[24:27], v[64:67], v[56:59]
	v_mfma_f32_16x16x32_bf16 v[60:63], v[32:35], v[64:67], v[60:63]
	s_barrier
	s_setprio 0
	ds_read_b128 v[64:67], v154 offset:16384
	ds_read_b128 v[92:95], v154 offset:17408
	ds_read_b128 v[96:99], v154 offset:18432
	ds_read_b128 v[110:113], v154 offset:19456
	ds_read_b128 v[114:117], v154 offset:20480
	ds_read_b128 v[122:125], v154 offset:21504
	ds_read_b128 v[126:129], v154 offset:22528
	ds_read_b128 v[130:133], v154 offset:23552
	s_mov_b32 m0, s29
	s_nop 0
	global_load_lds_dwordx4 v146, s[30:31] offset:0
	s_nop 0
	s_mov_b32 m0, s46
	s_nop 0
	global_load_lds_dwordx4 v148, s[30:31] offset:0
	s_add_u32 s30, s38, 0x80100
	s_addc_u32 s31, s39, 0
	s_mov_b32 m0, s47
	s_nop 0
	global_load_lds_dwordx4 v146, s[30:31] offset:0
	s_nop 0
	s_mov_b32 m0, s52
	s_nop 0
	global_load_lds_dwordx4 v148, s[30:31] offset:0
	s_nop 0
	s_mov_b32 m0, s21
	s_nop 0
	global_load_lds_dwordx4 v1, s[24:25] offset:0
	s_nop 0
	s_mov_b32 m0, s53
	s_nop 0
	global_load_lds_dwordx4 v147, s[24:25] offset:0
	s_waitcnt vmcnt(16)
	s_waitcnt lgkmcnt(0)
	s_barrier
	s_setprio 1
	v_mfma_f32_16x16x32_bf16 v[138:141], v[4:7], v[64:67], 0
	v_mfma_f32_16x16x32_bf16 v[158:161], v[4:7], v[96:99], 0
	v_mfma_f32_16x16x32_bf16 v[166:169], v[4:7], v[114:117], 0
	v_mfma_f32_16x16x32_bf16 v[4:7], v[4:7], v[126:129], 0
	v_mfma_f32_16x16x32_bf16 v[138:141], v[8:11], v[92:95], v[138:141]
	v_mfma_f32_16x16x32_bf16 v[158:161], v[8:11], v[110:113], v[158:161]
	v_mfma_f32_16x16x32_bf16 v[166:169], v[8:11], v[122:125], v[166:169]
	v_mfma_f32_16x16x32_bf16 v[4:7], v[8:11], v[130:133], v[4:7]
	v_mfma_f32_16x16x32_bf16 v[8:11], v[12:15], v[126:129], 0
	v_mfma_f32_16x16x32_bf16 v[142:145], v[12:15], v[64:67], 0
	v_mfma_f32_16x16x32_bf16 v[162:165], v[12:15], v[96:99], 0
	v_mfma_f32_16x16x32_bf16 v[170:173], v[12:15], v[114:117], 0
	v_mfma_f32_16x16x32_bf16 v[8:11], v[16:19], v[130:133], v[8:11]
	v_mfma_f32_16x16x32_bf16 v[142:145], v[16:19], v[92:95], v[142:145]
	v_mfma_f32_16x16x32_bf16 v[162:165], v[16:19], v[110:113], v[162:165]
	v_mfma_f32_16x16x32_bf16 v[170:173], v[16:19], v[122:125], v[170:173]
	v_mfma_f32_16x16x32_bf16 v[12:15], v[20:23], v[64:67], 0
	v_mfma_f32_16x16x32_bf16 v[174:177], v[24:27], v[92:95], v[12:15]
	v_mfma_f32_16x16x32_bf16 v[12:15], v[28:31], v[64:67], 0
	v_mfma_f32_16x16x32_bf16 v[178:181], v[32:35], v[92:95], v[12:15]
	v_mfma_f32_16x16x32_bf16 v[12:15], v[20:23], v[96:99], 0
	v_mfma_f32_16x16x32_bf16 v[182:185], v[24:27], v[110:113], v[12:15]
	v_mfma_f32_16x16x32_bf16 v[12:15], v[28:31], v[96:99], 0
	v_mfma_f32_16x16x32_bf16 v[186:189], v[32:35], v[110:113], v[12:15]
	v_mfma_f32_16x16x32_bf16 v[12:15], v[20:23], v[114:117], 0
	v_mfma_f32_16x16x32_bf16 v[190:193], v[24:27], v[122:125], v[12:15]
	v_mfma_f32_16x16x32_bf16 v[12:15], v[28:31], v[114:117], 0
	v_mfma_f32_16x16x32_bf16 v[194:197], v[32:35], v[122:125], v[12:15]
	v_mfma_f32_16x16x32_bf16 v[12:15], v[20:23], v[126:129], 0
	v_mfma_f32_16x16x32_bf16 v[198:201], v[24:27], v[130:133], v[12:15]
	v_mfma_f32_16x16x32_bf16 v[12:15], v[28:31], v[126:129], 0
	v_mfma_f32_16x16x32_bf16 v[202:205], v[32:35], v[130:133], v[12:15]
	s_barrier
; #define PG8_KSETUP() const bool last = (t == nt - 2); const char* a1 = cA + (size_t)(t + 1) * kstep; \
;             const char* a2 = last ? nA : cA + (size_t)(t + 2) * kstep; const char* b2 = last ? nB : cB + (size_t)(t + 2) * kstep; const char* a3 = a2 + kstep; const char* b3 = b2 + kstep; \
;             if (last && has_next) S.a_ready(nxt)
; template <class Epi, class Sched, bool ALIGN_EPI = false, bool SP2 = false>
; __device__ __forceinline__ void gemm_phase(PG8_LAS unsigned char* lds, const Gemm g, const Sched& S, const Epi& E) {
;     ...
;         int t0 = 0;
;         if constexpr (SP2 && Epi::NVM == 16) { if (ui > 0) { const int t = 0; PG8_KSETUP(); PG8_KITER_SP2(24, 24); t0 = 2; } }
;         if constexpr (SP2 && Epi::NVM == 8) { if (ui > 0) { const int t = 0; PG8_KSETUP(); PG8_KITER_SP2(16, 16); t0 = 2; } }
	s_setprio 0
	s_nop 4
	ds_read_b128 v[12:15], v155
	ds_read_b128 v[16:19], v155 offset:1024
	ds_read_b128 v[22:25], v155 offset:2048
	ds_read_b128 v[26:29], v155 offset:3072
	ds_read_b128 v[206:209], v156
	ds_read_b128 v[210:213], v156 offset:1024
	ds_read_b128 v[214:217], v156 offset:2048
	ds_read_b128 v[218:221], v156 offset:3072
	ds_read_b128 v[30:33], v154 offset:32768
	ds_read_b128 v[64:67], v154 offset:33792
	ds_read_b128 v[222:225], v154 offset:34816
	ds_read_b128 v[226:229], v154 offset:35840
	ds_read_b128 v[230:233], v154 offset:36864
	ds_read_b128 v[234:237], v154 offset:37888
	ds_read_b128 v[238:241], v154 offset:38912
	ds_read_b128 v[242:245], v154 offset:39936
	s_add_u32 s24, s36, 0x80100
	s_addc_u32 s25, s37, 0
	s_mov_b32 m0, s54
	s_nop 0
	global_load_lds_dwordx4 v1, s[24:25] offset:0
	s_nop 0
	s_mov_b32 m0, s55
	s_nop 0
	global_load_lds_dwordx4 v147, s[24:25] offset:0
	s_waitcnt vmcnt(8)
	s_waitcnt lgkmcnt(0)
	s_barrier
	s_setprio 1
	v_mfma_f32_16x16x32_bf16 v[68:71], v[12:15], v[30:33], v[68:71]
	v_mfma_f32_16x16x32_bf16 v[130:133], v[16:19], v[64:67], v[68:71]
	v_mfma_f32_16x16x32_bf16 v[68:71], v[22:25], v[30:33], v[72:75]
	v_mfma_f32_16x16x32_bf16 v[126:129], v[26:29], v[64:67], v[68:71]
	v_mfma_f32_16x16x32_bf16 v[68:71], v[12:15], v[222:225], v[76:79]
	v_mfma_f32_16x16x32_bf16 v[114:117], v[16:19], v[226:229], v[68:71]
	v_mfma_f32_16x16x32_bf16 v[68:71], v[22:25], v[222:225], v[80:83]
	v_mfma_f32_16x16x32_bf16 v[110:113], v[26:29], v[226:229], v[68:71]
	v_mfma_f32_16x16x32_bf16 v[68:71], v[12:15], v[230:233], v[84:87]
	v_mfma_f32_16x16x32_bf16 v[98:101], v[16:19], v[234:237], v[68:71]
	v_mfma_f32_16x16x32_bf16 v[68:71], v[22:25], v[230:233], v[88:91]
	v_mfma_f32_16x16x32_bf16 v[94:97], v[26:29], v[234:237], v[68:71]
	v_mfma_f32_16x16x32_bf16 v[68:71], v[12:15], v[238:241], v[102:105]
	v_mfma_f32_16x16x32_bf16 v[82:85], v[16:19], v[242:245], v[68:71]
	v_mfma_f32_16x16x32_bf16 v[68:71], v[22:25], v[238:241], v[106:109]
	v_mfma_f32_16x16x32_bf16 v[78:81], v[26:29], v[242:245], v[68:71]
	v_mfma_f32_16x16x32_bf16 v[68:71], v[206:209], v[30:33], v[118:121]
	v_mfma_f32_16x16x32_bf16 v[30:33], v[214:217], v[30:33], v[36:39]
	v_mfma_f32_16x16x32_bf16 v[118:121], v[218:221], v[64:67], v[30:33]
	v_mfma_f32_16x16x32_bf16 v[30:33], v[206:209], v[222:225], v[40:43]
	v_mfma_f32_16x16x32_bf16 v[106:109], v[210:213], v[226:229], v[30:33]
	v_mfma_f32_16x16x32_bf16 v[30:33], v[214:217], v[222:225], v[44:47]
	v_mfma_f32_16x16x32_bf16 v[102:105], v[218:221], v[226:229], v[30:33]
	v_mfma_f32_16x16x32_bf16 v[30:33], v[206:209], v[230:233], v[48:51]
	v_mfma_f32_16x16x32_bf16 v[90:93], v[210:213], v[234:237], v[30:33]
	v_mfma_f32_16x16x32_bf16 v[30:33], v[214:217], v[230:233], v[52:55]
	v_mfma_f32_16x16x32_bf16 v[86:89], v[218:221], v[234:237], v[30:33]
	v_mfma_f32_16x16x32_bf16 v[30:33], v[206:209], v[238:241], v[56:59]
	v_mfma_f32_16x16x32_bf16 v[74:77], v[210:213], v[242:245], v[30:33]
	v_mfma_f32_16x16x32_bf16 v[30:33], v[214:217], v[238:241], v[60:63]
	v_mfma_f32_16x16x32_bf16 v[122:125], v[210:213], v[64:67], v[68:71]
	v_mfma_f32_16x16x32_bf16 v[66:69], v[218:221], v[242:245], v[30:33]
	s_barrier
	s_setprio 0
	ds_read_b128 v[38:41], v154 offset:49152
	ds_read_b128 v[42:45], v154 offset:50176
	ds_read_b128 v[222:225], v154 offset:51200
	ds_read_b128 v[226:229], v154 offset:52224
	ds_read_b128 v[230:233], v154 offset:53248
	ds_read_b128 v[234:237], v154 offset:54272
	ds_read_b128 v[238:241], v154 offset:55296
	ds_read_b128 v[242:245], v154 offset:56320
	s_add_u32 s24, s38, 0x180
	s_addc_u32 s25, s39, 0
	s_mov_b32 m0, s56
	s_nop 0
	global_load_lds_dwordx4 v146, s[24:25] offset:0
	s_nop 0
	s_mov_b32 m0, s57
	s_nop 0
	global_load_lds_dwordx4 v148, s[24:25] offset:0
	s_add_u32 s24, s38, 0x80180
	s_addc_u32 s25, s39, 0
	s_mov_b32 m0, s64
	s_nop 0
	global_load_lds_dwordx4 v146, s[24:25] offset:0
	s_nop 0
	s_mov_b32 m0, s65
	s_nop 0
	global_load_lds_dwordx4 v148, s[24:25] offset:0
	s_nop 0
	s_mov_b32 m0, s58
	s_nop 0
	global_load_lds_dwordx4 v1, s[22:23] offset:0
	s_nop 0
	s_mov_b32 m0, s59
	s_nop 0
	global_load_lds_dwordx4 v147, s[22:23] offset:0
	s_waitcnt vmcnt(8)
	s_waitcnt lgkmcnt(0)
	s_barrier
	s_setprio 1
	v_mfma_f32_16x16x32_bf16 v[30:33], v[12:15], v[38:41], v[138:141]
	v_mfma_f32_16x16x32_bf16 v[70:73], v[16:19], v[42:45], v[30:33]
	v_mfma_f32_16x16x32_bf16 v[30:33], v[22:25], v[38:41], v[142:145]
	v_mfma_f32_16x16x32_bf16 v[62:65], v[26:29], v[42:45], v[30:33]
	v_mfma_f32_16x16x32_bf16 v[30:33], v[12:15], v[222:225], v[158:161]
	v_mfma_f32_16x16x32_bf16 v[50:53], v[16:19], v[226:229], v[30:33]
	v_mfma_f32_16x16x32_bf16 v[30:33], v[22:25], v[222:225], v[162:165]
	v_mfma_f32_16x16x32_bf16 v[46:49], v[26:29], v[226:229], v[30:33]
	v_mfma_f32_16x16x32_bf16 v[30:33], v[12:15], v[230:233], v[166:169]
	v_mfma_f32_16x16x32_bf16 v[4:7], v[12:15], v[238:241], v[4:7]
	v_mfma_f32_16x16x32_bf16 v[34:37], v[16:19], v[234:237], v[30:33]
	v_mfma_f32_16x16x32_bf16 v[30:33], v[22:25], v[230:233], v[170:173]
	v_mfma_f32_16x16x32_bf16 v[18:21], v[16:19], v[242:245], v[4:7]
	v_mfma_f32_16x16x32_bf16 v[4:7], v[22:25], v[238:241], v[8:11]
	v_mfma_f32_16x16x32_bf16 v[30:33], v[26:29], v[234:237], v[30:33]
	v_mfma_f32_16x16x32_bf16 v[14:17], v[26:29], v[242:245], v[4:7]
	v_mfma_f32_16x16x32_bf16 v[4:7], v[206:209], v[38:41], v[174:177]
	v_mfma_f32_16x16x32_bf16 v[58:61], v[210:213], v[42:45], v[4:7]
	v_mfma_f32_16x16x32_bf16 v[4:7], v[214:217], v[38:41], v[178:181]
	v_mfma_f32_16x16x32_bf16 v[54:57], v[218:221], v[42:45], v[4:7]
	v_mfma_f32_16x16x32_bf16 v[4:7], v[206:209], v[222:225], v[182:185]
	v_mfma_f32_16x16x32_bf16 v[42:45], v[210:213], v[226:229], v[4:7]
	v_mfma_f32_16x16x32_bf16 v[4:7], v[214:217], v[222:225], v[186:189]
	v_mfma_f32_16x16x32_bf16 v[38:41], v[218:221], v[226:229], v[4:7]
	v_mfma_f32_16x16x32_bf16 v[4:7], v[206:209], v[230:233], v[190:193]
	v_mfma_f32_16x16x32_bf16 v[26:29], v[210:213], v[234:237], v[4:7]
	v_mfma_f32_16x16x32_bf16 v[4:7], v[214:217], v[230:233], v[194:197]
	v_mfma_f32_16x16x32_bf16 v[22:25], v[218:221], v[234:237], v[4:7]
	v_mfma_f32_16x16x32_bf16 v[4:7], v[206:209], v[238:241], v[198:201]
	v_mfma_f32_16x16x32_bf16 v[10:13], v[210:213], v[242:245], v[4:7]
	v_mfma_f32_16x16x32_bf16 v[4:7], v[214:217], v[238:241], v[202:205]
	v_mfma_f32_16x16x32_bf16 v[6:9], v[218:221], v[242:245], v[4:7]
	s_barrier
	s_setprio 0
	s_mov_b32 s40, 2
	s_branch .LBB0_2290

; #define PG8_KSETUP() const bool last = (t == nt - 2); const char* a1 = cA + (size_t)(t + 1) * kstep; \
;             const char* a2 = last ? nA : cA + (size_t)(t + 2) * kstep; const char* b2 = last ? nB : cB + (size_t)(t + 2) * kstep; const char* a3 = a2 + kstep; const char* b3 = b2 + kstep; \
;             if (last && has_next) S.a_ready(nxt)
; template <class Epi, class Sched, bool ALIGN_EPI = false, bool SP2 = false>
; __device__ __forceinline__ void gemm_phase(PG8_LAS unsigned char* lds, const Gemm g, const Sched& S, const Epi& E) {
;     ...
;         int t0 = 0;
;         if constexpr (SP2 && Epi::NVM == 16) { if (ui > 0) { const int t = 0; PG8_KSETUP(); PG8_KITER_SP2(24, 24); t0 = 2; } }
;         if constexpr (SP2 && Epi::NVM == 8) { if (ui > 0) { const int t = 0; PG8_KSETUP(); PG8_KITER_SP2(16, 16); t0 = 2; } }
;         for (int t = t0; t < nt; t += 2) {
;             PG8_KSETUP();
;             if constexpr (SP2) {
;             PG8_KITER_SP2(8, 8);
.LBB0_2291:
	ds_read_b128 v[138:141], v152
	ds_read_b128 v[142:145], v152 offset:1024
	ds_read_b128 v[158:161], v152 offset:2048
	ds_read_b128 v[162:165], v152 offset:3072
	ds_read_b128 v[166:169], v153
	ds_read_b128 v[170:173], v153 offset:1024
	ds_read_b128 v[174:177], v153 offset:2048
	ds_read_b128 v[178:181], v153 offset:3072
	s_cmp_eq_u32 s78, 28
	s_cselect_b32 s40, s76, s81
	s_cselect_b32 s41, s19, s82
	s_cselect_b32 s38, s77, s79
	s_cselect_b32 s39, s17, s80
	s_add_u32 s36, s40, 0x80
	s_addc_u32 s37, s41, 0
	ds_read_b128 v[182:185], v154
	ds_read_b128 v[186:189], v154 offset:1024
	ds_read_b128 v[190:193], v154 offset:2048
	ds_read_b128 v[194:197], v154 offset:3072
	ds_read_b128 v[198:201], v154 offset:4096
	ds_read_b128 v[202:205], v154 offset:5120
	ds_read_b128 v[206:209], v154 offset:6144
	ds_read_b128 v[210:213], v154 offset:7168
	s_add_u32 s30, s81, 0x7ff80
	s_addc_u32 s31, s82, 0
	s_mov_b32 m0, s66
	s_nop 0
	global_load_lds_dwordx4 v1, s[30:31] offset:0
	s_nop 0
	s_mov_b32 m0, s67
	s_nop 0
	global_load_lds_dwordx4 v147, s[30:31] offset:0
	s_waitcnt vmcnt(8)
	s_waitcnt lgkmcnt(0)
	s_barrier
	s_setprio 1
	v_mfma_f32_16x16x32_bf16 v[130:133], v[138:141], v[182:185], v[130:133]
	v_mfma_f32_16x16x32_bf16 v[130:133], v[142:145], v[186:189], v[130:133]
	v_mfma_f32_16x16x32_bf16 v[126:129], v[158:161], v[182:185], v[126:129]
	v_mfma_f32_16x16x32_bf16 v[126:129], v[162:165], v[186:189], v[126:129]
	v_mfma_f32_16x16x32_bf16 v[114:117], v[138:141], v[190:193], v[114:117]
	v_mfma_f32_16x16x32_bf16 v[114:117], v[142:145], v[194:197], v[114:117]
	v_mfma_f32_16x16x32_bf16 v[110:113], v[158:161], v[190:193], v[110:113]
	v_mfma_f32_16x16x32_bf16 v[110:113], v[162:165], v[194:197], v[110:113]
	v_mfma_f32_16x16x32_bf16 v[98:101], v[138:141], v[198:201], v[98:101]
	v_mfma_f32_16x16x32_bf16 v[98:101], v[142:145], v[202:205], v[98:101]
	v_mfma_f32_16x16x32_bf16 v[94:97], v[158:161], v[198:201], v[94:97]
	v_mfma_f32_16x16x32_bf16 v[94:97], v[162:165], v[202:205], v[94:97]
	v_mfma_f32_16x16x32_bf16 v[82:85], v[138:141], v[206:209], v[82:85]
	v_mfma_f32_16x16x32_bf16 v[82:85], v[142:145], v[210:213], v[82:85]
	v_mfma_f32_16x16x32_bf16 v[78:81], v[158:161], v[206:209], v[78:81]
	v_mfma_f32_16x16x32_bf16 v[78:81], v[162:165], v[210:213], v[78:81]
	v_mfma_f32_16x16x32_bf16 v[122:125], v[166:169], v[182:185], v[122:125]
	v_mfma_f32_16x16x32_bf16 v[122:125], v[170:173], v[186:189], v[122:125]
	v_mfma_f32_16x16x32_bf16 v[118:121], v[174:177], v[182:185], v[118:121]
	v_mfma_f32_16x16x32_bf16 v[118:121], v[178:181], v[186:189], v[118:121]
	v_mfma_f32_16x16x32_bf16 v[106:109], v[166:169], v[190:193], v[106:109]
	v_mfma_f32_16x16x32_bf16 v[106:109], v[170:173], v[194:197], v[106:109]
	v_mfma_f32_16x16x32_bf16 v[102:105], v[174:177], v[190:193], v[102:105]
	v_mfma_f32_16x16x32_bf16 v[102:105], v[178:181], v[194:197], v[102:105]
	v_mfma_f32_16x16x32_bf16 v[90:93], v[166:169], v[198:201], v[90:93]
	v_mfma_f32_16x16x32_bf16 v[90:93], v[170:173], v[202:205], v[90:93]
	v_mfma_f32_16x16x32_bf16 v[86:89], v[174:177], v[198:201], v[86:89]
	v_mfma_f32_16x16x32_bf16 v[86:89], v[178:181], v[202:205], v[86:89]
	v_mfma_f32_16x16x32_bf16 v[74:77], v[166:169], v[206:209], v[74:77]
	v_mfma_f32_16x16x32_bf16 v[74:77], v[170:173], v[210:213], v[74:77]
	v_mfma_f32_16x16x32_bf16 v[66:69], v[174:177], v[206:209], v[66:69]
	v_mfma_f32_16x16x32_bf16 v[66:69], v[178:181], v[210:213], v[66:69]
	s_barrier
	s_setprio 0
	ds_read_b128 v[182:185], v154 offset:16384
	ds_read_b128 v[186:189], v154 offset:17408
	ds_read_b128 v[190:193], v154 offset:18432
	ds_read_b128 v[194:197], v154 offset:19456
	ds_read_b128 v[198:201], v154 offset:20480
	ds_read_b128 v[202:205], v154 offset:21504
	ds_read_b128 v[206:209], v154 offset:22528
	ds_read_b128 v[210:213], v154 offset:23552
	s_mov_b32 m0, s29
	s_nop 0
	global_load_lds_dwordx4 v146, s[38:39] offset:0
	s_add_u32 s30, s38, 0x80000
	s_mov_b32 m0, s46
	s_nop 0
	global_load_lds_dwordx4 v148, s[38:39] offset:0
	s_addc_u32 s31, s39, 0
	s_mov_b32 m0, s47
	s_nop 0
	global_load_lds_dwordx4 v146, s[30:31] offset:0
	s_nop 0
	s_mov_b32 m0, s52
	s_nop 0
	global_load_lds_dwordx4 v148, s[30:31] offset:0
	s_nop 0
	s_mov_b32 m0, s21
	s_nop 0
	global_load_lds_dwordx4 v1, s[40:41] offset:0
	s_nop 0
	s_mov_b32 m0, s53
	s_nop 0
	global_load_lds_dwordx4 v147, s[40:41] offset:0
	s_waitcnt vmcnt(8)
	s_waitcnt lgkmcnt(0)
	s_barrier
	s_setprio 1
	v_mfma_f32_16x16x32_bf16 v[70:73], v[138:141], v[182:185], v[70:73]
	v_mfma_f32_16x16x32_bf16 v[70:73], v[142:145], v[186:189], v[70:73]
	v_mfma_f32_16x16x32_bf16 v[62:65], v[158:161], v[182:185], v[62:65]
	v_mfma_f32_16x16x32_bf16 v[62:65], v[162:165], v[186:189], v[62:65]
	v_mfma_f32_16x16x32_bf16 v[50:53], v[138:141], v[190:193], v[50:53]
	v_mfma_f32_16x16x32_bf16 v[50:53], v[142:145], v[194:197], v[50:53]
	v_mfma_f32_16x16x32_bf16 v[46:49], v[158:161], v[190:193], v[46:49]
	v_mfma_f32_16x16x32_bf16 v[46:49], v[162:165], v[194:197], v[46:49]
	v_mfma_f32_16x16x32_bf16 v[34:37], v[138:141], v[198:201], v[34:37]
	v_mfma_f32_16x16x32_bf16 v[34:37], v[142:145], v[202:205], v[34:37]
	v_mfma_f32_16x16x32_bf16 v[30:33], v[158:161], v[198:201], v[30:33]
	v_mfma_f32_16x16x32_bf16 v[30:33], v[162:165], v[202:205], v[30:33]
	v_mfma_f32_16x16x32_bf16 v[18:21], v[138:141], v[206:209], v[18:21]
	v_mfma_f32_16x16x32_bf16 v[18:21], v[142:145], v[210:213], v[18:21]
	v_mfma_f32_16x16x32_bf16 v[14:17], v[158:161], v[206:209], v[14:17]
	v_mfma_f32_16x16x32_bf16 v[14:17], v[162:165], v[210:213], v[14:17]
	v_mfma_f32_16x16x32_bf16 v[58:61], v[166:169], v[182:185], v[58:61]
	v_mfma_f32_16x16x32_bf16 v[54:57], v[174:177], v[182:185], v[54:57]
	v_mfma_f32_16x16x32_bf16 v[42:45], v[166:169], v[190:193], v[42:45]
	v_mfma_f32_16x16x32_bf16 v[38:41], v[174:177], v[190:193], v[38:41]
	v_mfma_f32_16x16x32_bf16 v[26:29], v[166:169], v[198:201], v[26:29]
	v_mfma_f32_16x16x32_bf16 v[22:25], v[174:177], v[198:201], v[22:25]
	v_mfma_f32_16x16x32_bf16 v[10:13], v[166:169], v[206:209], v[10:13]
	v_mfma_f32_16x16x32_bf16 v[4:7], v[174:177], v[206:209], v[6:9]
	v_mfma_f32_16x16x32_bf16 v[58:61], v[170:173], v[186:189], v[58:61]
	v_mfma_f32_16x16x32_bf16 v[54:57], v[178:181], v[186:189], v[54:57]
	v_mfma_f32_16x16x32_bf16 v[42:45], v[170:173], v[194:197], v[42:45]
	v_mfma_f32_16x16x32_bf16 v[38:41], v[178:181], v[194:197], v[38:41]
	v_mfma_f32_16x16x32_bf16 v[26:29], v[170:173], v[202:205], v[26:29]
	v_mfma_f32_16x16x32_bf16 v[22:25], v[178:181], v[202:205], v[22:25]
	v_mfma_f32_16x16x32_bf16 v[10:13], v[170:173], v[210:213], v[10:13]
	v_mfma_f32_16x16x32_bf16 v[4:7], v[178:181], v[210:213], v[4:7]
	s_barrier
; #define PG8_KSETUP() const bool last = (t == nt - 2); const char* a1 = cA + (size_t)(t + 1) * kstep; \
;             const char* a2 = last ? nA : cA + (size_t)(t + 2) * kstep; const char* b2 = last ? nB : cB + (size_t)(t + 2) * kstep; const char* a3 = a2 + kstep; const char* b3 = b2 + kstep; \
;             if (last && has_next) S.a_ready(nxt)
; template <class Epi, class Sched, bool ALIGN_EPI = false, bool SP2 = false>
; __device__ __forceinline__ void gemm_phase(PG8_LAS unsigned char* lds, const Gemm g, const Sched& S, const Epi& E) {
;     ...
;         int t0 = 0;
;         if constexpr (SP2 && Epi::NVM == 16) { if (ui > 0) { const int t = 0; PG8_KSETUP(); PG8_KITER_SP2(24, 24); t0 = 2; } }
;         if constexpr (SP2 && Epi::NVM == 8) { if (ui > 0) { const int t = 0; PG8_KSETUP(); PG8_KITER_SP2(16, 16); t0 = 2; } }
;         for (int t = t0; t < nt; t += 2) {
;             PG8_KSETUP();
;             if constexpr (SP2) {
;             PG8_KITER_SP2(8, 8);
	s_setprio 0
	ds_read_b128 v[138:141], v155
	ds_read_b128 v[142:145], v155 offset:1024
	ds_read_b128 v[158:161], v155 offset:2048
	ds_read_b128 v[162:165], v155 offset:3072
	ds_read_b128 v[166:169], v156
	ds_read_b128 v[170:173], v156 offset:1024
	ds_read_b128 v[174:177], v156 offset:2048
	ds_read_b128 v[178:181], v156 offset:3072
	ds_read_b128 v[182:185], v154 offset:32768
	ds_read_b128 v[186:189], v154 offset:33792
	ds_read_b128 v[190:193], v154 offset:34816
	ds_read_b128 v[194:197], v154 offset:35840
	ds_read_b128 v[198:201], v154 offset:36864
	ds_read_b128 v[202:205], v154 offset:37888
	ds_read_b128 v[206:209], v154 offset:38912
	ds_read_b128 v[210:213], v154 offset:39936
	s_add_u32 s30, s40, 0x80000
	s_addc_u32 s31, s41, 0
	s_mov_b32 m0, s54
	s_nop 0
	global_load_lds_dwordx4 v1, s[30:31] offset:0
	s_nop 0
	s_mov_b32 m0, s55
	s_nop 0
	global_load_lds_dwordx4 v147, s[30:31] offset:0
	s_waitcnt vmcnt(8)
	s_waitcnt lgkmcnt(0)
	s_barrier
	s_setprio 1
	v_mfma_f32_16x16x32_bf16 v[130:133], v[138:141], v[182:185], v[130:133]
	v_mfma_f32_16x16x32_bf16 v[130:133], v[142:145], v[186:189], v[130:133]
	v_mfma_f32_16x16x32_bf16 v[126:129], v[158:161], v[182:185], v[126:129]
	v_mfma_f32_16x16x32_bf16 v[126:129], v[162:165], v[186:189], v[126:129]
	v_mfma_f32_16x16x32_bf16 v[114:117], v[138:141], v[190:193], v[114:117]
	v_mfma_f32_16x16x32_bf16 v[114:117], v[142:145], v[194:197], v[114:117]
	v_mfma_f32_16x16x32_bf16 v[110:113], v[158:161], v[190:193], v[110:113]
	v_mfma_f32_16x16x32_bf16 v[110:113], v[162:165], v[194:197], v[110:113]
	v_mfma_f32_16x16x32_bf16 v[98:101], v[138:141], v[198:201], v[98:101]
	v_mfma_f32_16x16x32_bf16 v[98:101], v[142:145], v[202:205], v[98:101]
	v_mfma_f32_16x16x32_bf16 v[94:97], v[158:161], v[198:201], v[94:97]
	v_mfma_f32_16x16x32_bf16 v[94:97], v[162:165], v[202:205], v[94:97]
	v_mfma_f32_16x16x32_bf16 v[82:85], v[138:141], v[206:209], v[82:85]
	v_mfma_f32_16x16x32_bf16 v[82:85], v[142:145], v[210:213], v[82:85]
	v_mfma_f32_16x16x32_bf16 v[78:81], v[158:161], v[206:209], v[78:81]
	v_mfma_f32_16x16x32_bf16 v[78:81], v[162:165], v[210:213], v[78:81]
	v_mfma_f32_16x16x32_bf16 v[122:125], v[166:169], v[182:185], v[122:125]
	v_mfma_f32_16x16x32_bf16 v[122:125], v[170:173], v[186:189], v[122:125]
	v_mfma_f32_16x16x32_bf16 v[118:121], v[174:177], v[182:185], v[118:121]
	v_mfma_f32_16x16x32_bf16 v[118:121], v[178:181], v[186:189], v[118:121]
	v_mfma_f32_16x16x32_bf16 v[106:109], v[166:169], v[190:193], v[106:109]
	v_mfma_f32_16x16x32_bf16 v[106:109], v[170:173], v[194:197], v[106:109]
	v_mfma_f32_16x16x32_bf16 v[102:105], v[174:177], v[190:193], v[102:105]
	v_mfma_f32_16x16x32_bf16 v[102:105], v[178:181], v[194:197], v[102:105]
	v_mfma_f32_16x16x32_bf16 v[90:93], v[166:169], v[198:201], v[90:93]
	v_mfma_f32_16x16x32_bf16 v[90:93], v[170:173], v[202:205], v[90:93]
	v_mfma_f32_16x16x32_bf16 v[86:89], v[174:177], v[198:201], v[86:89]
	v_mfma_f32_16x16x32_bf16 v[86:89], v[178:181], v[202:205], v[86:89]
	v_mfma_f32_16x16x32_bf16 v[74:77], v[166:169], v[206:209], v[74:77]
	v_mfma_f32_16x16x32_bf16 v[74:77], v[170:173], v[210:213], v[74:77]
	v_mfma_f32_16x16x32_bf16 v[66:69], v[174:177], v[206:209], v[66:69]
	v_mfma_f32_16x16x32_bf16 v[66:69], v[178:181], v[210:213], v[66:69]
	s_barrier
	s_setprio 0
	ds_read_b128 v[182:185], v154 offset:49152
	ds_read_b128 v[186:189], v154 offset:50176
	ds_read_b128 v[190:193], v154 offset:51200
	ds_read_b128 v[194:197], v154 offset:52224
	ds_read_b128 v[198:201], v154 offset:53248
	ds_read_b128 v[202:205], v154 offset:54272
	ds_read_b128 v[206:209], v154 offset:55296
	ds_read_b128 v[210:213], v154 offset:56320
	s_add_u32 s30, s38, 0x80
	s_addc_u32 s31, s39, 0
	s_mov_b32 m0, s56
	s_nop 0
	global_load_lds_dwordx4 v146, s[30:31] offset:0
	s_nop 0
	s_mov_b32 m0, s57
	s_nop 0
	global_load_lds_dwordx4 v148, s[30:31] offset:0
	s_add_u32 s30, s38, 0x80080
	s_addc_u32 s31, s39, 0
	s_mov_b32 m0, s64
	s_nop 0
	global_load_lds_dwordx4 v146, s[30:31] offset:0
	s_nop 0
	s_mov_b32 m0, s65
	s_nop 0
	global_load_lds_dwordx4 v148, s[30:31] offset:0
	s_nop 0
	s_mov_b32 m0, s58
	s_nop 0
	global_load_lds_dwordx4 v1, s[36:37] offset:0
	s_nop 0
	s_mov_b32 m0, s59
	s_nop 0
	global_load_lds_dwordx4 v147, s[36:37] offset:0
	s_waitcnt vmcnt(8)
	s_waitcnt lgkmcnt(0)
	s_barrier
	s_setprio 1
	v_mfma_f32_16x16x32_bf16 v[70:73], v[138:141], v[182:185], v[70:73]
	v_mfma_f32_16x16x32_bf16 v[70:73], v[142:145], v[186:189], v[70:73]
	v_mfma_f32_16x16x32_bf16 v[62:65], v[158:161], v[182:185], v[62:65]
	v_mfma_f32_16x16x32_bf16 v[62:65], v[162:165], v[186:189], v[62:65]
	v_mfma_f32_16x16x32_bf16 v[50:53], v[138:141], v[190:193], v[50:53]
	v_mfma_f32_16x16x32_bf16 v[50:53], v[142:145], v[194:197], v[50:53]
	v_mfma_f32_16x16x32_bf16 v[46:49], v[158:161], v[190:193], v[46:49]
	v_mfma_f32_16x16x32_bf16 v[46:49], v[162:165], v[194:197], v[46:49]
	v_mfma_f32_16x16x32_bf16 v[34:37], v[138:141], v[198:201], v[34:37]
	v_mfma_f32_16x16x32_bf16 v[34:37], v[142:145], v[202:205], v[34:37]
	v_mfma_f32_16x16x32_bf16 v[30:33], v[158:161], v[198:201], v[30:33]
	v_mfma_f32_16x16x32_bf16 v[30:33], v[162:165], v[202:205], v[30:33]
	v_mfma_f32_16x16x32_bf16 v[18:21], v[138:141], v[206:209], v[18:21]
	v_mfma_f32_16x16x32_bf16 v[18:21], v[142:145], v[210:213], v[18:21]
	v_mfma_f32_16x16x32_bf16 v[14:17], v[158:161], v[206:209], v[14:17]
	v_mfma_f32_16x16x32_bf16 v[14:17], v[162:165], v[210:213], v[14:17]
	v_mfma_f32_16x16x32_bf16 v[58:61], v[166:169], v[182:185], v[58:61]
	v_mfma_f32_16x16x32_bf16 v[54:57], v[174:177], v[182:185], v[54:57]
	v_mfma_f32_16x16x32_bf16 v[42:45], v[166:169], v[190:193], v[42:45]
	v_mfma_f32_16x16x32_bf16 v[38:41], v[174:177], v[190:193], v[38:41]
	v_mfma_f32_16x16x32_bf16 v[26:29], v[166:169], v[198:201], v[26:29]
	v_mfma_f32_16x16x32_bf16 v[22:25], v[174:177], v[198:201], v[22:25]
	v_mfma_f32_16x16x32_bf16 v[8:11], v[166:169], v[206:209], v[10:13]
	v_mfma_f32_16x16x32_bf16 v[4:7], v[174:177], v[206:209], v[4:7]
	v_mfma_f32_16x16x32_bf16 v[58:61], v[170:173], v[186:189], v[58:61]
	v_mfma_f32_16x16x32_bf16 v[54:57], v[178:181], v[186:189], v[54:57]
	v_mfma_f32_16x16x32_bf16 v[42:45], v[170:173], v[194:197], v[42:45]
	v_mfma_f32_16x16x32_bf16 v[38:41], v[178:181], v[194:197], v[38:41]
	v_mfma_f32_16x16x32_bf16 v[26:29], v[170:173], v[202:205], v[26:29]
	v_mfma_f32_16x16x32_bf16 v[22:25], v[178:181], v[202:205], v[22:25]
	v_mfma_f32_16x16x32_bf16 v[10:13], v[170:173], v[210:213], v[8:11]
	v_mfma_f32_16x16x32_bf16 v[6:9], v[178:181], v[210:213], v[4:7]
	s_barrier
	s_setprio 0
	s_add_i32 s78, s78, 2
	s_add_u32 s79, s79, 0x100
	s_addc_u32 s80, s80, 0
	s_add_u32 s81, s81, 0x100
	s_addc_u32 s82, s82, 0
	s_cmp_gt_u32 s78, 29
	s_cbranch_scc0 .LBB0_2291
	s_and_b64 vcc, exec, s[14:15]
	s_cbranch_vccz .LBB0_2294
	s_barrier

; #define PG8_KSETUP() const bool last = (t == nt - 2); const char* a1 = cA + (size_t)(t + 1) * kstep; \
;             const char* a2 = last ? nA : cA + (size_t)(t + 2) * kstep; const char* b2 = last ? nB : cB + (size_t)(t + 2) * kstep; const char* a3 = a2 + kstep; const char* b3 = b2 + kstep; \
;             if (last && has_next) S.a_ready(nxt)
; template <class Epi, class Sched, bool ALIGN_EPI = false, bool SP2 = false>
; __device__ __forceinline__ void gemm_phase(PG8_LAS unsigned char* lds, const Gemm g, const Sched& S, const Epi& E) {
;     ...
;         int t0 = 0;
;         if constexpr (SP2 && Epi::NVM == 16) { if (ui > 0) { const int t = 0; PG8_KSETUP(); PG8_KITER_SP2(24, 24); t0 = 2; } }
.LBB0_2373:
	ds_read_b128 v[4:7], v147
	ds_read_b128 v[8:11], v147 offset:1024
	ds_read_b128 v[12:15], v147 offset:2048
	ds_read_b128 v[16:19], v147 offset:3072
	ds_read_b128 v[20:23], v148
	ds_read_b128 v[24:27], v148 offset:1024
	ds_read_b128 v[28:31], v148 offset:2048
	ds_read_b128 v[32:35], v148 offset:3072
	s_add_u32 s44, s36, 0x100
	s_addc_u32 s45, s37, 0
	s_add_u32 s30, s38, 0x100
	s_addc_u32 s31, s39, 0
	s_add_u32 s40, s36, 0x180
	s_addc_u32 s41, s37, 0
	ds_read_b128 v[36:39], v149
	ds_read_b128 v[40:43], v149 offset:1024
	ds_read_b128 v[44:47], v149 offset:2048
	ds_read_b128 v[48:51], v149 offset:3072
	ds_read_b128 v[52:55], v149 offset:4096
	ds_read_b128 v[56:59], v149 offset:5120
	ds_read_b128 v[60:63], v149 offset:6144
	ds_read_b128 v[64:67], v149 offset:7168
	s_add_u32 s42, s36, 0x160080
	s_addc_u32 s43, s37, 0
	s_mov_b32 m0, s72
	s_nop 0
	global_load_lds_dwordx4 v1, s[42:43] offset:0
	s_nop 0
	s_mov_b32 m0, s73
	s_nop 0
	global_load_lds_dwordx4 v143, s[42:43] offset:0
	s_waitcnt vmcnt(24)
	s_waitcnt lgkmcnt(0)
	s_barrier
	s_setprio 1
	v_mfma_f32_16x16x32_bf16 v[92:95], v[4:7], v[60:63], 0
	v_mfma_f32_16x16x32_bf16 v[68:71], v[4:7], v[36:39], 0
	v_mfma_f32_16x16x32_bf16 v[72:75], v[12:15], v[36:39], 0
	v_mfma_f32_16x16x32_bf16 v[76:79], v[4:7], v[44:47], 0
	v_mfma_f32_16x16x32_bf16 v[80:83], v[12:15], v[44:47], 0
	v_mfma_f32_16x16x32_bf16 v[84:87], v[4:7], v[52:55], 0
	v_mfma_f32_16x16x32_bf16 v[88:91], v[12:15], v[52:55], 0
	v_mfma_f32_16x16x32_bf16 v[102:105], v[8:11], v[64:67], v[92:95]
	v_mfma_f32_16x16x32_bf16 v[92:95], v[12:15], v[60:63], 0
	v_mfma_f32_16x16x32_bf16 v[68:71], v[8:11], v[40:43], v[68:71]
	v_mfma_f32_16x16x32_bf16 v[72:75], v[16:19], v[40:43], v[72:75]
	v_mfma_f32_16x16x32_bf16 v[76:79], v[8:11], v[48:51], v[76:79]
	v_mfma_f32_16x16x32_bf16 v[80:83], v[16:19], v[48:51], v[80:83]
	v_mfma_f32_16x16x32_bf16 v[84:87], v[8:11], v[56:59], v[84:87]
	v_mfma_f32_16x16x32_bf16 v[88:91], v[16:19], v[56:59], v[88:91]
	v_mfma_f32_16x16x32_bf16 v[106:109], v[16:19], v[64:67], v[92:95]
	v_mfma_f32_16x16x32_bf16 v[92:95], v[20:23], v[36:39], 0
	v_mfma_f32_16x16x32_bf16 v[36:39], v[28:31], v[36:39], 0
	v_mfma_f32_16x16x32_bf16 v[118:121], v[24:27], v[40:43], v[92:95]
	v_mfma_f32_16x16x32_bf16 v[36:39], v[32:35], v[40:43], v[36:39]
	v_mfma_f32_16x16x32_bf16 v[40:43], v[20:23], v[44:47], 0
	v_mfma_f32_16x16x32_bf16 v[44:47], v[28:31], v[44:47], 0
	v_mfma_f32_16x16x32_bf16 v[40:43], v[24:27], v[48:51], v[40:43]
	v_mfma_f32_16x16x32_bf16 v[44:47], v[32:35], v[48:51], v[44:47]
	v_mfma_f32_16x16x32_bf16 v[48:51], v[20:23], v[52:55], 0
	v_mfma_f32_16x16x32_bf16 v[52:55], v[28:31], v[52:55], 0
	v_mfma_f32_16x16x32_bf16 v[48:51], v[24:27], v[56:59], v[48:51]
	v_mfma_f32_16x16x32_bf16 v[52:55], v[32:35], v[56:59], v[52:55]
	v_mfma_f32_16x16x32_bf16 v[56:59], v[20:23], v[60:63], 0
	v_mfma_f32_16x16x32_bf16 v[60:63], v[28:31], v[60:63], 0
	v_mfma_f32_16x16x32_bf16 v[56:59], v[24:27], v[64:67], v[56:59]
	v_mfma_f32_16x16x32_bf16 v[60:63], v[32:35], v[64:67], v[60:63]
	s_barrier
	s_setprio 0
	ds_read_b128 v[64:67], v149 offset:16384
	ds_read_b128 v[92:95], v149 offset:17408
	ds_read_b128 v[96:99], v149 offset:18432
	ds_read_b128 v[110:113], v149 offset:19456
	ds_read_b128 v[114:117], v149 offset:20480
	ds_read_b128 v[122:125], v149 offset:21504
	ds_read_b128 v[126:129], v149 offset:22528
	ds_read_b128 v[130:133], v149 offset:23552
	s_mov_b32 m0, s52
	s_nop 0
	global_load_lds_dwordx4 v142, s[30:31] offset:0
	s_nop 0
	s_mov_b32 m0, s53
	s_nop 0
	global_load_lds_dwordx4 v144, s[30:31] offset:0
	s_add_u32 s30, s38, 0x160100
	s_addc_u32 s31, s39, 0
	s_mov_b32 m0, s54
	s_nop 0
	global_load_lds_dwordx4 v142, s[30:31] offset:0
	s_nop 0
	s_mov_b32 m0, s55
	s_nop 0
	global_load_lds_dwordx4 v144, s[30:31] offset:0
	s_nop 0
	s_mov_b32 m0, s47
	s_nop 0
	global_load_lds_dwordx4 v1, s[44:45] offset:0
	s_nop 0
	s_mov_b32 m0, s56
	s_nop 0
	global_load_lds_dwordx4 v143, s[44:45] offset:0
	s_waitcnt vmcnt(24)
	s_waitcnt lgkmcnt(0)
	s_barrier
	s_setprio 1
	v_mfma_f32_16x16x32_bf16 v[138:141], v[4:7], v[64:67], 0
	v_mfma_f32_16x16x32_bf16 v[156:159], v[4:7], v[96:99], 0
	v_mfma_f32_16x16x32_bf16 v[164:167], v[4:7], v[114:117], 0
	v_mfma_f32_16x16x32_bf16 v[4:7], v[4:7], v[126:129], 0
	v_mfma_f32_16x16x32_bf16 v[138:141], v[8:11], v[92:95], v[138:141]
	v_mfma_f32_16x16x32_bf16 v[156:159], v[8:11], v[110:113], v[156:159]
	v_mfma_f32_16x16x32_bf16 v[164:167], v[8:11], v[122:125], v[164:167]
	v_mfma_f32_16x16x32_bf16 v[4:7], v[8:11], v[130:133], v[4:7]
	v_mfma_f32_16x16x32_bf16 v[8:11], v[12:15], v[126:129], 0
	v_mfma_f32_16x16x32_bf16 v[152:155], v[12:15], v[64:67], 0
	v_mfma_f32_16x16x32_bf16 v[160:163], v[12:15], v[96:99], 0
	v_mfma_f32_16x16x32_bf16 v[168:171], v[12:15], v[114:117], 0
	v_mfma_f32_16x16x32_bf16 v[8:11], v[16:19], v[130:133], v[8:11]
	v_mfma_f32_16x16x32_bf16 v[152:155], v[16:19], v[92:95], v[152:155]
	v_mfma_f32_16x16x32_bf16 v[160:163], v[16:19], v[110:113], v[160:163]
	v_mfma_f32_16x16x32_bf16 v[168:171], v[16:19], v[122:125], v[168:171]
	v_mfma_f32_16x16x32_bf16 v[12:15], v[20:23], v[64:67], 0
	v_mfma_f32_16x16x32_bf16 v[172:175], v[24:27], v[92:95], v[12:15]
	v_mfma_f32_16x16x32_bf16 v[12:15], v[28:31], v[64:67], 0
	v_mfma_f32_16x16x32_bf16 v[176:179], v[32:35], v[92:95], v[12:15]
	v_mfma_f32_16x16x32_bf16 v[12:15], v[20:23], v[96:99], 0
	v_mfma_f32_16x16x32_bf16 v[180:183], v[24:27], v[110:113], v[12:15]
	v_mfma_f32_16x16x32_bf16 v[12:15], v[28:31], v[96:99], 0
	v_mfma_f32_16x16x32_bf16 v[184:187], v[32:35], v[110:113], v[12:15]
	v_mfma_f32_16x16x32_bf16 v[12:15], v[20:23], v[114:117], 0
	v_mfma_f32_16x16x32_bf16 v[188:191], v[24:27], v[122:125], v[12:15]
	v_mfma_f32_16x16x32_bf16 v[12:15], v[28:31], v[114:117], 0
	v_mfma_f32_16x16x32_bf16 v[192:195], v[32:35], v[122:125], v[12:15]
	v_mfma_f32_16x16x32_bf16 v[12:15], v[20:23], v[126:129], 0
	v_mfma_f32_16x16x32_bf16 v[196:199], v[24:27], v[130:133], v[12:15]
	v_mfma_f32_16x16x32_bf16 v[12:15], v[28:31], v[126:129], 0
	v_mfma_f32_16x16x32_bf16 v[200:203], v[32:35], v[130:133], v[12:15]
	s_barrier
; #define PG8_KSETUP() const bool last = (t == nt - 2); const char* a1 = cA + (size_t)(t + 1) * kstep; \
;             const char* a2 = last ? nA : cA + (size_t)(t + 2) * kstep; const char* b2 = last ? nB : cB + (size_t)(t + 2) * kstep; const char* a3 = a2 + kstep; const char* b3 = b2 + kstep; \
;             if (last && has_next) S.a_ready(nxt)
; template <class Epi, class Sched, bool ALIGN_EPI = false, bool SP2 = false>
; __device__ __forceinline__ void gemm_phase(PG8_LAS unsigned char* lds, const Gemm g, const Sched& S, const Epi& E) {
;     ...
;         int t0 = 0;
;         if constexpr (SP2 && Epi::NVM == 16) { if (ui > 0) { const int t = 0; PG8_KSETUP(); PG8_KITER_SP2(24, 24); t0 = 2; } }
	s_setprio 0
	s_nop 4
	ds_read_b128 v[12:15], v150
	ds_read_b128 v[16:19], v150 offset:1024
	ds_read_b128 v[22:25], v150 offset:2048
	ds_read_b128 v[26:29], v150 offset:3072
	ds_read_b128 v[204:207], v151
	ds_read_b128 v[208:211], v151 offset:1024
	ds_read_b128 v[212:215], v151 offset:2048
	ds_read_b128 v[216:219], v151 offset:3072
	ds_read_b128 v[30:33], v149 offset:32768
	ds_read_b128 v[64:67], v149 offset:33792
	ds_read_b128 v[220:223], v149 offset:34816
	ds_read_b128 v[224:227], v149 offset:35840
	ds_read_b128 v[228:231], v149 offset:36864
	ds_read_b128 v[232:235], v149 offset:37888
	ds_read_b128 v[236:239], v149 offset:38912
	ds_read_b128 v[240:243], v149 offset:39936
	s_add_u32 s30, s36, 0x160100
	s_addc_u32 s31, s37, 0
	s_mov_b32 m0, s57
	s_nop 0
	global_load_lds_dwordx4 v1, s[30:31] offset:0
	s_nop 0
	s_mov_b32 m0, s58
	s_nop 0
	global_load_lds_dwordx4 v143, s[30:31] offset:0
	s_waitcnt vmcnt(8)
	s_waitcnt lgkmcnt(0)
	s_barrier
	s_setprio 1
	v_mfma_f32_16x16x32_bf16 v[68:71], v[12:15], v[30:33], v[68:71]
	v_mfma_f32_16x16x32_bf16 v[130:133], v[16:19], v[64:67], v[68:71]
	v_mfma_f32_16x16x32_bf16 v[68:71], v[22:25], v[30:33], v[72:75]
	v_mfma_f32_16x16x32_bf16 v[126:129], v[26:29], v[64:67], v[68:71]
	v_mfma_f32_16x16x32_bf16 v[68:71], v[12:15], v[220:223], v[76:79]
	v_mfma_f32_16x16x32_bf16 v[114:117], v[16:19], v[224:227], v[68:71]
	v_mfma_f32_16x16x32_bf16 v[68:71], v[22:25], v[220:223], v[80:83]
	v_mfma_f32_16x16x32_bf16 v[110:113], v[26:29], v[224:227], v[68:71]
	v_mfma_f32_16x16x32_bf16 v[68:71], v[12:15], v[228:231], v[84:87]
	v_mfma_f32_16x16x32_bf16 v[98:101], v[16:19], v[232:235], v[68:71]
	v_mfma_f32_16x16x32_bf16 v[68:71], v[22:25], v[228:231], v[88:91]
	v_mfma_f32_16x16x32_bf16 v[94:97], v[26:29], v[232:235], v[68:71]
	v_mfma_f32_16x16x32_bf16 v[68:71], v[12:15], v[236:239], v[102:105]
	v_mfma_f32_16x16x32_bf16 v[82:85], v[16:19], v[240:243], v[68:71]
	v_mfma_f32_16x16x32_bf16 v[68:71], v[22:25], v[236:239], v[106:109]
	v_mfma_f32_16x16x32_bf16 v[78:81], v[26:29], v[240:243], v[68:71]
	v_mfma_f32_16x16x32_bf16 v[68:71], v[204:207], v[30:33], v[118:121]
	v_mfma_f32_16x16x32_bf16 v[30:33], v[212:215], v[30:33], v[36:39]
	v_mfma_f32_16x16x32_bf16 v[118:121], v[216:219], v[64:67], v[30:33]
	v_mfma_f32_16x16x32_bf16 v[30:33], v[204:207], v[220:223], v[40:43]
	v_mfma_f32_16x16x32_bf16 v[106:109], v[208:211], v[224:227], v[30:33]
	v_mfma_f32_16x16x32_bf16 v[30:33], v[212:215], v[220:223], v[44:47]
	v_mfma_f32_16x16x32_bf16 v[102:105], v[216:219], v[224:227], v[30:33]
	v_mfma_f32_16x16x32_bf16 v[30:33], v[204:207], v[228:231], v[48:51]
	v_mfma_f32_16x16x32_bf16 v[90:93], v[208:211], v[232:235], v[30:33]
	v_mfma_f32_16x16x32_bf16 v[30:33], v[212:215], v[228:231], v[52:55]
	v_mfma_f32_16x16x32_bf16 v[86:89], v[216:219], v[232:235], v[30:33]
	v_mfma_f32_16x16x32_bf16 v[30:33], v[204:207], v[236:239], v[56:59]
	v_mfma_f32_16x16x32_bf16 v[74:77], v[208:211], v[240:243], v[30:33]
	v_mfma_f32_16x16x32_bf16 v[30:33], v[212:215], v[236:239], v[60:63]
	v_mfma_f32_16x16x32_bf16 v[122:125], v[208:211], v[64:67], v[68:71]
	v_mfma_f32_16x16x32_bf16 v[70:73], v[216:219], v[240:243], v[30:33]
	s_barrier
	s_setprio 0
	ds_read_b128 v[38:41], v149 offset:49152
	ds_read_b128 v[42:45], v149 offset:50176
	ds_read_b128 v[220:223], v149 offset:51200
	ds_read_b128 v[224:227], v149 offset:52224
	ds_read_b128 v[228:231], v149 offset:53248
	ds_read_b128 v[232:235], v149 offset:54272
	ds_read_b128 v[236:239], v149 offset:55296
	ds_read_b128 v[240:243], v149 offset:56320
	s_add_u32 s30, s38, 0x180
	s_addc_u32 s31, s39, 0
	s_mov_b32 m0, s66
	s_nop 0
	global_load_lds_dwordx4 v142, s[30:31] offset:0
	s_nop 0
	s_mov_b32 m0, s67
	s_nop 0
	global_load_lds_dwordx4 v144, s[30:31] offset:0
	s_add_u32 s30, s38, 0x160180
	s_addc_u32 s31, s39, 0
	s_mov_b32 m0, s70
	s_nop 0
	global_load_lds_dwordx4 v142, s[30:31] offset:0
	s_nop 0
	s_mov_b32 m0, s71
	s_nop 0
	global_load_lds_dwordx4 v144, s[30:31] offset:0
	s_nop 0
	s_mov_b32 m0, s68
	s_nop 0
	global_load_lds_dwordx4 v1, s[40:41] offset:0
	s_nop 0
	s_mov_b32 m0, s69
	s_nop 0
	global_load_lds_dwordx4 v143, s[40:41] offset:0
	s_waitcnt vmcnt(8)
	s_waitcnt lgkmcnt(0)
	s_barrier
	s_setprio 1
	v_mfma_f32_16x16x32_bf16 v[30:33], v[12:15], v[38:41], v[138:141]
	v_mfma_f32_16x16x32_bf16 v[66:69], v[16:19], v[42:45], v[30:33]
	v_mfma_f32_16x16x32_bf16 v[30:33], v[22:25], v[38:41], v[152:155]
	v_mfma_f32_16x16x32_bf16 v[62:65], v[26:29], v[42:45], v[30:33]
	v_mfma_f32_16x16x32_bf16 v[30:33], v[12:15], v[220:223], v[156:159]
	v_mfma_f32_16x16x32_bf16 v[50:53], v[16:19], v[224:227], v[30:33]
	v_mfma_f32_16x16x32_bf16 v[30:33], v[22:25], v[220:223], v[160:163]
	v_mfma_f32_16x16x32_bf16 v[46:49], v[26:29], v[224:227], v[30:33]
	v_mfma_f32_16x16x32_bf16 v[30:33], v[12:15], v[228:231], v[164:167]
	v_mfma_f32_16x16x32_bf16 v[4:7], v[12:15], v[236:239], v[4:7]
	v_mfma_f32_16x16x32_bf16 v[34:37], v[16:19], v[232:235], v[30:33]
	v_mfma_f32_16x16x32_bf16 v[30:33], v[22:25], v[228:231], v[168:171]
	v_mfma_f32_16x16x32_bf16 v[18:21], v[16:19], v[240:243], v[4:7]
	v_mfma_f32_16x16x32_bf16 v[4:7], v[22:25], v[236:239], v[8:11]
	v_mfma_f32_16x16x32_bf16 v[30:33], v[26:29], v[232:235], v[30:33]
	v_mfma_f32_16x16x32_bf16 v[14:17], v[26:29], v[240:243], v[4:7]
	v_mfma_f32_16x16x32_bf16 v[4:7], v[204:207], v[38:41], v[172:175]
	v_mfma_f32_16x16x32_bf16 v[58:61], v[208:211], v[42:45], v[4:7]
	v_mfma_f32_16x16x32_bf16 v[4:7], v[212:215], v[38:41], v[176:179]
	v_mfma_f32_16x16x32_bf16 v[54:57], v[216:219], v[42:45], v[4:7]
	v_mfma_f32_16x16x32_bf16 v[4:7], v[204:207], v[220:223], v[180:183]
	v_mfma_f32_16x16x32_bf16 v[42:45], v[208:211], v[224:227], v[4:7]
	v_mfma_f32_16x16x32_bf16 v[4:7], v[212:215], v[220:223], v[184:187]
	v_mfma_f32_16x16x32_bf16 v[38:41], v[216:219], v[224:227], v[4:7]
	v_mfma_f32_16x16x32_bf16 v[4:7], v[204:207], v[228:231], v[188:191]
	v_mfma_f32_16x16x32_bf16 v[26:29], v[208:211], v[232:235], v[4:7]
	v_mfma_f32_16x16x32_bf16 v[4:7], v[212:215], v[228:231], v[192:195]
	v_mfma_f32_16x16x32_bf16 v[22:25], v[216:219], v[232:235], v[4:7]
	v_mfma_f32_16x16x32_bf16 v[4:7], v[204:207], v[236:239], v[196:199]
	v_mfma_f32_16x16x32_bf16 v[10:13], v[208:211], v[240:243], v[4:7]
	v_mfma_f32_16x16x32_bf16 v[4:7], v[212:215], v[236:239], v[200:203]
	v_mfma_f32_16x16x32_bf16 v[6:9], v[216:219], v[240:243], v[4:7]
	s_barrier
	s_setprio 0
	s_mov_b32 s40, 2
	s_branch .LBB0_2377

; #define PG8_KSETUP() const bool last = (t == nt - 2); const char* a1 = cA + (size_t)(t + 1) * kstep; \
;             const char* a2 = last ? nA : cA + (size_t)(t + 2) * kstep; const char* b2 = last ? nB : cB + (size_t)(t + 2) * kstep; const char* a3 = a2 + kstep; const char* b3 = b2 + kstep; \
;             if (last && has_next) S.a_ready(nxt)
; template <class Epi, class Sched, bool ALIGN_EPI = false, bool SP2 = false>
; __device__ __forceinline__ void gemm_phase(PG8_LAS unsigned char* lds, const Gemm g, const Sched& S, const Epi& E) {
;     ...
;         int t0 = 0;
;         if constexpr (SP2 && Epi::NVM == 16) { if (ui > 0) { const int t = 0; PG8_KSETUP(); PG8_KITER_SP2(24, 24); t0 = 2; } }
;         if constexpr (SP2 && Epi::NVM == 8) { if (ui > 0) { const int t = 0; PG8_KSETUP(); PG8_KITER_SP2(16, 16); t0 = 2; } }
;         for (int t = t0; t < nt; t += 2) {
;             PG8_KSETUP();
;             if constexpr (SP2) {
;             PG8_KITER_SP2(8, 8);
.LBB0_2378:
	ds_read_b128 v[138:141], v147
	ds_read_b128 v[152:155], v147 offset:1024
	ds_read_b128 v[156:159], v147 offset:2048
	ds_read_b128 v[160:163], v147 offset:3072
	ds_read_b128 v[164:167], v148
	ds_read_b128 v[168:171], v148 offset:1024
	ds_read_b128 v[172:175], v148 offset:2048
	ds_read_b128 v[176:179], v148 offset:3072
	s_cmpk_eq_i32 s82, 0x54
	s_cselect_b32 s44, s8, s85
	s_cselect_b32 s45, s9, s86
	s_cselect_b32 s40, s28, s83
	s_cselect_b32 s41, s29, s84
	s_add_u32 s38, s44, 0x80
	s_addc_u32 s39, s45, 0
	ds_read_b128 v[180:183], v149
	ds_read_b128 v[184:187], v149 offset:1024
	ds_read_b128 v[188:191], v149 offset:2048
	ds_read_b128 v[192:195], v149 offset:3072
	ds_read_b128 v[196:199], v149 offset:4096
	ds_read_b128 v[200:203], v149 offset:5120
	ds_read_b128 v[204:207], v149 offset:6144
	ds_read_b128 v[208:211], v149 offset:7168
	s_mov_b32 m0, s72
	s_nop 0
	global_load_lds_dwordx4 v1, s[36:37] offset:0
	s_nop 0
	s_mov_b32 m0, s73
	s_nop 0
	global_load_lds_dwordx4 v143, s[36:37] offset:0
	s_waitcnt vmcnt(8)
	s_waitcnt lgkmcnt(0)
	s_barrier
	s_setprio 1
	v_mfma_f32_16x16x32_bf16 v[130:133], v[138:141], v[180:183], v[130:133]
	v_mfma_f32_16x16x32_bf16 v[130:133], v[152:155], v[184:187], v[130:133]
	v_mfma_f32_16x16x32_bf16 v[126:129], v[156:159], v[180:183], v[126:129]
	v_mfma_f32_16x16x32_bf16 v[126:129], v[160:163], v[184:187], v[126:129]
	v_mfma_f32_16x16x32_bf16 v[114:117], v[138:141], v[188:191], v[114:117]
	v_mfma_f32_16x16x32_bf16 v[114:117], v[152:155], v[192:195], v[114:117]
	v_mfma_f32_16x16x32_bf16 v[110:113], v[156:159], v[188:191], v[110:113]
	v_mfma_f32_16x16x32_bf16 v[110:113], v[160:163], v[192:195], v[110:113]
	v_mfma_f32_16x16x32_bf16 v[98:101], v[138:141], v[196:199], v[98:101]
	v_mfma_f32_16x16x32_bf16 v[98:101], v[152:155], v[200:203], v[98:101]
	v_mfma_f32_16x16x32_bf16 v[94:97], v[156:159], v[196:199], v[94:97]
	v_mfma_f32_16x16x32_bf16 v[94:97], v[160:163], v[200:203], v[94:97]
	v_mfma_f32_16x16x32_bf16 v[82:85], v[138:141], v[204:207], v[82:85]
	v_mfma_f32_16x16x32_bf16 v[82:85], v[152:155], v[208:211], v[82:85]
	v_mfma_f32_16x16x32_bf16 v[78:81], v[156:159], v[204:207], v[78:81]
	v_mfma_f32_16x16x32_bf16 v[78:81], v[160:163], v[208:211], v[78:81]
	v_mfma_f32_16x16x32_bf16 v[122:125], v[164:167], v[180:183], v[122:125]
	v_mfma_f32_16x16x32_bf16 v[122:125], v[168:171], v[184:187], v[122:125]
	v_mfma_f32_16x16x32_bf16 v[118:121], v[172:175], v[180:183], v[118:121]
	v_mfma_f32_16x16x32_bf16 v[118:121], v[176:179], v[184:187], v[118:121]
	v_mfma_f32_16x16x32_bf16 v[106:109], v[164:167], v[188:191], v[106:109]
	v_mfma_f32_16x16x32_bf16 v[106:109], v[168:171], v[192:195], v[106:109]
	v_mfma_f32_16x16x32_bf16 v[102:105], v[172:175], v[188:191], v[102:105]
	v_mfma_f32_16x16x32_bf16 v[102:105], v[176:179], v[192:195], v[102:105]
	v_mfma_f32_16x16x32_bf16 v[90:93], v[164:167], v[196:199], v[90:93]
	v_mfma_f32_16x16x32_bf16 v[90:93], v[168:171], v[200:203], v[90:93]
	v_mfma_f32_16x16x32_bf16 v[86:89], v[172:175], v[196:199], v[86:89]
	v_mfma_f32_16x16x32_bf16 v[86:89], v[176:179], v[200:203], v[86:89]
	v_mfma_f32_16x16x32_bf16 v[74:77], v[164:167], v[204:207], v[74:77]
	v_mfma_f32_16x16x32_bf16 v[74:77], v[168:171], v[208:211], v[74:77]
	v_mfma_f32_16x16x32_bf16 v[70:73], v[172:175], v[204:207], v[70:73]
	v_mfma_f32_16x16x32_bf16 v[70:73], v[176:179], v[208:211], v[70:73]
	s_barrier
	s_setprio 0
	ds_read_b128 v[180:183], v149 offset:16384
	ds_read_b128 v[184:187], v149 offset:17408
	ds_read_b128 v[188:191], v149 offset:18432
	ds_read_b128 v[192:195], v149 offset:19456
	ds_read_b128 v[196:199], v149 offset:20480
	ds_read_b128 v[200:203], v149 offset:21504
	ds_read_b128 v[204:207], v149 offset:22528
	ds_read_b128 v[208:211], v149 offset:23552
	s_mov_b32 m0, s52
	s_nop 0
	global_load_lds_dwordx4 v142, s[40:41] offset:0
	s_add_u32 s30, s40, 0x160000
	s_mov_b32 m0, s53
	s_nop 0
	global_load_lds_dwordx4 v144, s[40:41] offset:0
	s_addc_u32 s31, s41, 0
	s_mov_b32 m0, s54
	s_nop 0
	global_load_lds_dwordx4 v142, s[30:31] offset:0
	s_nop 0
	s_mov_b32 m0, s55
	s_nop 0
	global_load_lds_dwordx4 v144, s[30:31] offset:0
	s_nop 0
	s_mov_b32 m0, s47
	s_nop 0
	global_load_lds_dwordx4 v1, s[44:45] offset:0
	s_nop 0
	s_mov_b32 m0, s56
	s_nop 0
	global_load_lds_dwordx4 v143, s[44:45] offset:0
	s_waitcnt vmcnt(8)
	s_waitcnt lgkmcnt(0)
	s_barrier
	s_setprio 1
	v_mfma_f32_16x16x32_bf16 v[66:69], v[138:141], v[180:183], v[66:69]
	v_mfma_f32_16x16x32_bf16 v[66:69], v[152:155], v[184:187], v[66:69]
	v_mfma_f32_16x16x32_bf16 v[62:65], v[156:159], v[180:183], v[62:65]
	v_mfma_f32_16x16x32_bf16 v[62:65], v[160:163], v[184:187], v[62:65]
	v_mfma_f32_16x16x32_bf16 v[50:53], v[138:141], v[188:191], v[50:53]
	v_mfma_f32_16x16x32_bf16 v[50:53], v[152:155], v[192:195], v[50:53]
	v_mfma_f32_16x16x32_bf16 v[46:49], v[156:159], v[188:191], v[46:49]
	v_mfma_f32_16x16x32_bf16 v[46:49], v[160:163], v[192:195], v[46:49]
	v_mfma_f32_16x16x32_bf16 v[34:37], v[138:141], v[196:199], v[34:37]
	v_mfma_f32_16x16x32_bf16 v[34:37], v[152:155], v[200:203], v[34:37]
	v_mfma_f32_16x16x32_bf16 v[30:33], v[156:159], v[196:199], v[30:33]
	v_mfma_f32_16x16x32_bf16 v[30:33], v[160:163], v[200:203], v[30:33]
	v_mfma_f32_16x16x32_bf16 v[18:21], v[138:141], v[204:207], v[18:21]
	v_mfma_f32_16x16x32_bf16 v[18:21], v[152:155], v[208:211], v[18:21]
	v_mfma_f32_16x16x32_bf16 v[14:17], v[156:159], v[204:207], v[14:17]
	v_mfma_f32_16x16x32_bf16 v[14:17], v[160:163], v[208:211], v[14:17]
	v_mfma_f32_16x16x32_bf16 v[58:61], v[164:167], v[180:183], v[58:61]
	v_mfma_f32_16x16x32_bf16 v[54:57], v[172:175], v[180:183], v[54:57]
	v_mfma_f32_16x16x32_bf16 v[42:45], v[164:167], v[188:191], v[42:45]
	v_mfma_f32_16x16x32_bf16 v[38:41], v[172:175], v[188:191], v[38:41]
	v_mfma_f32_16x16x32_bf16 v[26:29], v[164:167], v[196:199], v[26:29]
	v_mfma_f32_16x16x32_bf16 v[22:25], v[172:175], v[196:199], v[22:25]
	v_mfma_f32_16x16x32_bf16 v[10:13], v[164:167], v[204:207], v[10:13]
	v_mfma_f32_16x16x32_bf16 v[4:7], v[172:175], v[204:207], v[6:9]
	v_mfma_f32_16x16x32_bf16 v[58:61], v[168:171], v[184:187], v[58:61]
	v_mfma_f32_16x16x32_bf16 v[54:57], v[176:179], v[184:187], v[54:57]
	v_mfma_f32_16x16x32_bf16 v[42:45], v[168:171], v[192:195], v[42:45]
	v_mfma_f32_16x16x32_bf16 v[38:41], v[176:179], v[192:195], v[38:41]
	v_mfma_f32_16x16x32_bf16 v[26:29], v[168:171], v[200:203], v[26:29]
	v_mfma_f32_16x16x32_bf16 v[22:25], v[176:179], v[200:203], v[22:25]
	v_mfma_f32_16x16x32_bf16 v[10:13], v[168:171], v[208:211], v[10:13]
	v_mfma_f32_16x16x32_bf16 v[4:7], v[176:179], v[208:211], v[4:7]
	s_barrier
; #define PG8_KSETUP() const bool last = (t == nt - 2); const char* a1 = cA + (size_t)(t + 1) * kstep; \
;             const char* a2 = last ? nA : cA + (size_t)(t + 2) * kstep; const char* b2 = last ? nB : cB + (size_t)(t + 2) * kstep; const char* a3 = a2 + kstep; const char* b3 = b2 + kstep; \
;             if (last && has_next) S.a_ready(nxt)
; template <class Epi, class Sched, bool ALIGN_EPI = false, bool SP2 = false>
; __device__ __forceinline__ void gemm_phase(PG8_LAS unsigned char* lds, const Gemm g, const Sched& S, const Epi& E) {
;     ...
;         int t0 = 0;
;         if constexpr (SP2 && Epi::NVM == 16) { if (ui > 0) { const int t = 0; PG8_KSETUP(); PG8_KITER_SP2(24, 24); t0 = 2; } }
;         if constexpr (SP2 && Epi::NVM == 8) { if (ui > 0) { const int t = 0; PG8_KSETUP(); PG8_KITER_SP2(16, 16); t0 = 2; } }
;         for (int t = t0; t < nt; t += 2) {
;             PG8_KSETUP();
;             if constexpr (SP2) {
;             PG8_KITER_SP2(8, 8);
	s_setprio 0
	ds_read_b128 v[138:141], v150
	ds_read_b128 v[152:155], v150 offset:1024
	ds_read_b128 v[156:159], v150 offset:2048
	ds_read_b128 v[160:163], v150 offset:3072
	ds_read_b128 v[164:167], v151
	ds_read_b128 v[168:171], v151 offset:1024
	ds_read_b128 v[172:175], v151 offset:2048
	ds_read_b128 v[176:179], v151 offset:3072
	ds_read_b128 v[180:183], v149 offset:32768
	ds_read_b128 v[184:187], v149 offset:33792
	ds_read_b128 v[188:191], v149 offset:34816
	ds_read_b128 v[192:195], v149 offset:35840
	ds_read_b128 v[196:199], v149 offset:36864
	ds_read_b128 v[200:203], v149 offset:37888
	ds_read_b128 v[204:207], v149 offset:38912
	ds_read_b128 v[208:211], v149 offset:39936
	s_add_u32 s30, s44, 0x160000
	s_addc_u32 s31, s45, 0
	s_mov_b32 m0, s57
	s_nop 0
	global_load_lds_dwordx4 v1, s[30:31] offset:0
	s_nop 0
	s_mov_b32 m0, s58
	s_nop 0
	global_load_lds_dwordx4 v143, s[30:31] offset:0
	s_waitcnt vmcnt(8)
	s_waitcnt lgkmcnt(0)
	s_barrier
	s_setprio 1
	v_mfma_f32_16x16x32_bf16 v[130:133], v[138:141], v[180:183], v[130:133]
	v_mfma_f32_16x16x32_bf16 v[130:133], v[152:155], v[184:187], v[130:133]
	v_mfma_f32_16x16x32_bf16 v[126:129], v[156:159], v[180:183], v[126:129]
	v_mfma_f32_16x16x32_bf16 v[126:129], v[160:163], v[184:187], v[126:129]
	v_mfma_f32_16x16x32_bf16 v[114:117], v[138:141], v[188:191], v[114:117]
	v_mfma_f32_16x16x32_bf16 v[114:117], v[152:155], v[192:195], v[114:117]
	v_mfma_f32_16x16x32_bf16 v[110:113], v[156:159], v[188:191], v[110:113]
	v_mfma_f32_16x16x32_bf16 v[110:113], v[160:163], v[192:195], v[110:113]
	v_mfma_f32_16x16x32_bf16 v[98:101], v[138:141], v[196:199], v[98:101]
	v_mfma_f32_16x16x32_bf16 v[98:101], v[152:155], v[200:203], v[98:101]
	v_mfma_f32_16x16x32_bf16 v[94:97], v[156:159], v[196:199], v[94:97]
	v_mfma_f32_16x16x32_bf16 v[94:97], v[160:163], v[200:203], v[94:97]
	v_mfma_f32_16x16x32_bf16 v[82:85], v[138:141], v[204:207], v[82:85]
	v_mfma_f32_16x16x32_bf16 v[82:85], v[152:155], v[208:211], v[82:85]
	v_mfma_f32_16x16x32_bf16 v[78:81], v[156:159], v[204:207], v[78:81]
	v_mfma_f32_16x16x32_bf16 v[78:81], v[160:163], v[208:211], v[78:81]
	v_mfma_f32_16x16x32_bf16 v[122:125], v[164:167], v[180:183], v[122:125]
	v_mfma_f32_16x16x32_bf16 v[122:125], v[168:171], v[184:187], v[122:125]
	v_mfma_f32_16x16x32_bf16 v[118:121], v[172:175], v[180:183], v[118:121]
	v_mfma_f32_16x16x32_bf16 v[118:121], v[176:179], v[184:187], v[118:121]
	v_mfma_f32_16x16x32_bf16 v[106:109], v[164:167], v[188:191], v[106:109]
	v_mfma_f32_16x16x32_bf16 v[106:109], v[168:171], v[192:195], v[106:109]
	v_mfma_f32_16x16x32_bf16 v[102:105], v[172:175], v[188:191], v[102:105]
	v_mfma_f32_16x16x32_bf16 v[102:105], v[176:179], v[192:195], v[102:105]
	v_mfma_f32_16x16x32_bf16 v[90:93], v[164:167], v[196:199], v[90:93]
	v_mfma_f32_16x16x32_bf16 v[90:93], v[168:171], v[200:203], v[90:93]
	v_mfma_f32_16x16x32_bf16 v[86:89], v[172:175], v[196:199], v[86:89]
	v_mfma_f32_16x16x32_bf16 v[86:89], v[176:179], v[200:203], v[86:89]
	v_mfma_f32_16x16x32_bf16 v[74:77], v[164:167], v[204:207], v[74:77]
	v_mfma_f32_16x16x32_bf16 v[74:77], v[168:171], v[208:211], v[74:77]
	v_mfma_f32_16x16x32_bf16 v[70:73], v[172:175], v[204:207], v[70:73]
	v_mfma_f32_16x16x32_bf16 v[70:73], v[176:179], v[208:211], v[70:73]
	s_barrier
	s_setprio 0
	ds_read_b128 v[180:183], v149 offset:49152
	ds_read_b128 v[184:187], v149 offset:50176
	ds_read_b128 v[188:191], v149 offset:51200
	ds_read_b128 v[192:195], v149 offset:52224
	ds_read_b128 v[196:199], v149 offset:53248
	ds_read_b128 v[200:203], v149 offset:54272
	ds_read_b128 v[204:207], v149 offset:55296
	ds_read_b128 v[208:211], v149 offset:56320
	s_add_u32 s30, s40, 0x80
	s_addc_u32 s31, s41, 0
	s_mov_b32 m0, s66
	s_nop 0
	global_load_lds_dwordx4 v142, s[30:31] offset:0
	s_nop 0
	s_mov_b32 m0, s67
	s_nop 0
	global_load_lds_dwordx4 v144, s[30:31] offset:0
	s_add_u32 s30, s40, 0x160080
	s_addc_u32 s31, s41, 0
	s_mov_b32 m0, s70
	s_nop 0
	global_load_lds_dwordx4 v142, s[30:31] offset:0
	s_nop 0
	s_mov_b32 m0, s71
	s_nop 0
	global_load_lds_dwordx4 v144, s[30:31] offset:0
	s_nop 0
	s_mov_b32 m0, s68
	s_nop 0
	global_load_lds_dwordx4 v1, s[38:39] offset:0
	s_nop 0
	s_mov_b32 m0, s69
	s_nop 0
	global_load_lds_dwordx4 v143, s[38:39] offset:0
	s_waitcnt vmcnt(8)
	s_waitcnt lgkmcnt(0)
	s_barrier
	s_setprio 1
	v_mfma_f32_16x16x32_bf16 v[66:69], v[138:141], v[180:183], v[66:69]
	v_mfma_f32_16x16x32_bf16 v[66:69], v[152:155], v[184:187], v[66:69]
	v_mfma_f32_16x16x32_bf16 v[62:65], v[156:159], v[180:183], v[62:65]
	v_mfma_f32_16x16x32_bf16 v[62:65], v[160:163], v[184:187], v[62:65]
	v_mfma_f32_16x16x32_bf16 v[50:53], v[138:141], v[188:191], v[50:53]
	v_mfma_f32_16x16x32_bf16 v[50:53], v[152:155], v[192:195], v[50:53]
	v_mfma_f32_16x16x32_bf16 v[46:49], v[156:159], v[188:191], v[46:49]
	v_mfma_f32_16x16x32_bf16 v[46:49], v[160:163], v[192:195], v[46:49]
	v_mfma_f32_16x16x32_bf16 v[34:37], v[138:141], v[196:199], v[34:37]
	v_mfma_f32_16x16x32_bf16 v[34:37], v[152:155], v[200:203], v[34:37]
	v_mfma_f32_16x16x32_bf16 v[30:33], v[156:159], v[196:199], v[30:33]
	v_mfma_f32_16x16x32_bf16 v[30:33], v[160:163], v[200:203], v[30:33]
	v_mfma_f32_16x16x32_bf16 v[18:21], v[138:141], v[204:207], v[18:21]
	v_mfma_f32_16x16x32_bf16 v[18:21], v[152:155], v[208:211], v[18:21]
	v_mfma_f32_16x16x32_bf16 v[14:17], v[156:159], v[204:207], v[14:17]
	v_mfma_f32_16x16x32_bf16 v[14:17], v[160:163], v[208:211], v[14:17]
	v_mfma_f32_16x16x32_bf16 v[58:61], v[164:167], v[180:183], v[58:61]
	v_mfma_f32_16x16x32_bf16 v[54:57], v[172:175], v[180:183], v[54:57]
	v_mfma_f32_16x16x32_bf16 v[42:45], v[164:167], v[188:191], v[42:45]
	v_mfma_f32_16x16x32_bf16 v[38:41], v[172:175], v[188:191], v[38:41]
	v_mfma_f32_16x16x32_bf16 v[26:29], v[164:167], v[196:199], v[26:29]
	v_mfma_f32_16x16x32_bf16 v[22:25], v[172:175], v[196:199], v[22:25]
	v_mfma_f32_16x16x32_bf16 v[8:11], v[164:167], v[204:207], v[10:13]
	v_mfma_f32_16x16x32_bf16 v[4:7], v[172:175], v[204:207], v[4:7]
	v_mfma_f32_16x16x32_bf16 v[58:61], v[168:171], v[184:187], v[58:61]
	v_mfma_f32_16x16x32_bf16 v[54:57], v[176:179], v[184:187], v[54:57]
	v_mfma_f32_16x16x32_bf16 v[42:45], v[168:171], v[192:195], v[42:45]
	v_mfma_f32_16x16x32_bf16 v[38:41], v[176:179], v[192:195], v[38:41]
	v_mfma_f32_16x16x32_bf16 v[26:29], v[168:171], v[200:203], v[26:29]
	v_mfma_f32_16x16x32_bf16 v[22:25], v[176:179], v[200:203], v[22:25]
	v_mfma_f32_16x16x32_bf16 v[10:13], v[168:171], v[208:211], v[8:11]
	v_mfma_f32_16x16x32_bf16 v[6:9], v[176:179], v[208:211], v[4:7]
	s_barrier
	s_setprio 0
	s_add_i32 s82, s82, 2
	s_add_u32 s83, s83, 0x100
	s_addc_u32 s84, s84, 0
	s_add_u32 s85, s85, 0x100
	s_addc_u32 s86, s86, 0
	s_add_u32 s36, s36, 0x100
	s_addc_u32 s37, s37, 0
	s_cmpk_gt_u32 s82, 0x55
	s_cbranch_scc0 .LBB0_2378
	s_and_b64 vcc, exec, s[16:17]
	s_cbranch_vccz .LBB0_2381
	s_barrier

; #define PG8_KSETUP() const bool last = (t == nt - 2); const char* a1 = cA + (size_t)(t + 1) * kstep; \
;             const char* a2 = last ? nA : cA + (size_t)(t + 2) * kstep; const char* b2 = last ? nB : cB + (size_t)(t + 2) * kstep; const char* a3 = a2 + kstep; const char* b3 = b2 + kstep; \
;             if (last && has_next) S.a_ready(nxt)
; template <class Epi, class Sched, bool ALIGN_EPI = false, bool SP2 = false>
; __device__ __forceinline__ void gemm_phase(PG8_LAS unsigned char* lds, const Gemm g, const Sched& S, const Epi& E) {
;     ...
;         int t0 = 0;
;         if constexpr (SP2 && Epi::NVM == 16) { if (ui > 0) { const int t = 0; PG8_KSETUP(); PG8_KITER_SP2(24, 24); t0 = 2; } }
;         if constexpr (SP2 && Epi::NVM == 8) { if (ui > 0) { const int t = 0; PG8_KSETUP(); PG8_KITER_SP2(16, 16); t0 = 2; } }
;         for (int t = t0; t < nt; t += 2) {
;             PG8_KSETUP();
;             if constexpr (SP2) {
;             PG8_KITER_SP2(8, 8);
.LBB0_2536:
	ds_read_b128 v[160:163], v155
	ds_read_b128 v[168:171], v155 offset:1024
	ds_read_b128 v[172:175], v155 offset:2048
	ds_read_b128 v[176:179], v155 offset:3072
	ds_read_b128 v[180:183], v159
	ds_read_b128 v[184:187], v159 offset:1024
	ds_read_b128 v[188:191], v159 offset:2048
	ds_read_b128 v[192:195], v159 offset:3072
	s_cmp_eq_u32 s91, 28
	s_cselect_b32 s56, s45, s89
	s_cselect_b32 s57, s37, s90
	s_cselect_b32 s54, s86, s87
	s_cselect_b32 s55, s29, s88
	s_add_u32 s46, s56, 0x80
	s_addc_u32 s47, s57, 0
	ds_read_b128 v[196:199], v164
	ds_read_b128 v[200:203], v164 offset:1024
	ds_read_b128 v[204:207], v164 offset:2048
	ds_read_b128 v[208:211], v164 offset:3072
	ds_read_b128 v[212:215], v164 offset:4096
	ds_read_b128 v[216:219], v164 offset:5120
	ds_read_b128 v[220:223], v164 offset:6144
	ds_read_b128 v[224:227], v164 offset:7168
	s_add_u32 s30, s89, 0x7ff80
	s_addc_u32 s31, s90, 0
	s_mov_b32 m0, s78
	s_nop 0
	global_load_lds_dwordx4 v1, s[30:31] offset:0
	s_nop 0
	s_mov_b32 m0, s79
	s_nop 0
	global_load_lds_dwordx4 v139, s[30:31] offset:0
	s_waitcnt vmcnt(8)
	s_waitcnt lgkmcnt(0)
	s_barrier
	s_setprio 1
	v_mfma_f32_16x16x32_bf16 v[126:129], v[160:163], v[196:199], v[126:129]
	v_mfma_f32_16x16x32_bf16 v[126:129], v[168:171], v[200:203], v[126:129]
	v_mfma_f32_16x16x32_bf16 v[122:125], v[172:175], v[196:199], v[122:125]
	v_mfma_f32_16x16x32_bf16 v[122:125], v[176:179], v[200:203], v[122:125]
	v_mfma_f32_16x16x32_bf16 v[114:117], v[160:163], v[204:207], v[114:117]
	v_mfma_f32_16x16x32_bf16 v[114:117], v[168:171], v[208:211], v[114:117]
	v_mfma_f32_16x16x32_bf16 v[106:109], v[172:175], v[204:207], v[106:109]
	v_mfma_f32_16x16x32_bf16 v[106:109], v[176:179], v[208:211], v[106:109]
	v_mfma_f32_16x16x32_bf16 v[98:101], v[160:163], v[212:215], v[98:101]
	v_mfma_f32_16x16x32_bf16 v[98:101], v[168:171], v[216:219], v[98:101]
	v_mfma_f32_16x16x32_bf16 v[90:93], v[172:175], v[212:215], v[90:93]
	v_mfma_f32_16x16x32_bf16 v[90:93], v[176:179], v[216:219], v[90:93]
	v_mfma_f32_16x16x32_bf16 v[82:85], v[160:163], v[220:223], v[82:85]
	v_mfma_f32_16x16x32_bf16 v[82:85], v[168:171], v[224:227], v[82:85]
	v_mfma_f32_16x16x32_bf16 v[74:77], v[172:175], v[220:223], v[74:77]
	v_mfma_f32_16x16x32_bf16 v[74:77], v[176:179], v[224:227], v[74:77]
	v_mfma_f32_16x16x32_bf16 v[118:121], v[180:183], v[196:199], v[118:121]
	v_mfma_f32_16x16x32_bf16 v[118:121], v[184:187], v[200:203], v[118:121]
	v_mfma_f32_16x16x32_bf16 v[110:113], v[188:191], v[196:199], v[110:113]
	v_mfma_f32_16x16x32_bf16 v[110:113], v[192:195], v[200:203], v[110:113]
	v_mfma_f32_16x16x32_bf16 v[102:105], v[180:183], v[204:207], v[102:105]
	v_mfma_f32_16x16x32_bf16 v[102:105], v[184:187], v[208:211], v[102:105]
	v_mfma_f32_16x16x32_bf16 v[94:97], v[188:191], v[204:207], v[94:97]
	v_mfma_f32_16x16x32_bf16 v[94:97], v[192:195], v[208:211], v[94:97]
	v_mfma_f32_16x16x32_bf16 v[86:89], v[180:183], v[212:215], v[86:89]
	v_mfma_f32_16x16x32_bf16 v[86:89], v[184:187], v[216:219], v[86:89]
	v_mfma_f32_16x16x32_bf16 v[78:81], v[188:191], v[212:215], v[78:81]
	v_mfma_f32_16x16x32_bf16 v[78:81], v[192:195], v[216:219], v[78:81]
	v_mfma_f32_16x16x32_bf16 v[70:73], v[180:183], v[220:223], v[70:73]
	v_mfma_f32_16x16x32_bf16 v[70:73], v[184:187], v[224:227], v[70:73]
	v_mfma_f32_16x16x32_bf16 v[66:69], v[188:191], v[220:223], v[66:69]
	v_mfma_f32_16x16x32_bf16 v[66:69], v[192:195], v[224:227], v[66:69]
	s_barrier
	s_setprio 0
	ds_read_b128 v[196:199], v164 offset:16384
	ds_read_b128 v[200:203], v164 offset:17408
	ds_read_b128 v[204:207], v164 offset:18432
	ds_read_b128 v[208:211], v164 offset:19456
	ds_read_b128 v[212:215], v164 offset:20480
	ds_read_b128 v[216:219], v164 offset:21504
	ds_read_b128 v[220:223], v164 offset:22528
	ds_read_b128 v[224:227], v164 offset:23552
	s_mov_b32 m0, s64
	s_nop 0
	global_load_lds_dwordx4 v137, s[54:55] offset:0
	s_add_u32 s30, s54, 0x80000
	s_mov_b32 m0, s65
	s_nop 0
	global_load_lds_dwordx4 v141, s[54:55] offset:0
	s_addc_u32 s31, s55, 0
	s_mov_b32 m0, s66
	s_nop 0
	global_load_lds_dwordx4 v137, s[30:31] offset:0
	s_nop 0
	s_mov_b32 m0, s67
	s_nop 0
	global_load_lds_dwordx4 v141, s[30:31] offset:0
	s_nop 0
	s_mov_b32 m0, s53
	s_nop 0
	global_load_lds_dwordx4 v1, s[56:57] offset:0
	s_nop 0
	s_mov_b32 m0, s68
	s_nop 0
	global_load_lds_dwordx4 v139, s[56:57] offset:0
	s_waitcnt vmcnt(8)
	s_waitcnt lgkmcnt(0)
	s_barrier
	s_setprio 1
	v_mfma_f32_16x16x32_bf16 v[62:65], v[160:163], v[196:199], v[62:65]
	v_mfma_f32_16x16x32_bf16 v[62:65], v[168:171], v[200:203], v[62:65]
	v_mfma_f32_16x16x32_bf16 v[58:61], v[172:175], v[196:199], v[58:61]
	v_mfma_f32_16x16x32_bf16 v[58:61], v[176:179], v[200:203], v[58:61]
	v_mfma_f32_16x16x32_bf16 v[50:53], v[160:163], v[204:207], v[50:53]
	v_mfma_f32_16x16x32_bf16 v[50:53], v[168:171], v[208:211], v[50:53]
	v_mfma_f32_16x16x32_bf16 v[42:45], v[172:175], v[204:207], v[42:45]
	v_mfma_f32_16x16x32_bf16 v[42:45], v[176:179], v[208:211], v[42:45]
	v_mfma_f32_16x16x32_bf16 v[34:37], v[160:163], v[212:215], v[34:37]
	v_mfma_f32_16x16x32_bf16 v[34:37], v[168:171], v[216:219], v[34:37]
	v_mfma_f32_16x16x32_bf16 v[26:29], v[172:175], v[212:215], v[26:29]
	v_mfma_f32_16x16x32_bf16 v[26:29], v[176:179], v[216:219], v[26:29]
	v_mfma_f32_16x16x32_bf16 v[18:21], v[160:163], v[220:223], v[18:21]
	v_mfma_f32_16x16x32_bf16 v[18:21], v[168:171], v[224:227], v[18:21]
	v_mfma_f32_16x16x32_bf16 v[10:13], v[172:175], v[220:223], v[10:13]
	v_mfma_f32_16x16x32_bf16 v[10:13], v[176:179], v[224:227], v[10:13]
	v_mfma_f32_16x16x32_bf16 v[54:57], v[180:183], v[196:199], v[54:57]
	v_mfma_f32_16x16x32_bf16 v[54:57], v[184:187], v[200:203], v[54:57]
	v_mfma_f32_16x16x32_bf16 v[46:49], v[188:191], v[196:199], v[46:49]
	v_mfma_f32_16x16x32_bf16 v[46:49], v[192:195], v[200:203], v[46:49]
	v_mfma_f32_16x16x32_bf16 v[38:41], v[180:183], v[204:207], v[38:41]
	v_mfma_f32_16x16x32_bf16 v[38:41], v[184:187], v[208:211], v[38:41]
	v_mfma_f32_16x16x32_bf16 v[30:33], v[188:191], v[204:207], v[30:33]
	v_mfma_f32_16x16x32_bf16 v[30:33], v[192:195], v[208:211], v[30:33]
	v_mfma_f32_16x16x32_bf16 v[22:25], v[180:183], v[212:215], v[22:25]
	v_mfma_f32_16x16x32_bf16 v[22:25], v[184:187], v[216:219], v[22:25]
	v_mfma_f32_16x16x32_bf16 v[14:17], v[188:191], v[212:215], v[14:17]
	v_mfma_f32_16x16x32_bf16 v[14:17], v[192:195], v[216:219], v[14:17]
	v_mfma_f32_16x16x32_bf16 v[6:9], v[180:183], v[220:223], v[6:9]
	v_mfma_f32_16x16x32_bf16 v[6:9], v[184:187], v[224:227], v[6:9]
	v_mfma_f32_16x16x32_bf16 v[2:5], v[188:191], v[220:223], v[2:5]
	v_mfma_f32_16x16x32_bf16 v[2:5], v[192:195], v[224:227], v[2:5]
	s_barrier
; #define PG8_KSETUP() const bool last = (t == nt - 2); const char* a1 = cA + (size_t)(t + 1) * kstep; \
;             const char* a2 = last ? nA : cA + (size_t)(t + 2) * kstep; const char* b2 = last ? nB : cB + (size_t)(t + 2) * kstep; const char* a3 = a2 + kstep; const char* b3 = b2 + kstep; \
;             if (last && has_next) S.a_ready(nxt)
; template <class Epi, class Sched, bool ALIGN_EPI = false, bool SP2 = false>
; __device__ __forceinline__ void gemm_phase(PG8_LAS unsigned char* lds, const Gemm g, const Sched& S, const Epi& E) {
;     ...
;         int t0 = 0;
;         if constexpr (SP2 && Epi::NVM == 16) { if (ui > 0) { const int t = 0; PG8_KSETUP(); PG8_KITER_SP2(24, 24); t0 = 2; } }
;         if constexpr (SP2 && Epi::NVM == 8) { if (ui > 0) { const int t = 0; PG8_KSETUP(); PG8_KITER_SP2(16, 16); t0 = 2; } }
;         for (int t = t0; t < nt; t += 2) {
;             PG8_KSETUP();
;             if constexpr (SP2) {
;             PG8_KITER_SP2(8, 8);
	s_setprio 0
	ds_read_b128 v[160:163], v165
	ds_read_b128 v[168:171], v165 offset:1024
	ds_read_b128 v[172:175], v165 offset:2048
	ds_read_b128 v[176:179], v165 offset:3072
	ds_read_b128 v[180:183], v166
	ds_read_b128 v[184:187], v166 offset:1024
	ds_read_b128 v[188:191], v166 offset:2048
	ds_read_b128 v[192:195], v166 offset:3072
	ds_read_b128 v[196:199], v164 offset:32768
	ds_read_b128 v[200:203], v164 offset:33792
	ds_read_b128 v[204:207], v164 offset:34816
	ds_read_b128 v[208:211], v164 offset:35840
	ds_read_b128 v[212:215], v164 offset:36864
	ds_read_b128 v[216:219], v164 offset:37888
	ds_read_b128 v[220:223], v164 offset:38912
	ds_read_b128 v[224:227], v164 offset:39936
	s_add_u32 s30, s56, 0x80000
	s_addc_u32 s31, s57, 0
	s_mov_b32 m0, s69
	s_nop 0
	global_load_lds_dwordx4 v1, s[30:31] offset:0
	s_nop 0
	s_mov_b32 m0, s70
	s_nop 0
	global_load_lds_dwordx4 v139, s[30:31] offset:0
	s_waitcnt vmcnt(8)
	s_waitcnt lgkmcnt(0)
	s_barrier
	s_setprio 1
	v_mfma_f32_16x16x32_bf16 v[126:129], v[160:163], v[196:199], v[126:129]
	v_mfma_f32_16x16x32_bf16 v[126:129], v[168:171], v[200:203], v[126:129]
	v_mfma_f32_16x16x32_bf16 v[122:125], v[172:175], v[196:199], v[122:125]
	v_mfma_f32_16x16x32_bf16 v[122:125], v[176:179], v[200:203], v[122:125]
	v_mfma_f32_16x16x32_bf16 v[114:117], v[160:163], v[204:207], v[114:117]
	v_mfma_f32_16x16x32_bf16 v[114:117], v[168:171], v[208:211], v[114:117]
	v_mfma_f32_16x16x32_bf16 v[106:109], v[172:175], v[204:207], v[106:109]
	v_mfma_f32_16x16x32_bf16 v[106:109], v[176:179], v[208:211], v[106:109]
	v_mfma_f32_16x16x32_bf16 v[98:101], v[160:163], v[212:215], v[98:101]
	v_mfma_f32_16x16x32_bf16 v[98:101], v[168:171], v[216:219], v[98:101]
	v_mfma_f32_16x16x32_bf16 v[90:93], v[172:175], v[212:215], v[90:93]
	v_mfma_f32_16x16x32_bf16 v[90:93], v[176:179], v[216:219], v[90:93]
	v_mfma_f32_16x16x32_bf16 v[82:85], v[160:163], v[220:223], v[82:85]
	v_mfma_f32_16x16x32_bf16 v[82:85], v[168:171], v[224:227], v[82:85]
	v_mfma_f32_16x16x32_bf16 v[74:77], v[172:175], v[220:223], v[74:77]
	v_mfma_f32_16x16x32_bf16 v[74:77], v[176:179], v[224:227], v[74:77]
	v_mfma_f32_16x16x32_bf16 v[118:121], v[180:183], v[196:199], v[118:121]
	v_mfma_f32_16x16x32_bf16 v[118:121], v[184:187], v[200:203], v[118:121]
	v_mfma_f32_16x16x32_bf16 v[110:113], v[188:191], v[196:199], v[110:113]
	v_mfma_f32_16x16x32_bf16 v[110:113], v[192:195], v[200:203], v[110:113]
	v_mfma_f32_16x16x32_bf16 v[102:105], v[180:183], v[204:207], v[102:105]
	v_mfma_f32_16x16x32_bf16 v[102:105], v[184:187], v[208:211], v[102:105]
	v_mfma_f32_16x16x32_bf16 v[94:97], v[188:191], v[204:207], v[94:97]
	v_mfma_f32_16x16x32_bf16 v[94:97], v[192:195], v[208:211], v[94:97]
	v_mfma_f32_16x16x32_bf16 v[86:89], v[180:183], v[212:215], v[86:89]
	v_mfma_f32_16x16x32_bf16 v[86:89], v[184:187], v[216:219], v[86:89]
	v_mfma_f32_16x16x32_bf16 v[78:81], v[188:191], v[212:215], v[78:81]
	v_mfma_f32_16x16x32_bf16 v[78:81], v[192:195], v[216:219], v[78:81]
	v_mfma_f32_16x16x32_bf16 v[70:73], v[180:183], v[220:223], v[70:73]
	v_mfma_f32_16x16x32_bf16 v[70:73], v[184:187], v[224:227], v[70:73]
	v_mfma_f32_16x16x32_bf16 v[66:69], v[188:191], v[220:223], v[66:69]
	v_mfma_f32_16x16x32_bf16 v[66:69], v[192:195], v[224:227], v[66:69]
	s_barrier
	s_setprio 0
	ds_read_b128 v[196:199], v164 offset:49152
	ds_read_b128 v[200:203], v164 offset:50176
	ds_read_b128 v[204:207], v164 offset:51200
	ds_read_b128 v[208:211], v164 offset:52224
	ds_read_b128 v[212:215], v164 offset:53248
	ds_read_b128 v[216:219], v164 offset:54272
	ds_read_b128 v[220:223], v164 offset:55296
	ds_read_b128 v[224:227], v164 offset:56320
	s_add_u32 s30, s54, 0x80
	s_addc_u32 s31, s55, 0
	s_mov_b32 m0, s72
	s_nop 0
	global_load_lds_dwordx4 v137, s[30:31] offset:0
	s_nop 0
	s_mov_b32 m0, s73
	s_nop 0
	global_load_lds_dwordx4 v141, s[30:31] offset:0
	s_add_u32 s30, s54, 0x80080
	s_addc_u32 s31, s55, 0
	s_mov_b32 m0, s76
	s_nop 0
	global_load_lds_dwordx4 v137, s[30:31] offset:0
	s_nop 0
	s_mov_b32 m0, s77
	s_nop 0
	global_load_lds_dwordx4 v141, s[30:31] offset:0
	s_nop 0
	s_mov_b32 m0, s74
	s_nop 0
	global_load_lds_dwordx4 v1, s[46:47] offset:0
	s_nop 0
	s_mov_b32 m0, s75
	s_nop 0
	global_load_lds_dwordx4 v139, s[46:47] offset:0
	s_waitcnt vmcnt(8)
	s_waitcnt lgkmcnt(0)
	s_barrier
	s_setprio 1
	v_mfma_f32_16x16x32_bf16 v[62:65], v[160:163], v[196:199], v[62:65]
	v_mfma_f32_16x16x32_bf16 v[62:65], v[168:171], v[200:203], v[62:65]
	v_mfma_f32_16x16x32_bf16 v[58:61], v[172:175], v[196:199], v[58:61]
	v_mfma_f32_16x16x32_bf16 v[58:61], v[176:179], v[200:203], v[58:61]
	v_mfma_f32_16x16x32_bf16 v[50:53], v[160:163], v[204:207], v[50:53]
	v_mfma_f32_16x16x32_bf16 v[50:53], v[168:171], v[208:211], v[50:53]
	v_mfma_f32_16x16x32_bf16 v[42:45], v[172:175], v[204:207], v[42:45]
	v_mfma_f32_16x16x32_bf16 v[42:45], v[176:179], v[208:211], v[42:45]
	v_mfma_f32_16x16x32_bf16 v[34:37], v[160:163], v[212:215], v[34:37]
	v_mfma_f32_16x16x32_bf16 v[34:37], v[168:171], v[216:219], v[34:37]
	v_mfma_f32_16x16x32_bf16 v[26:29], v[172:175], v[212:215], v[26:29]
	v_mfma_f32_16x16x32_bf16 v[26:29], v[176:179], v[216:219], v[26:29]
	v_mfma_f32_16x16x32_bf16 v[18:21], v[160:163], v[220:223], v[18:21]
	v_mfma_f32_16x16x32_bf16 v[18:21], v[168:171], v[224:227], v[18:21]
	v_mfma_f32_16x16x32_bf16 v[10:13], v[172:175], v[220:223], v[10:13]
	v_mfma_f32_16x16x32_bf16 v[10:13], v[176:179], v[224:227], v[10:13]
	v_mfma_f32_16x16x32_bf16 v[54:57], v[180:183], v[196:199], v[54:57]
	v_mfma_f32_16x16x32_bf16 v[54:57], v[184:187], v[200:203], v[54:57]
	v_mfma_f32_16x16x32_bf16 v[46:49], v[188:191], v[196:199], v[46:49]
	v_mfma_f32_16x16x32_bf16 v[46:49], v[192:195], v[200:203], v[46:49]
	v_mfma_f32_16x16x32_bf16 v[38:41], v[180:183], v[204:207], v[38:41]
	v_mfma_f32_16x16x32_bf16 v[38:41], v[184:187], v[208:211], v[38:41]
	v_mfma_f32_16x16x32_bf16 v[30:33], v[188:191], v[204:207], v[30:33]
	v_mfma_f32_16x16x32_bf16 v[30:33], v[192:195], v[208:211], v[30:33]
	v_mfma_f32_16x16x32_bf16 v[22:25], v[180:183], v[212:215], v[22:25]
	v_mfma_f32_16x16x32_bf16 v[22:25], v[184:187], v[216:219], v[22:25]
	v_mfma_f32_16x16x32_bf16 v[14:17], v[188:191], v[212:215], v[14:17]
	v_mfma_f32_16x16x32_bf16 v[14:17], v[192:195], v[216:219], v[14:17]
	v_mfma_f32_16x16x32_bf16 v[6:9], v[180:183], v[220:223], v[6:9]
	v_mfma_f32_16x16x32_bf16 v[6:9], v[184:187], v[224:227], v[6:9]
	v_mfma_f32_16x16x32_bf16 v[2:5], v[188:191], v[220:223], v[2:5]
	v_mfma_f32_16x16x32_bf16 v[2:5], v[192:195], v[224:227], v[2:5]
	s_barrier
	s_setprio 0
	s_add_i32 s91, s91, 2
	s_add_u32 s87, s87, 0x100
	s_addc_u32 s88, s88, 0
	s_add_u32 s89, s89, 0x100
	s_addc_u32 s90, s90, 0
	s_cmp_gt_u32 s91, 29
	s_cbranch_scc0 .LBB0_2536
	s_and_b64 vcc, exec, s[18:19]
	s_cbranch_vccz .LBB0_2539
	s_barrier

; #define PG8_KSETUP() const bool last = (t == nt - 2); const char* a1 = cA + (size_t)(t + 1) * kstep; \
;             const char* a2 = last ? nA : cA + (size_t)(t + 2) * kstep; const char* b2 = last ? nB : cB + (size_t)(t + 2) * kstep; const char* a3 = a2 + kstep; const char* b3 = b2 + kstep; \
;             if (last && has_next) S.a_ready(nxt)
; template <class Epi, class Sched, bool ALIGN_EPI = false, bool SP2 = false>
; __device__ __forceinline__ void gemm_phase(PG8_LAS unsigned char* lds, const Gemm g, const Sched& S, const Epi& E) {
;     ...
;         int t0 = 0;
;         if constexpr (SP2 && Epi::NVM == 16) { if (ui > 0) { const int t = 0; PG8_KSETUP(); PG8_KITER_SP2(24, 24); t0 = 2; } }
.LBB0_2710:
	s_cmp_eq_u32 s29, 0
	s_mov_b32 s56, 0
	s_cbranch_scc1 .LBB0_2712
	ds_read_b128 v[4:7], v147
	ds_read_b128 v[8:11], v147 offset:1024
	ds_read_b128 v[12:15], v147 offset:2048
	ds_read_b128 v[16:19], v147 offset:3072
	ds_read_b128 v[20:23], v148
	ds_read_b128 v[24:27], v148 offset:1024
	ds_read_b128 v[28:31], v148 offset:2048
	ds_read_b128 v[32:35], v148 offset:3072
	s_add_u32 s40, s46, 0x100
	s_addc_u32 s41, s47, 0
	s_add_u32 s30, s54, 0x100
	s_addc_u32 s31, s55, 0
	s_add_u32 s38, s46, 0x180
	s_addc_u32 s39, s47, 0
	ds_read_b128 v[36:39], v149
	ds_read_b128 v[40:43], v149 offset:1024
	ds_read_b128 v[44:47], v149 offset:2048
	ds_read_b128 v[48:51], v149 offset:3072
	ds_read_b128 v[52:55], v149 offset:4096
	ds_read_b128 v[56:59], v149 offset:5120
	ds_read_b128 v[60:63], v149 offset:6144
	ds_read_b128 v[64:67], v149 offset:7168
	s_add_u32 s48, s46, 0x80080
	s_addc_u32 s49, s47, 0
	s_mov_b32 m0, s77
	s_nop 0
	global_load_lds_dwordx4 v1, s[48:49] offset:0
	s_nop 0
	s_mov_b32 m0, s78
	s_nop 0
	global_load_lds_dwordx4 v143, s[48:49] offset:0
	s_waitcnt vmcnt(24)
	s_waitcnt lgkmcnt(0)
	s_barrier
	s_setprio 1
	v_mfma_f32_16x16x32_bf16 v[92:95], v[4:7], v[60:63], 0
	v_mfma_f32_16x16x32_bf16 v[68:71], v[4:7], v[36:39], 0
	v_mfma_f32_16x16x32_bf16 v[72:75], v[12:15], v[36:39], 0
	v_mfma_f32_16x16x32_bf16 v[76:79], v[4:7], v[44:47], 0
	v_mfma_f32_16x16x32_bf16 v[80:83], v[12:15], v[44:47], 0
	v_mfma_f32_16x16x32_bf16 v[84:87], v[4:7], v[52:55], 0
	v_mfma_f32_16x16x32_bf16 v[88:91], v[12:15], v[52:55], 0
	v_mfma_f32_16x16x32_bf16 v[102:105], v[8:11], v[64:67], v[92:95]
	v_mfma_f32_16x16x32_bf16 v[92:95], v[12:15], v[60:63], 0
	v_mfma_f32_16x16x32_bf16 v[68:71], v[8:11], v[40:43], v[68:71]
	v_mfma_f32_16x16x32_bf16 v[72:75], v[16:19], v[40:43], v[72:75]
	v_mfma_f32_16x16x32_bf16 v[76:79], v[8:11], v[48:51], v[76:79]
	v_mfma_f32_16x16x32_bf16 v[80:83], v[16:19], v[48:51], v[80:83]
	v_mfma_f32_16x16x32_bf16 v[84:87], v[8:11], v[56:59], v[84:87]
	v_mfma_f32_16x16x32_bf16 v[88:91], v[16:19], v[56:59], v[88:91]
	v_mfma_f32_16x16x32_bf16 v[106:109], v[16:19], v[64:67], v[92:95]
	v_mfma_f32_16x16x32_bf16 v[92:95], v[20:23], v[36:39], 0
	v_mfma_f32_16x16x32_bf16 v[36:39], v[28:31], v[36:39], 0
	v_mfma_f32_16x16x32_bf16 v[118:121], v[24:27], v[40:43], v[92:95]
	v_mfma_f32_16x16x32_bf16 v[36:39], v[32:35], v[40:43], v[36:39]
	v_mfma_f32_16x16x32_bf16 v[40:43], v[20:23], v[44:47], 0
	v_mfma_f32_16x16x32_bf16 v[44:47], v[28:31], v[44:47], 0
	v_mfma_f32_16x16x32_bf16 v[40:43], v[24:27], v[48:51], v[40:43]
	v_mfma_f32_16x16x32_bf16 v[44:47], v[32:35], v[48:51], v[44:47]
	v_mfma_f32_16x16x32_bf16 v[48:51], v[20:23], v[52:55], 0
	v_mfma_f32_16x16x32_bf16 v[52:55], v[28:31], v[52:55], 0
	v_mfma_f32_16x16x32_bf16 v[48:51], v[24:27], v[56:59], v[48:51]
	v_mfma_f32_16x16x32_bf16 v[52:55], v[32:35], v[56:59], v[52:55]
	v_mfma_f32_16x16x32_bf16 v[56:59], v[20:23], v[60:63], 0
	v_mfma_f32_16x16x32_bf16 v[60:63], v[28:31], v[60:63], 0
	v_mfma_f32_16x16x32_bf16 v[56:59], v[24:27], v[64:67], v[56:59]
	v_mfma_f32_16x16x32_bf16 v[60:63], v[32:35], v[64:67], v[60:63]
	s_barrier
	s_setprio 0
	ds_read_b128 v[64:67], v149 offset:16384
	ds_read_b128 v[92:95], v149 offset:17408
	ds_read_b128 v[96:99], v149 offset:18432
	ds_read_b128 v[110:113], v149 offset:19456
	ds_read_b128 v[114:117], v149 offset:20480
	ds_read_b128 v[122:125], v149 offset:21504
	ds_read_b128 v[126:129], v149 offset:22528
	ds_read_b128 v[130:133], v149 offset:23552
	s_mov_b32 m0, s45
	s_nop 0
	global_load_lds_dwordx4 v142, s[30:31] offset:0
	s_nop 0
	s_mov_b32 m0, s52
	s_nop 0
	global_load_lds_dwordx4 v144, s[30:31] offset:0
	s_add_u32 s30, s54, 0x80100
	s_addc_u32 s31, s55, 0
	s_mov_b32 m0, s53
	s_nop 0
	global_load_lds_dwordx4 v142, s[30:31] offset:0
	s_nop 0
	s_mov_b32 m0, s64
	s_nop 0
	global_load_lds_dwordx4 v144, s[30:31] offset:0
	s_nop 0
	s_mov_b32 m0, s33
	s_nop 0
	global_load_lds_dwordx4 v1, s[40:41] offset:0
	s_nop 0
	s_mov_b32 m0, s65
	s_nop 0
	global_load_lds_dwordx4 v143, s[40:41] offset:0
	s_waitcnt vmcnt(24)
	s_waitcnt lgkmcnt(0)
	s_barrier
	s_setprio 1
	v_mfma_f32_16x16x32_bf16 v[138:141], v[4:7], v[64:67], 0
	v_mfma_f32_16x16x32_bf16 v[156:159], v[4:7], v[96:99], 0
	v_mfma_f32_16x16x32_bf16 v[164:167], v[4:7], v[114:117], 0
	v_mfma_f32_16x16x32_bf16 v[4:7], v[4:7], v[126:129], 0
	v_mfma_f32_16x16x32_bf16 v[138:141], v[8:11], v[92:95], v[138:141]
	v_mfma_f32_16x16x32_bf16 v[156:159], v[8:11], v[110:113], v[156:159]
	v_mfma_f32_16x16x32_bf16 v[164:167], v[8:11], v[122:125], v[164:167]
	v_mfma_f32_16x16x32_bf16 v[4:7], v[8:11], v[130:133], v[4:7]
	v_mfma_f32_16x16x32_bf16 v[8:11], v[12:15], v[126:129], 0
	v_mfma_f32_16x16x32_bf16 v[152:155], v[12:15], v[64:67], 0
	v_mfma_f32_16x16x32_bf16 v[160:163], v[12:15], v[96:99], 0
	v_mfma_f32_16x16x32_bf16 v[168:171], v[12:15], v[114:117], 0
	v_mfma_f32_16x16x32_bf16 v[8:11], v[16:19], v[130:133], v[8:11]
	v_mfma_f32_16x16x32_bf16 v[152:155], v[16:19], v[92:95], v[152:155]
	v_mfma_f32_16x16x32_bf16 v[160:163], v[16:19], v[110:113], v[160:163]
	v_mfma_f32_16x16x32_bf16 v[168:171], v[16:19], v[122:125], v[168:171]
	v_mfma_f32_16x16x32_bf16 v[12:15], v[20:23], v[64:67], 0
	v_mfma_f32_16x16x32_bf16 v[172:175], v[24:27], v[92:95], v[12:15]
	v_mfma_f32_16x16x32_bf16 v[12:15], v[28:31], v[64:67], 0
	v_mfma_f32_16x16x32_bf16 v[176:179], v[32:35], v[92:95], v[12:15]
	v_mfma_f32_16x16x32_bf16 v[12:15], v[20:23], v[96:99], 0
	v_mfma_f32_16x16x32_bf16 v[180:183], v[24:27], v[110:113], v[12:15]
	v_mfma_f32_16x16x32_bf16 v[12:15], v[28:31], v[96:99], 0
	v_mfma_f32_16x16x32_bf16 v[184:187], v[32:35], v[110:113], v[12:15]
	v_mfma_f32_16x16x32_bf16 v[12:15], v[20:23], v[114:117], 0
	v_mfma_f32_16x16x32_bf16 v[188:191], v[24:27], v[122:125], v[12:15]
	v_mfma_f32_16x16x32_bf16 v[12:15], v[28:31], v[114:117], 0
	v_mfma_f32_16x16x32_bf16 v[192:195], v[32:35], v[122:125], v[12:15]
	v_mfma_f32_16x16x32_bf16 v[12:15], v[20:23], v[126:129], 0
	v_mfma_f32_16x16x32_bf16 v[196:199], v[24:27], v[130:133], v[12:15]
	v_mfma_f32_16x16x32_bf16 v[12:15], v[28:31], v[126:129], 0
	v_mfma_f32_16x16x32_bf16 v[200:203], v[32:35], v[130:133], v[12:15]
	s_barrier
; #define PG8_KSETUP() const bool last = (t == nt - 2); const char* a1 = cA + (size_t)(t + 1) * kstep; \
;             const char* a2 = last ? nA : cA + (size_t)(t + 2) * kstep; const char* b2 = last ? nB : cB + (size_t)(t + 2) * kstep; const char* a3 = a2 + kstep; const char* b3 = b2 + kstep; \
;             if (last && has_next) S.a_ready(nxt)
; template <class Epi, class Sched, bool ALIGN_EPI = false, bool SP2 = false>
; __device__ __forceinline__ void gemm_phase(PG8_LAS unsigned char* lds, const Gemm g, const Sched& S, const Epi& E) {
;     ...
;         int t0 = 0;
;         if constexpr (SP2 && Epi::NVM == 16) { if (ui > 0) { const int t = 0; PG8_KSETUP(); PG8_KITER_SP2(24, 24); t0 = 2; } }
	s_setprio 0
	s_nop 4
	ds_read_b128 v[12:15], v150
	ds_read_b128 v[16:19], v150 offset:1024
	ds_read_b128 v[22:25], v150 offset:2048
	ds_read_b128 v[26:29], v150 offset:3072
	ds_read_b128 v[204:207], v151
	ds_read_b128 v[208:211], v151 offset:1024
	ds_read_b128 v[212:215], v151 offset:2048
	ds_read_b128 v[216:219], v151 offset:3072
	ds_read_b128 v[30:33], v149 offset:32768
	ds_read_b128 v[64:67], v149 offset:33792
	ds_read_b128 v[220:223], v149 offset:34816
	ds_read_b128 v[224:227], v149 offset:35840
	ds_read_b128 v[228:231], v149 offset:36864
	ds_read_b128 v[232:235], v149 offset:37888
	ds_read_b128 v[236:239], v149 offset:38912
	ds_read_b128 v[240:243], v149 offset:39936
	s_add_u32 s30, s46, 0x80100
	s_addc_u32 s31, s47, 0
	s_mov_b32 m0, s66
	s_nop 0
	global_load_lds_dwordx4 v1, s[30:31] offset:0
	s_nop 0
	s_mov_b32 m0, s67
	s_nop 0
	global_load_lds_dwordx4 v143, s[30:31] offset:0
	s_waitcnt vmcnt(8)
	s_waitcnt lgkmcnt(0)
	s_barrier
	s_setprio 1
	v_mfma_f32_16x16x32_bf16 v[68:71], v[12:15], v[30:33], v[68:71]
	v_mfma_f32_16x16x32_bf16 v[130:133], v[16:19], v[64:67], v[68:71]
	v_mfma_f32_16x16x32_bf16 v[68:71], v[22:25], v[30:33], v[72:75]
	v_mfma_f32_16x16x32_bf16 v[126:129], v[26:29], v[64:67], v[68:71]
	v_mfma_f32_16x16x32_bf16 v[68:71], v[12:15], v[220:223], v[76:79]
	v_mfma_f32_16x16x32_bf16 v[114:117], v[16:19], v[224:227], v[68:71]
	v_mfma_f32_16x16x32_bf16 v[68:71], v[22:25], v[220:223], v[80:83]
	v_mfma_f32_16x16x32_bf16 v[110:113], v[26:29], v[224:227], v[68:71]
	v_mfma_f32_16x16x32_bf16 v[68:71], v[12:15], v[228:231], v[84:87]
	v_mfma_f32_16x16x32_bf16 v[98:101], v[16:19], v[232:235], v[68:71]
	v_mfma_f32_16x16x32_bf16 v[68:71], v[22:25], v[228:231], v[88:91]
	v_mfma_f32_16x16x32_bf16 v[94:97], v[26:29], v[232:235], v[68:71]
	v_mfma_f32_16x16x32_bf16 v[68:71], v[12:15], v[236:239], v[102:105]
	v_mfma_f32_16x16x32_bf16 v[82:85], v[16:19], v[240:243], v[68:71]
	v_mfma_f32_16x16x32_bf16 v[68:71], v[22:25], v[236:239], v[106:109]
	v_mfma_f32_16x16x32_bf16 v[78:81], v[26:29], v[240:243], v[68:71]
	v_mfma_f32_16x16x32_bf16 v[68:71], v[204:207], v[30:33], v[118:121]
	v_mfma_f32_16x16x32_bf16 v[30:33], v[212:215], v[30:33], v[36:39]
	v_mfma_f32_16x16x32_bf16 v[118:121], v[216:219], v[64:67], v[30:33]
	v_mfma_f32_16x16x32_bf16 v[30:33], v[204:207], v[220:223], v[40:43]
	v_mfma_f32_16x16x32_bf16 v[106:109], v[208:211], v[224:227], v[30:33]
	v_mfma_f32_16x16x32_bf16 v[30:33], v[212:215], v[220:223], v[44:47]
	v_mfma_f32_16x16x32_bf16 v[102:105], v[216:219], v[224:227], v[30:33]
	v_mfma_f32_16x16x32_bf16 v[30:33], v[204:207], v[228:231], v[48:51]
	v_mfma_f32_16x16x32_bf16 v[90:93], v[208:211], v[232:235], v[30:33]
	v_mfma_f32_16x16x32_bf16 v[30:33], v[212:215], v[228:231], v[52:55]
	v_mfma_f32_16x16x32_bf16 v[86:89], v[216:219], v[232:235], v[30:33]
	v_mfma_f32_16x16x32_bf16 v[30:33], v[204:207], v[236:239], v[56:59]
	v_mfma_f32_16x16x32_bf16 v[74:77], v[208:211], v[240:243], v[30:33]
	v_mfma_f32_16x16x32_bf16 v[30:33], v[212:215], v[236:239], v[60:63]
	v_mfma_f32_16x16x32_bf16 v[122:125], v[208:211], v[64:67], v[68:71]
	v_mfma_f32_16x16x32_bf16 v[70:73], v[216:219], v[240:243], v[30:33]
	s_barrier
	s_setprio 0
	ds_read_b128 v[38:41], v149 offset:49152
	ds_read_b128 v[42:45], v149 offset:50176
	ds_read_b128 v[220:223], v149 offset:51200
	ds_read_b128 v[224:227], v149 offset:52224
	ds_read_b128 v[228:231], v149 offset:53248
	ds_read_b128 v[232:235], v149 offset:54272
	ds_read_b128 v[236:239], v149 offset:55296
	ds_read_b128 v[240:243], v149 offset:56320
	s_add_u32 s30, s54, 0x180
	s_addc_u32 s31, s55, 0
	s_mov_b32 m0, s71
	s_nop 0
	global_load_lds_dwordx4 v142, s[30:31] offset:0
	s_nop 0
	s_mov_b32 m0, s72
	s_nop 0
	global_load_lds_dwordx4 v144, s[30:31] offset:0
	s_add_u32 s30, s54, 0x80180
	s_addc_u32 s31, s55, 0
	s_mov_b32 m0, s75
	s_nop 0
	global_load_lds_dwordx4 v142, s[30:31] offset:0
	s_nop 0
	s_mov_b32 m0, s76
	s_nop 0
	global_load_lds_dwordx4 v144, s[30:31] offset:0
	s_nop 0
	s_mov_b32 m0, s73
	s_nop 0
	global_load_lds_dwordx4 v1, s[38:39] offset:0
	s_nop 0
	s_mov_b32 m0, s74
	s_nop 0
	global_load_lds_dwordx4 v143, s[38:39] offset:0
	s_waitcnt vmcnt(8)
	s_waitcnt lgkmcnt(0)
	s_barrier
	s_setprio 1
	v_mfma_f32_16x16x32_bf16 v[30:33], v[12:15], v[38:41], v[138:141]
	v_mfma_f32_16x16x32_bf16 v[66:69], v[16:19], v[42:45], v[30:33]
	v_mfma_f32_16x16x32_bf16 v[30:33], v[22:25], v[38:41], v[152:155]
	v_mfma_f32_16x16x32_bf16 v[62:65], v[26:29], v[42:45], v[30:33]
	v_mfma_f32_16x16x32_bf16 v[30:33], v[12:15], v[220:223], v[156:159]
	v_mfma_f32_16x16x32_bf16 v[50:53], v[16:19], v[224:227], v[30:33]
	v_mfma_f32_16x16x32_bf16 v[30:33], v[22:25], v[220:223], v[160:163]
	v_mfma_f32_16x16x32_bf16 v[46:49], v[26:29], v[224:227], v[30:33]
	v_mfma_f32_16x16x32_bf16 v[30:33], v[12:15], v[228:231], v[164:167]
	v_mfma_f32_16x16x32_bf16 v[4:7], v[12:15], v[236:239], v[4:7]
	v_mfma_f32_16x16x32_bf16 v[34:37], v[16:19], v[232:235], v[30:33]
	v_mfma_f32_16x16x32_bf16 v[30:33], v[22:25], v[228:231], v[168:171]
	v_mfma_f32_16x16x32_bf16 v[18:21], v[16:19], v[240:243], v[4:7]
	v_mfma_f32_16x16x32_bf16 v[4:7], v[22:25], v[236:239], v[8:11]
	v_mfma_f32_16x16x32_bf16 v[30:33], v[26:29], v[232:235], v[30:33]
	v_mfma_f32_16x16x32_bf16 v[14:17], v[26:29], v[240:243], v[4:7]
	v_mfma_f32_16x16x32_bf16 v[4:7], v[204:207], v[38:41], v[172:175]
	v_mfma_f32_16x16x32_bf16 v[58:61], v[208:211], v[42:45], v[4:7]
	v_mfma_f32_16x16x32_bf16 v[4:7], v[212:215], v[38:41], v[176:179]
	v_mfma_f32_16x16x32_bf16 v[54:57], v[216:219], v[42:45], v[4:7]
	v_mfma_f32_16x16x32_bf16 v[4:7], v[204:207], v[220:223], v[180:183]
	v_mfma_f32_16x16x32_bf16 v[42:45], v[208:211], v[224:227], v[4:7]
	v_mfma_f32_16x16x32_bf16 v[4:7], v[212:215], v[220:223], v[184:187]
	v_mfma_f32_16x16x32_bf16 v[38:41], v[216:219], v[224:227], v[4:7]
	v_mfma_f32_16x16x32_bf16 v[4:7], v[204:207], v[228:231], v[188:191]
	v_mfma_f32_16x16x32_bf16 v[26:29], v[208:211], v[232:235], v[4:7]
	v_mfma_f32_16x16x32_bf16 v[4:7], v[212:215], v[228:231], v[192:195]
	v_mfma_f32_16x16x32_bf16 v[22:25], v[216:219], v[232:235], v[4:7]
	v_mfma_f32_16x16x32_bf16 v[4:7], v[204:207], v[236:239], v[196:199]
	v_mfma_f32_16x16x32_bf16 v[10:13], v[208:211], v[240:243], v[4:7]
	v_mfma_f32_16x16x32_bf16 v[4:7], v[212:215], v[236:239], v[200:203]
	v_mfma_f32_16x16x32_bf16 v[6:9], v[216:219], v[240:243], v[4:7]
	s_barrier
	s_setprio 0
	s_mov_b32 s56, 2
	s_branch .LBB0_2713

; #define PG8_KSETUP() const bool last = (t == nt - 2); const char* a1 = cA + (size_t)(t + 1) * kstep; \
;             const char* a2 = last ? nA : cA + (size_t)(t + 2) * kstep; const char* b2 = last ? nB : cB + (size_t)(t + 2) * kstep; const char* a3 = a2 + kstep; const char* b3 = b2 + kstep; \
;             if (last && has_next) S.a_ready(nxt)
; template <class Epi, class Sched, bool ALIGN_EPI = false, bool SP2 = false>
; __device__ __forceinline__ void gemm_phase(PG8_LAS unsigned char* lds, const Gemm g, const Sched& S, const Epi& E) {
;     ...
;         int t0 = 0;
;         if constexpr (SP2 && Epi::NVM == 16) { if (ui > 0) { const int t = 0; PG8_KSETUP(); PG8_KITER_SP2(24, 24); t0 = 2; } }
;         if constexpr (SP2 && Epi::NVM == 8) { if (ui > 0) { const int t = 0; PG8_KSETUP(); PG8_KITER_SP2(16, 16); t0 = 2; } }
;         for (int t = t0; t < nt; t += 2) {
;             PG8_KSETUP();
;             if constexpr (SP2) {
;             PG8_KITER_SP2(8, 8);
.LBB0_2714:
	ds_read_b128 v[138:141], v147
	ds_read_b128 v[152:155], v147 offset:1024
	ds_read_b128 v[156:159], v147 offset:2048
	ds_read_b128 v[160:163], v147 offset:3072
	ds_read_b128 v[164:167], v148
	ds_read_b128 v[168:171], v148 offset:1024
	ds_read_b128 v[172:175], v148 offset:2048
	ds_read_b128 v[176:179], v148 offset:3072
	s_cmp_eq_u32 s84, 28
	s_cselect_b32 s58, s43, s87
	s_cselect_b32 s59, s37, s88
	s_cselect_b32 s56, s83, s85
	s_cselect_b32 s57, s29, s86
	s_add_u32 s54, s58, 0x80
	s_addc_u32 s55, s59, 0
	ds_read_b128 v[180:183], v149
	ds_read_b128 v[184:187], v149 offset:1024
	ds_read_b128 v[188:191], v149 offset:2048
	ds_read_b128 v[192:195], v149 offset:3072
	ds_read_b128 v[196:199], v149 offset:4096
	ds_read_b128 v[200:203], v149 offset:5120
	ds_read_b128 v[204:207], v149 offset:6144
	ds_read_b128 v[208:211], v149 offset:7168
	s_mov_b32 m0, s77
	s_nop 0
	global_load_lds_dwordx4 v1, s[46:47] offset:0
	s_nop 0
	s_mov_b32 m0, s78
	s_nop 0
	global_load_lds_dwordx4 v143, s[46:47] offset:0
	s_waitcnt vmcnt(8)
	s_waitcnt lgkmcnt(0)
	s_barrier
	s_setprio 1
	v_mfma_f32_16x16x32_bf16 v[130:133], v[138:141], v[180:183], v[130:133]
	v_mfma_f32_16x16x32_bf16 v[130:133], v[152:155], v[184:187], v[130:133]
	v_mfma_f32_16x16x32_bf16 v[126:129], v[156:159], v[180:183], v[126:129]
	v_mfma_f32_16x16x32_bf16 v[126:129], v[160:163], v[184:187], v[126:129]
	v_mfma_f32_16x16x32_bf16 v[114:117], v[138:141], v[188:191], v[114:117]
	v_mfma_f32_16x16x32_bf16 v[114:117], v[152:155], v[192:195], v[114:117]
	v_mfma_f32_16x16x32_bf16 v[110:113], v[156:159], v[188:191], v[110:113]
	v_mfma_f32_16x16x32_bf16 v[110:113], v[160:163], v[192:195], v[110:113]
	v_mfma_f32_16x16x32_bf16 v[98:101], v[138:141], v[196:199], v[98:101]
	v_mfma_f32_16x16x32_bf16 v[98:101], v[152:155], v[200:203], v[98:101]
	v_mfma_f32_16x16x32_bf16 v[94:97], v[156:159], v[196:199], v[94:97]
	v_mfma_f32_16x16x32_bf16 v[94:97], v[160:163], v[200:203], v[94:97]
	v_mfma_f32_16x16x32_bf16 v[82:85], v[138:141], v[204:207], v[82:85]
	v_mfma_f32_16x16x32_bf16 v[82:85], v[152:155], v[208:211], v[82:85]
	v_mfma_f32_16x16x32_bf16 v[78:81], v[156:159], v[204:207], v[78:81]
	v_mfma_f32_16x16x32_bf16 v[78:81], v[160:163], v[208:211], v[78:81]
	v_mfma_f32_16x16x32_bf16 v[122:125], v[164:167], v[180:183], v[122:125]
	v_mfma_f32_16x16x32_bf16 v[122:125], v[168:171], v[184:187], v[122:125]
	v_mfma_f32_16x16x32_bf16 v[118:121], v[172:175], v[180:183], v[118:121]
	v_mfma_f32_16x16x32_bf16 v[118:121], v[176:179], v[184:187], v[118:121]
	v_mfma_f32_16x16x32_bf16 v[106:109], v[164:167], v[188:191], v[106:109]
	v_mfma_f32_16x16x32_bf16 v[106:109], v[168:171], v[192:195], v[106:109]
	v_mfma_f32_16x16x32_bf16 v[102:105], v[172:175], v[188:191], v[102:105]
	v_mfma_f32_16x16x32_bf16 v[102:105], v[176:179], v[192:195], v[102:105]
	v_mfma_f32_16x16x32_bf16 v[90:93], v[164:167], v[196:199], v[90:93]
	v_mfma_f32_16x16x32_bf16 v[90:93], v[168:171], v[200:203], v[90:93]
	v_mfma_f32_16x16x32_bf16 v[86:89], v[172:175], v[196:199], v[86:89]
	v_mfma_f32_16x16x32_bf16 v[86:89], v[176:179], v[200:203], v[86:89]
	v_mfma_f32_16x16x32_bf16 v[74:77], v[164:167], v[204:207], v[74:77]
	v_mfma_f32_16x16x32_bf16 v[74:77], v[168:171], v[208:211], v[74:77]
	v_mfma_f32_16x16x32_bf16 v[70:73], v[172:175], v[204:207], v[70:73]
	v_mfma_f32_16x16x32_bf16 v[70:73], v[176:179], v[208:211], v[70:73]
	s_barrier
	s_setprio 0
	ds_read_b128 v[180:183], v149 offset:16384
	ds_read_b128 v[184:187], v149 offset:17408
	ds_read_b128 v[188:191], v149 offset:18432
	ds_read_b128 v[192:195], v149 offset:19456
	ds_read_b128 v[196:199], v149 offset:20480
	ds_read_b128 v[200:203], v149 offset:21504
	ds_read_b128 v[204:207], v149 offset:22528
	ds_read_b128 v[208:211], v149 offset:23552
	s_mov_b32 m0, s45
	s_nop 0
	global_load_lds_dwordx4 v142, s[56:57] offset:0
	s_add_u32 s30, s56, 0x80000
	s_mov_b32 m0, s52
	s_nop 0
	global_load_lds_dwordx4 v144, s[56:57] offset:0
	s_addc_u32 s31, s57, 0
	s_mov_b32 m0, s53
	s_nop 0
	global_load_lds_dwordx4 v142, s[30:31] offset:0
	s_nop 0
	s_mov_b32 m0, s64
	s_nop 0
	global_load_lds_dwordx4 v144, s[30:31] offset:0
	s_nop 0
	s_mov_b32 m0, s33
	s_nop 0
	global_load_lds_dwordx4 v1, s[58:59] offset:0
	s_nop 0
	s_mov_b32 m0, s65
	s_nop 0
	global_load_lds_dwordx4 v143, s[58:59] offset:0
	s_waitcnt vmcnt(8)
	s_waitcnt lgkmcnt(0)
	s_barrier
	s_setprio 1
	v_mfma_f32_16x16x32_bf16 v[66:69], v[138:141], v[180:183], v[66:69]
	v_mfma_f32_16x16x32_bf16 v[66:69], v[152:155], v[184:187], v[66:69]
	v_mfma_f32_16x16x32_bf16 v[62:65], v[156:159], v[180:183], v[62:65]
	v_mfma_f32_16x16x32_bf16 v[62:65], v[160:163], v[184:187], v[62:65]
	v_mfma_f32_16x16x32_bf16 v[50:53], v[138:141], v[188:191], v[50:53]
	v_mfma_f32_16x16x32_bf16 v[50:53], v[152:155], v[192:195], v[50:53]
	v_mfma_f32_16x16x32_bf16 v[46:49], v[156:159], v[188:191], v[46:49]
	v_mfma_f32_16x16x32_bf16 v[46:49], v[160:163], v[192:195], v[46:49]
	v_mfma_f32_16x16x32_bf16 v[34:37], v[138:141], v[196:199], v[34:37]
	v_mfma_f32_16x16x32_bf16 v[34:37], v[152:155], v[200:203], v[34:37]
	v_mfma_f32_16x16x32_bf16 v[30:33], v[156:159], v[196:199], v[30:33]
	v_mfma_f32_16x16x32_bf16 v[30:33], v[160:163], v[200:203], v[30:33]
	v_mfma_f32_16x16x32_bf16 v[18:21], v[138:141], v[204:207], v[18:21]
	v_mfma_f32_16x16x32_bf16 v[18:21], v[152:155], v[208:211], v[18:21]
	v_mfma_f32_16x16x32_bf16 v[14:17], v[156:159], v[204:207], v[14:17]
	v_mfma_f32_16x16x32_bf16 v[14:17], v[160:163], v[208:211], v[14:17]
	v_mfma_f32_16x16x32_bf16 v[58:61], v[164:167], v[180:183], v[58:61]
	v_mfma_f32_16x16x32_bf16 v[54:57], v[172:175], v[180:183], v[54:57]
	v_mfma_f32_16x16x32_bf16 v[42:45], v[164:167], v[188:191], v[42:45]
	v_mfma_f32_16x16x32_bf16 v[38:41], v[172:175], v[188:191], v[38:41]
	v_mfma_f32_16x16x32_bf16 v[26:29], v[164:167], v[196:199], v[26:29]
	v_mfma_f32_16x16x32_bf16 v[22:25], v[172:175], v[196:199], v[22:25]
	v_mfma_f32_16x16x32_bf16 v[10:13], v[164:167], v[204:207], v[10:13]
	v_mfma_f32_16x16x32_bf16 v[4:7], v[172:175], v[204:207], v[6:9]
	v_mfma_f32_16x16x32_bf16 v[58:61], v[168:171], v[184:187], v[58:61]
	v_mfma_f32_16x16x32_bf16 v[54:57], v[176:179], v[184:187], v[54:57]
	v_mfma_f32_16x16x32_bf16 v[42:45], v[168:171], v[192:195], v[42:45]
	v_mfma_f32_16x16x32_bf16 v[38:41], v[176:179], v[192:195], v[38:41]
	v_mfma_f32_16x16x32_bf16 v[26:29], v[168:171], v[200:203], v[26:29]
	v_mfma_f32_16x16x32_bf16 v[22:25], v[176:179], v[200:203], v[22:25]
	v_mfma_f32_16x16x32_bf16 v[10:13], v[168:171], v[208:211], v[10:13]
	v_mfma_f32_16x16x32_bf16 v[4:7], v[176:179], v[208:211], v[4:7]
	s_barrier
; #define PG8_KSETUP() const bool last = (t == nt - 2); const char* a1 = cA + (size_t)(t + 1) * kstep; \
;             const char* a2 = last ? nA : cA + (size_t)(t + 2) * kstep; const char* b2 = last ? nB : cB + (size_t)(t + 2) * kstep; const char* a3 = a2 + kstep; const char* b3 = b2 + kstep; \
;             if (last && has_next) S.a_ready(nxt)
; template <class Epi, class Sched, bool ALIGN_EPI = false, bool SP2 = false>
; __device__ __forceinline__ void gemm_phase(PG8_LAS unsigned char* lds, const Gemm g, const Sched& S, const Epi& E) {
;     ...
;         int t0 = 0;
;         if constexpr (SP2 && Epi::NVM == 16) { if (ui > 0) { const int t = 0; PG8_KSETUP(); PG8_KITER_SP2(24, 24); t0 = 2; } }
;         if constexpr (SP2 && Epi::NVM == 8) { if (ui > 0) { const int t = 0; PG8_KSETUP(); PG8_KITER_SP2(16, 16); t0 = 2; } }
;         for (int t = t0; t < nt; t += 2) {
;             PG8_KSETUP();
;             if constexpr (SP2) {
;             PG8_KITER_SP2(8, 8);
	s_setprio 0
	ds_read_b128 v[138:141], v150
	ds_read_b128 v[152:155], v150 offset:1024
	ds_read_b128 v[156:159], v150 offset:2048
	ds_read_b128 v[160:163], v150 offset:3072
	ds_read_b128 v[164:167], v151
	ds_read_b128 v[168:171], v151 offset:1024
	ds_read_b128 v[172:175], v151 offset:2048
	ds_read_b128 v[176:179], v151 offset:3072
	ds_read_b128 v[180:183], v149 offset:32768
	ds_read_b128 v[184:187], v149 offset:33792
	ds_read_b128 v[188:191], v149 offset:34816
	ds_read_b128 v[192:195], v149 offset:35840
	ds_read_b128 v[196:199], v149 offset:36864
	ds_read_b128 v[200:203], v149 offset:37888
	ds_read_b128 v[204:207], v149 offset:38912
	ds_read_b128 v[208:211], v149 offset:39936
	s_add_u32 s30, s58, 0x80000
	s_addc_u32 s31, s59, 0
	s_mov_b32 m0, s66
	s_nop 0
	global_load_lds_dwordx4 v1, s[30:31] offset:0
	s_nop 0
	s_mov_b32 m0, s67
	s_nop 0
	global_load_lds_dwordx4 v143, s[30:31] offset:0
	s_waitcnt vmcnt(8)
	s_waitcnt lgkmcnt(0)
	s_barrier
	s_setprio 1
	v_mfma_f32_16x16x32_bf16 v[130:133], v[138:141], v[180:183], v[130:133]
	v_mfma_f32_16x16x32_bf16 v[130:133], v[152:155], v[184:187], v[130:133]
	v_mfma_f32_16x16x32_bf16 v[126:129], v[156:159], v[180:183], v[126:129]
	v_mfma_f32_16x16x32_bf16 v[126:129], v[160:163], v[184:187], v[126:129]
	v_mfma_f32_16x16x32_bf16 v[114:117], v[138:141], v[188:191], v[114:117]
	v_mfma_f32_16x16x32_bf16 v[114:117], v[152:155], v[192:195], v[114:117]
	v_mfma_f32_16x16x32_bf16 v[110:113], v[156:159], v[188:191], v[110:113]
	v_mfma_f32_16x16x32_bf16 v[110:113], v[160:163], v[192:195], v[110:113]
	v_mfma_f32_16x16x32_bf16 v[98:101], v[138:141], v[196:199], v[98:101]
	v_mfma_f32_16x16x32_bf16 v[98:101], v[152:155], v[200:203], v[98:101]
	v_mfma_f32_16x16x32_bf16 v[94:97], v[156:159], v[196:199], v[94:97]
	v_mfma_f32_16x16x32_bf16 v[94:97], v[160:163], v[200:203], v[94:97]
	v_mfma_f32_16x16x32_bf16 v[82:85], v[138:141], v[204:207], v[82:85]
	v_mfma_f32_16x16x32_bf16 v[82:85], v[152:155], v[208:211], v[82:85]
	v_mfma_f32_16x16x32_bf16 v[78:81], v[156:159], v[204:207], v[78:81]
	v_mfma_f32_16x16x32_bf16 v[78:81], v[160:163], v[208:211], v[78:81]
	v_mfma_f32_16x16x32_bf16 v[122:125], v[164:167], v[180:183], v[122:125]
	v_mfma_f32_16x16x32_bf16 v[122:125], v[168:171], v[184:187], v[122:125]
	v_mfma_f32_16x16x32_bf16 v[118:121], v[172:175], v[180:183], v[118:121]
	v_mfma_f32_16x16x32_bf16 v[118:121], v[176:179], v[184:187], v[118:121]
	v_mfma_f32_16x16x32_bf16 v[106:109], v[164:167], v[188:191], v[106:109]
	v_mfma_f32_16x16x32_bf16 v[106:109], v[168:171], v[192:195], v[106:109]
	v_mfma_f32_16x16x32_bf16 v[102:105], v[172:175], v[188:191], v[102:105]
	v_mfma_f32_16x16x32_bf16 v[102:105], v[176:179], v[192:195], v[102:105]
	v_mfma_f32_16x16x32_bf16 v[90:93], v[164:167], v[196:199], v[90:93]
	v_mfma_f32_16x16x32_bf16 v[90:93], v[168:171], v[200:203], v[90:93]
	v_mfma_f32_16x16x32_bf16 v[86:89], v[172:175], v[196:199], v[86:89]
	v_mfma_f32_16x16x32_bf16 v[86:89], v[176:179], v[200:203], v[86:89]
	v_mfma_f32_16x16x32_bf16 v[74:77], v[164:167], v[204:207], v[74:77]
	v_mfma_f32_16x16x32_bf16 v[74:77], v[168:171], v[208:211], v[74:77]
	v_mfma_f32_16x16x32_bf16 v[70:73], v[172:175], v[204:207], v[70:73]
	v_mfma_f32_16x16x32_bf16 v[70:73], v[176:179], v[208:211], v[70:73]
	s_barrier
	s_setprio 0
	ds_read_b128 v[180:183], v149 offset:49152
	ds_read_b128 v[184:187], v149 offset:50176
	ds_read_b128 v[188:191], v149 offset:51200
	ds_read_b128 v[192:195], v149 offset:52224
	ds_read_b128 v[196:199], v149 offset:53248
	ds_read_b128 v[200:203], v149 offset:54272
	ds_read_b128 v[204:207], v149 offset:55296
	ds_read_b128 v[208:211], v149 offset:56320
	s_add_u32 s30, s56, 0x80
	s_addc_u32 s31, s57, 0
	s_mov_b32 m0, s71
	s_nop 0
	global_load_lds_dwordx4 v142, s[30:31] offset:0
	s_nop 0
	s_mov_b32 m0, s72
	s_nop 0
	global_load_lds_dwordx4 v144, s[30:31] offset:0
	s_add_u32 s30, s56, 0x80080
	s_addc_u32 s31, s57, 0
	s_mov_b32 m0, s75
	s_nop 0
	global_load_lds_dwordx4 v142, s[30:31] offset:0
	s_nop 0
	s_mov_b32 m0, s76
	s_nop 0
	global_load_lds_dwordx4 v144, s[30:31] offset:0
	s_nop 0
	s_mov_b32 m0, s73
	s_nop 0
	global_load_lds_dwordx4 v1, s[54:55] offset:0
	s_nop 0
	s_mov_b32 m0, s74
	s_nop 0
	global_load_lds_dwordx4 v143, s[54:55] offset:0
	s_waitcnt vmcnt(8)
	s_waitcnt lgkmcnt(0)
	s_barrier
	s_setprio 1
	v_mfma_f32_16x16x32_bf16 v[66:69], v[138:141], v[180:183], v[66:69]
	v_mfma_f32_16x16x32_bf16 v[66:69], v[152:155], v[184:187], v[66:69]
	v_mfma_f32_16x16x32_bf16 v[62:65], v[156:159], v[180:183], v[62:65]
	v_mfma_f32_16x16x32_bf16 v[62:65], v[160:163], v[184:187], v[62:65]
	v_mfma_f32_16x16x32_bf16 v[50:53], v[138:141], v[188:191], v[50:53]
	v_mfma_f32_16x16x32_bf16 v[50:53], v[152:155], v[192:195], v[50:53]
	v_mfma_f32_16x16x32_bf16 v[46:49], v[156:159], v[188:191], v[46:49]
	v_mfma_f32_16x16x32_bf16 v[46:49], v[160:163], v[192:195], v[46:49]
	v_mfma_f32_16x16x32_bf16 v[34:37], v[138:141], v[196:199], v[34:37]
	v_mfma_f32_16x16x32_bf16 v[34:37], v[152:155], v[200:203], v[34:37]
	v_mfma_f32_16x16x32_bf16 v[30:33], v[156:159], v[196:199], v[30:33]
	v_mfma_f32_16x16x32_bf16 v[30:33], v[160:163], v[200:203], v[30:33]
	v_mfma_f32_16x16x32_bf16 v[18:21], v[138:141], v[204:207], v[18:21]
	v_mfma_f32_16x16x32_bf16 v[18:21], v[152:155], v[208:211], v[18:21]
	v_mfma_f32_16x16x32_bf16 v[14:17], v[156:159], v[204:207], v[14:17]
	v_mfma_f32_16x16x32_bf16 v[14:17], v[160:163], v[208:211], v[14:17]
	v_mfma_f32_16x16x32_bf16 v[58:61], v[164:167], v[180:183], v[58:61]
	v_mfma_f32_16x16x32_bf16 v[54:57], v[172:175], v[180:183], v[54:57]
	v_mfma_f32_16x16x32_bf16 v[42:45], v[164:167], v[188:191], v[42:45]
	v_mfma_f32_16x16x32_bf16 v[38:41], v[172:175], v[188:191], v[38:41]
	v_mfma_f32_16x16x32_bf16 v[26:29], v[164:167], v[196:199], v[26:29]
	v_mfma_f32_16x16x32_bf16 v[22:25], v[172:175], v[196:199], v[22:25]
	v_mfma_f32_16x16x32_bf16 v[8:11], v[164:167], v[204:207], v[10:13]
	v_mfma_f32_16x16x32_bf16 v[4:7], v[172:175], v[204:207], v[4:7]
	v_mfma_f32_16x16x32_bf16 v[58:61], v[168:171], v[184:187], v[58:61]
	v_mfma_f32_16x16x32_bf16 v[54:57], v[176:179], v[184:187], v[54:57]
	v_mfma_f32_16x16x32_bf16 v[42:45], v[168:171], v[192:195], v[42:45]
	v_mfma_f32_16x16x32_bf16 v[38:41], v[176:179], v[192:195], v[38:41]
	v_mfma_f32_16x16x32_bf16 v[26:29], v[168:171], v[200:203], v[26:29]
	v_mfma_f32_16x16x32_bf16 v[22:25], v[176:179], v[200:203], v[22:25]
	v_mfma_f32_16x16x32_bf16 v[10:13], v[168:171], v[208:211], v[8:11]
	v_mfma_f32_16x16x32_bf16 v[6:9], v[176:179], v[208:211], v[4:7]
	s_barrier
	s_setprio 0
	s_add_i32 s84, s84, 2
	s_add_u32 s85, s85, 0x100
	s_addc_u32 s86, s86, 0
	s_add_u32 s87, s87, 0x100
	s_addc_u32 s88, s88, 0
	s_add_u32 s46, s46, 0x100
	s_addc_u32 s47, s47, 0
	s_cmp_gt_u32 s84, 29
	s_cbranch_scc0 .LBB0_2714
	s_and_b64 vcc, exec, s[18:19]
	s_cbranch_vccz .LBB0_2717
	s_barrier

; #define PG8_KSETUP() const bool last = (t == nt - 2); const char* a1 = cA + (size_t)(t + 1) * kstep; \
;             const char* a2 = last ? nA : cA + (size_t)(t + 2) * kstep; const char* b2 = last ? nB : cB + (size_t)(t + 2) * kstep; const char* a3 = a2 + kstep; const char* b3 = b2 + kstep; \
;             if (last && has_next) S.a_ready(nxt)
; template <class Epi, class Sched, bool ALIGN_EPI = false, bool SP2 = false>
; __device__ __forceinline__ void gemm_phase(PG8_LAS unsigned char* lds, const Gemm g, const Sched& S, const Epi& E) {
;     ...
;         int t0 = 0;
;         if constexpr (SP2 && Epi::NVM == 16) { if (ui > 0) { const int t = 0; PG8_KSETUP(); PG8_KITER_SP2(24, 24); t0 = 2; } }
;         if constexpr (SP2 && Epi::NVM == 8) { if (ui > 0) { const int t = 0; PG8_KSETUP(); PG8_KITER_SP2(16, 16); t0 = 2; } }
.LBB0_2869:
	s_cmp_lg_u32 s73, 0
	s_mov_b32 s40, 0
	s_cbranch_scc0 .LBB0_2871
	ds_read_b128 v[4:7], v152
	ds_read_b128 v[8:11], v152 offset:1024
	ds_read_b128 v[12:15], v152 offset:2048
	ds_read_b128 v[16:19], v152 offset:3072
	ds_read_b128 v[20:23], v153
	ds_read_b128 v[24:27], v153 offset:1024
	ds_read_b128 v[28:31], v153 offset:2048
	ds_read_b128 v[32:35], v153 offset:3072
	s_add_u32 s24, s36, 0x100
	s_addc_u32 s25, s37, 0
	s_add_u32 s30, s38, 0x100
	s_addc_u32 s31, s39, 0
	s_add_u32 s22, s36, 0x180
	s_addc_u32 s23, s37, 0
	ds_read_b128 v[36:39], v154
	ds_read_b128 v[40:43], v154 offset:1024
	ds_read_b128 v[44:47], v154 offset:2048
	ds_read_b128 v[48:51], v154 offset:3072
	ds_read_b128 v[52:55], v154 offset:4096
	ds_read_b128 v[56:59], v154 offset:5120
	ds_read_b128 v[60:63], v154 offset:6144
	ds_read_b128 v[64:67], v154 offset:7168
	s_add_u32 s40, s36, 0x80080
	s_addc_u32 s41, s37, 0
	s_mov_b32 m0, s64
	s_nop 0
	global_load_lds_dwordx4 v1, s[40:41] offset:0
	s_nop 0
	s_mov_b32 m0, s65
	s_nop 0
	global_load_lds_dwordx4 v147, s[40:41] offset:0
	s_waitcnt vmcnt(16)
	s_waitcnt lgkmcnt(0)
	s_barrier
	s_setprio 1
	v_mfma_f32_16x16x32_bf16 v[92:95], v[4:7], v[60:63], 0
	v_mfma_f32_16x16x32_bf16 v[68:71], v[4:7], v[36:39], 0
	v_mfma_f32_16x16x32_bf16 v[72:75], v[12:15], v[36:39], 0
	v_mfma_f32_16x16x32_bf16 v[76:79], v[4:7], v[44:47], 0
	v_mfma_f32_16x16x32_bf16 v[80:83], v[12:15], v[44:47], 0
	v_mfma_f32_16x16x32_bf16 v[84:87], v[4:7], v[52:55], 0
	v_mfma_f32_16x16x32_bf16 v[88:91], v[12:15], v[52:55], 0
	v_mfma_f32_16x16x32_bf16 v[102:105], v[8:11], v[64:67], v[92:95]
	v_mfma_f32_16x16x32_bf16 v[92:95], v[12:15], v[60:63], 0
	v_mfma_f32_16x16x32_bf16 v[68:71], v[8:11], v[40:43], v[68:71]
	v_mfma_f32_16x16x32_bf16 v[72:75], v[16:19], v[40:43], v[72:75]
	v_mfma_f32_16x16x32_bf16 v[76:79], v[8:11], v[48:51], v[76:79]
	v_mfma_f32_16x16x32_bf16 v[80:83], v[16:19], v[48:51], v[80:83]
	v_mfma_f32_16x16x32_bf16 v[84:87], v[8:11], v[56:59], v[84:87]
	v_mfma_f32_16x16x32_bf16 v[88:91], v[16:19], v[56:59], v[88:91]
	v_mfma_f32_16x16x32_bf16 v[106:109], v[16:19], v[64:67], v[92:95]
	v_mfma_f32_16x16x32_bf16 v[92:95], v[20:23], v[36:39], 0
	v_mfma_f32_16x16x32_bf16 v[36:39], v[28:31], v[36:39], 0
	v_mfma_f32_16x16x32_bf16 v[118:121], v[24:27], v[40:43], v[92:95]
	v_mfma_f32_16x16x32_bf16 v[36:39], v[32:35], v[40:43], v[36:39]
	v_mfma_f32_16x16x32_bf16 v[40:43], v[20:23], v[44:47], 0
	v_mfma_f32_16x16x32_bf16 v[44:47], v[28:31], v[44:47], 0
	v_mfma_f32_16x16x32_bf16 v[40:43], v[24:27], v[48:51], v[40:43]
	v_mfma_f32_16x16x32_bf16 v[44:47], v[32:35], v[48:51], v[44:47]
	v_mfma_f32_16x16x32_bf16 v[48:51], v[20:23], v[52:55], 0
	v_mfma_f32_16x16x32_bf16 v[52:55], v[28:31], v[52:55], 0
	v_mfma_f32_16x16x32_bf16 v[48:51], v[24:27], v[56:59], v[48:51]
	v_mfma_f32_16x16x32_bf16 v[52:55], v[32:35], v[56:59], v[52:55]
	v_mfma_f32_16x16x32_bf16 v[56:59], v[20:23], v[60:63], 0
	v_mfma_f32_16x16x32_bf16 v[60:63], v[28:31], v[60:63], 0
	v_mfma_f32_16x16x32_bf16 v[56:59], v[24:27], v[64:67], v[56:59]
	v_mfma_f32_16x16x32_bf16 v[60:63], v[32:35], v[64:67], v[60:63]
	s_barrier
	s_setprio 0
	ds_read_b128 v[64:67], v154 offset:16384
	ds_read_b128 v[92:95], v154 offset:17408
	ds_read_b128 v[96:99], v154 offset:18432
	ds_read_b128 v[110:113], v154 offset:19456
	ds_read_b128 v[114:117], v154 offset:20480
	ds_read_b128 v[122:125], v154 offset:21504
	ds_read_b128 v[126:129], v154 offset:22528
	ds_read_b128 v[130:133], v154 offset:23552
	s_mov_b32 m0, s29
	s_nop 0
	global_load_lds_dwordx4 v146, s[30:31] offset:0
	s_nop 0
	s_mov_b32 m0, s44
	s_nop 0
	global_load_lds_dwordx4 v148, s[30:31] offset:0
	s_add_u32 s30, s38, 0x80100
	s_addc_u32 s31, s39, 0
	s_mov_b32 m0, s45
	s_nop 0
	global_load_lds_dwordx4 v146, s[30:31] offset:0
	s_nop 0
	s_mov_b32 m0, s46
	s_nop 0
	global_load_lds_dwordx4 v148, s[30:31] offset:0
	s_nop 0
	s_mov_b32 m0, s21
	s_nop 0
	global_load_lds_dwordx4 v1, s[24:25] offset:0
	s_nop 0
	s_mov_b32 m0, s47
	s_nop 0
	global_load_lds_dwordx4 v147, s[24:25] offset:0
	s_waitcnt vmcnt(16)
	s_waitcnt lgkmcnt(0)
	s_barrier
	s_setprio 1
	v_mfma_f32_16x16x32_bf16 v[138:141], v[4:7], v[64:67], 0
	v_mfma_f32_16x16x32_bf16 v[158:161], v[4:7], v[96:99], 0
	v_mfma_f32_16x16x32_bf16 v[166:169], v[4:7], v[114:117], 0
	v_mfma_f32_16x16x32_bf16 v[4:7], v[4:7], v[126:129], 0
	v_mfma_f32_16x16x32_bf16 v[138:141], v[8:11], v[92:95], v[138:141]
	v_mfma_f32_16x16x32_bf16 v[158:161], v[8:11], v[110:113], v[158:161]
	v_mfma_f32_16x16x32_bf16 v[166:169], v[8:11], v[122:125], v[166:169]
	v_mfma_f32_16x16x32_bf16 v[4:7], v[8:11], v[130:133], v[4:7]
	v_mfma_f32_16x16x32_bf16 v[8:11], v[12:15], v[126:129], 0
	v_mfma_f32_16x16x32_bf16 v[142:145], v[12:15], v[64:67], 0
	v_mfma_f32_16x16x32_bf16 v[162:165], v[12:15], v[96:99], 0
	v_mfma_f32_16x16x32_bf16 v[170:173], v[12:15], v[114:117], 0
	v_mfma_f32_16x16x32_bf16 v[8:11], v[16:19], v[130:133], v[8:11]
	v_mfma_f32_16x16x32_bf16 v[142:145], v[16:19], v[92:95], v[142:145]
	v_mfma_f32_16x16x32_bf16 v[162:165], v[16:19], v[110:113], v[162:165]
	v_mfma_f32_16x16x32_bf16 v[170:173], v[16:19], v[122:125], v[170:173]
	v_mfma_f32_16x16x32_bf16 v[12:15], v[20:23], v[64:67], 0
	v_mfma_f32_16x16x32_bf16 v[174:177], v[24:27], v[92:95], v[12:15]
	v_mfma_f32_16x16x32_bf16 v[12:15], v[28:31], v[64:67], 0
	v_mfma_f32_16x16x32_bf16 v[178:181], v[32:35], v[92:95], v[12:15]
	v_mfma_f32_16x16x32_bf16 v[12:15], v[20:23], v[96:99], 0
	v_mfma_f32_16x16x32_bf16 v[182:185], v[24:27], v[110:113], v[12:15]
	v_mfma_f32_16x16x32_bf16 v[12:15], v[28:31], v[96:99], 0
	v_mfma_f32_16x16x32_bf16 v[186:189], v[32:35], v[110:113], v[12:15]
	v_mfma_f32_16x16x32_bf16 v[12:15], v[20:23], v[114:117], 0
	v_mfma_f32_16x16x32_bf16 v[190:193], v[24:27], v[122:125], v[12:15]
	v_mfma_f32_16x16x32_bf16 v[12:15], v[28:31], v[114:117], 0
	v_mfma_f32_16x16x32_bf16 v[194:197], v[32:35], v[122:125], v[12:15]
	v_mfma_f32_16x16x32_bf16 v[12:15], v[20:23], v[126:129], 0
	v_mfma_f32_16x16x32_bf16 v[198:201], v[24:27], v[130:133], v[12:15]
	v_mfma_f32_16x16x32_bf16 v[12:15], v[28:31], v[126:129], 0
	v_mfma_f32_16x16x32_bf16 v[202:205], v[32:35], v[130:133], v[12:15]
	s_barrier
; #define PG8_KSETUP() const bool last = (t == nt - 2); const char* a1 = cA + (size_t)(t + 1) * kstep; \
;             const char* a2 = last ? nA : cA + (size_t)(t + 2) * kstep; const char* b2 = last ? nB : cB + (size_t)(t + 2) * kstep; const char* a3 = a2 + kstep; const char* b3 = b2 + kstep; \
;             if (last && has_next) S.a_ready(nxt)
; template <class Epi, class Sched, bool ALIGN_EPI = false, bool SP2 = false>
; __device__ __forceinline__ void gemm_phase(PG8_LAS unsigned char* lds, const Gemm g, const Sched& S, const Epi& E) {
;     ...
;         int t0 = 0;
;         if constexpr (SP2 && Epi::NVM == 16) { if (ui > 0) { const int t = 0; PG8_KSETUP(); PG8_KITER_SP2(24, 24); t0 = 2; } }
;         if constexpr (SP2 && Epi::NVM == 8) { if (ui > 0) { const int t = 0; PG8_KSETUP(); PG8_KITER_SP2(16, 16); t0 = 2; } }
	s_setprio 0
	s_nop 4
	ds_read_b128 v[12:15], v155
	ds_read_b128 v[16:19], v155 offset:1024
	ds_read_b128 v[22:25], v155 offset:2048
	ds_read_b128 v[26:29], v155 offset:3072
	ds_read_b128 v[206:209], v156
	ds_read_b128 v[210:213], v156 offset:1024
	ds_read_b128 v[214:217], v156 offset:2048
	ds_read_b128 v[218:221], v156 offset:3072
	ds_read_b128 v[30:33], v154 offset:32768
	ds_read_b128 v[64:67], v154 offset:33792
	ds_read_b128 v[222:225], v154 offset:34816
	ds_read_b128 v[226:229], v154 offset:35840
	ds_read_b128 v[230:233], v154 offset:36864
	ds_read_b128 v[234:237], v154 offset:37888
	ds_read_b128 v[238:241], v154 offset:38912
	ds_read_b128 v[242:245], v154 offset:39936
	s_add_u32 s24, s36, 0x80100
	s_addc_u32 s25, s37, 0
	s_mov_b32 m0, s52
	s_nop 0
	global_load_lds_dwordx4 v1, s[24:25] offset:0
	s_nop 0
	s_mov_b32 m0, s53
	s_nop 0
	global_load_lds_dwordx4 v147, s[24:25] offset:0
	s_waitcnt vmcnt(8)
	s_waitcnt lgkmcnt(0)
	s_barrier
	s_setprio 1
	v_mfma_f32_16x16x32_bf16 v[68:71], v[12:15], v[30:33], v[68:71]
	v_mfma_f32_16x16x32_bf16 v[130:133], v[16:19], v[64:67], v[68:71]
	v_mfma_f32_16x16x32_bf16 v[68:71], v[22:25], v[30:33], v[72:75]
	v_mfma_f32_16x16x32_bf16 v[126:129], v[26:29], v[64:67], v[68:71]
	v_mfma_f32_16x16x32_bf16 v[68:71], v[12:15], v[222:225], v[76:79]
	v_mfma_f32_16x16x32_bf16 v[114:117], v[16:19], v[226:229], v[68:71]
	v_mfma_f32_16x16x32_bf16 v[68:71], v[22:25], v[222:225], v[80:83]
	v_mfma_f32_16x16x32_bf16 v[110:113], v[26:29], v[226:229], v[68:71]
	v_mfma_f32_16x16x32_bf16 v[68:71], v[12:15], v[230:233], v[84:87]
	v_mfma_f32_16x16x32_bf16 v[98:101], v[16:19], v[234:237], v[68:71]
	v_mfma_f32_16x16x32_bf16 v[68:71], v[22:25], v[230:233], v[88:91]
	v_mfma_f32_16x16x32_bf16 v[94:97], v[26:29], v[234:237], v[68:71]
	v_mfma_f32_16x16x32_bf16 v[68:71], v[12:15], v[238:241], v[102:105]
	v_mfma_f32_16x16x32_bf16 v[82:85], v[16:19], v[242:245], v[68:71]
	v_mfma_f32_16x16x32_bf16 v[68:71], v[22:25], v[238:241], v[106:109]
	v_mfma_f32_16x16x32_bf16 v[78:81], v[26:29], v[242:245], v[68:71]
	v_mfma_f32_16x16x32_bf16 v[68:71], v[206:209], v[30:33], v[118:121]
	v_mfma_f32_16x16x32_bf16 v[30:33], v[214:217], v[30:33], v[36:39]
	v_mfma_f32_16x16x32_bf16 v[118:121], v[218:221], v[64:67], v[30:33]
	v_mfma_f32_16x16x32_bf16 v[30:33], v[206:209], v[222:225], v[40:43]
	v_mfma_f32_16x16x32_bf16 v[106:109], v[210:213], v[226:229], v[30:33]
	v_mfma_f32_16x16x32_bf16 v[30:33], v[214:217], v[222:225], v[44:47]
	v_mfma_f32_16x16x32_bf16 v[102:105], v[218:221], v[226:229], v[30:33]
	v_mfma_f32_16x16x32_bf16 v[30:33], v[206:209], v[230:233], v[48:51]
	v_mfma_f32_16x16x32_bf16 v[90:93], v[210:213], v[234:237], v[30:33]
	v_mfma_f32_16x16x32_bf16 v[30:33], v[214:217], v[230:233], v[52:55]
	v_mfma_f32_16x16x32_bf16 v[86:89], v[218:221], v[234:237], v[30:33]
	v_mfma_f32_16x16x32_bf16 v[30:33], v[206:209], v[238:241], v[56:59]
	v_mfma_f32_16x16x32_bf16 v[74:77], v[210:213], v[242:245], v[30:33]
	v_mfma_f32_16x16x32_bf16 v[30:33], v[214:217], v[238:241], v[60:63]
	v_mfma_f32_16x16x32_bf16 v[122:125], v[210:213], v[64:67], v[68:71]
	v_mfma_f32_16x16x32_bf16 v[66:69], v[218:221], v[242:245], v[30:33]
	s_barrier
	s_setprio 0
	ds_read_b128 v[38:41], v154 offset:49152
	ds_read_b128 v[42:45], v154 offset:50176
	ds_read_b128 v[222:225], v154 offset:51200
	ds_read_b128 v[226:229], v154 offset:52224
	ds_read_b128 v[230:233], v154 offset:53248
	ds_read_b128 v[234:237], v154 offset:54272
	ds_read_b128 v[238:241], v154 offset:55296
	ds_read_b128 v[242:245], v154 offset:56320
	s_add_u32 s24, s38, 0x180
	s_addc_u32 s25, s39, 0
	s_mov_b32 m0, s54
	s_nop 0
	global_load_lds_dwordx4 v146, s[24:25] offset:0
	s_nop 0
	s_mov_b32 m0, s55
	s_nop 0
	global_load_lds_dwordx4 v148, s[24:25] offset:0
	s_add_u32 s24, s38, 0x80180
	s_addc_u32 s25, s39, 0
	s_mov_b32 m0, s58
	s_nop 0
	global_load_lds_dwordx4 v146, s[24:25] offset:0
	s_nop 0
	s_mov_b32 m0, s59
	s_nop 0
	global_load_lds_dwordx4 v148, s[24:25] offset:0
	s_nop 0
	s_mov_b32 m0, s56
	s_nop 0
	global_load_lds_dwordx4 v1, s[22:23] offset:0
	s_nop 0
	s_mov_b32 m0, s57
	s_nop 0
	global_load_lds_dwordx4 v147, s[22:23] offset:0
	s_waitcnt vmcnt(8)
	s_waitcnt lgkmcnt(0)
	s_barrier
	s_setprio 1
	v_mfma_f32_16x16x32_bf16 v[30:33], v[12:15], v[38:41], v[138:141]
	v_mfma_f32_16x16x32_bf16 v[70:73], v[16:19], v[42:45], v[30:33]
	v_mfma_f32_16x16x32_bf16 v[30:33], v[22:25], v[38:41], v[142:145]
	v_mfma_f32_16x16x32_bf16 v[62:65], v[26:29], v[42:45], v[30:33]
	v_mfma_f32_16x16x32_bf16 v[30:33], v[12:15], v[222:225], v[158:161]
	v_mfma_f32_16x16x32_bf16 v[50:53], v[16:19], v[226:229], v[30:33]
	v_mfma_f32_16x16x32_bf16 v[30:33], v[22:25], v[222:225], v[162:165]
	v_mfma_f32_16x16x32_bf16 v[46:49], v[26:29], v[226:229], v[30:33]
	v_mfma_f32_16x16x32_bf16 v[30:33], v[12:15], v[230:233], v[166:169]
	v_mfma_f32_16x16x32_bf16 v[4:7], v[12:15], v[238:241], v[4:7]
	v_mfma_f32_16x16x32_bf16 v[34:37], v[16:19], v[234:237], v[30:33]
	v_mfma_f32_16x16x32_bf16 v[30:33], v[22:25], v[230:233], v[170:173]
	v_mfma_f32_16x16x32_bf16 v[18:21], v[16:19], v[242:245], v[4:7]
	v_mfma_f32_16x16x32_bf16 v[4:7], v[22:25], v[238:241], v[8:11]
	v_mfma_f32_16x16x32_bf16 v[30:33], v[26:29], v[234:237], v[30:33]
	v_mfma_f32_16x16x32_bf16 v[14:17], v[26:29], v[242:245], v[4:7]
	v_mfma_f32_16x16x32_bf16 v[4:7], v[206:209], v[38:41], v[174:177]
	v_mfma_f32_16x16x32_bf16 v[58:61], v[210:213], v[42:45], v[4:7]
	v_mfma_f32_16x16x32_bf16 v[4:7], v[214:217], v[38:41], v[178:181]
	v_mfma_f32_16x16x32_bf16 v[54:57], v[218:221], v[42:45], v[4:7]
	v_mfma_f32_16x16x32_bf16 v[4:7], v[206:209], v[222:225], v[182:185]
	v_mfma_f32_16x16x32_bf16 v[42:45], v[210:213], v[226:229], v[4:7]
	v_mfma_f32_16x16x32_bf16 v[4:7], v[214:217], v[222:225], v[186:189]
	v_mfma_f32_16x16x32_bf16 v[38:41], v[218:221], v[226:229], v[4:7]
	v_mfma_f32_16x16x32_bf16 v[4:7], v[206:209], v[230:233], v[190:193]
	v_mfma_f32_16x16x32_bf16 v[26:29], v[210:213], v[234:237], v[4:7]
	v_mfma_f32_16x16x32_bf16 v[4:7], v[214:217], v[230:233], v[194:197]
	v_mfma_f32_16x16x32_bf16 v[22:25], v[218:221], v[234:237], v[4:7]
	v_mfma_f32_16x16x32_bf16 v[4:7], v[206:209], v[238:241], v[198:201]
	v_mfma_f32_16x16x32_bf16 v[10:13], v[210:213], v[242:245], v[4:7]
	v_mfma_f32_16x16x32_bf16 v[4:7], v[214:217], v[238:241], v[202:205]
	v_mfma_f32_16x16x32_bf16 v[6:9], v[218:221], v[242:245], v[4:7]
	s_barrier
	s_setprio 0
	s_mov_b32 s40, 2
	s_branch .LBB0_2872

.LBB0_2873:
	ds_read_b128 v[138:141], v152
	ds_read_b128 v[142:145], v152 offset:1024
	ds_read_b128 v[158:161], v152 offset:2048
	ds_read_b128 v[162:165], v152 offset:3072
	ds_read_b128 v[166:169], v153
	ds_read_b128 v[170:173], v153 offset:1024
	ds_read_b128 v[174:177], v153 offset:2048
	ds_read_b128 v[178:181], v153 offset:3072
	s_cmp_eq_u32 s76, 28
	s_cselect_b32 s40, s74, s79
	s_cselect_b32 s41, s19, s80
	s_cselect_b32 s38, s75, s77
	s_cselect_b32 s39, s17, s78
	s_add_u32 s36, s40, 0x80
	s_addc_u32 s37, s41, 0
	ds_read_b128 v[182:185], v154
	ds_read_b128 v[186:189], v154 offset:1024
	ds_read_b128 v[190:193], v154 offset:2048
	ds_read_b128 v[194:197], v154 offset:3072
	ds_read_b128 v[198:201], v154 offset:4096
	ds_read_b128 v[202:205], v154 offset:5120
	ds_read_b128 v[206:209], v154 offset:6144
	ds_read_b128 v[210:213], v154 offset:7168
	s_add_u32 s30, s79, 0x7ff80
	s_addc_u32 s31, s80, 0
	s_mov_b32 m0, s64
	s_nop 0
	global_load_lds_dwordx4 v1, s[30:31] offset:0
	s_nop 0
	s_mov_b32 m0, s65
	s_nop 0
	global_load_lds_dwordx4 v147, s[30:31] offset:0
	s_waitcnt vmcnt(8)
	s_waitcnt lgkmcnt(0)
	s_barrier
	s_setprio 1
	v_mfma_f32_16x16x32_bf16 v[130:133], v[138:141], v[182:185], v[130:133]
	v_mfma_f32_16x16x32_bf16 v[130:133], v[142:145], v[186:189], v[130:133]
	v_mfma_f32_16x16x32_bf16 v[126:129], v[158:161], v[182:185], v[126:129]
	v_mfma_f32_16x16x32_bf16 v[126:129], v[162:165], v[186:189], v[126:129]
	v_mfma_f32_16x16x32_bf16 v[114:117], v[138:141], v[190:193], v[114:117]
	v_mfma_f32_16x16x32_bf16 v[114:117], v[142:145], v[194:197], v[114:117]
	v_mfma_f32_16x16x32_bf16 v[110:113], v[158:161], v[190:193], v[110:113]
	v_mfma_f32_16x16x32_bf16 v[110:113], v[162:165], v[194:197], v[110:113]
	v_mfma_f32_16x16x32_bf16 v[98:101], v[138:141], v[198:201], v[98:101]
	v_mfma_f32_16x16x32_bf16 v[98:101], v[142:145], v[202:205], v[98:101]
	v_mfma_f32_16x16x32_bf16 v[94:97], v[158:161], v[198:201], v[94:97]
	v_mfma_f32_16x16x32_bf16 v[94:97], v[162:165], v[202:205], v[94:97]
	v_mfma_f32_16x16x32_bf16 v[82:85], v[138:141], v[206:209], v[82:85]
	v_mfma_f32_16x16x32_bf16 v[82:85], v[142:145], v[210:213], v[82:85]
	v_mfma_f32_16x16x32_bf16 v[78:81], v[158:161], v[206:209], v[78:81]
	v_mfma_f32_16x16x32_bf16 v[78:81], v[162:165], v[210:213], v[78:81]
	v_mfma_f32_16x16x32_bf16 v[122:125], v[166:169], v[182:185], v[122:125]
	v_mfma_f32_16x16x32_bf16 v[122:125], v[170:173], v[186:189], v[122:125]
	v_mfma_f32_16x16x32_bf16 v[118:121], v[174:177], v[182:185], v[118:121]
	v_mfma_f32_16x16x32_bf16 v[118:121], v[178:181], v[186:189], v[118:121]
	v_mfma_f32_16x16x32_bf16 v[106:109], v[166:169], v[190:193], v[106:109]
	v_mfma_f32_16x16x32_bf16 v[106:109], v[170:173], v[194:197], v[106:109]
	v_mfma_f32_16x16x32_bf16 v[102:105], v[174:177], v[190:193], v[102:105]
	v_mfma_f32_16x16x32_bf16 v[102:105], v[178:181], v[194:197], v[102:105]
	v_mfma_f32_16x16x32_bf16 v[90:93], v[166:169], v[198:201], v[90:93]
	v_mfma_f32_16x16x32_bf16 v[90:93], v[170:173], v[202:205], v[90:93]
	v_mfma_f32_16x16x32_bf16 v[86:89], v[174:177], v[198:201], v[86:89]
	v_mfma_f32_16x16x32_bf16 v[86:89], v[178:181], v[202:205], v[86:89]
	v_mfma_f32_16x16x32_bf16 v[74:77], v[166:169], v[206:209], v[74:77]
	v_mfma_f32_16x16x32_bf16 v[74:77], v[170:173], v[210:213], v[74:77]
	v_mfma_f32_16x16x32_bf16 v[66:69], v[174:177], v[206:209], v[66:69]
	v_mfma_f32_16x16x32_bf16 v[66:69], v[178:181], v[210:213], v[66:69]
	s_barrier
	s_setprio 0
	ds_read_b128 v[182:185], v154 offset:16384
	ds_read_b128 v[186:189], v154 offset:17408
	ds_read_b128 v[190:193], v154 offset:18432
	ds_read_b128 v[194:197], v154 offset:19456
	ds_read_b128 v[198:201], v154 offset:20480
	ds_read_b128 v[202:205], v154 offset:21504
	ds_read_b128 v[206:209], v154 offset:22528
	ds_read_b128 v[210:213], v154 offset:23552
	s_mov_b32 m0, s29
	s_nop 0
	global_load_lds_dwordx4 v146, s[38:39] offset:0
	s_add_u32 s30, s38, 0x80000
	s_mov_b32 m0, s44
	s_nop 0
	global_load_lds_dwordx4 v148, s[38:39] offset:0
	s_addc_u32 s31, s39, 0
	s_mov_b32 m0, s45
	s_nop 0
	global_load_lds_dwordx4 v146, s[30:31] offset:0
	s_nop 0
	s_mov_b32 m0, s46
	s_nop 0
	global_load_lds_dwordx4 v148, s[30:31] offset:0
	s_nop 0
	s_mov_b32 m0, s21
	s_nop 0
	global_load_lds_dwordx4 v1, s[40:41] offset:0
	s_nop 0
	s_mov_b32 m0, s47
	s_nop 0
	global_load_lds_dwordx4 v147, s[40:41] offset:0
	s_waitcnt vmcnt(8)
	s_waitcnt lgkmcnt(0)
	s_barrier
	s_setprio 1
	v_mfma_f32_16x16x32_bf16 v[70:73], v[138:141], v[182:185], v[70:73]
	v_mfma_f32_16x16x32_bf16 v[70:73], v[142:145], v[186:189], v[70:73]
	v_mfma_f32_16x16x32_bf16 v[62:65], v[158:161], v[182:185], v[62:65]
	v_mfma_f32_16x16x32_bf16 v[62:65], v[162:165], v[186:189], v[62:65]
	v_mfma_f32_16x16x32_bf16 v[50:53], v[138:141], v[190:193], v[50:53]
	v_mfma_f32_16x16x32_bf16 v[50:53], v[142:145], v[194:197], v[50:53]
	v_mfma_f32_16x16x32_bf16 v[46:49], v[158:161], v[190:193], v[46:49]
	v_mfma_f32_16x16x32_bf16 v[46:49], v[162:165], v[194:197], v[46:49]
	v_mfma_f32_16x16x32_bf16 v[34:37], v[138:141], v[198:201], v[34:37]
	v_mfma_f32_16x16x32_bf16 v[34:37], v[142:145], v[202:205], v[34:37]
	v_mfma_f32_16x16x32_bf16 v[30:33], v[158:161], v[198:201], v[30:33]
	v_mfma_f32_16x16x32_bf16 v[30:33], v[162:165], v[202:205], v[30:33]
	v_mfma_f32_16x16x32_bf16 v[18:21], v[138:141], v[206:209], v[18:21]
	v_mfma_f32_16x16x32_bf16 v[18:21], v[142:145], v[210:213], v[18:21]
	v_mfma_f32_16x16x32_bf16 v[14:17], v[158:161], v[206:209], v[14:17]
	v_mfma_f32_16x16x32_bf16 v[14:17], v[162:165], v[210:213], v[14:17]
	v_mfma_f32_16x16x32_bf16 v[58:61], v[166:169], v[182:185], v[58:61]
	v_mfma_f32_16x16x32_bf16 v[54:57], v[174:177], v[182:185], v[54:57]
	v_mfma_f32_16x16x32_bf16 v[42:45], v[166:169], v[190:193], v[42:45]
	v_mfma_f32_16x16x32_bf16 v[38:41], v[174:177], v[190:193], v[38:41]
	v_mfma_f32_16x16x32_bf16 v[26:29], v[166:169], v[198:201], v[26:29]
	v_mfma_f32_16x16x32_bf16 v[22:25], v[174:177], v[198:201], v[22:25]
	v_mfma_f32_16x16x32_bf16 v[10:13], v[166:169], v[206:209], v[10:13]
	v_mfma_f32_16x16x32_bf16 v[4:7], v[174:177], v[206:209], v[6:9]
	v_mfma_f32_16x16x32_bf16 v[58:61], v[170:173], v[186:189], v[58:61]
	v_mfma_f32_16x16x32_bf16 v[54:57], v[178:181], v[186:189], v[54:57]
	v_mfma_f32_16x16x32_bf16 v[42:45], v[170:173], v[194:197], v[42:45]
	v_mfma_f32_16x16x32_bf16 v[38:41], v[178:181], v[194:197], v[38:41]
	v_mfma_f32_16x16x32_bf16 v[26:29], v[170:173], v[202:205], v[26:29]
	v_mfma_f32_16x16x32_bf16 v[22:25], v[178:181], v[202:205], v[22:25]
	v_mfma_f32_16x16x32_bf16 v[10:13], v[170:173], v[210:213], v[10:13]
	v_mfma_f32_16x16x32_bf16 v[4:7], v[178:181], v[210:213], v[4:7]
	s_barrier
; #define PG8_BAR __builtin_amdgcn_s_barrier()
; #define PG8_KSETUP() const bool last = (t == nt - 2); const char* a1 = cA + (size_t)(t + 1) * kstep; \
;             const char* a2 = last ? nA : cA + (size_t)(t + 2) * kstep; const char* b2 = last ? nB : cB + (size_t)(t + 2) * kstep; const char* a3 = a2 + kstep; const char* b3 = b2 + kstep; \
;             if (last && has_next) S.a_ready(nxt)
; template <class Epi, class Sched, bool ALIGN_EPI = false, bool SP2 = false>
; __device__ __forceinline__ void gemm_phase(PG8_LAS unsigned char* lds, const Gemm g, const Sched& S, const Epi& E) {
;     ...
;         int t0 = 0;
;         if constexpr (SP2 && Epi::NVM == 16) { if (ui > 0) { const int t = 0; PG8_KSETUP(); PG8_KITER_SP2(24, 24); t0 = 2; } }
;         if constexpr (SP2 && Epi::NVM == 8) { if (ui > 0) { const int t = 0; PG8_KSETUP(); PG8_KITER_SP2(16, 16); t0 = 2; } }
;         for (int t = t0; t < nt; t += 2) {
;     ...
;         if constexpr (ALIGN_EPI) { if (wr == 0) PG8_BAR; }
	s_setprio 0
	ds_read_b128 v[138:141], v155
	ds_read_b128 v[142:145], v155 offset:1024
	ds_read_b128 v[158:161], v155 offset:2048
	ds_read_b128 v[162:165], v155 offset:3072
	ds_read_b128 v[166:169], v156
	ds_read_b128 v[170:173], v156 offset:1024
	ds_read_b128 v[174:177], v156 offset:2048
	ds_read_b128 v[178:181], v156 offset:3072
	ds_read_b128 v[182:185], v154 offset:32768
	ds_read_b128 v[186:189], v154 offset:33792
	ds_read_b128 v[190:193], v154 offset:34816
	ds_read_b128 v[194:197], v154 offset:35840
	ds_read_b128 v[198:201], v154 offset:36864
	ds_read_b128 v[202:205], v154 offset:37888
	ds_read_b128 v[206:209], v154 offset:38912
	ds_read_b128 v[210:213], v154 offset:39936
	s_add_u32 s30, s40, 0x80000
	s_addc_u32 s31, s41, 0
	s_mov_b32 m0, s52
	s_nop 0
	global_load_lds_dwordx4 v1, s[30:31] offset:0
	s_nop 0
	s_mov_b32 m0, s53
	s_nop 0
	global_load_lds_dwordx4 v147, s[30:31] offset:0
	s_waitcnt vmcnt(8)
	s_waitcnt lgkmcnt(0)
	s_barrier
	s_setprio 1
	v_mfma_f32_16x16x32_bf16 v[130:133], v[138:141], v[182:185], v[130:133]
	v_mfma_f32_16x16x32_bf16 v[130:133], v[142:145], v[186:189], v[130:133]
	v_mfma_f32_16x16x32_bf16 v[126:129], v[158:161], v[182:185], v[126:129]
	v_mfma_f32_16x16x32_bf16 v[126:129], v[162:165], v[186:189], v[126:129]
	v_mfma_f32_16x16x32_bf16 v[114:117], v[138:141], v[190:193], v[114:117]
	v_mfma_f32_16x16x32_bf16 v[114:117], v[142:145], v[194:197], v[114:117]
	v_mfma_f32_16x16x32_bf16 v[110:113], v[158:161], v[190:193], v[110:113]
	v_mfma_f32_16x16x32_bf16 v[110:113], v[162:165], v[194:197], v[110:113]
	v_mfma_f32_16x16x32_bf16 v[98:101], v[138:141], v[198:201], v[98:101]
	v_mfma_f32_16x16x32_bf16 v[98:101], v[142:145], v[202:205], v[98:101]
	v_mfma_f32_16x16x32_bf16 v[94:97], v[158:161], v[198:201], v[94:97]
	v_mfma_f32_16x16x32_bf16 v[94:97], v[162:165], v[202:205], v[94:97]
	v_mfma_f32_16x16x32_bf16 v[82:85], v[138:141], v[206:209], v[82:85]
	v_mfma_f32_16x16x32_bf16 v[82:85], v[142:145], v[210:213], v[82:85]
	v_mfma_f32_16x16x32_bf16 v[78:81], v[158:161], v[206:209], v[78:81]
	v_mfma_f32_16x16x32_bf16 v[78:81], v[162:165], v[210:213], v[78:81]
	v_mfma_f32_16x16x32_bf16 v[122:125], v[166:169], v[182:185], v[122:125]
	v_mfma_f32_16x16x32_bf16 v[122:125], v[170:173], v[186:189], v[122:125]
	v_mfma_f32_16x16x32_bf16 v[118:121], v[174:177], v[182:185], v[118:121]
	v_mfma_f32_16x16x32_bf16 v[118:121], v[178:181], v[186:189], v[118:121]
	v_mfma_f32_16x16x32_bf16 v[106:109], v[166:169], v[190:193], v[106:109]
	v_mfma_f32_16x16x32_bf16 v[106:109], v[170:173], v[194:197], v[106:109]
	v_mfma_f32_16x16x32_bf16 v[102:105], v[174:177], v[190:193], v[102:105]
	v_mfma_f32_16x16x32_bf16 v[102:105], v[178:181], v[194:197], v[102:105]
	v_mfma_f32_16x16x32_bf16 v[90:93], v[166:169], v[198:201], v[90:93]
	v_mfma_f32_16x16x32_bf16 v[90:93], v[170:173], v[202:205], v[90:93]
	v_mfma_f32_16x16x32_bf16 v[86:89], v[174:177], v[198:201], v[86:89]
	v_mfma_f32_16x16x32_bf16 v[86:89], v[178:181], v[202:205], v[86:89]
	v_mfma_f32_16x16x32_bf16 v[74:77], v[166:169], v[206:209], v[74:77]
	v_mfma_f32_16x16x32_bf16 v[74:77], v[170:173], v[210:213], v[74:77]
	v_mfma_f32_16x16x32_bf16 v[66:69], v[174:177], v[206:209], v[66:69]
	v_mfma_f32_16x16x32_bf16 v[66:69], v[178:181], v[210:213], v[66:69]
	s_barrier
	s_setprio 0
	ds_read_b128 v[182:185], v154 offset:49152
	ds_read_b128 v[186:189], v154 offset:50176
	ds_read_b128 v[190:193], v154 offset:51200
	ds_read_b128 v[194:197], v154 offset:52224
	ds_read_b128 v[198:201], v154 offset:53248
	ds_read_b128 v[202:205], v154 offset:54272
	ds_read_b128 v[206:209], v154 offset:55296
	ds_read_b128 v[210:213], v154 offset:56320
	s_add_u32 s30, s38, 0x80
	s_addc_u32 s31, s39, 0
	s_mov_b32 m0, s54
	s_nop 0
	global_load_lds_dwordx4 v146, s[30:31] offset:0
	s_nop 0
	s_mov_b32 m0, s55
	s_nop 0
	global_load_lds_dwordx4 v148, s[30:31] offset:0
	s_add_u32 s30, s38, 0x80080
	s_addc_u32 s31, s39, 0
	s_mov_b32 m0, s58
	s_nop 0
	global_load_lds_dwordx4 v146, s[30:31] offset:0
	s_nop 0
	s_mov_b32 m0, s59
	s_nop 0
	global_load_lds_dwordx4 v148, s[30:31] offset:0
	s_nop 0
	s_mov_b32 m0, s56
	s_nop 0
	global_load_lds_dwordx4 v1, s[36:37] offset:0
	s_nop 0
	s_mov_b32 m0, s57
	s_nop 0
	global_load_lds_dwordx4 v147, s[36:37] offset:0
	s_waitcnt vmcnt(8)
	s_waitcnt lgkmcnt(0)
	s_barrier
	s_setprio 1
	v_mfma_f32_16x16x32_bf16 v[70:73], v[138:141], v[182:185], v[70:73]
	v_mfma_f32_16x16x32_bf16 v[70:73], v[142:145], v[186:189], v[70:73]
	v_mfma_f32_16x16x32_bf16 v[62:65], v[158:161], v[182:185], v[62:65]
	v_mfma_f32_16x16x32_bf16 v[62:65], v[162:165], v[186:189], v[62:65]
	v_mfma_f32_16x16x32_bf16 v[50:53], v[138:141], v[190:193], v[50:53]
	v_mfma_f32_16x16x32_bf16 v[50:53], v[142:145], v[194:197], v[50:53]
	v_mfma_f32_16x16x32_bf16 v[46:49], v[158:161], v[190:193], v[46:49]
	v_mfma_f32_16x16x32_bf16 v[46:49], v[162:165], v[194:197], v[46:49]
	v_mfma_f32_16x16x32_bf16 v[34:37], v[138:141], v[198:201], v[34:37]
	v_mfma_f32_16x16x32_bf16 v[34:37], v[142:145], v[202:205], v[34:37]
	v_mfma_f32_16x16x32_bf16 v[30:33], v[158:161], v[198:201], v[30:33]
	v_mfma_f32_16x16x32_bf16 v[30:33], v[162:165], v[202:205], v[30:33]
	v_mfma_f32_16x16x32_bf16 v[18:21], v[138:141], v[206:209], v[18:21]
	v_mfma_f32_16x16x32_bf16 v[18:21], v[142:145], v[210:213], v[18:21]
	v_mfma_f32_16x16x32_bf16 v[14:17], v[158:161], v[206:209], v[14:17]
	v_mfma_f32_16x16x32_bf16 v[14:17], v[162:165], v[210:213], v[14:17]
	v_mfma_f32_16x16x32_bf16 v[58:61], v[166:169], v[182:185], v[58:61]
	v_mfma_f32_16x16x32_bf16 v[54:57], v[174:177], v[182:185], v[54:57]
	v_mfma_f32_16x16x32_bf16 v[42:45], v[166:169], v[190:193], v[42:45]
	v_mfma_f32_16x16x32_bf16 v[38:41], v[174:177], v[190:193], v[38:41]
	v_mfma_f32_16x16x32_bf16 v[26:29], v[166:169], v[198:201], v[26:29]
	v_mfma_f32_16x16x32_bf16 v[22:25], v[174:177], v[198:201], v[22:25]
	v_mfma_f32_16x16x32_bf16 v[8:11], v[166:169], v[206:209], v[10:13]
	v_mfma_f32_16x16x32_bf16 v[4:7], v[174:177], v[206:209], v[4:7]
	v_mfma_f32_16x16x32_bf16 v[58:61], v[170:173], v[186:189], v[58:61]
	v_mfma_f32_16x16x32_bf16 v[54:57], v[178:181], v[186:189], v[54:57]
	v_mfma_f32_16x16x32_bf16 v[42:45], v[170:173], v[194:197], v[42:45]
	v_mfma_f32_16x16x32_bf16 v[38:41], v[178:181], v[194:197], v[38:41]
	v_mfma_f32_16x16x32_bf16 v[26:29], v[170:173], v[202:205], v[26:29]
	v_mfma_f32_16x16x32_bf16 v[22:25], v[178:181], v[202:205], v[22:25]
	v_mfma_f32_16x16x32_bf16 v[10:13], v[170:173], v[210:213], v[8:11]
	v_mfma_f32_16x16x32_bf16 v[6:9], v[178:181], v[210:213], v[4:7]
	s_barrier
	s_setprio 0
	s_add_i32 s76, s76, 2
	s_add_u32 s77, s77, 0x100
	s_addc_u32 s78, s78, 0
	s_add_u32 s79, s79, 0x100
	s_addc_u32 s80, s80, 0
	s_cmp_gt_u32 s76, 29
	s_cbranch_scc0 .LBB0_2873
	s_and_b64 vcc, exec, s[14:15]
	s_cbranch_vccz .LBB0_2876
	s_barrier

; #define PG8_KSETUP() const bool last = (t == nt - 2); const char* a1 = cA + (size_t)(t + 1) * kstep; \
;             const char* a2 = last ? nA : cA + (size_t)(t + 2) * kstep; const char* b2 = last ? nB : cB + (size_t)(t + 2) * kstep; const char* a3 = a2 + kstep; const char* b3 = b2 + kstep; \
;             if (last && has_next) S.a_ready(nxt)
; template <class Epi, class Sched, bool ALIGN_EPI = false, bool SP2 = false>
; __device__ __forceinline__ void gemm_phase(PG8_LAS unsigned char* lds, const Gemm g, const Sched& S, const Epi& E) {
;     ...
;         if constexpr (SP2 && Epi::NVM == 16) { if (ui > 0) { const int t = 0; PG8_KSETUP(); PG8_KITER_SP2(24, 24); t0 = 2; } }
.LBB0_2955:
	ds_read_b128 v[4:7], v147
	ds_read_b128 v[8:11], v147 offset:1024
	ds_read_b128 v[12:15], v147 offset:2048
	ds_read_b128 v[16:19], v147 offset:3072
	ds_read_b128 v[20:23], v148
	ds_read_b128 v[24:27], v148 offset:1024
	ds_read_b128 v[28:31], v148 offset:2048
	ds_read_b128 v[32:35], v148 offset:3072
	s_add_u32 s42, s36, 0x100
	s_addc_u32 s43, s37, 0
	s_add_u32 s30, s38, 0x100
	s_addc_u32 s31, s39, 0
	s_add_u32 s40, s36, 0x180
	s_addc_u32 s41, s37, 0
	ds_read_b128 v[36:39], v149
	ds_read_b128 v[40:43], v149 offset:1024
	ds_read_b128 v[44:47], v149 offset:2048
	ds_read_b128 v[48:51], v149 offset:3072
	ds_read_b128 v[52:55], v149 offset:4096
	ds_read_b128 v[56:59], v149 offset:5120
	ds_read_b128 v[60:63], v149 offset:6144
	ds_read_b128 v[64:67], v149 offset:7168
	s_add_u32 s48, s36, 0x160080
	s_addc_u32 s49, s37, 0
	s_mov_b32 m0, s70
	s_nop 0
	global_load_lds_dwordx4 v1, s[48:49] offset:0
	s_nop 0
	s_mov_b32 m0, s71
	s_nop 0
	global_load_lds_dwordx4 v143, s[48:49] offset:0
	s_waitcnt vmcnt(24)
	s_waitcnt lgkmcnt(0)
	s_barrier
	s_setprio 1
	v_mfma_f32_16x16x32_bf16 v[92:95], v[4:7], v[60:63], 0
	v_mfma_f32_16x16x32_bf16 v[68:71], v[4:7], v[36:39], 0
	v_mfma_f32_16x16x32_bf16 v[72:75], v[12:15], v[36:39], 0
	v_mfma_f32_16x16x32_bf16 v[76:79], v[4:7], v[44:47], 0
	v_mfma_f32_16x16x32_bf16 v[80:83], v[12:15], v[44:47], 0
	v_mfma_f32_16x16x32_bf16 v[84:87], v[4:7], v[52:55], 0
	v_mfma_f32_16x16x32_bf16 v[88:91], v[12:15], v[52:55], 0
	v_mfma_f32_16x16x32_bf16 v[102:105], v[8:11], v[64:67], v[92:95]
	v_mfma_f32_16x16x32_bf16 v[92:95], v[12:15], v[60:63], 0
	v_mfma_f32_16x16x32_bf16 v[68:71], v[8:11], v[40:43], v[68:71]
	v_mfma_f32_16x16x32_bf16 v[72:75], v[16:19], v[40:43], v[72:75]
	v_mfma_f32_16x16x32_bf16 v[76:79], v[8:11], v[48:51], v[76:79]
	v_mfma_f32_16x16x32_bf16 v[80:83], v[16:19], v[48:51], v[80:83]
	v_mfma_f32_16x16x32_bf16 v[84:87], v[8:11], v[56:59], v[84:87]
	v_mfma_f32_16x16x32_bf16 v[88:91], v[16:19], v[56:59], v[88:91]
	v_mfma_f32_16x16x32_bf16 v[106:109], v[16:19], v[64:67], v[92:95]
	v_mfma_f32_16x16x32_bf16 v[92:95], v[20:23], v[36:39], 0
	v_mfma_f32_16x16x32_bf16 v[36:39], v[28:31], v[36:39], 0
	v_mfma_f32_16x16x32_bf16 v[118:121], v[24:27], v[40:43], v[92:95]
	v_mfma_f32_16x16x32_bf16 v[36:39], v[32:35], v[40:43], v[36:39]
	v_mfma_f32_16x16x32_bf16 v[40:43], v[20:23], v[44:47], 0
	v_mfma_f32_16x16x32_bf16 v[44:47], v[28:31], v[44:47], 0
	v_mfma_f32_16x16x32_bf16 v[40:43], v[24:27], v[48:51], v[40:43]
	v_mfma_f32_16x16x32_bf16 v[44:47], v[32:35], v[48:51], v[44:47]
	v_mfma_f32_16x16x32_bf16 v[48:51], v[20:23], v[52:55], 0
	v_mfma_f32_16x16x32_bf16 v[52:55], v[28:31], v[52:55], 0
	v_mfma_f32_16x16x32_bf16 v[48:51], v[24:27], v[56:59], v[48:51]
	v_mfma_f32_16x16x32_bf16 v[52:55], v[32:35], v[56:59], v[52:55]
	v_mfma_f32_16x16x32_bf16 v[56:59], v[20:23], v[60:63], 0
	v_mfma_f32_16x16x32_bf16 v[60:63], v[28:31], v[60:63], 0
	v_mfma_f32_16x16x32_bf16 v[56:59], v[24:27], v[64:67], v[56:59]
	v_mfma_f32_16x16x32_bf16 v[60:63], v[32:35], v[64:67], v[60:63]
	s_barrier
	s_setprio 0
	ds_read_b128 v[64:67], v149 offset:16384
	ds_read_b128 v[92:95], v149 offset:17408
	ds_read_b128 v[96:99], v149 offset:18432
	ds_read_b128 v[110:113], v149 offset:19456
	ds_read_b128 v[114:117], v149 offset:20480
	ds_read_b128 v[122:125], v149 offset:21504
	ds_read_b128 v[126:129], v149 offset:22528
	ds_read_b128 v[130:133], v149 offset:23552
	s_mov_b32 m0, s46
	s_nop 0
	global_load_lds_dwordx4 v142, s[30:31] offset:0
	s_nop 0
	s_mov_b32 m0, s47
	s_nop 0
	global_load_lds_dwordx4 v144, s[30:31] offset:0
	s_add_u32 s30, s38, 0x160100
	s_addc_u32 s31, s39, 0
	s_mov_b32 m0, s52
	s_nop 0
	global_load_lds_dwordx4 v142, s[30:31] offset:0
	s_nop 0
	s_mov_b32 m0, s53
	s_nop 0
	global_load_lds_dwordx4 v144, s[30:31] offset:0
	s_nop 0
	s_mov_b32 m0, s45
	s_nop 0
	global_load_lds_dwordx4 v1, s[42:43] offset:0
	s_nop 0
	s_mov_b32 m0, s54
	s_nop 0
	global_load_lds_dwordx4 v143, s[42:43] offset:0
	s_waitcnt vmcnt(24)
	s_waitcnt lgkmcnt(0)
	s_barrier
	s_setprio 1
	v_mfma_f32_16x16x32_bf16 v[138:141], v[4:7], v[64:67], 0
	v_mfma_f32_16x16x32_bf16 v[156:159], v[4:7], v[96:99], 0
	v_mfma_f32_16x16x32_bf16 v[164:167], v[4:7], v[114:117], 0
	v_mfma_f32_16x16x32_bf16 v[4:7], v[4:7], v[126:129], 0
	v_mfma_f32_16x16x32_bf16 v[138:141], v[8:11], v[92:95], v[138:141]
	v_mfma_f32_16x16x32_bf16 v[156:159], v[8:11], v[110:113], v[156:159]
	v_mfma_f32_16x16x32_bf16 v[164:167], v[8:11], v[122:125], v[164:167]
	v_mfma_f32_16x16x32_bf16 v[4:7], v[8:11], v[130:133], v[4:7]
	v_mfma_f32_16x16x32_bf16 v[8:11], v[12:15], v[126:129], 0
	v_mfma_f32_16x16x32_bf16 v[152:155], v[12:15], v[64:67], 0
	v_mfma_f32_16x16x32_bf16 v[160:163], v[12:15], v[96:99], 0
	v_mfma_f32_16x16x32_bf16 v[168:171], v[12:15], v[114:117], 0
	v_mfma_f32_16x16x32_bf16 v[8:11], v[16:19], v[130:133], v[8:11]
	v_mfma_f32_16x16x32_bf16 v[152:155], v[16:19], v[92:95], v[152:155]
	v_mfma_f32_16x16x32_bf16 v[160:163], v[16:19], v[110:113], v[160:163]
	v_mfma_f32_16x16x32_bf16 v[168:171], v[16:19], v[122:125], v[168:171]
	v_mfma_f32_16x16x32_bf16 v[12:15], v[20:23], v[64:67], 0
	v_mfma_f32_16x16x32_bf16 v[172:175], v[24:27], v[92:95], v[12:15]
	v_mfma_f32_16x16x32_bf16 v[12:15], v[28:31], v[64:67], 0
	v_mfma_f32_16x16x32_bf16 v[176:179], v[32:35], v[92:95], v[12:15]
	v_mfma_f32_16x16x32_bf16 v[12:15], v[20:23], v[96:99], 0
	v_mfma_f32_16x16x32_bf16 v[180:183], v[24:27], v[110:113], v[12:15]
	v_mfma_f32_16x16x32_bf16 v[12:15], v[28:31], v[96:99], 0
	v_mfma_f32_16x16x32_bf16 v[184:187], v[32:35], v[110:113], v[12:15]
	v_mfma_f32_16x16x32_bf16 v[12:15], v[20:23], v[114:117], 0
	v_mfma_f32_16x16x32_bf16 v[188:191], v[24:27], v[122:125], v[12:15]
	v_mfma_f32_16x16x32_bf16 v[12:15], v[28:31], v[114:117], 0
	v_mfma_f32_16x16x32_bf16 v[192:195], v[32:35], v[122:125], v[12:15]
	v_mfma_f32_16x16x32_bf16 v[12:15], v[20:23], v[126:129], 0
	v_mfma_f32_16x16x32_bf16 v[196:199], v[24:27], v[130:133], v[12:15]
	v_mfma_f32_16x16x32_bf16 v[12:15], v[28:31], v[126:129], 0
	v_mfma_f32_16x16x32_bf16 v[200:203], v[32:35], v[130:133], v[12:15]
	s_barrier
; #define PG8_KSETUP() const bool last = (t == nt - 2); const char* a1 = cA + (size_t)(t + 1) * kstep; \
;             const char* a2 = last ? nA : cA + (size_t)(t + 2) * kstep; const char* b2 = last ? nB : cB + (size_t)(t + 2) * kstep; const char* a3 = a2 + kstep; const char* b3 = b2 + kstep; \
;             if (last && has_next) S.a_ready(nxt)
; template <class Epi, class Sched, bool ALIGN_EPI = false, bool SP2 = false>
; __device__ __forceinline__ void gemm_phase(PG8_LAS unsigned char* lds, const Gemm g, const Sched& S, const Epi& E) {
;     ...
;         int t0 = 0;
;         if constexpr (SP2 && Epi::NVM == 16) { if (ui > 0) { const int t = 0; PG8_KSETUP(); PG8_KITER_SP2(24, 24); t0 = 2; } }
	s_setprio 0
	s_nop 4
	ds_read_b128 v[12:15], v150
	ds_read_b128 v[16:19], v150 offset:1024
	ds_read_b128 v[22:25], v150 offset:2048
	ds_read_b128 v[26:29], v150 offset:3072
	ds_read_b128 v[204:207], v151
	ds_read_b128 v[208:211], v151 offset:1024
	ds_read_b128 v[212:215], v151 offset:2048
	ds_read_b128 v[216:219], v151 offset:3072
	ds_read_b128 v[30:33], v149 offset:32768
	ds_read_b128 v[64:67], v149 offset:33792
	ds_read_b128 v[220:223], v149 offset:34816
	ds_read_b128 v[224:227], v149 offset:35840
	ds_read_b128 v[228:231], v149 offset:36864
	ds_read_b128 v[232:235], v149 offset:37888
	ds_read_b128 v[236:239], v149 offset:38912
	ds_read_b128 v[240:243], v149 offset:39936
	s_add_u32 s30, s36, 0x160100
	s_addc_u32 s31, s37, 0
	s_mov_b32 m0, s55
	s_nop 0
	global_load_lds_dwordx4 v1, s[30:31] offset:0
	s_nop 0
	s_mov_b32 m0, s56
	s_nop 0
	global_load_lds_dwordx4 v143, s[30:31] offset:0
	s_waitcnt vmcnt(8)
	s_waitcnt lgkmcnt(0)
	s_barrier
	s_setprio 1
	v_mfma_f32_16x16x32_bf16 v[68:71], v[12:15], v[30:33], v[68:71]
	v_mfma_f32_16x16x32_bf16 v[130:133], v[16:19], v[64:67], v[68:71]
	v_mfma_f32_16x16x32_bf16 v[68:71], v[22:25], v[30:33], v[72:75]
	v_mfma_f32_16x16x32_bf16 v[126:129], v[26:29], v[64:67], v[68:71]
	v_mfma_f32_16x16x32_bf16 v[68:71], v[12:15], v[220:223], v[76:79]
	v_mfma_f32_16x16x32_bf16 v[114:117], v[16:19], v[224:227], v[68:71]
	v_mfma_f32_16x16x32_bf16 v[68:71], v[22:25], v[220:223], v[80:83]
	v_mfma_f32_16x16x32_bf16 v[110:113], v[26:29], v[224:227], v[68:71]
	v_mfma_f32_16x16x32_bf16 v[68:71], v[12:15], v[228:231], v[84:87]
	v_mfma_f32_16x16x32_bf16 v[98:101], v[16:19], v[232:235], v[68:71]
	v_mfma_f32_16x16x32_bf16 v[68:71], v[22:25], v[228:231], v[88:91]
	v_mfma_f32_16x16x32_bf16 v[94:97], v[26:29], v[232:235], v[68:71]
	v_mfma_f32_16x16x32_bf16 v[68:71], v[12:15], v[236:239], v[102:105]
	v_mfma_f32_16x16x32_bf16 v[82:85], v[16:19], v[240:243], v[68:71]
	v_mfma_f32_16x16x32_bf16 v[68:71], v[22:25], v[236:239], v[106:109]
	v_mfma_f32_16x16x32_bf16 v[78:81], v[26:29], v[240:243], v[68:71]
	v_mfma_f32_16x16x32_bf16 v[68:71], v[204:207], v[30:33], v[118:121]
	v_mfma_f32_16x16x32_bf16 v[30:33], v[212:215], v[30:33], v[36:39]
	v_mfma_f32_16x16x32_bf16 v[118:121], v[216:219], v[64:67], v[30:33]
	v_mfma_f32_16x16x32_bf16 v[30:33], v[204:207], v[220:223], v[40:43]
	v_mfma_f32_16x16x32_bf16 v[106:109], v[208:211], v[224:227], v[30:33]
	v_mfma_f32_16x16x32_bf16 v[30:33], v[212:215], v[220:223], v[44:47]
	v_mfma_f32_16x16x32_bf16 v[102:105], v[216:219], v[224:227], v[30:33]
	v_mfma_f32_16x16x32_bf16 v[30:33], v[204:207], v[228:231], v[48:51]
	v_mfma_f32_16x16x32_bf16 v[90:93], v[208:211], v[232:235], v[30:33]
	v_mfma_f32_16x16x32_bf16 v[30:33], v[212:215], v[228:231], v[52:55]
	v_mfma_f32_16x16x32_bf16 v[86:89], v[216:219], v[232:235], v[30:33]
	v_mfma_f32_16x16x32_bf16 v[30:33], v[204:207], v[236:239], v[56:59]
	v_mfma_f32_16x16x32_bf16 v[74:77], v[208:211], v[240:243], v[30:33]
	v_mfma_f32_16x16x32_bf16 v[30:33], v[212:215], v[236:239], v[60:63]
	v_mfma_f32_16x16x32_bf16 v[122:125], v[208:211], v[64:67], v[68:71]
	v_mfma_f32_16x16x32_bf16 v[70:73], v[216:219], v[240:243], v[30:33]
	s_barrier
	s_setprio 0
	ds_read_b128 v[38:41], v149 offset:49152
	ds_read_b128 v[42:45], v149 offset:50176
	ds_read_b128 v[220:223], v149 offset:51200
	ds_read_b128 v[224:227], v149 offset:52224
	ds_read_b128 v[228:231], v149 offset:53248
	ds_read_b128 v[232:235], v149 offset:54272
	ds_read_b128 v[236:239], v149 offset:55296
	ds_read_b128 v[240:243], v149 offset:56320
	s_add_u32 s30, s38, 0x180
	s_addc_u32 s31, s39, 0
	s_mov_b32 m0, s64
	s_nop 0
	global_load_lds_dwordx4 v142, s[30:31] offset:0
	s_nop 0
	s_mov_b32 m0, s65
	s_nop 0
	global_load_lds_dwordx4 v144, s[30:31] offset:0
	s_add_u32 s30, s38, 0x160180
	s_addc_u32 s31, s39, 0
	s_mov_b32 m0, s68
	s_nop 0
	global_load_lds_dwordx4 v142, s[30:31] offset:0
	s_nop 0
	s_mov_b32 m0, s69
	s_nop 0
	global_load_lds_dwordx4 v144, s[30:31] offset:0
	s_nop 0
	s_mov_b32 m0, s66
	s_nop 0
	global_load_lds_dwordx4 v1, s[40:41] offset:0
	s_nop 0
	s_mov_b32 m0, s67
	s_nop 0
	global_load_lds_dwordx4 v143, s[40:41] offset:0
	s_waitcnt vmcnt(8)
	s_waitcnt lgkmcnt(0)
	s_barrier
	s_setprio 1
	v_mfma_f32_16x16x32_bf16 v[30:33], v[12:15], v[38:41], v[138:141]
	v_mfma_f32_16x16x32_bf16 v[66:69], v[16:19], v[42:45], v[30:33]
	v_mfma_f32_16x16x32_bf16 v[30:33], v[22:25], v[38:41], v[152:155]
	v_mfma_f32_16x16x32_bf16 v[62:65], v[26:29], v[42:45], v[30:33]
	v_mfma_f32_16x16x32_bf16 v[30:33], v[12:15], v[220:223], v[156:159]
	v_mfma_f32_16x16x32_bf16 v[50:53], v[16:19], v[224:227], v[30:33]
	v_mfma_f32_16x16x32_bf16 v[30:33], v[22:25], v[220:223], v[160:163]
	v_mfma_f32_16x16x32_bf16 v[46:49], v[26:29], v[224:227], v[30:33]
	v_mfma_f32_16x16x32_bf16 v[30:33], v[12:15], v[228:231], v[164:167]
	v_mfma_f32_16x16x32_bf16 v[4:7], v[12:15], v[236:239], v[4:7]
	v_mfma_f32_16x16x32_bf16 v[34:37], v[16:19], v[232:235], v[30:33]
	v_mfma_f32_16x16x32_bf16 v[30:33], v[22:25], v[228:231], v[168:171]
	v_mfma_f32_16x16x32_bf16 v[18:21], v[16:19], v[240:243], v[4:7]
	v_mfma_f32_16x16x32_bf16 v[4:7], v[22:25], v[236:239], v[8:11]
	v_mfma_f32_16x16x32_bf16 v[30:33], v[26:29], v[232:235], v[30:33]
	v_mfma_f32_16x16x32_bf16 v[14:17], v[26:29], v[240:243], v[4:7]
	v_mfma_f32_16x16x32_bf16 v[4:7], v[204:207], v[38:41], v[172:175]
	v_mfma_f32_16x16x32_bf16 v[58:61], v[208:211], v[42:45], v[4:7]
	v_mfma_f32_16x16x32_bf16 v[4:7], v[212:215], v[38:41], v[176:179]
	v_mfma_f32_16x16x32_bf16 v[54:57], v[216:219], v[42:45], v[4:7]
	v_mfma_f32_16x16x32_bf16 v[4:7], v[204:207], v[220:223], v[180:183]
	v_mfma_f32_16x16x32_bf16 v[42:45], v[208:211], v[224:227], v[4:7]
	v_mfma_f32_16x16x32_bf16 v[4:7], v[212:215], v[220:223], v[184:187]
	v_mfma_f32_16x16x32_bf16 v[38:41], v[216:219], v[224:227], v[4:7]
	v_mfma_f32_16x16x32_bf16 v[4:7], v[204:207], v[228:231], v[188:191]
	v_mfma_f32_16x16x32_bf16 v[26:29], v[208:211], v[232:235], v[4:7]
	v_mfma_f32_16x16x32_bf16 v[4:7], v[212:215], v[228:231], v[192:195]
	v_mfma_f32_16x16x32_bf16 v[22:25], v[216:219], v[232:235], v[4:7]
	v_mfma_f32_16x16x32_bf16 v[4:7], v[204:207], v[236:239], v[196:199]
	v_mfma_f32_16x16x32_bf16 v[10:13], v[208:211], v[240:243], v[4:7]
	v_mfma_f32_16x16x32_bf16 v[4:7], v[212:215], v[236:239], v[200:203]
	v_mfma_f32_16x16x32_bf16 v[6:9], v[216:219], v[240:243], v[4:7]
	s_barrier
	s_setprio 0
	s_mov_b32 s40, 2
	s_branch .LBB0_2959

.LBB0_2960:
	ds_read_b128 v[138:141], v147
	ds_read_b128 v[152:155], v147 offset:1024
	ds_read_b128 v[156:159], v147 offset:2048
	ds_read_b128 v[160:163], v147 offset:3072
	ds_read_b128 v[164:167], v148
	ds_read_b128 v[168:171], v148 offset:1024
	ds_read_b128 v[172:175], v148 offset:2048
	ds_read_b128 v[176:179], v148 offset:3072
	s_cmpk_eq_i32 s80, 0x54
	s_cselect_b32 s42, s8, s83
	s_cselect_b32 s43, s9, s84
	s_cselect_b32 s40, s28, s81
	s_cselect_b32 s41, s29, s82
	s_add_u32 s38, s42, 0x80
	s_addc_u32 s39, s43, 0
	ds_read_b128 v[180:183], v149
	ds_read_b128 v[184:187], v149 offset:1024
	ds_read_b128 v[188:191], v149 offset:2048
	ds_read_b128 v[192:195], v149 offset:3072
	ds_read_b128 v[196:199], v149 offset:4096
	ds_read_b128 v[200:203], v149 offset:5120
	ds_read_b128 v[204:207], v149 offset:6144
	ds_read_b128 v[208:211], v149 offset:7168
	s_mov_b32 m0, s70
	s_nop 0
	global_load_lds_dwordx4 v1, s[36:37] offset:0
	s_nop 0
	s_mov_b32 m0, s71
	s_nop 0
	global_load_lds_dwordx4 v143, s[36:37] offset:0
	s_waitcnt vmcnt(8)
	s_waitcnt lgkmcnt(0)
	s_barrier
	s_setprio 1
	v_mfma_f32_16x16x32_bf16 v[130:133], v[138:141], v[180:183], v[130:133]
	v_mfma_f32_16x16x32_bf16 v[130:133], v[152:155], v[184:187], v[130:133]
	v_mfma_f32_16x16x32_bf16 v[126:129], v[156:159], v[180:183], v[126:129]
	v_mfma_f32_16x16x32_bf16 v[126:129], v[160:163], v[184:187], v[126:129]
	v_mfma_f32_16x16x32_bf16 v[114:117], v[138:141], v[188:191], v[114:117]
	v_mfma_f32_16x16x32_bf16 v[114:117], v[152:155], v[192:195], v[114:117]
	v_mfma_f32_16x16x32_bf16 v[110:113], v[156:159], v[188:191], v[110:113]
	v_mfma_f32_16x16x32_bf16 v[110:113], v[160:163], v[192:195], v[110:113]
	v_mfma_f32_16x16x32_bf16 v[98:101], v[138:141], v[196:199], v[98:101]
	v_mfma_f32_16x16x32_bf16 v[98:101], v[152:155], v[200:203], v[98:101]
	v_mfma_f32_16x16x32_bf16 v[94:97], v[156:159], v[196:199], v[94:97]
	v_mfma_f32_16x16x32_bf16 v[94:97], v[160:163], v[200:203], v[94:97]
	v_mfma_f32_16x16x32_bf16 v[82:85], v[138:141], v[204:207], v[82:85]
	v_mfma_f32_16x16x32_bf16 v[82:85], v[152:155], v[208:211], v[82:85]
	v_mfma_f32_16x16x32_bf16 v[78:81], v[156:159], v[204:207], v[78:81]
	v_mfma_f32_16x16x32_bf16 v[78:81], v[160:163], v[208:211], v[78:81]
	v_mfma_f32_16x16x32_bf16 v[122:125], v[164:167], v[180:183], v[122:125]
	v_mfma_f32_16x16x32_bf16 v[122:125], v[168:171], v[184:187], v[122:125]
	v_mfma_f32_16x16x32_bf16 v[118:121], v[172:175], v[180:183], v[118:121]
	v_mfma_f32_16x16x32_bf16 v[118:121], v[176:179], v[184:187], v[118:121]
	v_mfma_f32_16x16x32_bf16 v[106:109], v[164:167], v[188:191], v[106:109]
	v_mfma_f32_16x16x32_bf16 v[106:109], v[168:171], v[192:195], v[106:109]
	v_mfma_f32_16x16x32_bf16 v[102:105], v[172:175], v[188:191], v[102:105]
	v_mfma_f32_16x16x32_bf16 v[102:105], v[176:179], v[192:195], v[102:105]
	v_mfma_f32_16x16x32_bf16 v[90:93], v[164:167], v[196:199], v[90:93]
	v_mfma_f32_16x16x32_bf16 v[90:93], v[168:171], v[200:203], v[90:93]
	v_mfma_f32_16x16x32_bf16 v[86:89], v[172:175], v[196:199], v[86:89]
	v_mfma_f32_16x16x32_bf16 v[86:89], v[176:179], v[200:203], v[86:89]
	v_mfma_f32_16x16x32_bf16 v[74:77], v[164:167], v[204:207], v[74:77]
	v_mfma_f32_16x16x32_bf16 v[74:77], v[168:171], v[208:211], v[74:77]
	v_mfma_f32_16x16x32_bf16 v[70:73], v[172:175], v[204:207], v[70:73]
	v_mfma_f32_16x16x32_bf16 v[70:73], v[176:179], v[208:211], v[70:73]
	s_barrier
	s_setprio 0
	ds_read_b128 v[180:183], v149 offset:16384
	ds_read_b128 v[184:187], v149 offset:17408
	ds_read_b128 v[188:191], v149 offset:18432
	ds_read_b128 v[192:195], v149 offset:19456
	ds_read_b128 v[196:199], v149 offset:20480
	ds_read_b128 v[200:203], v149 offset:21504
	ds_read_b128 v[204:207], v149 offset:22528
	ds_read_b128 v[208:211], v149 offset:23552
	s_mov_b32 m0, s46
	s_nop 0
	global_load_lds_dwordx4 v142, s[40:41] offset:0
	s_add_u32 s30, s40, 0x160000
	s_mov_b32 m0, s47
	s_nop 0
	global_load_lds_dwordx4 v144, s[40:41] offset:0
	s_addc_u32 s31, s41, 0
	s_mov_b32 m0, s52
	s_nop 0
	global_load_lds_dwordx4 v142, s[30:31] offset:0
	s_nop 0
	s_mov_b32 m0, s53
	s_nop 0
	global_load_lds_dwordx4 v144, s[30:31] offset:0
	s_nop 0
	s_mov_b32 m0, s45
	s_nop 0
	global_load_lds_dwordx4 v1, s[42:43] offset:0
	s_nop 0
	s_mov_b32 m0, s54
	s_nop 0
	global_load_lds_dwordx4 v143, s[42:43] offset:0
	s_waitcnt vmcnt(8)
	s_waitcnt lgkmcnt(0)
	s_barrier
	s_setprio 1
	v_mfma_f32_16x16x32_bf16 v[66:69], v[138:141], v[180:183], v[66:69]
	v_mfma_f32_16x16x32_bf16 v[66:69], v[152:155], v[184:187], v[66:69]
	v_mfma_f32_16x16x32_bf16 v[62:65], v[156:159], v[180:183], v[62:65]
	v_mfma_f32_16x16x32_bf16 v[62:65], v[160:163], v[184:187], v[62:65]
	v_mfma_f32_16x16x32_bf16 v[50:53], v[138:141], v[188:191], v[50:53]
	v_mfma_f32_16x16x32_bf16 v[50:53], v[152:155], v[192:195], v[50:53]
	v_mfma_f32_16x16x32_bf16 v[46:49], v[156:159], v[188:191], v[46:49]
	v_mfma_f32_16x16x32_bf16 v[46:49], v[160:163], v[192:195], v[46:49]
	v_mfma_f32_16x16x32_bf16 v[34:37], v[138:141], v[196:199], v[34:37]
	v_mfma_f32_16x16x32_bf16 v[34:37], v[152:155], v[200:203], v[34:37]
	v_mfma_f32_16x16x32_bf16 v[30:33], v[156:159], v[196:199], v[30:33]
	v_mfma_f32_16x16x32_bf16 v[30:33], v[160:163], v[200:203], v[30:33]
	v_mfma_f32_16x16x32_bf16 v[18:21], v[138:141], v[204:207], v[18:21]
	v_mfma_f32_16x16x32_bf16 v[18:21], v[152:155], v[208:211], v[18:21]
	v_mfma_f32_16x16x32_bf16 v[14:17], v[156:159], v[204:207], v[14:17]
	v_mfma_f32_16x16x32_bf16 v[14:17], v[160:163], v[208:211], v[14:17]
	v_mfma_f32_16x16x32_bf16 v[58:61], v[164:167], v[180:183], v[58:61]
	v_mfma_f32_16x16x32_bf16 v[54:57], v[172:175], v[180:183], v[54:57]
	v_mfma_f32_16x16x32_bf16 v[42:45], v[164:167], v[188:191], v[42:45]
	v_mfma_f32_16x16x32_bf16 v[38:41], v[172:175], v[188:191], v[38:41]
	v_mfma_f32_16x16x32_bf16 v[26:29], v[164:167], v[196:199], v[26:29]
	v_mfma_f32_16x16x32_bf16 v[22:25], v[172:175], v[196:199], v[22:25]
	v_mfma_f32_16x16x32_bf16 v[10:13], v[164:167], v[204:207], v[10:13]
	v_mfma_f32_16x16x32_bf16 v[4:7], v[172:175], v[204:207], v[6:9]
	v_mfma_f32_16x16x32_bf16 v[58:61], v[168:171], v[184:187], v[58:61]
	v_mfma_f32_16x16x32_bf16 v[54:57], v[176:179], v[184:187], v[54:57]
	v_mfma_f32_16x16x32_bf16 v[42:45], v[168:171], v[192:195], v[42:45]
	v_mfma_f32_16x16x32_bf16 v[38:41], v[176:179], v[192:195], v[38:41]
	v_mfma_f32_16x16x32_bf16 v[26:29], v[168:171], v[200:203], v[26:29]
	v_mfma_f32_16x16x32_bf16 v[22:25], v[176:179], v[200:203], v[22:25]
	v_mfma_f32_16x16x32_bf16 v[10:13], v[168:171], v[208:211], v[10:13]
	v_mfma_f32_16x16x32_bf16 v[4:7], v[176:179], v[208:211], v[4:7]
	s_barrier
; #define PG8_BAR __builtin_amdgcn_s_barrier()
; #define PG8_KSETUP() const bool last = (t == nt - 2); const char* a1 = cA + (size_t)(t + 1) * kstep; \
;             const char* a2 = last ? nA : cA + (size_t)(t + 2) * kstep; const char* b2 = last ? nB : cB + (size_t)(t + 2) * kstep; const char* a3 = a2 + kstep; const char* b3 = b2 + kstep; \
;             if (last && has_next) S.a_ready(nxt)
; template <class Epi, class Sched, bool ALIGN_EPI = false, bool SP2 = false>
; __device__ __forceinline__ void gemm_phase(PG8_LAS unsigned char* lds, const Gemm g, const Sched& S, const Epi& E) {
;     ...
;         int t0 = 0;
;         if constexpr (SP2 && Epi::NVM == 16) { if (ui > 0) { const int t = 0; PG8_KSETUP(); PG8_KITER_SP2(24, 24); t0 = 2; } }
;         if constexpr (SP2 && Epi::NVM == 8) { if (ui > 0) { const int t = 0; PG8_KSETUP(); PG8_KITER_SP2(16, 16); t0 = 2; } }
;         for (int t = t0; t < nt; t += 2) {
;     ...
;         if constexpr (ALIGN_EPI) { if (wr == 0) PG8_BAR; }
	s_setprio 0
	ds_read_b128 v[138:141], v150
	ds_read_b128 v[152:155], v150 offset:1024
	ds_read_b128 v[156:159], v150 offset:2048
	ds_read_b128 v[160:163], v150 offset:3072
	ds_read_b128 v[164:167], v151
	ds_read_b128 v[168:171], v151 offset:1024
	ds_read_b128 v[172:175], v151 offset:2048
	ds_read_b128 v[176:179], v151 offset:3072
	ds_read_b128 v[180:183], v149 offset:32768
	ds_read_b128 v[184:187], v149 offset:33792
	ds_read_b128 v[188:191], v149 offset:34816
	ds_read_b128 v[192:195], v149 offset:35840
	ds_read_b128 v[196:199], v149 offset:36864
	ds_read_b128 v[200:203], v149 offset:37888
	ds_read_b128 v[204:207], v149 offset:38912
	ds_read_b128 v[208:211], v149 offset:39936
	s_add_u32 s30, s42, 0x160000
	s_addc_u32 s31, s43, 0
	s_mov_b32 m0, s55
	s_nop 0
	global_load_lds_dwordx4 v1, s[30:31] offset:0
	s_nop 0
	s_mov_b32 m0, s56
	s_nop 0
	global_load_lds_dwordx4 v143, s[30:31] offset:0
	s_waitcnt vmcnt(8)
	s_waitcnt lgkmcnt(0)
	s_barrier
	s_setprio 1
	v_mfma_f32_16x16x32_bf16 v[130:133], v[138:141], v[180:183], v[130:133]
	v_mfma_f32_16x16x32_bf16 v[130:133], v[152:155], v[184:187], v[130:133]
	v_mfma_f32_16x16x32_bf16 v[126:129], v[156:159], v[180:183], v[126:129]
	v_mfma_f32_16x16x32_bf16 v[126:129], v[160:163], v[184:187], v[126:129]
	v_mfma_f32_16x16x32_bf16 v[114:117], v[138:141], v[188:191], v[114:117]
	v_mfma_f32_16x16x32_bf16 v[114:117], v[152:155], v[192:195], v[114:117]
	v_mfma_f32_16x16x32_bf16 v[110:113], v[156:159], v[188:191], v[110:113]
	v_mfma_f32_16x16x32_bf16 v[110:113], v[160:163], v[192:195], v[110:113]
	v_mfma_f32_16x16x32_bf16 v[98:101], v[138:141], v[196:199], v[98:101]
	v_mfma_f32_16x16x32_bf16 v[98:101], v[152:155], v[200:203], v[98:101]
	v_mfma_f32_16x16x32_bf16 v[94:97], v[156:159], v[196:199], v[94:97]
	v_mfma_f32_16x16x32_bf16 v[94:97], v[160:163], v[200:203], v[94:97]
	v_mfma_f32_16x16x32_bf16 v[82:85], v[138:141], v[204:207], v[82:85]
	v_mfma_f32_16x16x32_bf16 v[82:85], v[152:155], v[208:211], v[82:85]
	v_mfma_f32_16x16x32_bf16 v[78:81], v[156:159], v[204:207], v[78:81]
	v_mfma_f32_16x16x32_bf16 v[78:81], v[160:163], v[208:211], v[78:81]
	v_mfma_f32_16x16x32_bf16 v[122:125], v[164:167], v[180:183], v[122:125]
	v_mfma_f32_16x16x32_bf16 v[122:125], v[168:171], v[184:187], v[122:125]
	v_mfma_f32_16x16x32_bf16 v[118:121], v[172:175], v[180:183], v[118:121]
	v_mfma_f32_16x16x32_bf16 v[118:121], v[176:179], v[184:187], v[118:121]
	v_mfma_f32_16x16x32_bf16 v[106:109], v[164:167], v[188:191], v[106:109]
	v_mfma_f32_16x16x32_bf16 v[106:109], v[168:171], v[192:195], v[106:109]
	v_mfma_f32_16x16x32_bf16 v[102:105], v[172:175], v[188:191], v[102:105]
	v_mfma_f32_16x16x32_bf16 v[102:105], v[176:179], v[192:195], v[102:105]
	v_mfma_f32_16x16x32_bf16 v[90:93], v[164:167], v[196:199], v[90:93]
	v_mfma_f32_16x16x32_bf16 v[90:93], v[168:171], v[200:203], v[90:93]
	v_mfma_f32_16x16x32_bf16 v[86:89], v[172:175], v[196:199], v[86:89]
	v_mfma_f32_16x16x32_bf16 v[86:89], v[176:179], v[200:203], v[86:89]
	v_mfma_f32_16x16x32_bf16 v[74:77], v[164:167], v[204:207], v[74:77]
	v_mfma_f32_16x16x32_bf16 v[74:77], v[168:171], v[208:211], v[74:77]
	v_mfma_f32_16x16x32_bf16 v[70:73], v[172:175], v[204:207], v[70:73]
	v_mfma_f32_16x16x32_bf16 v[70:73], v[176:179], v[208:211], v[70:73]
	s_barrier
	s_setprio 0
	ds_read_b128 v[180:183], v149 offset:49152
	ds_read_b128 v[184:187], v149 offset:50176
	ds_read_b128 v[188:191], v149 offset:51200
	ds_read_b128 v[192:195], v149 offset:52224
	ds_read_b128 v[196:199], v149 offset:53248
	ds_read_b128 v[200:203], v149 offset:54272
	ds_read_b128 v[204:207], v149 offset:55296
	ds_read_b128 v[208:211], v149 offset:56320
	s_add_u32 s30, s40, 0x80
	s_addc_u32 s31, s41, 0
	s_mov_b32 m0, s64
	s_nop 0
	global_load_lds_dwordx4 v142, s[30:31] offset:0
	s_nop 0
	s_mov_b32 m0, s65
	s_nop 0
	global_load_lds_dwordx4 v144, s[30:31] offset:0
	s_add_u32 s30, s40, 0x160080
	s_addc_u32 s31, s41, 0
	s_mov_b32 m0, s68
	s_nop 0
	global_load_lds_dwordx4 v142, s[30:31] offset:0
	s_nop 0
	s_mov_b32 m0, s69
	s_nop 0
	global_load_lds_dwordx4 v144, s[30:31] offset:0
	s_nop 0
	s_mov_b32 m0, s66
	s_nop 0
	global_load_lds_dwordx4 v1, s[38:39] offset:0
	s_nop 0
	s_mov_b32 m0, s67
	s_nop 0
	global_load_lds_dwordx4 v143, s[38:39] offset:0
	s_waitcnt vmcnt(8)
	s_waitcnt lgkmcnt(0)
	s_barrier
	s_setprio 1
	v_mfma_f32_16x16x32_bf16 v[66:69], v[138:141], v[180:183], v[66:69]
	v_mfma_f32_16x16x32_bf16 v[66:69], v[152:155], v[184:187], v[66:69]
	v_mfma_f32_16x16x32_bf16 v[62:65], v[156:159], v[180:183], v[62:65]
	v_mfma_f32_16x16x32_bf16 v[62:65], v[160:163], v[184:187], v[62:65]
	v_mfma_f32_16x16x32_bf16 v[50:53], v[138:141], v[188:191], v[50:53]
	v_mfma_f32_16x16x32_bf16 v[50:53], v[152:155], v[192:195], v[50:53]
	v_mfma_f32_16x16x32_bf16 v[46:49], v[156:159], v[188:191], v[46:49]
	v_mfma_f32_16x16x32_bf16 v[46:49], v[160:163], v[192:195], v[46:49]
	v_mfma_f32_16x16x32_bf16 v[34:37], v[138:141], v[196:199], v[34:37]
	v_mfma_f32_16x16x32_bf16 v[34:37], v[152:155], v[200:203], v[34:37]
	v_mfma_f32_16x16x32_bf16 v[30:33], v[156:159], v[196:199], v[30:33]
	v_mfma_f32_16x16x32_bf16 v[30:33], v[160:163], v[200:203], v[30:33]
	v_mfma_f32_16x16x32_bf16 v[18:21], v[138:141], v[204:207], v[18:21]
	v_mfma_f32_16x16x32_bf16 v[18:21], v[152:155], v[208:211], v[18:21]
	v_mfma_f32_16x16x32_bf16 v[14:17], v[156:159], v[204:207], v[14:17]
	v_mfma_f32_16x16x32_bf16 v[14:17], v[160:163], v[208:211], v[14:17]
	v_mfma_f32_16x16x32_bf16 v[58:61], v[164:167], v[180:183], v[58:61]
	v_mfma_f32_16x16x32_bf16 v[54:57], v[172:175], v[180:183], v[54:57]
	v_mfma_f32_16x16x32_bf16 v[42:45], v[164:167], v[188:191], v[42:45]
	v_mfma_f32_16x16x32_bf16 v[38:41], v[172:175], v[188:191], v[38:41]
	v_mfma_f32_16x16x32_bf16 v[26:29], v[164:167], v[196:199], v[26:29]
	v_mfma_f32_16x16x32_bf16 v[22:25], v[172:175], v[196:199], v[22:25]
	v_mfma_f32_16x16x32_bf16 v[8:11], v[164:167], v[204:207], v[10:13]
	v_mfma_f32_16x16x32_bf16 v[4:7], v[172:175], v[204:207], v[4:7]
	v_mfma_f32_16x16x32_bf16 v[58:61], v[168:171], v[184:187], v[58:61]
	v_mfma_f32_16x16x32_bf16 v[54:57], v[176:179], v[184:187], v[54:57]
	v_mfma_f32_16x16x32_bf16 v[42:45], v[168:171], v[192:195], v[42:45]
	v_mfma_f32_16x16x32_bf16 v[38:41], v[176:179], v[192:195], v[38:41]
	v_mfma_f32_16x16x32_bf16 v[26:29], v[168:171], v[200:203], v[26:29]
	v_mfma_f32_16x16x32_bf16 v[22:25], v[176:179], v[200:203], v[22:25]
	v_mfma_f32_16x16x32_bf16 v[10:13], v[168:171], v[208:211], v[8:11]
	v_mfma_f32_16x16x32_bf16 v[6:9], v[176:179], v[208:211], v[4:7]
	s_barrier
	s_setprio 0
	s_add_i32 s80, s80, 2
	s_add_u32 s81, s81, 0x100
	s_addc_u32 s82, s82, 0
	s_add_u32 s83, s83, 0x100
	s_addc_u32 s84, s84, 0
	s_add_u32 s36, s36, 0x100
	s_addc_u32 s37, s37, 0
	s_cmpk_gt_u32 s80, 0x55
	s_cbranch_scc0 .LBB0_2960
	s_and_b64 vcc, exec, s[16:17]
	s_cbranch_vccz .LBB0_2963
	s_barrier

.LBB0_3114:
	ds_read_b128 v[136:139], v149
	ds_read_b128 v[154:157], v149 offset:1024
	ds_read_b128 v[158:161], v149 offset:2048
	ds_read_b128 v[162:165], v149 offset:3072
	ds_read_b128 v[166:169], v150
	ds_read_b128 v[170:173], v150 offset:1024
	ds_read_b128 v[174:177], v150 offset:2048
	ds_read_b128 v[178:181], v150 offset:3072
	s_cmp_eq_u32 s78, 28
	s_cselect_b32 s40, s72, s76
	s_cselect_b32 s41, s19, s77
	s_cselect_b32 s38, s73, s74
	s_cselect_b32 s39, s17, s75
	s_add_u32 s36, s40, 0x80
	s_addc_u32 s37, s41, 0
	ds_read_b128 v[182:185], v151
	ds_read_b128 v[186:189], v151 offset:1024
	ds_read_b128 v[190:193], v151 offset:2048
	ds_read_b128 v[194:197], v151 offset:3072
	ds_read_b128 v[198:201], v151 offset:4096
	ds_read_b128 v[202:205], v151 offset:5120
	ds_read_b128 v[206:209], v151 offset:6144
	ds_read_b128 v[210:213], v151 offset:7168
	s_mov_b32 m0, s67
	s_nop 0
	global_load_lds_dwordx4 v1, s[28:29] offset:0
	s_nop 0
	s_mov_b32 m0, s68
	s_nop 0
	global_load_lds_dwordx4 v143, s[28:29] offset:0
	s_waitcnt vmcnt(8)
	s_waitcnt lgkmcnt(0)
	s_barrier
	s_setprio 1
	v_mfma_f32_16x16x32_bf16 v[126:129], v[136:139], v[182:185], v[126:129]
	v_mfma_f32_16x16x32_bf16 v[126:129], v[154:157], v[186:189], v[126:129]
	v_mfma_f32_16x16x32_bf16 v[122:125], v[158:161], v[182:185], v[122:125]
	v_mfma_f32_16x16x32_bf16 v[122:125], v[162:165], v[186:189], v[122:125]
	v_mfma_f32_16x16x32_bf16 v[114:117], v[136:139], v[190:193], v[114:117]
	v_mfma_f32_16x16x32_bf16 v[114:117], v[154:157], v[194:197], v[114:117]
	v_mfma_f32_16x16x32_bf16 v[106:109], v[158:161], v[190:193], v[106:109]
	v_mfma_f32_16x16x32_bf16 v[106:109], v[162:165], v[194:197], v[106:109]
	v_mfma_f32_16x16x32_bf16 v[98:101], v[136:139], v[198:201], v[98:101]
	v_mfma_f32_16x16x32_bf16 v[98:101], v[154:157], v[202:205], v[98:101]
	v_mfma_f32_16x16x32_bf16 v[90:93], v[158:161], v[198:201], v[90:93]
	v_mfma_f32_16x16x32_bf16 v[90:93], v[162:165], v[202:205], v[90:93]
	v_mfma_f32_16x16x32_bf16 v[82:85], v[136:139], v[206:209], v[82:85]
	v_mfma_f32_16x16x32_bf16 v[82:85], v[154:157], v[210:213], v[82:85]
	v_mfma_f32_16x16x32_bf16 v[74:77], v[158:161], v[206:209], v[74:77]
	v_mfma_f32_16x16x32_bf16 v[74:77], v[162:165], v[210:213], v[74:77]
	v_mfma_f32_16x16x32_bf16 v[118:121], v[166:169], v[182:185], v[118:121]
	v_mfma_f32_16x16x32_bf16 v[118:121], v[170:173], v[186:189], v[118:121]
	v_mfma_f32_16x16x32_bf16 v[110:113], v[174:177], v[182:185], v[110:113]
	v_mfma_f32_16x16x32_bf16 v[110:113], v[178:181], v[186:189], v[110:113]
	v_mfma_f32_16x16x32_bf16 v[102:105], v[166:169], v[190:193], v[102:105]
	v_mfma_f32_16x16x32_bf16 v[102:105], v[170:173], v[194:197], v[102:105]
	v_mfma_f32_16x16x32_bf16 v[94:97], v[174:177], v[190:193], v[94:97]
	v_mfma_f32_16x16x32_bf16 v[94:97], v[178:181], v[194:197], v[94:97]
	v_mfma_f32_16x16x32_bf16 v[86:89], v[166:169], v[198:201], v[86:89]
	v_mfma_f32_16x16x32_bf16 v[86:89], v[170:173], v[202:205], v[86:89]
	v_mfma_f32_16x16x32_bf16 v[78:81], v[174:177], v[198:201], v[78:81]
	v_mfma_f32_16x16x32_bf16 v[78:81], v[178:181], v[202:205], v[78:81]
	v_mfma_f32_16x16x32_bf16 v[70:73], v[166:169], v[206:209], v[70:73]
	v_mfma_f32_16x16x32_bf16 v[70:73], v[170:173], v[210:213], v[70:73]
	v_mfma_f32_16x16x32_bf16 v[66:69], v[174:177], v[206:209], v[66:69]
	v_mfma_f32_16x16x32_bf16 v[66:69], v[178:181], v[210:213], v[66:69]
	s_barrier
	s_setprio 0
	ds_read_b128 v[182:185], v151 offset:16384
	ds_read_b128 v[186:189], v151 offset:17408
	ds_read_b128 v[190:193], v151 offset:18432
	ds_read_b128 v[194:197], v151 offset:19456
	ds_read_b128 v[198:201], v151 offset:20480
	ds_read_b128 v[202:205], v151 offset:21504
	ds_read_b128 v[206:209], v151 offset:22528
	ds_read_b128 v[210:213], v151 offset:23552
	s_mov_b32 m0, s25
	s_nop 0
	global_load_lds_dwordx4 v135, s[38:39] offset:0
	s_add_u32 s30, s38, 0x80000
	s_mov_b32 m0, s46
	s_nop 0
	global_load_lds_dwordx4 v145, s[38:39] offset:0
	s_addc_u32 s31, s39, 0
	s_mov_b32 m0, s47
	s_nop 0
	global_load_lds_dwordx4 v135, s[30:31] offset:0
	s_nop 0
	s_mov_b32 m0, s52
	s_nop 0
	global_load_lds_dwordx4 v145, s[30:31] offset:0
	s_nop 0
	s_mov_b32 m0, s43
	s_nop 0
	global_load_lds_dwordx4 v1, s[40:41] offset:0
	s_nop 0
	s_mov_b32 m0, s53
	s_nop 0
	global_load_lds_dwordx4 v143, s[40:41] offset:0
	s_waitcnt vmcnt(8)
	s_waitcnt lgkmcnt(0)
	s_barrier
	s_setprio 1
	v_mfma_f32_16x16x32_bf16 v[62:65], v[136:139], v[182:185], v[62:65]
	v_mfma_f32_16x16x32_bf16 v[62:65], v[154:157], v[186:189], v[62:65]
	v_mfma_f32_16x16x32_bf16 v[58:61], v[158:161], v[182:185], v[58:61]
	v_mfma_f32_16x16x32_bf16 v[58:61], v[162:165], v[186:189], v[58:61]
	v_mfma_f32_16x16x32_bf16 v[50:53], v[136:139], v[190:193], v[50:53]
	v_mfma_f32_16x16x32_bf16 v[50:53], v[154:157], v[194:197], v[50:53]
	v_mfma_f32_16x16x32_bf16 v[42:45], v[158:161], v[190:193], v[42:45]
	v_mfma_f32_16x16x32_bf16 v[42:45], v[162:165], v[194:197], v[42:45]
	v_mfma_f32_16x16x32_bf16 v[34:37], v[136:139], v[198:201], v[34:37]
	v_mfma_f32_16x16x32_bf16 v[34:37], v[154:157], v[202:205], v[34:37]
	v_mfma_f32_16x16x32_bf16 v[26:29], v[158:161], v[198:201], v[26:29]
	v_mfma_f32_16x16x32_bf16 v[26:29], v[162:165], v[202:205], v[26:29]
	v_mfma_f32_16x16x32_bf16 v[18:21], v[136:139], v[206:209], v[18:21]
	v_mfma_f32_16x16x32_bf16 v[18:21], v[154:157], v[210:213], v[18:21]
	v_mfma_f32_16x16x32_bf16 v[10:13], v[158:161], v[206:209], v[10:13]
	v_mfma_f32_16x16x32_bf16 v[10:13], v[162:165], v[210:213], v[10:13]
	v_mfma_f32_16x16x32_bf16 v[54:57], v[166:169], v[182:185], v[54:57]
	v_mfma_f32_16x16x32_bf16 v[54:57], v[170:173], v[186:189], v[54:57]
	v_mfma_f32_16x16x32_bf16 v[46:49], v[174:177], v[182:185], v[46:49]
	v_mfma_f32_16x16x32_bf16 v[46:49], v[178:181], v[186:189], v[46:49]
	v_mfma_f32_16x16x32_bf16 v[38:41], v[166:169], v[190:193], v[38:41]
	v_mfma_f32_16x16x32_bf16 v[38:41], v[170:173], v[194:197], v[38:41]
	v_mfma_f32_16x16x32_bf16 v[30:33], v[174:177], v[190:193], v[30:33]
	v_mfma_f32_16x16x32_bf16 v[30:33], v[178:181], v[194:197], v[30:33]
	v_mfma_f32_16x16x32_bf16 v[22:25], v[166:169], v[198:201], v[22:25]
	v_mfma_f32_16x16x32_bf16 v[22:25], v[170:173], v[202:205], v[22:25]
	v_mfma_f32_16x16x32_bf16 v[14:17], v[174:177], v[198:201], v[14:17]
	v_mfma_f32_16x16x32_bf16 v[14:17], v[178:181], v[202:205], v[14:17]
	v_mfma_f32_16x16x32_bf16 v[6:9], v[166:169], v[206:209], v[6:9]
	v_mfma_f32_16x16x32_bf16 v[6:9], v[170:173], v[210:213], v[6:9]
	v_mfma_f32_16x16x32_bf16 v[2:5], v[174:177], v[206:209], v[2:5]
	v_mfma_f32_16x16x32_bf16 v[2:5], v[178:181], v[210:213], v[2:5]
	s_barrier
; #define PG8_BAR __builtin_amdgcn_s_barrier()
; #define PG8_KSETUP() const bool last = (t == nt - 2); const char* a1 = cA + (size_t)(t + 1) * kstep; \
;             const char* a2 = last ? nA : cA + (size_t)(t + 2) * kstep; const char* b2 = last ? nB : cB + (size_t)(t + 2) * kstep; const char* a3 = a2 + kstep; const char* b3 = b2 + kstep; \
;             if (last && has_next) S.a_ready(nxt)
; template <class Epi, class Sched, bool ALIGN_EPI = false, bool SP2 = false>
; __device__ __forceinline__ void gemm_phase(PG8_LAS unsigned char* lds, const Gemm g, const Sched& S, const Epi& E) {
;     ...
;         int t0 = 0;
;         if constexpr (SP2 && Epi::NVM == 16) { if (ui > 0) { const int t = 0; PG8_KSETUP(); PG8_KITER_SP2(24, 24); t0 = 2; } }
;         if constexpr (SP2 && Epi::NVM == 8) { if (ui > 0) { const int t = 0; PG8_KSETUP(); PG8_KITER_SP2(16, 16); t0 = 2; } }
;         for (int t = t0; t < nt; t += 2) {
;     ...
;         if constexpr (ALIGN_EPI) { if (wr == 0) PG8_BAR; }
	s_setprio 0
	ds_read_b128 v[136:139], v152
	ds_read_b128 v[154:157], v152 offset:1024
	ds_read_b128 v[158:161], v152 offset:2048
	ds_read_b128 v[162:165], v152 offset:3072
	ds_read_b128 v[166:169], v153
	ds_read_b128 v[170:173], v153 offset:1024
	ds_read_b128 v[174:177], v153 offset:2048
	ds_read_b128 v[178:181], v153 offset:3072
	ds_read_b128 v[182:185], v151 offset:32768
	ds_read_b128 v[186:189], v151 offset:33792
	ds_read_b128 v[190:193], v151 offset:34816
	ds_read_b128 v[194:197], v151 offset:35840
	ds_read_b128 v[198:201], v151 offset:36864
	ds_read_b128 v[202:205], v151 offset:37888
	ds_read_b128 v[206:209], v151 offset:38912
	ds_read_b128 v[210:213], v151 offset:39936
	s_add_u32 s30, s40, 0x80000
	s_addc_u32 s31, s41, 0
	s_mov_b32 m0, s54
	s_nop 0
	global_load_lds_dwordx4 v1, s[30:31] offset:0
	s_nop 0
	s_mov_b32 m0, s55
	s_nop 0
	global_load_lds_dwordx4 v143, s[30:31] offset:0
	s_waitcnt vmcnt(8)
	s_waitcnt lgkmcnt(0)
	s_barrier
	s_setprio 1
	v_mfma_f32_16x16x32_bf16 v[126:129], v[136:139], v[182:185], v[126:129]
	v_mfma_f32_16x16x32_bf16 v[126:129], v[154:157], v[186:189], v[126:129]
	v_mfma_f32_16x16x32_bf16 v[122:125], v[158:161], v[182:185], v[122:125]
	v_mfma_f32_16x16x32_bf16 v[122:125], v[162:165], v[186:189], v[122:125]
	v_mfma_f32_16x16x32_bf16 v[114:117], v[136:139], v[190:193], v[114:117]
	v_mfma_f32_16x16x32_bf16 v[114:117], v[154:157], v[194:197], v[114:117]
	v_mfma_f32_16x16x32_bf16 v[106:109], v[158:161], v[190:193], v[106:109]
	v_mfma_f32_16x16x32_bf16 v[106:109], v[162:165], v[194:197], v[106:109]
	v_mfma_f32_16x16x32_bf16 v[98:101], v[136:139], v[198:201], v[98:101]
	v_mfma_f32_16x16x32_bf16 v[98:101], v[154:157], v[202:205], v[98:101]
	v_mfma_f32_16x16x32_bf16 v[90:93], v[158:161], v[198:201], v[90:93]
	v_mfma_f32_16x16x32_bf16 v[90:93], v[162:165], v[202:205], v[90:93]
	v_mfma_f32_16x16x32_bf16 v[82:85], v[136:139], v[206:209], v[82:85]
	v_mfma_f32_16x16x32_bf16 v[82:85], v[154:157], v[210:213], v[82:85]
	v_mfma_f32_16x16x32_bf16 v[74:77], v[158:161], v[206:209], v[74:77]
	v_mfma_f32_16x16x32_bf16 v[74:77], v[162:165], v[210:213], v[74:77]
	v_mfma_f32_16x16x32_bf16 v[118:121], v[166:169], v[182:185], v[118:121]
	v_mfma_f32_16x16x32_bf16 v[118:121], v[170:173], v[186:189], v[118:121]
	v_mfma_f32_16x16x32_bf16 v[110:113], v[174:177], v[182:185], v[110:113]
	v_mfma_f32_16x16x32_bf16 v[110:113], v[178:181], v[186:189], v[110:113]
	v_mfma_f32_16x16x32_bf16 v[102:105], v[166:169], v[190:193], v[102:105]
	v_mfma_f32_16x16x32_bf16 v[102:105], v[170:173], v[194:197], v[102:105]
	v_mfma_f32_16x16x32_bf16 v[94:97], v[174:177], v[190:193], v[94:97]
	v_mfma_f32_16x16x32_bf16 v[94:97], v[178:181], v[194:197], v[94:97]
	v_mfma_f32_16x16x32_bf16 v[86:89], v[166:169], v[198:201], v[86:89]
	v_mfma_f32_16x16x32_bf16 v[86:89], v[170:173], v[202:205], v[86:89]
	v_mfma_f32_16x16x32_bf16 v[78:81], v[174:177], v[198:201], v[78:81]
	v_mfma_f32_16x16x32_bf16 v[78:81], v[178:181], v[202:205], v[78:81]
	v_mfma_f32_16x16x32_bf16 v[70:73], v[166:169], v[206:209], v[70:73]
	v_mfma_f32_16x16x32_bf16 v[70:73], v[170:173], v[210:213], v[70:73]
	v_mfma_f32_16x16x32_bf16 v[66:69], v[174:177], v[206:209], v[66:69]
	v_mfma_f32_16x16x32_bf16 v[66:69], v[178:181], v[210:213], v[66:69]
	s_barrier
	s_setprio 0
	ds_read_b128 v[182:185], v151 offset:49152
	ds_read_b128 v[186:189], v151 offset:50176
	ds_read_b128 v[190:193], v151 offset:51200
	ds_read_b128 v[194:197], v151 offset:52224
	ds_read_b128 v[198:201], v151 offset:53248
	ds_read_b128 v[202:205], v151 offset:54272
	ds_read_b128 v[206:209], v151 offset:55296
	ds_read_b128 v[210:213], v151 offset:56320
	s_add_u32 s30, s38, 0x80
	s_addc_u32 s31, s39, 0
	s_mov_b32 m0, s57
	s_nop 0
	global_load_lds_dwordx4 v135, s[30:31] offset:0
	s_nop 0
	s_mov_b32 m0, s58
	s_nop 0
	global_load_lds_dwordx4 v145, s[30:31] offset:0
	s_add_u32 s30, s38, 0x80080
	s_addc_u32 s31, s39, 0
	s_mov_b32 m0, s65
	s_nop 0
	global_load_lds_dwordx4 v135, s[30:31] offset:0
	s_nop 0
	s_mov_b32 m0, s66
	s_nop 0
	global_load_lds_dwordx4 v145, s[30:31] offset:0
	s_nop 0
	s_mov_b32 m0, s59
	s_nop 0
	global_load_lds_dwordx4 v1, s[36:37] offset:0
	s_nop 0
	s_mov_b32 m0, s64
	s_nop 0
	global_load_lds_dwordx4 v143, s[36:37] offset:0
	s_waitcnt vmcnt(8)
	s_waitcnt lgkmcnt(0)
	s_barrier
	s_setprio 1
	v_mfma_f32_16x16x32_bf16 v[62:65], v[136:139], v[182:185], v[62:65]
	v_mfma_f32_16x16x32_bf16 v[62:65], v[154:157], v[186:189], v[62:65]
	v_mfma_f32_16x16x32_bf16 v[58:61], v[158:161], v[182:185], v[58:61]
	v_mfma_f32_16x16x32_bf16 v[58:61], v[162:165], v[186:189], v[58:61]
	v_mfma_f32_16x16x32_bf16 v[50:53], v[136:139], v[190:193], v[50:53]
	v_mfma_f32_16x16x32_bf16 v[50:53], v[154:157], v[194:197], v[50:53]
	v_mfma_f32_16x16x32_bf16 v[42:45], v[158:161], v[190:193], v[42:45]
	v_mfma_f32_16x16x32_bf16 v[42:45], v[162:165], v[194:197], v[42:45]
	v_mfma_f32_16x16x32_bf16 v[34:37], v[136:139], v[198:201], v[34:37]
	v_mfma_f32_16x16x32_bf16 v[34:37], v[154:157], v[202:205], v[34:37]
	v_mfma_f32_16x16x32_bf16 v[26:29], v[158:161], v[198:201], v[26:29]
	v_mfma_f32_16x16x32_bf16 v[26:29], v[162:165], v[202:205], v[26:29]
	v_mfma_f32_16x16x32_bf16 v[18:21], v[136:139], v[206:209], v[18:21]
	v_mfma_f32_16x16x32_bf16 v[18:21], v[154:157], v[210:213], v[18:21]
	v_mfma_f32_16x16x32_bf16 v[10:13], v[158:161], v[206:209], v[10:13]
	v_mfma_f32_16x16x32_bf16 v[10:13], v[162:165], v[210:213], v[10:13]
	v_mfma_f32_16x16x32_bf16 v[54:57], v[166:169], v[182:185], v[54:57]
	v_mfma_f32_16x16x32_bf16 v[54:57], v[170:173], v[186:189], v[54:57]
	v_mfma_f32_16x16x32_bf16 v[46:49], v[174:177], v[182:185], v[46:49]
	v_mfma_f32_16x16x32_bf16 v[46:49], v[178:181], v[186:189], v[46:49]
	v_mfma_f32_16x16x32_bf16 v[38:41], v[166:169], v[190:193], v[38:41]
	v_mfma_f32_16x16x32_bf16 v[38:41], v[170:173], v[194:197], v[38:41]
	v_mfma_f32_16x16x32_bf16 v[30:33], v[174:177], v[190:193], v[30:33]
	v_mfma_f32_16x16x32_bf16 v[30:33], v[178:181], v[194:197], v[30:33]
	v_mfma_f32_16x16x32_bf16 v[22:25], v[166:169], v[198:201], v[22:25]
	v_mfma_f32_16x16x32_bf16 v[22:25], v[170:173], v[202:205], v[22:25]
	v_mfma_f32_16x16x32_bf16 v[14:17], v[174:177], v[198:201], v[14:17]
	v_mfma_f32_16x16x32_bf16 v[14:17], v[178:181], v[202:205], v[14:17]
	v_mfma_f32_16x16x32_bf16 v[6:9], v[166:169], v[206:209], v[6:9]
	v_mfma_f32_16x16x32_bf16 v[6:9], v[170:173], v[210:213], v[6:9]
	v_mfma_f32_16x16x32_bf16 v[2:5], v[174:177], v[206:209], v[2:5]
	v_mfma_f32_16x16x32_bf16 v[2:5], v[178:181], v[210:213], v[2:5]
	s_barrier
	s_setprio 0
	s_add_i32 s78, s78, 2
	s_add_u32 s74, s74, 0x100
	s_addc_u32 s75, s75, 0
	s_add_u32 s76, s76, 0x100
	s_addc_u32 s77, s77, 0
	s_add_u32 s28, s28, 0x100
	s_addc_u32 s29, s29, 0
	s_cmp_gt_u32 s78, 29
	s_cbranch_scc0 .LBB0_3114
	s_and_b64 vcc, exec, s[14:15]
	s_cbranch_vccz .LBB0_3117
	s_barrier

; #define PG8_KSETUP() const bool last = (t == nt - 2); const char* a1 = cA + (size_t)(t + 1) * kstep; \
;             const char* a2 = last ? nA : cA + (size_t)(t + 2) * kstep; const char* b2 = last ? nB : cB + (size_t)(t + 2) * kstep; const char* a3 = a2 + kstep; const char* b3 = b2 + kstep; \
;             if (last && has_next) S.a_ready(nxt)
; template <class Epi, class Sched, bool ALIGN_EPI = false, bool SP2 = false>
; __device__ __forceinline__ void gemm_phase(PG8_LAS unsigned char* lds, const Gemm g, const Sched& S, const Epi& E) {
;     ...
;         if constexpr (SP2 && Epi::NVM == 16) { if (ui > 0) { const int t = 0; PG8_KSETUP(); PG8_KITER_SP2(24, 24); t0 = 2; } }
.LBB0_3464:
	s_cmp_eq_u32 s29, 0
	s_mov_b32 s50, 0
	s_cbranch_scc1 .LBB0_3466
	ds_read_b128 v[4:7], v147
	ds_read_b128 v[8:11], v147 offset:1024
	ds_read_b128 v[12:15], v147 offset:2048
	ds_read_b128 v[16:19], v147 offset:3072
	ds_read_b128 v[20:23], v148
	ds_read_b128 v[24:27], v148 offset:1024
	ds_read_b128 v[28:31], v148 offset:2048
	ds_read_b128 v[32:35], v148 offset:3072
	s_add_u32 s40, s46, 0x100
	s_addc_u32 s41, s47, 0
	s_add_u32 s30, s48, 0x100
	s_addc_u32 s31, s49, 0
	s_add_u32 s38, s46, 0x180
	s_addc_u32 s39, s47, 0
	ds_read_b128 v[36:39], v149
	ds_read_b128 v[40:43], v149 offset:1024
	ds_read_b128 v[44:47], v149 offset:2048
	ds_read_b128 v[48:51], v149 offset:3072
	ds_read_b128 v[52:55], v149 offset:4096
	ds_read_b128 v[56:59], v149 offset:5120
	ds_read_b128 v[60:63], v149 offset:6144
	ds_read_b128 v[64:67], v149 offset:7168
	s_add_u32 s50, s46, 0x80080
	s_addc_u32 s51, s47, 0
	s_mov_b32 m0, s73
	s_nop 0
	global_load_lds_dwordx4 v1, s[50:51] offset:0
	s_nop 0
	s_mov_b32 m0, s74
	s_nop 0
	global_load_lds_dwordx4 v143, s[50:51] offset:0
	s_waitcnt vmcnt(24)
	s_waitcnt lgkmcnt(0)
	s_barrier
	s_setprio 1
	v_mfma_f32_16x16x32_bf16 v[92:95], v[4:7], v[60:63], 0
	v_mfma_f32_16x16x32_bf16 v[68:71], v[4:7], v[36:39], 0
	v_mfma_f32_16x16x32_bf16 v[72:75], v[12:15], v[36:39], 0
	v_mfma_f32_16x16x32_bf16 v[76:79], v[4:7], v[44:47], 0
	v_mfma_f32_16x16x32_bf16 v[80:83], v[12:15], v[44:47], 0
	v_mfma_f32_16x16x32_bf16 v[84:87], v[4:7], v[52:55], 0
	v_mfma_f32_16x16x32_bf16 v[88:91], v[12:15], v[52:55], 0
	v_mfma_f32_16x16x32_bf16 v[102:105], v[8:11], v[64:67], v[92:95]
	v_mfma_f32_16x16x32_bf16 v[92:95], v[12:15], v[60:63], 0
	v_mfma_f32_16x16x32_bf16 v[68:71], v[8:11], v[40:43], v[68:71]
	v_mfma_f32_16x16x32_bf16 v[72:75], v[16:19], v[40:43], v[72:75]
	v_mfma_f32_16x16x32_bf16 v[76:79], v[8:11], v[48:51], v[76:79]
	v_mfma_f32_16x16x32_bf16 v[80:83], v[16:19], v[48:51], v[80:83]
	v_mfma_f32_16x16x32_bf16 v[84:87], v[8:11], v[56:59], v[84:87]
	v_mfma_f32_16x16x32_bf16 v[88:91], v[16:19], v[56:59], v[88:91]
	v_mfma_f32_16x16x32_bf16 v[106:109], v[16:19], v[64:67], v[92:95]
	v_mfma_f32_16x16x32_bf16 v[92:95], v[20:23], v[36:39], 0
	v_mfma_f32_16x16x32_bf16 v[36:39], v[28:31], v[36:39], 0
	v_mfma_f32_16x16x32_bf16 v[118:121], v[24:27], v[40:43], v[92:95]
	v_mfma_f32_16x16x32_bf16 v[36:39], v[32:35], v[40:43], v[36:39]
	v_mfma_f32_16x16x32_bf16 v[40:43], v[20:23], v[44:47], 0
	v_mfma_f32_16x16x32_bf16 v[44:47], v[28:31], v[44:47], 0
	v_mfma_f32_16x16x32_bf16 v[40:43], v[24:27], v[48:51], v[40:43]
	v_mfma_f32_16x16x32_bf16 v[44:47], v[32:35], v[48:51], v[44:47]
	v_mfma_f32_16x16x32_bf16 v[48:51], v[20:23], v[52:55], 0
	v_mfma_f32_16x16x32_bf16 v[52:55], v[28:31], v[52:55], 0
	v_mfma_f32_16x16x32_bf16 v[48:51], v[24:27], v[56:59], v[48:51]
	v_mfma_f32_16x16x32_bf16 v[52:55], v[32:35], v[56:59], v[52:55]
	v_mfma_f32_16x16x32_bf16 v[56:59], v[20:23], v[60:63], 0
	v_mfma_f32_16x16x32_bf16 v[60:63], v[28:31], v[60:63], 0
	v_mfma_f32_16x16x32_bf16 v[56:59], v[24:27], v[64:67], v[56:59]
	v_mfma_f32_16x16x32_bf16 v[60:63], v[32:35], v[64:67], v[60:63]
	s_barrier
	s_setprio 0
	ds_read_b128 v[64:67], v149 offset:16384
	ds_read_b128 v[92:95], v149 offset:17408
	ds_read_b128 v[96:99], v149 offset:18432
	ds_read_b128 v[110:113], v149 offset:19456
	ds_read_b128 v[114:117], v149 offset:20480
	ds_read_b128 v[122:125], v149 offset:21504
	ds_read_b128 v[126:129], v149 offset:22528
	ds_read_b128 v[130:133], v149 offset:23552
	s_mov_b32 m0, s45
	s_nop 0
	global_load_lds_dwordx4 v142, s[30:31] offset:0
	s_nop 0
	s_mov_b32 m0, s54
	s_nop 0
	global_load_lds_dwordx4 v144, s[30:31] offset:0
	s_add_u32 s30, s48, 0x80100
	s_addc_u32 s31, s49, 0
	s_mov_b32 m0, s55
	s_nop 0
	global_load_lds_dwordx4 v142, s[30:31] offset:0
	s_nop 0
	s_mov_b32 m0, s56
	s_nop 0
	global_load_lds_dwordx4 v144, s[30:31] offset:0
	s_nop 0
	s_mov_b32 m0, s33
	s_nop 0
	global_load_lds_dwordx4 v1, s[40:41] offset:0
	s_nop 0
	s_mov_b32 m0, s57
	s_nop 0
	global_load_lds_dwordx4 v143, s[40:41] offset:0
	s_waitcnt vmcnt(24)
	s_waitcnt lgkmcnt(0)
	s_barrier
	s_setprio 1
	v_mfma_f32_16x16x32_bf16 v[138:141], v[4:7], v[64:67], 0
	v_mfma_f32_16x16x32_bf16 v[156:159], v[4:7], v[96:99], 0
	v_mfma_f32_16x16x32_bf16 v[164:167], v[4:7], v[114:117], 0
	v_mfma_f32_16x16x32_bf16 v[4:7], v[4:7], v[126:129], 0
	v_mfma_f32_16x16x32_bf16 v[138:141], v[8:11], v[92:95], v[138:141]
	v_mfma_f32_16x16x32_bf16 v[156:159], v[8:11], v[110:113], v[156:159]
	v_mfma_f32_16x16x32_bf16 v[164:167], v[8:11], v[122:125], v[164:167]
	v_mfma_f32_16x16x32_bf16 v[4:7], v[8:11], v[130:133], v[4:7]
	v_mfma_f32_16x16x32_bf16 v[8:11], v[12:15], v[126:129], 0
	v_mfma_f32_16x16x32_bf16 v[152:155], v[12:15], v[64:67], 0
	v_mfma_f32_16x16x32_bf16 v[160:163], v[12:15], v[96:99], 0
	v_mfma_f32_16x16x32_bf16 v[168:171], v[12:15], v[114:117], 0
	v_mfma_f32_16x16x32_bf16 v[8:11], v[16:19], v[130:133], v[8:11]
	v_mfma_f32_16x16x32_bf16 v[152:155], v[16:19], v[92:95], v[152:155]
	v_mfma_f32_16x16x32_bf16 v[160:163], v[16:19], v[110:113], v[160:163]
	v_mfma_f32_16x16x32_bf16 v[168:171], v[16:19], v[122:125], v[168:171]
	v_mfma_f32_16x16x32_bf16 v[12:15], v[20:23], v[64:67], 0
	v_mfma_f32_16x16x32_bf16 v[172:175], v[24:27], v[92:95], v[12:15]
	v_mfma_f32_16x16x32_bf16 v[12:15], v[28:31], v[64:67], 0
	v_mfma_f32_16x16x32_bf16 v[176:179], v[32:35], v[92:95], v[12:15]
	v_mfma_f32_16x16x32_bf16 v[12:15], v[20:23], v[96:99], 0
	v_mfma_f32_16x16x32_bf16 v[180:183], v[24:27], v[110:113], v[12:15]
	v_mfma_f32_16x16x32_bf16 v[12:15], v[28:31], v[96:99], 0
	v_mfma_f32_16x16x32_bf16 v[184:187], v[32:35], v[110:113], v[12:15]
	v_mfma_f32_16x16x32_bf16 v[12:15], v[20:23], v[114:117], 0
	v_mfma_f32_16x16x32_bf16 v[188:191], v[24:27], v[122:125], v[12:15]
	v_mfma_f32_16x16x32_bf16 v[12:15], v[28:31], v[114:117], 0
	v_mfma_f32_16x16x32_bf16 v[192:195], v[32:35], v[122:125], v[12:15]
	v_mfma_f32_16x16x32_bf16 v[12:15], v[20:23], v[126:129], 0
	v_mfma_f32_16x16x32_bf16 v[196:199], v[24:27], v[130:133], v[12:15]
	v_mfma_f32_16x16x32_bf16 v[12:15], v[28:31], v[126:129], 0
	v_mfma_f32_16x16x32_bf16 v[200:203], v[32:35], v[130:133], v[12:15]
	s_barrier
; #define PG8_KSETUP() const bool last = (t == nt - 2); const char* a1 = cA + (size_t)(t + 1) * kstep; \
;             const char* a2 = last ? nA : cA + (size_t)(t + 2) * kstep; const char* b2 = last ? nB : cB + (size_t)(t + 2) * kstep; const char* a3 = a2 + kstep; const char* b3 = b2 + kstep; \
;             if (last && has_next) S.a_ready(nxt)
; template <class Epi, class Sched, bool ALIGN_EPI = false, bool SP2 = false>
; __device__ __forceinline__ void gemm_phase(PG8_LAS unsigned char* lds, const Gemm g, const Sched& S, const Epi& E) {
;     ...
;         int t0 = 0;
;         if constexpr (SP2 && Epi::NVM == 16) { if (ui > 0) { const int t = 0; PG8_KSETUP(); PG8_KITER_SP2(24, 24); t0 = 2; } }
	s_setprio 0
	s_nop 4
	ds_read_b128 v[12:15], v150
	ds_read_b128 v[16:19], v150 offset:1024
	ds_read_b128 v[22:25], v150 offset:2048
	ds_read_b128 v[26:29], v150 offset:3072
	ds_read_b128 v[204:207], v151
	ds_read_b128 v[208:211], v151 offset:1024
	ds_read_b128 v[212:215], v151 offset:2048
	ds_read_b128 v[216:219], v151 offset:3072
	ds_read_b128 v[30:33], v149 offset:32768
	ds_read_b128 v[64:67], v149 offset:33792
	ds_read_b128 v[220:223], v149 offset:34816
	ds_read_b128 v[224:227], v149 offset:35840
	ds_read_b128 v[228:231], v149 offset:36864
	ds_read_b128 v[232:235], v149 offset:37888
	ds_read_b128 v[236:239], v149 offset:38912
	ds_read_b128 v[240:243], v149 offset:39936
	s_add_u32 s30, s46, 0x80100
	s_addc_u32 s31, s47, 0
	s_mov_b32 m0, s58
	s_nop 0
	global_load_lds_dwordx4 v1, s[30:31] offset:0
	s_nop 0
	s_mov_b32 m0, s59
	s_nop 0
	global_load_lds_dwordx4 v143, s[30:31] offset:0
	s_waitcnt vmcnt(8)
	s_waitcnt lgkmcnt(0)
	s_barrier
	s_setprio 1
	v_mfma_f32_16x16x32_bf16 v[68:71], v[12:15], v[30:33], v[68:71]
	v_mfma_f32_16x16x32_bf16 v[130:133], v[16:19], v[64:67], v[68:71]
	v_mfma_f32_16x16x32_bf16 v[68:71], v[22:25], v[30:33], v[72:75]
	v_mfma_f32_16x16x32_bf16 v[126:129], v[26:29], v[64:67], v[68:71]
	v_mfma_f32_16x16x32_bf16 v[68:71], v[12:15], v[220:223], v[76:79]
	v_mfma_f32_16x16x32_bf16 v[114:117], v[16:19], v[224:227], v[68:71]
	v_mfma_f32_16x16x32_bf16 v[68:71], v[22:25], v[220:223], v[80:83]
	v_mfma_f32_16x16x32_bf16 v[110:113], v[26:29], v[224:227], v[68:71]
	v_mfma_f32_16x16x32_bf16 v[68:71], v[12:15], v[228:231], v[84:87]
	v_mfma_f32_16x16x32_bf16 v[98:101], v[16:19], v[232:235], v[68:71]
	v_mfma_f32_16x16x32_bf16 v[68:71], v[22:25], v[228:231], v[88:91]
	v_mfma_f32_16x16x32_bf16 v[94:97], v[26:29], v[232:235], v[68:71]
	v_mfma_f32_16x16x32_bf16 v[68:71], v[12:15], v[236:239], v[102:105]
	v_mfma_f32_16x16x32_bf16 v[82:85], v[16:19], v[240:243], v[68:71]
	v_mfma_f32_16x16x32_bf16 v[68:71], v[22:25], v[236:239], v[106:109]
	v_mfma_f32_16x16x32_bf16 v[78:81], v[26:29], v[240:243], v[68:71]
	v_mfma_f32_16x16x32_bf16 v[68:71], v[204:207], v[30:33], v[118:121]
	v_mfma_f32_16x16x32_bf16 v[30:33], v[212:215], v[30:33], v[36:39]
	v_mfma_f32_16x16x32_bf16 v[118:121], v[216:219], v[64:67], v[30:33]
	v_mfma_f32_16x16x32_bf16 v[30:33], v[204:207], v[220:223], v[40:43]
	v_mfma_f32_16x16x32_bf16 v[106:109], v[208:211], v[224:227], v[30:33]
	v_mfma_f32_16x16x32_bf16 v[30:33], v[212:215], v[220:223], v[44:47]
	v_mfma_f32_16x16x32_bf16 v[102:105], v[216:219], v[224:227], v[30:33]
	v_mfma_f32_16x16x32_bf16 v[30:33], v[204:207], v[228:231], v[48:51]
	v_mfma_f32_16x16x32_bf16 v[90:93], v[208:211], v[232:235], v[30:33]
	v_mfma_f32_16x16x32_bf16 v[30:33], v[212:215], v[228:231], v[52:55]
	v_mfma_f32_16x16x32_bf16 v[86:89], v[216:219], v[232:235], v[30:33]
	v_mfma_f32_16x16x32_bf16 v[30:33], v[204:207], v[236:239], v[56:59]
	v_mfma_f32_16x16x32_bf16 v[74:77], v[208:211], v[240:243], v[30:33]
	v_mfma_f32_16x16x32_bf16 v[30:33], v[212:215], v[236:239], v[60:63]
	v_mfma_f32_16x16x32_bf16 v[122:125], v[208:211], v[64:67], v[68:71]
	v_mfma_f32_16x16x32_bf16 v[70:73], v[216:219], v[240:243], v[30:33]
	s_barrier
	s_setprio 0
	ds_read_b128 v[38:41], v149 offset:49152
	ds_read_b128 v[42:45], v149 offset:50176
	ds_read_b128 v[220:223], v149 offset:51200
	ds_read_b128 v[224:227], v149 offset:52224
	ds_read_b128 v[228:231], v149 offset:53248
	ds_read_b128 v[232:235], v149 offset:54272
	ds_read_b128 v[236:239], v149 offset:55296
	ds_read_b128 v[240:243], v149 offset:56320
	s_add_u32 s30, s48, 0x180
	s_addc_u32 s31, s49, 0
	s_mov_b32 m0, s67
	s_nop 0
	global_load_lds_dwordx4 v142, s[30:31] offset:0
	s_nop 0
	s_mov_b32 m0, s68
	s_nop 0
	global_load_lds_dwordx4 v144, s[30:31] offset:0
	s_add_u32 s30, s48, 0x80180
	s_addc_u32 s31, s49, 0
	s_mov_b32 m0, s71
	s_nop 0
	global_load_lds_dwordx4 v142, s[30:31] offset:0
	s_nop 0
	s_mov_b32 m0, s72
	s_nop 0
	global_load_lds_dwordx4 v144, s[30:31] offset:0
	s_nop 0
	s_mov_b32 m0, s69
	s_nop 0
	global_load_lds_dwordx4 v1, s[38:39] offset:0
	s_nop 0
	s_mov_b32 m0, s70
	s_nop 0
	global_load_lds_dwordx4 v143, s[38:39] offset:0
	s_waitcnt vmcnt(8)
	s_waitcnt lgkmcnt(0)
	s_barrier
	s_setprio 1
	v_mfma_f32_16x16x32_bf16 v[30:33], v[12:15], v[38:41], v[138:141]
	v_mfma_f32_16x16x32_bf16 v[66:69], v[16:19], v[42:45], v[30:33]
	v_mfma_f32_16x16x32_bf16 v[30:33], v[22:25], v[38:41], v[152:155]
	v_mfma_f32_16x16x32_bf16 v[62:65], v[26:29], v[42:45], v[30:33]
	v_mfma_f32_16x16x32_bf16 v[30:33], v[12:15], v[220:223], v[156:159]
	v_mfma_f32_16x16x32_bf16 v[50:53], v[16:19], v[224:227], v[30:33]
	v_mfma_f32_16x16x32_bf16 v[30:33], v[22:25], v[220:223], v[160:163]
	v_mfma_f32_16x16x32_bf16 v[46:49], v[26:29], v[224:227], v[30:33]
	v_mfma_f32_16x16x32_bf16 v[30:33], v[12:15], v[228:231], v[164:167]
	v_mfma_f32_16x16x32_bf16 v[4:7], v[12:15], v[236:239], v[4:7]
	v_mfma_f32_16x16x32_bf16 v[34:37], v[16:19], v[232:235], v[30:33]
	v_mfma_f32_16x16x32_bf16 v[30:33], v[22:25], v[228:231], v[168:171]
	v_mfma_f32_16x16x32_bf16 v[18:21], v[16:19], v[240:243], v[4:7]
	v_mfma_f32_16x16x32_bf16 v[4:7], v[22:25], v[236:239], v[8:11]
	v_mfma_f32_16x16x32_bf16 v[30:33], v[26:29], v[232:235], v[30:33]
	v_mfma_f32_16x16x32_bf16 v[14:17], v[26:29], v[240:243], v[4:7]
	v_mfma_f32_16x16x32_bf16 v[4:7], v[204:207], v[38:41], v[172:175]
	v_mfma_f32_16x16x32_bf16 v[58:61], v[208:211], v[42:45], v[4:7]
	v_mfma_f32_16x16x32_bf16 v[4:7], v[212:215], v[38:41], v[176:179]
	v_mfma_f32_16x16x32_bf16 v[54:57], v[216:219], v[42:45], v[4:7]
	v_mfma_f32_16x16x32_bf16 v[4:7], v[204:207], v[220:223], v[180:183]
	v_mfma_f32_16x16x32_bf16 v[42:45], v[208:211], v[224:227], v[4:7]
	v_mfma_f32_16x16x32_bf16 v[4:7], v[212:215], v[220:223], v[184:187]
	v_mfma_f32_16x16x32_bf16 v[38:41], v[216:219], v[224:227], v[4:7]
	v_mfma_f32_16x16x32_bf16 v[4:7], v[204:207], v[228:231], v[188:191]
	v_mfma_f32_16x16x32_bf16 v[26:29], v[208:211], v[232:235], v[4:7]
	v_mfma_f32_16x16x32_bf16 v[4:7], v[212:215], v[228:231], v[192:195]
	v_mfma_f32_16x16x32_bf16 v[22:25], v[216:219], v[232:235], v[4:7]
	v_mfma_f32_16x16x32_bf16 v[4:7], v[204:207], v[236:239], v[196:199]
	v_mfma_f32_16x16x32_bf16 v[10:13], v[208:211], v[240:243], v[4:7]
	v_mfma_f32_16x16x32_bf16 v[4:7], v[212:215], v[236:239], v[200:203]
	v_mfma_f32_16x16x32_bf16 v[6:9], v[216:219], v[240:243], v[4:7]
	s_barrier
	s_setprio 0
	s_mov_b32 s50, 2
	s_branch .LBB0_3467

.LBB0_3468:
	ds_read_b128 v[138:141], v147
	ds_read_b128 v[152:155], v147 offset:1024
	ds_read_b128 v[156:159], v147 offset:2048
	ds_read_b128 v[160:163], v147 offset:3072
	ds_read_b128 v[164:167], v148
	ds_read_b128 v[168:171], v148 offset:1024
	ds_read_b128 v[172:175], v148 offset:2048
	ds_read_b128 v[176:179], v148 offset:3072
	s_cmp_eq_u32 s80, 28
	s_cselect_b32 s52, s43, s83
	s_cselect_b32 s53, s37, s84
	s_cselect_b32 s50, s79, s81
	s_cselect_b32 s51, s29, s82
	s_add_u32 s48, s52, 0x80
	s_addc_u32 s49, s53, 0
	ds_read_b128 v[180:183], v149
	ds_read_b128 v[184:187], v149 offset:1024
	ds_read_b128 v[188:191], v149 offset:2048
	ds_read_b128 v[192:195], v149 offset:3072
	ds_read_b128 v[196:199], v149 offset:4096
	ds_read_b128 v[200:203], v149 offset:5120
	ds_read_b128 v[204:207], v149 offset:6144
	ds_read_b128 v[208:211], v149 offset:7168
	s_mov_b32 m0, s73
	s_nop 0
	global_load_lds_dwordx4 v1, s[46:47] offset:0
	s_nop 0
	s_mov_b32 m0, s74
	s_nop 0
	global_load_lds_dwordx4 v143, s[46:47] offset:0
	s_waitcnt vmcnt(8)
	s_waitcnt lgkmcnt(0)
	s_barrier
	s_setprio 1
	v_mfma_f32_16x16x32_bf16 v[130:133], v[138:141], v[180:183], v[130:133]
	v_mfma_f32_16x16x32_bf16 v[130:133], v[152:155], v[184:187], v[130:133]
	v_mfma_f32_16x16x32_bf16 v[126:129], v[156:159], v[180:183], v[126:129]
	v_mfma_f32_16x16x32_bf16 v[126:129], v[160:163], v[184:187], v[126:129]
	v_mfma_f32_16x16x32_bf16 v[114:117], v[138:141], v[188:191], v[114:117]
	v_mfma_f32_16x16x32_bf16 v[114:117], v[152:155], v[192:195], v[114:117]
	v_mfma_f32_16x16x32_bf16 v[110:113], v[156:159], v[188:191], v[110:113]
	v_mfma_f32_16x16x32_bf16 v[110:113], v[160:163], v[192:195], v[110:113]
	v_mfma_f32_16x16x32_bf16 v[98:101], v[138:141], v[196:199], v[98:101]
	v_mfma_f32_16x16x32_bf16 v[98:101], v[152:155], v[200:203], v[98:101]
	v_mfma_f32_16x16x32_bf16 v[94:97], v[156:159], v[196:199], v[94:97]
	v_mfma_f32_16x16x32_bf16 v[94:97], v[160:163], v[200:203], v[94:97]
	v_mfma_f32_16x16x32_bf16 v[82:85], v[138:141], v[204:207], v[82:85]
	v_mfma_f32_16x16x32_bf16 v[82:85], v[152:155], v[208:211], v[82:85]
	v_mfma_f32_16x16x32_bf16 v[78:81], v[156:159], v[204:207], v[78:81]
	v_mfma_f32_16x16x32_bf16 v[78:81], v[160:163], v[208:211], v[78:81]
	v_mfma_f32_16x16x32_bf16 v[122:125], v[164:167], v[180:183], v[122:125]
	v_mfma_f32_16x16x32_bf16 v[122:125], v[168:171], v[184:187], v[122:125]
	v_mfma_f32_16x16x32_bf16 v[118:121], v[172:175], v[180:183], v[118:121]
	v_mfma_f32_16x16x32_bf16 v[118:121], v[176:179], v[184:187], v[118:121]
	v_mfma_f32_16x16x32_bf16 v[106:109], v[164:167], v[188:191], v[106:109]
	v_mfma_f32_16x16x32_bf16 v[106:109], v[168:171], v[192:195], v[106:109]
	v_mfma_f32_16x16x32_bf16 v[102:105], v[172:175], v[188:191], v[102:105]
	v_mfma_f32_16x16x32_bf16 v[102:105], v[176:179], v[192:195], v[102:105]
	v_mfma_f32_16x16x32_bf16 v[90:93], v[164:167], v[196:199], v[90:93]
	v_mfma_f32_16x16x32_bf16 v[90:93], v[168:171], v[200:203], v[90:93]
	v_mfma_f32_16x16x32_bf16 v[86:89], v[172:175], v[196:199], v[86:89]
	v_mfma_f32_16x16x32_bf16 v[86:89], v[176:179], v[200:203], v[86:89]
	v_mfma_f32_16x16x32_bf16 v[74:77], v[164:167], v[204:207], v[74:77]
	v_mfma_f32_16x16x32_bf16 v[74:77], v[168:171], v[208:211], v[74:77]
	v_mfma_f32_16x16x32_bf16 v[70:73], v[172:175], v[204:207], v[70:73]
	v_mfma_f32_16x16x32_bf16 v[70:73], v[176:179], v[208:211], v[70:73]
	s_barrier
	s_setprio 0
	ds_read_b128 v[180:183], v149 offset:16384
	ds_read_b128 v[184:187], v149 offset:17408
	ds_read_b128 v[188:191], v149 offset:18432
	ds_read_b128 v[192:195], v149 offset:19456
	ds_read_b128 v[196:199], v149 offset:20480
	ds_read_b128 v[200:203], v149 offset:21504
	ds_read_b128 v[204:207], v149 offset:22528
	ds_read_b128 v[208:211], v149 offset:23552
	s_mov_b32 m0, s45
	s_nop 0
	global_load_lds_dwordx4 v142, s[50:51] offset:0
	s_add_u32 s30, s50, 0x80000
	s_mov_b32 m0, s54
	s_nop 0
	global_load_lds_dwordx4 v144, s[50:51] offset:0
	s_addc_u32 s31, s51, 0
	s_mov_b32 m0, s55
	s_nop 0
	global_load_lds_dwordx4 v142, s[30:31] offset:0
	s_nop 0
	s_mov_b32 m0, s56
	s_nop 0
	global_load_lds_dwordx4 v144, s[30:31] offset:0
	s_nop 0
	s_mov_b32 m0, s33
	s_nop 0
	global_load_lds_dwordx4 v1, s[52:53] offset:0
	s_nop 0
	s_mov_b32 m0, s57
	s_nop 0
	global_load_lds_dwordx4 v143, s[52:53] offset:0
	s_waitcnt vmcnt(8)
	s_waitcnt lgkmcnt(0)
	s_barrier
	s_setprio 1
	v_mfma_f32_16x16x32_bf16 v[66:69], v[138:141], v[180:183], v[66:69]
	v_mfma_f32_16x16x32_bf16 v[66:69], v[152:155], v[184:187], v[66:69]
	v_mfma_f32_16x16x32_bf16 v[62:65], v[156:159], v[180:183], v[62:65]
	v_mfma_f32_16x16x32_bf16 v[62:65], v[160:163], v[184:187], v[62:65]
	v_mfma_f32_16x16x32_bf16 v[50:53], v[138:141], v[188:191], v[50:53]
	v_mfma_f32_16x16x32_bf16 v[50:53], v[152:155], v[192:195], v[50:53]
	v_mfma_f32_16x16x32_bf16 v[46:49], v[156:159], v[188:191], v[46:49]
	v_mfma_f32_16x16x32_bf16 v[46:49], v[160:163], v[192:195], v[46:49]
	v_mfma_f32_16x16x32_bf16 v[34:37], v[138:141], v[196:199], v[34:37]
	v_mfma_f32_16x16x32_bf16 v[34:37], v[152:155], v[200:203], v[34:37]
	v_mfma_f32_16x16x32_bf16 v[30:33], v[156:159], v[196:199], v[30:33]
	v_mfma_f32_16x16x32_bf16 v[30:33], v[160:163], v[200:203], v[30:33]
	v_mfma_f32_16x16x32_bf16 v[18:21], v[138:141], v[204:207], v[18:21]
	v_mfma_f32_16x16x32_bf16 v[18:21], v[152:155], v[208:211], v[18:21]
	v_mfma_f32_16x16x32_bf16 v[14:17], v[156:159], v[204:207], v[14:17]
	v_mfma_f32_16x16x32_bf16 v[14:17], v[160:163], v[208:211], v[14:17]
	v_mfma_f32_16x16x32_bf16 v[58:61], v[164:167], v[180:183], v[58:61]
	v_mfma_f32_16x16x32_bf16 v[54:57], v[172:175], v[180:183], v[54:57]
	v_mfma_f32_16x16x32_bf16 v[42:45], v[164:167], v[188:191], v[42:45]
	v_mfma_f32_16x16x32_bf16 v[38:41], v[172:175], v[188:191], v[38:41]
	v_mfma_f32_16x16x32_bf16 v[26:29], v[164:167], v[196:199], v[26:29]
	v_mfma_f32_16x16x32_bf16 v[22:25], v[172:175], v[196:199], v[22:25]
	v_mfma_f32_16x16x32_bf16 v[10:13], v[164:167], v[204:207], v[10:13]
	v_mfma_f32_16x16x32_bf16 v[4:7], v[172:175], v[204:207], v[6:9]
	v_mfma_f32_16x16x32_bf16 v[58:61], v[168:171], v[184:187], v[58:61]
	v_mfma_f32_16x16x32_bf16 v[54:57], v[176:179], v[184:187], v[54:57]
	v_mfma_f32_16x16x32_bf16 v[42:45], v[168:171], v[192:195], v[42:45]
	v_mfma_f32_16x16x32_bf16 v[38:41], v[176:179], v[192:195], v[38:41]
	v_mfma_f32_16x16x32_bf16 v[26:29], v[168:171], v[200:203], v[26:29]
	v_mfma_f32_16x16x32_bf16 v[22:25], v[176:179], v[200:203], v[22:25]
	v_mfma_f32_16x16x32_bf16 v[10:13], v[168:171], v[208:211], v[10:13]
	v_mfma_f32_16x16x32_bf16 v[4:7], v[176:179], v[208:211], v[4:7]
	s_barrier
; #define PG8_BAR __builtin_amdgcn_s_barrier()
; #define PG8_KSETUP() const bool last = (t == nt - 2); const char* a1 = cA + (size_t)(t + 1) * kstep; \
;             const char* a2 = last ? nA : cA + (size_t)(t + 2) * kstep; const char* b2 = last ? nB : cB + (size_t)(t + 2) * kstep; const char* a3 = a2 + kstep; const char* b3 = b2 + kstep; \
;             if (last && has_next) S.a_ready(nxt)
; template <class Epi, class Sched, bool ALIGN_EPI = false, bool SP2 = false>
; __device__ __forceinline__ void gemm_phase(PG8_LAS unsigned char* lds, const Gemm g, const Sched& S, const Epi& E) {
;     ...
;         int t0 = 0;
;         if constexpr (SP2 && Epi::NVM == 16) { if (ui > 0) { const int t = 0; PG8_KSETUP(); PG8_KITER_SP2(24, 24); t0 = 2; } }
;         if constexpr (SP2 && Epi::NVM == 8) { if (ui > 0) { const int t = 0; PG8_KSETUP(); PG8_KITER_SP2(16, 16); t0 = 2; } }
;         for (int t = t0; t < nt; t += 2) {
;     ...
;         if constexpr (ALIGN_EPI) { if (wr == 0) PG8_BAR; }
	s_setprio 0
	ds_read_b128 v[138:141], v150
	ds_read_b128 v[152:155], v150 offset:1024
	ds_read_b128 v[156:159], v150 offset:2048
	ds_read_b128 v[160:163], v150 offset:3072
	ds_read_b128 v[164:167], v151
	ds_read_b128 v[168:171], v151 offset:1024
	ds_read_b128 v[172:175], v151 offset:2048
	ds_read_b128 v[176:179], v151 offset:3072
	ds_read_b128 v[180:183], v149 offset:32768
	ds_read_b128 v[184:187], v149 offset:33792
	ds_read_b128 v[188:191], v149 offset:34816
	ds_read_b128 v[192:195], v149 offset:35840
	ds_read_b128 v[196:199], v149 offset:36864
	ds_read_b128 v[200:203], v149 offset:37888
	ds_read_b128 v[204:207], v149 offset:38912
	ds_read_b128 v[208:211], v149 offset:39936
	s_add_u32 s30, s52, 0x80000
	s_addc_u32 s31, s53, 0
	s_mov_b32 m0, s58
	s_nop 0
	global_load_lds_dwordx4 v1, s[30:31] offset:0
	s_nop 0
	s_mov_b32 m0, s59
	s_nop 0
	global_load_lds_dwordx4 v143, s[30:31] offset:0
	s_waitcnt vmcnt(8)
	s_waitcnt lgkmcnt(0)
	s_barrier
	s_setprio 1
	v_mfma_f32_16x16x32_bf16 v[130:133], v[138:141], v[180:183], v[130:133]
	v_mfma_f32_16x16x32_bf16 v[130:133], v[152:155], v[184:187], v[130:133]
	v_mfma_f32_16x16x32_bf16 v[126:129], v[156:159], v[180:183], v[126:129]
	v_mfma_f32_16x16x32_bf16 v[126:129], v[160:163], v[184:187], v[126:129]
	v_mfma_f32_16x16x32_bf16 v[114:117], v[138:141], v[188:191], v[114:117]
	v_mfma_f32_16x16x32_bf16 v[114:117], v[152:155], v[192:195], v[114:117]
	v_mfma_f32_16x16x32_bf16 v[110:113], v[156:159], v[188:191], v[110:113]
	v_mfma_f32_16x16x32_bf16 v[110:113], v[160:163], v[192:195], v[110:113]
	v_mfma_f32_16x16x32_bf16 v[98:101], v[138:141], v[196:199], v[98:101]
	v_mfma_f32_16x16x32_bf16 v[98:101], v[152:155], v[200:203], v[98:101]
	v_mfma_f32_16x16x32_bf16 v[94:97], v[156:159], v[196:199], v[94:97]
	v_mfma_f32_16x16x32_bf16 v[94:97], v[160:163], v[200:203], v[94:97]
	v_mfma_f32_16x16x32_bf16 v[82:85], v[138:141], v[204:207], v[82:85]
	v_mfma_f32_16x16x32_bf16 v[82:85], v[152:155], v[208:211], v[82:85]
	v_mfma_f32_16x16x32_bf16 v[78:81], v[156:159], v[204:207], v[78:81]
	v_mfma_f32_16x16x32_bf16 v[78:81], v[160:163], v[208:211], v[78:81]
	v_mfma_f32_16x16x32_bf16 v[122:125], v[164:167], v[180:183], v[122:125]
	v_mfma_f32_16x16x32_bf16 v[122:125], v[168:171], v[184:187], v[122:125]
	v_mfma_f32_16x16x32_bf16 v[118:121], v[172:175], v[180:183], v[118:121]
	v_mfma_f32_16x16x32_bf16 v[118:121], v[176:179], v[184:187], v[118:121]
	v_mfma_f32_16x16x32_bf16 v[106:109], v[164:167], v[188:191], v[106:109]
	v_mfma_f32_16x16x32_bf16 v[106:109], v[168:171], v[192:195], v[106:109]
	v_mfma_f32_16x16x32_bf16 v[102:105], v[172:175], v[188:191], v[102:105]
	v_mfma_f32_16x16x32_bf16 v[102:105], v[176:179], v[192:195], v[102:105]
	v_mfma_f32_16x16x32_bf16 v[90:93], v[164:167], v[196:199], v[90:93]
	v_mfma_f32_16x16x32_bf16 v[90:93], v[168:171], v[200:203], v[90:93]
	v_mfma_f32_16x16x32_bf16 v[86:89], v[172:175], v[196:199], v[86:89]
	v_mfma_f32_16x16x32_bf16 v[86:89], v[176:179], v[200:203], v[86:89]
	v_mfma_f32_16x16x32_bf16 v[74:77], v[164:167], v[204:207], v[74:77]
	v_mfma_f32_16x16x32_bf16 v[74:77], v[168:171], v[208:211], v[74:77]
	v_mfma_f32_16x16x32_bf16 v[70:73], v[172:175], v[204:207], v[70:73]
	v_mfma_f32_16x16x32_bf16 v[70:73], v[176:179], v[208:211], v[70:73]
	s_barrier
	s_setprio 0
	ds_read_b128 v[180:183], v149 offset:49152
	ds_read_b128 v[184:187], v149 offset:50176
	ds_read_b128 v[188:191], v149 offset:51200
	ds_read_b128 v[192:195], v149 offset:52224
	ds_read_b128 v[196:199], v149 offset:53248
	ds_read_b128 v[200:203], v149 offset:54272
	ds_read_b128 v[204:207], v149 offset:55296
	ds_read_b128 v[208:211], v149 offset:56320
	s_add_u32 s30, s50, 0x80
	s_addc_u32 s31, s51, 0
	s_mov_b32 m0, s67
	s_nop 0
	global_load_lds_dwordx4 v142, s[30:31] offset:0
	s_nop 0
	s_mov_b32 m0, s68
	s_nop 0
	global_load_lds_dwordx4 v144, s[30:31] offset:0
	s_add_u32 s30, s50, 0x80080
	s_addc_u32 s31, s51, 0
	s_mov_b32 m0, s71
	s_nop 0
	global_load_lds_dwordx4 v142, s[30:31] offset:0
	s_nop 0
	s_mov_b32 m0, s72
	s_nop 0
	global_load_lds_dwordx4 v144, s[30:31] offset:0
	s_nop 0
	s_mov_b32 m0, s69
	s_nop 0
	global_load_lds_dwordx4 v1, s[48:49] offset:0
	s_nop 0
	s_mov_b32 m0, s70
	s_nop 0
	global_load_lds_dwordx4 v143, s[48:49] offset:0
	s_waitcnt vmcnt(8)
	s_waitcnt lgkmcnt(0)
	s_barrier
	s_setprio 1
	v_mfma_f32_16x16x32_bf16 v[66:69], v[138:141], v[180:183], v[66:69]
	v_mfma_f32_16x16x32_bf16 v[66:69], v[152:155], v[184:187], v[66:69]
	v_mfma_f32_16x16x32_bf16 v[62:65], v[156:159], v[180:183], v[62:65]
	v_mfma_f32_16x16x32_bf16 v[62:65], v[160:163], v[184:187], v[62:65]
	v_mfma_f32_16x16x32_bf16 v[50:53], v[138:141], v[188:191], v[50:53]
	v_mfma_f32_16x16x32_bf16 v[50:53], v[152:155], v[192:195], v[50:53]
	v_mfma_f32_16x16x32_bf16 v[46:49], v[156:159], v[188:191], v[46:49]
	v_mfma_f32_16x16x32_bf16 v[46:49], v[160:163], v[192:195], v[46:49]
	v_mfma_f32_16x16x32_bf16 v[34:37], v[138:141], v[196:199], v[34:37]
	v_mfma_f32_16x16x32_bf16 v[34:37], v[152:155], v[200:203], v[34:37]
	v_mfma_f32_16x16x32_bf16 v[30:33], v[156:159], v[196:199], v[30:33]
	v_mfma_f32_16x16x32_bf16 v[30:33], v[160:163], v[200:203], v[30:33]
	v_mfma_f32_16x16x32_bf16 v[18:21], v[138:141], v[204:207], v[18:21]
	v_mfma_f32_16x16x32_bf16 v[18:21], v[152:155], v[208:211], v[18:21]
	v_mfma_f32_16x16x32_bf16 v[14:17], v[156:159], v[204:207], v[14:17]
	v_mfma_f32_16x16x32_bf16 v[14:17], v[160:163], v[208:211], v[14:17]
	v_mfma_f32_16x16x32_bf16 v[58:61], v[164:167], v[180:183], v[58:61]
	v_mfma_f32_16x16x32_bf16 v[54:57], v[172:175], v[180:183], v[54:57]
	v_mfma_f32_16x16x32_bf16 v[42:45], v[164:167], v[188:191], v[42:45]
	v_mfma_f32_16x16x32_bf16 v[38:41], v[172:175], v[188:191], v[38:41]
	v_mfma_f32_16x16x32_bf16 v[26:29], v[164:167], v[196:199], v[26:29]
	v_mfma_f32_16x16x32_bf16 v[22:25], v[172:175], v[196:199], v[22:25]
	v_mfma_f32_16x16x32_bf16 v[8:11], v[164:167], v[204:207], v[10:13]
	v_mfma_f32_16x16x32_bf16 v[4:7], v[172:175], v[204:207], v[4:7]
	v_mfma_f32_16x16x32_bf16 v[58:61], v[168:171], v[184:187], v[58:61]
	v_mfma_f32_16x16x32_bf16 v[54:57], v[176:179], v[184:187], v[54:57]
	v_mfma_f32_16x16x32_bf16 v[42:45], v[168:171], v[192:195], v[42:45]
	v_mfma_f32_16x16x32_bf16 v[38:41], v[176:179], v[192:195], v[38:41]
	v_mfma_f32_16x16x32_bf16 v[26:29], v[168:171], v[200:203], v[26:29]
	v_mfma_f32_16x16x32_bf16 v[22:25], v[176:179], v[200:203], v[22:25]
	v_mfma_f32_16x16x32_bf16 v[10:13], v[168:171], v[208:211], v[8:11]
	v_mfma_f32_16x16x32_bf16 v[6:9], v[176:179], v[208:211], v[4:7]
	s_barrier
	s_setprio 0
	s_add_i32 s80, s80, 2
	s_add_u32 s81, s81, 0x100
	s_addc_u32 s82, s82, 0
	s_add_u32 s83, s83, 0x100
	s_addc_u32 s84, s84, 0
	s_add_u32 s46, s46, 0x100
	s_addc_u32 s47, s47, 0
	s_cmp_gt_u32 s80, 29
	s_cbranch_scc0 .LBB0_3468
	s_and_b64 vcc, exec, s[18:19]
	s_cbranch_vccz .LBB0_3471
	s_barrier

; #define PG8_KSETUP() const bool last = (t == nt - 2); const char* a1 = cA + (size_t)(t + 1) * kstep; \
;             const char* a2 = last ? nA : cA + (size_t)(t + 2) * kstep; const char* b2 = last ? nB : cB + (size_t)(t + 2) * kstep; const char* a3 = a2 + kstep; const char* b3 = b2 + kstep; \
;             if (last && has_next) S.a_ready(nxt)
; template <class Epi, class Sched, bool ALIGN_EPI = false, bool SP2 = false>
; __device__ __forceinline__ void gemm_phase(PG8_LAS unsigned char* lds, const Gemm g, const Sched& S, const Epi& E) {
;     ...
;         if constexpr (SP2 && Epi::NVM == 8) { if (ui > 0) { const int t = 0; PG8_KSETUP(); PG8_KITER_SP2(16, 16); t0 = 2; } }
.LBB0_3617:
	s_cmp_lg_u32 s69, 0
	s_mov_b32 s40, 0
	s_cbranch_scc0 .LBB0_3619
	ds_read_b128 v[4:7], v152
	ds_read_b128 v[8:11], v152 offset:1024
	ds_read_b128 v[12:15], v152 offset:2048
	ds_read_b128 v[16:19], v152 offset:3072
	ds_read_b128 v[20:23], v153
	ds_read_b128 v[24:27], v153 offset:1024
	ds_read_b128 v[28:31], v153 offset:2048
	ds_read_b128 v[32:35], v153 offset:3072
	s_add_u32 s24, s36, 0x100
	s_addc_u32 s25, s37, 0
	s_add_u32 s30, s38, 0x100
	s_addc_u32 s31, s39, 0
	s_add_u32 s22, s36, 0x180
	s_addc_u32 s23, s37, 0
	ds_read_b128 v[36:39], v154
	ds_read_b128 v[40:43], v154 offset:1024
	ds_read_b128 v[44:47], v154 offset:2048
	ds_read_b128 v[48:51], v154 offset:3072
	ds_read_b128 v[52:55], v154 offset:4096
	ds_read_b128 v[56:59], v154 offset:5120
	ds_read_b128 v[60:63], v154 offset:6144
	ds_read_b128 v[64:67], v154 offset:7168
	s_add_u32 s40, s36, 0x80080
	s_addc_u32 s41, s37, 0
	s_mov_b32 m0, s56
	s_nop 0
	global_load_lds_dwordx4 v1, s[40:41] offset:0
	s_nop 0
	s_mov_b32 m0, s57
	s_nop 0
	global_load_lds_dwordx4 v147, s[40:41] offset:0
	s_waitcnt vmcnt(16)
	s_waitcnt lgkmcnt(0)
	s_barrier
	s_setprio 1
	v_mfma_f32_16x16x32_bf16 v[92:95], v[4:7], v[60:63], 0
	v_mfma_f32_16x16x32_bf16 v[68:71], v[4:7], v[36:39], 0
	v_mfma_f32_16x16x32_bf16 v[72:75], v[12:15], v[36:39], 0
	v_mfma_f32_16x16x32_bf16 v[76:79], v[4:7], v[44:47], 0
	v_mfma_f32_16x16x32_bf16 v[80:83], v[12:15], v[44:47], 0
	v_mfma_f32_16x16x32_bf16 v[84:87], v[4:7], v[52:55], 0
	v_mfma_f32_16x16x32_bf16 v[88:91], v[12:15], v[52:55], 0
	v_mfma_f32_16x16x32_bf16 v[102:105], v[8:11], v[64:67], v[92:95]
	v_mfma_f32_16x16x32_bf16 v[92:95], v[12:15], v[60:63], 0
	v_mfma_f32_16x16x32_bf16 v[68:71], v[8:11], v[40:43], v[68:71]
	v_mfma_f32_16x16x32_bf16 v[72:75], v[16:19], v[40:43], v[72:75]
	v_mfma_f32_16x16x32_bf16 v[76:79], v[8:11], v[48:51], v[76:79]
	v_mfma_f32_16x16x32_bf16 v[80:83], v[16:19], v[48:51], v[80:83]
	v_mfma_f32_16x16x32_bf16 v[84:87], v[8:11], v[56:59], v[84:87]
	v_mfma_f32_16x16x32_bf16 v[88:91], v[16:19], v[56:59], v[88:91]
	v_mfma_f32_16x16x32_bf16 v[106:109], v[16:19], v[64:67], v[92:95]
	v_mfma_f32_16x16x32_bf16 v[92:95], v[20:23], v[36:39], 0
	v_mfma_f32_16x16x32_bf16 v[36:39], v[28:31], v[36:39], 0
	v_mfma_f32_16x16x32_bf16 v[118:121], v[24:27], v[40:43], v[92:95]
	v_mfma_f32_16x16x32_bf16 v[36:39], v[32:35], v[40:43], v[36:39]
	v_mfma_f32_16x16x32_bf16 v[40:43], v[20:23], v[44:47], 0
	v_mfma_f32_16x16x32_bf16 v[44:47], v[28:31], v[44:47], 0
	v_mfma_f32_16x16x32_bf16 v[40:43], v[24:27], v[48:51], v[40:43]
	v_mfma_f32_16x16x32_bf16 v[44:47], v[32:35], v[48:51], v[44:47]
	v_mfma_f32_16x16x32_bf16 v[48:51], v[20:23], v[52:55], 0
	v_mfma_f32_16x16x32_bf16 v[52:55], v[28:31], v[52:55], 0
	v_mfma_f32_16x16x32_bf16 v[48:51], v[24:27], v[56:59], v[48:51]
	v_mfma_f32_16x16x32_bf16 v[52:55], v[32:35], v[56:59], v[52:55]
	v_mfma_f32_16x16x32_bf16 v[56:59], v[20:23], v[60:63], 0
	v_mfma_f32_16x16x32_bf16 v[60:63], v[28:31], v[60:63], 0
	v_mfma_f32_16x16x32_bf16 v[56:59], v[24:27], v[64:67], v[56:59]
	v_mfma_f32_16x16x32_bf16 v[60:63], v[32:35], v[64:67], v[60:63]
	s_barrier
	s_setprio 0
	ds_read_b128 v[64:67], v154 offset:16384
	ds_read_b128 v[92:95], v154 offset:17408
	ds_read_b128 v[96:99], v154 offset:18432
	ds_read_b128 v[110:113], v154 offset:19456
	ds_read_b128 v[114:117], v154 offset:20480
	ds_read_b128 v[122:125], v154 offset:21504
	ds_read_b128 v[126:129], v154 offset:22528
	ds_read_b128 v[130:133], v154 offset:23552
	s_mov_b32 m0, s29
	s_nop 0
	global_load_lds_dwordx4 v146, s[30:31] offset:0
	s_nop 0
	s_mov_b32 m0, s44
	s_nop 0
	global_load_lds_dwordx4 v148, s[30:31] offset:0
	s_add_u32 s30, s38, 0x80100
	s_addc_u32 s31, s39, 0
	s_mov_b32 m0, s45
	s_nop 0
	global_load_lds_dwordx4 v146, s[30:31] offset:0
	s_nop 0
	s_mov_b32 m0, s46
	s_nop 0
	global_load_lds_dwordx4 v148, s[30:31] offset:0
	s_nop 0
	s_mov_b32 m0, s21
	s_nop 0
	global_load_lds_dwordx4 v1, s[24:25] offset:0
	s_nop 0
	s_mov_b32 m0, s47
	s_nop 0
	global_load_lds_dwordx4 v147, s[24:25] offset:0
	s_waitcnt vmcnt(16)
	s_waitcnt lgkmcnt(0)
	s_barrier
	s_setprio 1
	v_mfma_f32_16x16x32_bf16 v[138:141], v[4:7], v[64:67], 0
	v_mfma_f32_16x16x32_bf16 v[158:161], v[4:7], v[96:99], 0
	v_mfma_f32_16x16x32_bf16 v[166:169], v[4:7], v[114:117], 0
	v_mfma_f32_16x16x32_bf16 v[4:7], v[4:7], v[126:129], 0
	v_mfma_f32_16x16x32_bf16 v[138:141], v[8:11], v[92:95], v[138:141]
	v_mfma_f32_16x16x32_bf16 v[158:161], v[8:11], v[110:113], v[158:161]
	v_mfma_f32_16x16x32_bf16 v[166:169], v[8:11], v[122:125], v[166:169]
	v_mfma_f32_16x16x32_bf16 v[4:7], v[8:11], v[130:133], v[4:7]
	v_mfma_f32_16x16x32_bf16 v[8:11], v[12:15], v[126:129], 0
	v_mfma_f32_16x16x32_bf16 v[142:145], v[12:15], v[64:67], 0
	v_mfma_f32_16x16x32_bf16 v[162:165], v[12:15], v[96:99], 0
	v_mfma_f32_16x16x32_bf16 v[170:173], v[12:15], v[114:117], 0
	v_mfma_f32_16x16x32_bf16 v[8:11], v[16:19], v[130:133], v[8:11]
	v_mfma_f32_16x16x32_bf16 v[142:145], v[16:19], v[92:95], v[142:145]
	v_mfma_f32_16x16x32_bf16 v[162:165], v[16:19], v[110:113], v[162:165]
	v_mfma_f32_16x16x32_bf16 v[170:173], v[16:19], v[122:125], v[170:173]
	v_mfma_f32_16x16x32_bf16 v[12:15], v[20:23], v[64:67], 0
	v_mfma_f32_16x16x32_bf16 v[174:177], v[24:27], v[92:95], v[12:15]
	v_mfma_f32_16x16x32_bf16 v[12:15], v[28:31], v[64:67], 0
	v_mfma_f32_16x16x32_bf16 v[178:181], v[32:35], v[92:95], v[12:15]
	v_mfma_f32_16x16x32_bf16 v[12:15], v[20:23], v[96:99], 0
	v_mfma_f32_16x16x32_bf16 v[182:185], v[24:27], v[110:113], v[12:15]
	v_mfma_f32_16x16x32_bf16 v[12:15], v[28:31], v[96:99], 0
	v_mfma_f32_16x16x32_bf16 v[186:189], v[32:35], v[110:113], v[12:15]
	v_mfma_f32_16x16x32_bf16 v[12:15], v[20:23], v[114:117], 0
	v_mfma_f32_16x16x32_bf16 v[190:193], v[24:27], v[122:125], v[12:15]
	v_mfma_f32_16x16x32_bf16 v[12:15], v[28:31], v[114:117], 0
	v_mfma_f32_16x16x32_bf16 v[194:197], v[32:35], v[122:125], v[12:15]
	v_mfma_f32_16x16x32_bf16 v[12:15], v[20:23], v[126:129], 0
	v_mfma_f32_16x16x32_bf16 v[198:201], v[24:27], v[130:133], v[12:15]
	v_mfma_f32_16x16x32_bf16 v[12:15], v[28:31], v[126:129], 0
	v_mfma_f32_16x16x32_bf16 v[202:205], v[32:35], v[130:133], v[12:15]
	s_barrier
; #define PG8_KSETUP() const bool last = (t == nt - 2); const char* a1 = cA + (size_t)(t + 1) * kstep; \
;             const char* a2 = last ? nA : cA + (size_t)(t + 2) * kstep; const char* b2 = last ? nB : cB + (size_t)(t + 2) * kstep; const char* a3 = a2 + kstep; const char* b3 = b2 + kstep; \
;             if (last && has_next) S.a_ready(nxt)
; template <class Epi, class Sched, bool ALIGN_EPI = false, bool SP2 = false>
; __device__ __forceinline__ void gemm_phase(PG8_LAS unsigned char* lds, const Gemm g, const Sched& S, const Epi& E) {
;     ...
;         int t0 = 0;
;         if constexpr (SP2 && Epi::NVM == 16) { if (ui > 0) { const int t = 0; PG8_KSETUP(); PG8_KITER_SP2(24, 24); t0 = 2; } }
;         if constexpr (SP2 && Epi::NVM == 8) { if (ui > 0) { const int t = 0; PG8_KSETUP(); PG8_KITER_SP2(16, 16); t0 = 2; } }
	s_setprio 0
	s_nop 4
	ds_read_b128 v[12:15], v155
	ds_read_b128 v[16:19], v155 offset:1024
	ds_read_b128 v[22:25], v155 offset:2048
	ds_read_b128 v[26:29], v155 offset:3072
	ds_read_b128 v[206:209], v156
	ds_read_b128 v[210:213], v156 offset:1024
	ds_read_b128 v[214:217], v156 offset:2048
	ds_read_b128 v[218:221], v156 offset:3072
	ds_read_b128 v[30:33], v154 offset:32768
	ds_read_b128 v[64:67], v154 offset:33792
	ds_read_b128 v[222:225], v154 offset:34816
	ds_read_b128 v[226:229], v154 offset:35840
	ds_read_b128 v[230:233], v154 offset:36864
	ds_read_b128 v[234:237], v154 offset:37888
	ds_read_b128 v[238:241], v154 offset:38912
	ds_read_b128 v[242:245], v154 offset:39936
	s_add_u32 s24, s36, 0x80100
	s_addc_u32 s25, s37, 0
	s_mov_b32 m0, s48
	s_nop 0
	global_load_lds_dwordx4 v1, s[24:25] offset:0
	s_nop 0
	s_mov_b32 m0, s49
	s_nop 0
	global_load_lds_dwordx4 v147, s[24:25] offset:0
	s_waitcnt vmcnt(8)
	s_waitcnt lgkmcnt(0)
	s_barrier
	s_setprio 1
	v_mfma_f32_16x16x32_bf16 v[68:71], v[12:15], v[30:33], v[68:71]
	v_mfma_f32_16x16x32_bf16 v[130:133], v[16:19], v[64:67], v[68:71]
	v_mfma_f32_16x16x32_bf16 v[68:71], v[22:25], v[30:33], v[72:75]
	v_mfma_f32_16x16x32_bf16 v[126:129], v[26:29], v[64:67], v[68:71]
	v_mfma_f32_16x16x32_bf16 v[68:71], v[12:15], v[222:225], v[76:79]
	v_mfma_f32_16x16x32_bf16 v[114:117], v[16:19], v[226:229], v[68:71]
	v_mfma_f32_16x16x32_bf16 v[68:71], v[22:25], v[222:225], v[80:83]
	v_mfma_f32_16x16x32_bf16 v[110:113], v[26:29], v[226:229], v[68:71]
	v_mfma_f32_16x16x32_bf16 v[68:71], v[12:15], v[230:233], v[84:87]
	v_mfma_f32_16x16x32_bf16 v[98:101], v[16:19], v[234:237], v[68:71]
	v_mfma_f32_16x16x32_bf16 v[68:71], v[22:25], v[230:233], v[88:91]
	v_mfma_f32_16x16x32_bf16 v[94:97], v[26:29], v[234:237], v[68:71]
	v_mfma_f32_16x16x32_bf16 v[68:71], v[12:15], v[238:241], v[102:105]
	v_mfma_f32_16x16x32_bf16 v[82:85], v[16:19], v[242:245], v[68:71]
	v_mfma_f32_16x16x32_bf16 v[68:71], v[22:25], v[238:241], v[106:109]
	v_mfma_f32_16x16x32_bf16 v[78:81], v[26:29], v[242:245], v[68:71]
	v_mfma_f32_16x16x32_bf16 v[68:71], v[206:209], v[30:33], v[118:121]
	v_mfma_f32_16x16x32_bf16 v[30:33], v[214:217], v[30:33], v[36:39]
	v_mfma_f32_16x16x32_bf16 v[118:121], v[218:221], v[64:67], v[30:33]
	v_mfma_f32_16x16x32_bf16 v[30:33], v[206:209], v[222:225], v[40:43]
	v_mfma_f32_16x16x32_bf16 v[106:109], v[210:213], v[226:229], v[30:33]
	v_mfma_f32_16x16x32_bf16 v[30:33], v[214:217], v[222:225], v[44:47]
	v_mfma_f32_16x16x32_bf16 v[102:105], v[218:221], v[226:229], v[30:33]
	v_mfma_f32_16x16x32_bf16 v[30:33], v[206:209], v[230:233], v[48:51]
	v_mfma_f32_16x16x32_bf16 v[90:93], v[210:213], v[234:237], v[30:33]
	v_mfma_f32_16x16x32_bf16 v[30:33], v[214:217], v[230:233], v[52:55]
	v_mfma_f32_16x16x32_bf16 v[86:89], v[218:221], v[234:237], v[30:33]
	v_mfma_f32_16x16x32_bf16 v[30:33], v[206:209], v[238:241], v[56:59]
	v_mfma_f32_16x16x32_bf16 v[74:77], v[210:213], v[242:245], v[30:33]
	v_mfma_f32_16x16x32_bf16 v[30:33], v[214:217], v[238:241], v[60:63]
	v_mfma_f32_16x16x32_bf16 v[122:125], v[210:213], v[64:67], v[68:71]
	v_mfma_f32_16x16x32_bf16 v[66:69], v[218:221], v[242:245], v[30:33]
	s_barrier
	s_setprio 0
	ds_read_b128 v[38:41], v154 offset:49152
	ds_read_b128 v[42:45], v154 offset:50176
	ds_read_b128 v[222:225], v154 offset:51200
	ds_read_b128 v[226:229], v154 offset:52224
	ds_read_b128 v[230:233], v154 offset:53248
	ds_read_b128 v[234:237], v154 offset:54272
	ds_read_b128 v[238:241], v154 offset:55296
	ds_read_b128 v[242:245], v154 offset:56320
	s_add_u32 s24, s38, 0x180
	s_addc_u32 s25, s39, 0
	s_mov_b32 m0, s50
	s_nop 0
	global_load_lds_dwordx4 v146, s[24:25] offset:0
	s_nop 0
	s_mov_b32 m0, s51
	s_nop 0
	global_load_lds_dwordx4 v148, s[24:25] offset:0
	s_add_u32 s24, s38, 0x80180
	s_addc_u32 s25, s39, 0
	s_mov_b32 m0, s54
	s_nop 0
	global_load_lds_dwordx4 v146, s[24:25] offset:0
	s_nop 0
	s_mov_b32 m0, s55
	s_nop 0
	global_load_lds_dwordx4 v148, s[24:25] offset:0
	s_nop 0
	s_mov_b32 m0, s52
	s_nop 0
	global_load_lds_dwordx4 v1, s[22:23] offset:0
	s_nop 0
	s_mov_b32 m0, s53
	s_nop 0
	global_load_lds_dwordx4 v147, s[22:23] offset:0
	s_waitcnt vmcnt(8)
	s_waitcnt lgkmcnt(0)
	s_barrier
	s_setprio 1
	v_mfma_f32_16x16x32_bf16 v[30:33], v[12:15], v[38:41], v[138:141]
	v_mfma_f32_16x16x32_bf16 v[70:73], v[16:19], v[42:45], v[30:33]
	v_mfma_f32_16x16x32_bf16 v[30:33], v[22:25], v[38:41], v[142:145]
	v_mfma_f32_16x16x32_bf16 v[62:65], v[26:29], v[42:45], v[30:33]
	v_mfma_f32_16x16x32_bf16 v[30:33], v[12:15], v[222:225], v[158:161]
	v_mfma_f32_16x16x32_bf16 v[50:53], v[16:19], v[226:229], v[30:33]
	v_mfma_f32_16x16x32_bf16 v[30:33], v[22:25], v[222:225], v[162:165]
	v_mfma_f32_16x16x32_bf16 v[46:49], v[26:29], v[226:229], v[30:33]
	v_mfma_f32_16x16x32_bf16 v[30:33], v[12:15], v[230:233], v[166:169]
	v_mfma_f32_16x16x32_bf16 v[4:7], v[12:15], v[238:241], v[4:7]
	v_mfma_f32_16x16x32_bf16 v[34:37], v[16:19], v[234:237], v[30:33]
	v_mfma_f32_16x16x32_bf16 v[30:33], v[22:25], v[230:233], v[170:173]
	v_mfma_f32_16x16x32_bf16 v[18:21], v[16:19], v[242:245], v[4:7]
	v_mfma_f32_16x16x32_bf16 v[4:7], v[22:25], v[238:241], v[8:11]
	v_mfma_f32_16x16x32_bf16 v[30:33], v[26:29], v[234:237], v[30:33]
	v_mfma_f32_16x16x32_bf16 v[14:17], v[26:29], v[242:245], v[4:7]
	v_mfma_f32_16x16x32_bf16 v[4:7], v[206:209], v[38:41], v[174:177]
	v_mfma_f32_16x16x32_bf16 v[58:61], v[210:213], v[42:45], v[4:7]
	v_mfma_f32_16x16x32_bf16 v[4:7], v[214:217], v[38:41], v[178:181]
	v_mfma_f32_16x16x32_bf16 v[54:57], v[218:221], v[42:45], v[4:7]
	v_mfma_f32_16x16x32_bf16 v[4:7], v[206:209], v[222:225], v[182:185]
	v_mfma_f32_16x16x32_bf16 v[42:45], v[210:213], v[226:229], v[4:7]
	v_mfma_f32_16x16x32_bf16 v[4:7], v[214:217], v[222:225], v[186:189]
	v_mfma_f32_16x16x32_bf16 v[38:41], v[218:221], v[226:229], v[4:7]
	v_mfma_f32_16x16x32_bf16 v[4:7], v[206:209], v[230:233], v[190:193]
	v_mfma_f32_16x16x32_bf16 v[26:29], v[210:213], v[234:237], v[4:7]
	v_mfma_f32_16x16x32_bf16 v[4:7], v[214:217], v[230:233], v[194:197]
	v_mfma_f32_16x16x32_bf16 v[22:25], v[218:221], v[234:237], v[4:7]
	v_mfma_f32_16x16x32_bf16 v[4:7], v[206:209], v[238:241], v[198:201]
	v_mfma_f32_16x16x32_bf16 v[10:13], v[210:213], v[242:245], v[4:7]
	v_mfma_f32_16x16x32_bf16 v[4:7], v[214:217], v[238:241], v[202:205]
	v_mfma_f32_16x16x32_bf16 v[6:9], v[218:221], v[242:245], v[4:7]
	s_barrier
	s_setprio 0
	s_mov_b32 s40, 2
	s_branch .LBB0_3620

.LBB0_3621:
	ds_read_b128 v[138:141], v152
	ds_read_b128 v[142:145], v152 offset:1024
	ds_read_b128 v[158:161], v152 offset:2048
	ds_read_b128 v[162:165], v152 offset:3072
	ds_read_b128 v[166:169], v153
	ds_read_b128 v[170:173], v153 offset:1024
	ds_read_b128 v[174:177], v153 offset:2048
	ds_read_b128 v[178:181], v153 offset:3072
	s_cmp_eq_u32 s72, 28
	s_cselect_b32 s40, s70, s75
	s_cselect_b32 s41, s19, s76
	s_cselect_b32 s38, s71, s73
	s_cselect_b32 s39, s17, s74
	s_add_u32 s36, s40, 0x80
	s_addc_u32 s37, s41, 0
	ds_read_b128 v[182:185], v154
	ds_read_b128 v[186:189], v154 offset:1024
	ds_read_b128 v[190:193], v154 offset:2048
	ds_read_b128 v[194:197], v154 offset:3072
	ds_read_b128 v[198:201], v154 offset:4096
	ds_read_b128 v[202:205], v154 offset:5120
	ds_read_b128 v[206:209], v154 offset:6144
	ds_read_b128 v[210:213], v154 offset:7168
	s_add_u32 s30, s75, 0x7ff80
	s_addc_u32 s31, s76, 0
	s_mov_b32 m0, s56
	s_nop 0
	global_load_lds_dwordx4 v1, s[30:31] offset:0
	s_nop 0
	s_mov_b32 m0, s57
	s_nop 0
	global_load_lds_dwordx4 v147, s[30:31] offset:0
	s_waitcnt vmcnt(8)
	s_waitcnt lgkmcnt(0)
	s_barrier
	s_setprio 1
	v_mfma_f32_16x16x32_bf16 v[130:133], v[138:141], v[182:185], v[130:133]
	v_mfma_f32_16x16x32_bf16 v[130:133], v[142:145], v[186:189], v[130:133]
	v_mfma_f32_16x16x32_bf16 v[126:129], v[158:161], v[182:185], v[126:129]
	v_mfma_f32_16x16x32_bf16 v[126:129], v[162:165], v[186:189], v[126:129]
	v_mfma_f32_16x16x32_bf16 v[114:117], v[138:141], v[190:193], v[114:117]
	v_mfma_f32_16x16x32_bf16 v[114:117], v[142:145], v[194:197], v[114:117]
	v_mfma_f32_16x16x32_bf16 v[110:113], v[158:161], v[190:193], v[110:113]
	v_mfma_f32_16x16x32_bf16 v[110:113], v[162:165], v[194:197], v[110:113]
	v_mfma_f32_16x16x32_bf16 v[98:101], v[138:141], v[198:201], v[98:101]
	v_mfma_f32_16x16x32_bf16 v[98:101], v[142:145], v[202:205], v[98:101]
	v_mfma_f32_16x16x32_bf16 v[94:97], v[158:161], v[198:201], v[94:97]
	v_mfma_f32_16x16x32_bf16 v[94:97], v[162:165], v[202:205], v[94:97]
	v_mfma_f32_16x16x32_bf16 v[82:85], v[138:141], v[206:209], v[82:85]
	v_mfma_f32_16x16x32_bf16 v[82:85], v[142:145], v[210:213], v[82:85]
	v_mfma_f32_16x16x32_bf16 v[78:81], v[158:161], v[206:209], v[78:81]
	v_mfma_f32_16x16x32_bf16 v[78:81], v[162:165], v[210:213], v[78:81]
	v_mfma_f32_16x16x32_bf16 v[122:125], v[166:169], v[182:185], v[122:125]
	v_mfma_f32_16x16x32_bf16 v[122:125], v[170:173], v[186:189], v[122:125]
	v_mfma_f32_16x16x32_bf16 v[118:121], v[174:177], v[182:185], v[118:121]
	v_mfma_f32_16x16x32_bf16 v[118:121], v[178:181], v[186:189], v[118:121]
	v_mfma_f32_16x16x32_bf16 v[106:109], v[166:169], v[190:193], v[106:109]
	v_mfma_f32_16x16x32_bf16 v[106:109], v[170:173], v[194:197], v[106:109]
	v_mfma_f32_16x16x32_bf16 v[102:105], v[174:177], v[190:193], v[102:105]
	v_mfma_f32_16x16x32_bf16 v[102:105], v[178:181], v[194:197], v[102:105]
	v_mfma_f32_16x16x32_bf16 v[90:93], v[166:169], v[198:201], v[90:93]
	v_mfma_f32_16x16x32_bf16 v[90:93], v[170:173], v[202:205], v[90:93]
	v_mfma_f32_16x16x32_bf16 v[86:89], v[174:177], v[198:201], v[86:89]
	v_mfma_f32_16x16x32_bf16 v[86:89], v[178:181], v[202:205], v[86:89]
	v_mfma_f32_16x16x32_bf16 v[74:77], v[166:169], v[206:209], v[74:77]
	v_mfma_f32_16x16x32_bf16 v[74:77], v[170:173], v[210:213], v[74:77]
	v_mfma_f32_16x16x32_bf16 v[66:69], v[174:177], v[206:209], v[66:69]
	v_mfma_f32_16x16x32_bf16 v[66:69], v[178:181], v[210:213], v[66:69]
	s_barrier
	s_setprio 0
	ds_read_b128 v[182:185], v154 offset:16384
	ds_read_b128 v[186:189], v154 offset:17408
	ds_read_b128 v[190:193], v154 offset:18432
	ds_read_b128 v[194:197], v154 offset:19456
	ds_read_b128 v[198:201], v154 offset:20480
	ds_read_b128 v[202:205], v154 offset:21504
	ds_read_b128 v[206:209], v154 offset:22528
	ds_read_b128 v[210:213], v154 offset:23552
	s_mov_b32 m0, s29
	s_nop 0
	global_load_lds_dwordx4 v146, s[38:39] offset:0
	s_add_u32 s30, s38, 0x80000
	s_mov_b32 m0, s44
	s_nop 0
	global_load_lds_dwordx4 v148, s[38:39] offset:0
	s_addc_u32 s31, s39, 0
	s_mov_b32 m0, s45
	s_nop 0
	global_load_lds_dwordx4 v146, s[30:31] offset:0
	s_nop 0
	s_mov_b32 m0, s46
	s_nop 0
	global_load_lds_dwordx4 v148, s[30:31] offset:0
	s_nop 0
	s_mov_b32 m0, s21
	s_nop 0
	global_load_lds_dwordx4 v1, s[40:41] offset:0
	s_nop 0
	s_mov_b32 m0, s47
	s_nop 0
	global_load_lds_dwordx4 v147, s[40:41] offset:0
	s_waitcnt vmcnt(8)
	s_waitcnt lgkmcnt(0)
	s_barrier
	s_setprio 1
	v_mfma_f32_16x16x32_bf16 v[70:73], v[138:141], v[182:185], v[70:73]
	v_mfma_f32_16x16x32_bf16 v[70:73], v[142:145], v[186:189], v[70:73]
	v_mfma_f32_16x16x32_bf16 v[62:65], v[158:161], v[182:185], v[62:65]
	v_mfma_f32_16x16x32_bf16 v[62:65], v[162:165], v[186:189], v[62:65]
	v_mfma_f32_16x16x32_bf16 v[50:53], v[138:141], v[190:193], v[50:53]
	v_mfma_f32_16x16x32_bf16 v[50:53], v[142:145], v[194:197], v[50:53]
	v_mfma_f32_16x16x32_bf16 v[46:49], v[158:161], v[190:193], v[46:49]
	v_mfma_f32_16x16x32_bf16 v[46:49], v[162:165], v[194:197], v[46:49]
	v_mfma_f32_16x16x32_bf16 v[34:37], v[138:141], v[198:201], v[34:37]
	v_mfma_f32_16x16x32_bf16 v[34:37], v[142:145], v[202:205], v[34:37]
	v_mfma_f32_16x16x32_bf16 v[30:33], v[158:161], v[198:201], v[30:33]
	v_mfma_f32_16x16x32_bf16 v[30:33], v[162:165], v[202:205], v[30:33]
	v_mfma_f32_16x16x32_bf16 v[18:21], v[138:141], v[206:209], v[18:21]
	v_mfma_f32_16x16x32_bf16 v[18:21], v[142:145], v[210:213], v[18:21]
	v_mfma_f32_16x16x32_bf16 v[14:17], v[158:161], v[206:209], v[14:17]
	v_mfma_f32_16x16x32_bf16 v[14:17], v[162:165], v[210:213], v[14:17]
	v_mfma_f32_16x16x32_bf16 v[58:61], v[166:169], v[182:185], v[58:61]
	v_mfma_f32_16x16x32_bf16 v[54:57], v[174:177], v[182:185], v[54:57]
	v_mfma_f32_16x16x32_bf16 v[42:45], v[166:169], v[190:193], v[42:45]
	v_mfma_f32_16x16x32_bf16 v[38:41], v[174:177], v[190:193], v[38:41]
	v_mfma_f32_16x16x32_bf16 v[26:29], v[166:169], v[198:201], v[26:29]
	v_mfma_f32_16x16x32_bf16 v[22:25], v[174:177], v[198:201], v[22:25]
	v_mfma_f32_16x16x32_bf16 v[10:13], v[166:169], v[206:209], v[10:13]
	v_mfma_f32_16x16x32_bf16 v[4:7], v[174:177], v[206:209], v[6:9]
	v_mfma_f32_16x16x32_bf16 v[58:61], v[170:173], v[186:189], v[58:61]
	v_mfma_f32_16x16x32_bf16 v[54:57], v[178:181], v[186:189], v[54:57]
	v_mfma_f32_16x16x32_bf16 v[42:45], v[170:173], v[194:197], v[42:45]
	v_mfma_f32_16x16x32_bf16 v[38:41], v[178:181], v[194:197], v[38:41]
	v_mfma_f32_16x16x32_bf16 v[26:29], v[170:173], v[202:205], v[26:29]
	v_mfma_f32_16x16x32_bf16 v[22:25], v[178:181], v[202:205], v[22:25]
	v_mfma_f32_16x16x32_bf16 v[10:13], v[170:173], v[210:213], v[10:13]
	v_mfma_f32_16x16x32_bf16 v[4:7], v[178:181], v[210:213], v[4:7]
	s_barrier
; #define PG8_BAR __builtin_amdgcn_s_barrier()
; #define PG8_KSETUP() const bool last = (t == nt - 2); const char* a1 = cA + (size_t)(t + 1) * kstep; \
;             const char* a2 = last ? nA : cA + (size_t)(t + 2) * kstep; const char* b2 = last ? nB : cB + (size_t)(t + 2) * kstep; const char* a3 = a2 + kstep; const char* b3 = b2 + kstep; \
;             if (last && has_next) S.a_ready(nxt)
; template <class Epi, class Sched, bool ALIGN_EPI = false, bool SP2 = false>
; __device__ __forceinline__ void gemm_phase(PG8_LAS unsigned char* lds, const Gemm g, const Sched& S, const Epi& E) {
;     ...
;         int t0 = 0;
;         if constexpr (SP2 && Epi::NVM == 16) { if (ui > 0) { const int t = 0; PG8_KSETUP(); PG8_KITER_SP2(24, 24); t0 = 2; } }
;         if constexpr (SP2 && Epi::NVM == 8) { if (ui > 0) { const int t = 0; PG8_KSETUP(); PG8_KITER_SP2(16, 16); t0 = 2; } }
;         for (int t = t0; t < nt; t += 2) {
;     ...
;         if constexpr (ALIGN_EPI) { if (wr == 0) PG8_BAR; }
	s_setprio 0
	ds_read_b128 v[138:141], v155
	ds_read_b128 v[142:145], v155 offset:1024
	ds_read_b128 v[158:161], v155 offset:2048
	ds_read_b128 v[162:165], v155 offset:3072
	ds_read_b128 v[166:169], v156
	ds_read_b128 v[170:173], v156 offset:1024
	ds_read_b128 v[174:177], v156 offset:2048
	ds_read_b128 v[178:181], v156 offset:3072
	ds_read_b128 v[182:185], v154 offset:32768
	ds_read_b128 v[186:189], v154 offset:33792
	ds_read_b128 v[190:193], v154 offset:34816
	ds_read_b128 v[194:197], v154 offset:35840
	ds_read_b128 v[198:201], v154 offset:36864
	ds_read_b128 v[202:205], v154 offset:37888
	ds_read_b128 v[206:209], v154 offset:38912
	ds_read_b128 v[210:213], v154 offset:39936
	s_add_u32 s30, s40, 0x80000
	s_addc_u32 s31, s41, 0
	s_mov_b32 m0, s48
	s_nop 0
	global_load_lds_dwordx4 v1, s[30:31] offset:0
	s_nop 0
	s_mov_b32 m0, s49
	s_nop 0
	global_load_lds_dwordx4 v147, s[30:31] offset:0
	s_waitcnt vmcnt(8)
	s_waitcnt lgkmcnt(0)
	s_barrier
	s_setprio 1
	v_mfma_f32_16x16x32_bf16 v[130:133], v[138:141], v[182:185], v[130:133]
	v_mfma_f32_16x16x32_bf16 v[130:133], v[142:145], v[186:189], v[130:133]
	v_mfma_f32_16x16x32_bf16 v[126:129], v[158:161], v[182:185], v[126:129]
	v_mfma_f32_16x16x32_bf16 v[126:129], v[162:165], v[186:189], v[126:129]
	v_mfma_f32_16x16x32_bf16 v[114:117], v[138:141], v[190:193], v[114:117]
	v_mfma_f32_16x16x32_bf16 v[114:117], v[142:145], v[194:197], v[114:117]
	v_mfma_f32_16x16x32_bf16 v[110:113], v[158:161], v[190:193], v[110:113]
	v_mfma_f32_16x16x32_bf16 v[110:113], v[162:165], v[194:197], v[110:113]
	v_mfma_f32_16x16x32_bf16 v[98:101], v[138:141], v[198:201], v[98:101]
	v_mfma_f32_16x16x32_bf16 v[98:101], v[142:145], v[202:205], v[98:101]
	v_mfma_f32_16x16x32_bf16 v[94:97], v[158:161], v[198:201], v[94:97]
	v_mfma_f32_16x16x32_bf16 v[94:97], v[162:165], v[202:205], v[94:97]
	v_mfma_f32_16x16x32_bf16 v[82:85], v[138:141], v[206:209], v[82:85]
	v_mfma_f32_16x16x32_bf16 v[82:85], v[142:145], v[210:213], v[82:85]
	v_mfma_f32_16x16x32_bf16 v[78:81], v[158:161], v[206:209], v[78:81]
	v_mfma_f32_16x16x32_bf16 v[78:81], v[162:165], v[210:213], v[78:81]
	v_mfma_f32_16x16x32_bf16 v[122:125], v[166:169], v[182:185], v[122:125]
	v_mfma_f32_16x16x32_bf16 v[122:125], v[170:173], v[186:189], v[122:125]
	v_mfma_f32_16x16x32_bf16 v[118:121], v[174:177], v[182:185], v[118:121]
	v_mfma_f32_16x16x32_bf16 v[118:121], v[178:181], v[186:189], v[118:121]
	v_mfma_f32_16x16x32_bf16 v[106:109], v[166:169], v[190:193], v[106:109]
	v_mfma_f32_16x16x32_bf16 v[106:109], v[170:173], v[194:197], v[106:109]
	v_mfma_f32_16x16x32_bf16 v[102:105], v[174:177], v[190:193], v[102:105]
	v_mfma_f32_16x16x32_bf16 v[102:105], v[178:181], v[194:197], v[102:105]
	v_mfma_f32_16x16x32_bf16 v[90:93], v[166:169], v[198:201], v[90:93]
	v_mfma_f32_16x16x32_bf16 v[90:93], v[170:173], v[202:205], v[90:93]
	v_mfma_f32_16x16x32_bf16 v[86:89], v[174:177], v[198:201], v[86:89]
	v_mfma_f32_16x16x32_bf16 v[86:89], v[178:181], v[202:205], v[86:89]
	v_mfma_f32_16x16x32_bf16 v[74:77], v[166:169], v[206:209], v[74:77]
	v_mfma_f32_16x16x32_bf16 v[74:77], v[170:173], v[210:213], v[74:77]
	v_mfma_f32_16x16x32_bf16 v[66:69], v[174:177], v[206:209], v[66:69]
	v_mfma_f32_16x16x32_bf16 v[66:69], v[178:181], v[210:213], v[66:69]
	s_barrier
	s_setprio 0
	ds_read_b128 v[182:185], v154 offset:49152
	ds_read_b128 v[186:189], v154 offset:50176
	ds_read_b128 v[190:193], v154 offset:51200
	ds_read_b128 v[194:197], v154 offset:52224
	ds_read_b128 v[198:201], v154 offset:53248
	ds_read_b128 v[202:205], v154 offset:54272
	ds_read_b128 v[206:209], v154 offset:55296
	ds_read_b128 v[210:213], v154 offset:56320
	s_add_u32 s30, s38, 0x80
	s_addc_u32 s31, s39, 0
	s_mov_b32 m0, s50
	s_nop 0
	global_load_lds_dwordx4 v146, s[30:31] offset:0
	s_nop 0
	s_mov_b32 m0, s51
	s_nop 0
	global_load_lds_dwordx4 v148, s[30:31] offset:0
	s_add_u32 s30, s38, 0x80080
	s_addc_u32 s31, s39, 0
	s_mov_b32 m0, s54
	s_nop 0
	global_load_lds_dwordx4 v146, s[30:31] offset:0
	s_nop 0
	s_mov_b32 m0, s55
	s_nop 0
	global_load_lds_dwordx4 v148, s[30:31] offset:0
	s_nop 0
	s_mov_b32 m0, s52
	s_nop 0
	global_load_lds_dwordx4 v1, s[36:37] offset:0
	s_nop 0
	s_mov_b32 m0, s53
	s_nop 0
	global_load_lds_dwordx4 v147, s[36:37] offset:0
	s_waitcnt vmcnt(8)
	s_waitcnt lgkmcnt(0)
	s_barrier
	s_setprio 1
	v_mfma_f32_16x16x32_bf16 v[70:73], v[138:141], v[182:185], v[70:73]
	v_mfma_f32_16x16x32_bf16 v[70:73], v[142:145], v[186:189], v[70:73]
	v_mfma_f32_16x16x32_bf16 v[62:65], v[158:161], v[182:185], v[62:65]
	v_mfma_f32_16x16x32_bf16 v[62:65], v[162:165], v[186:189], v[62:65]
	v_mfma_f32_16x16x32_bf16 v[50:53], v[138:141], v[190:193], v[50:53]
	v_mfma_f32_16x16x32_bf16 v[50:53], v[142:145], v[194:197], v[50:53]
	v_mfma_f32_16x16x32_bf16 v[46:49], v[158:161], v[190:193], v[46:49]
	v_mfma_f32_16x16x32_bf16 v[46:49], v[162:165], v[194:197], v[46:49]
	v_mfma_f32_16x16x32_bf16 v[34:37], v[138:141], v[198:201], v[34:37]
	v_mfma_f32_16x16x32_bf16 v[34:37], v[142:145], v[202:205], v[34:37]
	v_mfma_f32_16x16x32_bf16 v[30:33], v[158:161], v[198:201], v[30:33]
	v_mfma_f32_16x16x32_bf16 v[30:33], v[162:165], v[202:205], v[30:33]
	v_mfma_f32_16x16x32_bf16 v[18:21], v[138:141], v[206:209], v[18:21]
	v_mfma_f32_16x16x32_bf16 v[18:21], v[142:145], v[210:213], v[18:21]
	v_mfma_f32_16x16x32_bf16 v[14:17], v[158:161], v[206:209], v[14:17]
	v_mfma_f32_16x16x32_bf16 v[14:17], v[162:165], v[210:213], v[14:17]
	v_mfma_f32_16x16x32_bf16 v[58:61], v[166:169], v[182:185], v[58:61]
	v_mfma_f32_16x16x32_bf16 v[54:57], v[174:177], v[182:185], v[54:57]
	v_mfma_f32_16x16x32_bf16 v[42:45], v[166:169], v[190:193], v[42:45]
	v_mfma_f32_16x16x32_bf16 v[38:41], v[174:177], v[190:193], v[38:41]
	v_mfma_f32_16x16x32_bf16 v[26:29], v[166:169], v[198:201], v[26:29]
	v_mfma_f32_16x16x32_bf16 v[22:25], v[174:177], v[198:201], v[22:25]
	v_mfma_f32_16x16x32_bf16 v[8:11], v[166:169], v[206:209], v[10:13]
	v_mfma_f32_16x16x32_bf16 v[4:7], v[174:177], v[206:209], v[4:7]
	v_mfma_f32_16x16x32_bf16 v[58:61], v[170:173], v[186:189], v[58:61]
	v_mfma_f32_16x16x32_bf16 v[54:57], v[178:181], v[186:189], v[54:57]
	v_mfma_f32_16x16x32_bf16 v[42:45], v[170:173], v[194:197], v[42:45]
	v_mfma_f32_16x16x32_bf16 v[38:41], v[178:181], v[194:197], v[38:41]
	v_mfma_f32_16x16x32_bf16 v[26:29], v[170:173], v[202:205], v[26:29]
	v_mfma_f32_16x16x32_bf16 v[22:25], v[178:181], v[202:205], v[22:25]
	v_mfma_f32_16x16x32_bf16 v[10:13], v[170:173], v[210:213], v[8:11]
	v_mfma_f32_16x16x32_bf16 v[6:9], v[178:181], v[210:213], v[4:7]
	s_barrier
	s_setprio 0
	s_add_i32 s72, s72, 2
	s_add_u32 s73, s73, 0x100
	s_addc_u32 s74, s74, 0
	s_add_u32 s75, s75, 0x100
	s_addc_u32 s76, s76, 0
	s_cmp_gt_u32 s72, 29
	s_cbranch_scc0 .LBB0_3621
	s_and_b64 vcc, exec, s[14:15]
	s_cbranch_vccz .LBB0_3624
	s_barrier

; #define PG8_KSETUP() const bool last = (t == nt - 2); const char* a1 = cA + (size_t)(t + 1) * kstep; \
;             const char* a2 = last ? nA : cA + (size_t)(t + 2) * kstep; const char* b2 = last ? nB : cB + (size_t)(t + 2) * kstep; const char* a3 = a2 + kstep; const char* b3 = b2 + kstep; \
;             if (last && has_next) S.a_ready(nxt)
; template <class Epi, class Sched, bool ALIGN_EPI = false, bool SP2 = false>
; __device__ __forceinline__ void gemm_phase(PG8_LAS unsigned char* lds, const Gemm g, const Sched& S, const Epi& E) {
;     ...
;         if constexpr (SP2 && Epi::NVM == 16) { if (ui > 0) { const int t = 0; PG8_KSETUP(); PG8_KITER_SP2(24, 24); t0 = 2; } }
.LBB0_3696:
	ds_read_b128 v[2:5], v150
	ds_read_b128 v[6:9], v150 offset:1024
	ds_read_b128 v[10:13], v150 offset:2048
	ds_read_b128 v[14:17], v150 offset:3072
	ds_read_b128 v[18:21], v151
	ds_read_b128 v[22:25], v151 offset:1024
	ds_read_b128 v[26:29], v151 offset:2048
	ds_read_b128 v[30:33], v151 offset:3072
	s_add_u32 s22, s16, 0x100
	s_addc_u32 s23, s17, 0
	s_add_u32 s30, s18, 0x100
	s_addc_u32 s31, s19, 0
	s_add_u32 s20, s16, 0x180
	s_addc_u32 s21, s17, 0
	ds_read_b128 v[34:37], v152
	ds_read_b128 v[38:41], v152 offset:1024
	ds_read_b128 v[42:45], v152 offset:2048
	ds_read_b128 v[46:49], v152 offset:3072
	ds_read_b128 v[50:53], v152 offset:4096
	ds_read_b128 v[54:57], v152 offset:5120
	ds_read_b128 v[58:61], v152 offset:6144
	ds_read_b128 v[62:65], v152 offset:7168
	s_add_u32 s56, s16, 0x160080
	s_addc_u32 s57, s17, 0
	s_mov_b32 m0, s48
	s_nop 0
	global_load_lds_dwordx4 v144, s[56:57] offset:0
	s_nop 0
	s_mov_b32 m0, s49
	s_nop 0
	global_load_lds_dwordx4 v146, s[56:57] offset:0
	s_waitcnt vmcnt(24)
	s_waitcnt lgkmcnt(0)
	s_barrier
	s_setprio 1
	v_mfma_f32_16x16x32_bf16 v[90:93], v[2:5], v[58:61], 0
	v_mfma_f32_16x16x32_bf16 v[66:69], v[2:5], v[34:37], 0
	v_mfma_f32_16x16x32_bf16 v[70:73], v[10:13], v[34:37], 0
	v_mfma_f32_16x16x32_bf16 v[74:77], v[2:5], v[42:45], 0
	v_mfma_f32_16x16x32_bf16 v[78:81], v[10:13], v[42:45], 0
	v_mfma_f32_16x16x32_bf16 v[82:85], v[2:5], v[50:53], 0
	v_mfma_f32_16x16x32_bf16 v[86:89], v[10:13], v[50:53], 0
	v_mfma_f32_16x16x32_bf16 v[100:103], v[6:9], v[62:65], v[90:93]
	v_mfma_f32_16x16x32_bf16 v[90:93], v[10:13], v[58:61], 0
	v_mfma_f32_16x16x32_bf16 v[66:69], v[6:9], v[38:41], v[66:69]
	v_mfma_f32_16x16x32_bf16 v[70:73], v[14:17], v[38:41], v[70:73]
	v_mfma_f32_16x16x32_bf16 v[74:77], v[6:9], v[46:49], v[74:77]
	v_mfma_f32_16x16x32_bf16 v[78:81], v[14:17], v[46:49], v[78:81]
	v_mfma_f32_16x16x32_bf16 v[82:85], v[6:9], v[54:57], v[82:85]
	v_mfma_f32_16x16x32_bf16 v[86:89], v[14:17], v[54:57], v[86:89]
	v_mfma_f32_16x16x32_bf16 v[104:107], v[14:17], v[62:65], v[90:93]
	v_mfma_f32_16x16x32_bf16 v[90:93], v[18:21], v[34:37], 0
	v_mfma_f32_16x16x32_bf16 v[34:37], v[26:29], v[34:37], 0
	v_mfma_f32_16x16x32_bf16 v[116:119], v[22:25], v[38:41], v[90:93]
	v_mfma_f32_16x16x32_bf16 v[34:37], v[30:33], v[38:41], v[34:37]
	v_mfma_f32_16x16x32_bf16 v[38:41], v[18:21], v[42:45], 0
	v_mfma_f32_16x16x32_bf16 v[42:45], v[26:29], v[42:45], 0
	v_mfma_f32_16x16x32_bf16 v[38:41], v[22:25], v[46:49], v[38:41]
	v_mfma_f32_16x16x32_bf16 v[42:45], v[30:33], v[46:49], v[42:45]
	v_mfma_f32_16x16x32_bf16 v[46:49], v[18:21], v[50:53], 0
	v_mfma_f32_16x16x32_bf16 v[50:53], v[26:29], v[50:53], 0
	v_mfma_f32_16x16x32_bf16 v[46:49], v[22:25], v[54:57], v[46:49]
	v_mfma_f32_16x16x32_bf16 v[50:53], v[30:33], v[54:57], v[50:53]
	v_mfma_f32_16x16x32_bf16 v[54:57], v[18:21], v[58:61], 0
	v_mfma_f32_16x16x32_bf16 v[58:61], v[26:29], v[58:61], 0
	v_mfma_f32_16x16x32_bf16 v[54:57], v[22:25], v[62:65], v[54:57]
	v_mfma_f32_16x16x32_bf16 v[58:61], v[30:33], v[62:65], v[58:61]
	s_barrier
	s_setprio 0
	ds_read_b128 v[62:65], v152 offset:16384
	ds_read_b128 v[90:93], v152 offset:17408
	ds_read_b128 v[94:97], v152 offset:18432
	ds_read_b128 v[108:111], v152 offset:19456
	ds_read_b128 v[112:115], v152 offset:20480
	ds_read_b128 v[120:123], v152 offset:21504
	ds_read_b128 v[124:127], v152 offset:22528
	ds_read_b128 v[128:131], v152 offset:23552
	s_mov_b32 m0, s34
	s_nop 0
	global_load_lds_dwordx4 v145, s[30:31] offset:0
	s_nop 0
	s_mov_b32 m0, s36
	s_nop 0
	global_load_lds_dwordx4 v147, s[30:31] offset:0
	s_add_u32 s30, s18, 0x160100
	s_addc_u32 s31, s19, 0
	s_mov_b32 m0, s37
	s_nop 0
	global_load_lds_dwordx4 v145, s[30:31] offset:0
	s_nop 0
	s_mov_b32 m0, s38
	s_nop 0
	global_load_lds_dwordx4 v147, s[30:31] offset:0
	s_nop 0
	s_mov_b32 m0, s28
	s_nop 0
	global_load_lds_dwordx4 v144, s[22:23] offset:0
	s_nop 0
	s_mov_b32 m0, s39
	s_nop 0
	global_load_lds_dwordx4 v146, s[22:23] offset:0
	s_waitcnt vmcnt(24)
	s_waitcnt lgkmcnt(0)
	s_barrier
	s_setprio 1
	v_mfma_f32_16x16x32_bf16 v[132:135], v[2:5], v[62:65], 0
	v_mfma_f32_16x16x32_bf16 v[156:159], v[2:5], v[94:97], 0
	v_mfma_f32_16x16x32_bf16 v[164:167], v[2:5], v[112:115], 0
	v_mfma_f32_16x16x32_bf16 v[2:5], v[2:5], v[124:127], 0
	v_mfma_f32_16x16x32_bf16 v[132:135], v[6:9], v[90:93], v[132:135]
	v_mfma_f32_16x16x32_bf16 v[156:159], v[6:9], v[108:111], v[156:159]
	v_mfma_f32_16x16x32_bf16 v[164:167], v[6:9], v[120:123], v[164:167]
	v_mfma_f32_16x16x32_bf16 v[2:5], v[6:9], v[128:131], v[2:5]
	v_mfma_f32_16x16x32_bf16 v[6:9], v[10:13], v[124:127], 0
	v_mfma_f32_16x16x32_bf16 v[140:143], v[10:13], v[62:65], 0
	v_mfma_f32_16x16x32_bf16 v[160:163], v[10:13], v[94:97], 0
	v_mfma_f32_16x16x32_bf16 v[168:171], v[10:13], v[112:115], 0
	v_mfma_f32_16x16x32_bf16 v[6:9], v[14:17], v[128:131], v[6:9]
	v_mfma_f32_16x16x32_bf16 v[140:143], v[14:17], v[90:93], v[140:143]
	v_mfma_f32_16x16x32_bf16 v[160:163], v[14:17], v[108:111], v[160:163]
	v_mfma_f32_16x16x32_bf16 v[168:171], v[14:17], v[120:123], v[168:171]
	v_mfma_f32_16x16x32_bf16 v[10:13], v[18:21], v[62:65], 0
	v_mfma_f32_16x16x32_bf16 v[172:175], v[22:25], v[90:93], v[10:13]
	v_mfma_f32_16x16x32_bf16 v[10:13], v[26:29], v[62:65], 0
	v_mfma_f32_16x16x32_bf16 v[176:179], v[30:33], v[90:93], v[10:13]
	v_mfma_f32_16x16x32_bf16 v[10:13], v[18:21], v[94:97], 0
	v_mfma_f32_16x16x32_bf16 v[180:183], v[22:25], v[108:111], v[10:13]
	v_mfma_f32_16x16x32_bf16 v[10:13], v[26:29], v[94:97], 0
	v_mfma_f32_16x16x32_bf16 v[184:187], v[30:33], v[108:111], v[10:13]
	v_mfma_f32_16x16x32_bf16 v[10:13], v[18:21], v[112:115], 0
	v_mfma_f32_16x16x32_bf16 v[188:191], v[22:25], v[120:123], v[10:13]
	v_mfma_f32_16x16x32_bf16 v[10:13], v[26:29], v[112:115], 0
	v_mfma_f32_16x16x32_bf16 v[192:195], v[30:33], v[120:123], v[10:13]
	v_mfma_f32_16x16x32_bf16 v[10:13], v[18:21], v[124:127], 0
	v_mfma_f32_16x16x32_bf16 v[196:199], v[22:25], v[128:131], v[10:13]
	v_mfma_f32_16x16x32_bf16 v[10:13], v[26:29], v[124:127], 0
	v_mfma_f32_16x16x32_bf16 v[200:203], v[30:33], v[128:131], v[10:13]
	s_barrier
; #define PG8_KSETUP() const bool last = (t == nt - 2); const char* a1 = cA + (size_t)(t + 1) * kstep; \
;             const char* a2 = last ? nA : cA + (size_t)(t + 2) * kstep; const char* b2 = last ? nB : cB + (size_t)(t + 2) * kstep; const char* a3 = a2 + kstep; const char* b3 = b2 + kstep; \
;             if (last && has_next) S.a_ready(nxt)
; template <class Epi, class Sched, bool ALIGN_EPI = false, bool SP2 = false>
; __device__ __forceinline__ void gemm_phase(PG8_LAS unsigned char* lds, const Gemm g, const Sched& S, const Epi& E) {
;     ...
;         int t0 = 0;
;         if constexpr (SP2 && Epi::NVM == 16) { if (ui > 0) { const int t = 0; PG8_KSETUP(); PG8_KITER_SP2(24, 24); t0 = 2; } }
	s_setprio 0
	s_nop 4
	ds_read_b128 v[10:13], v153
	ds_read_b128 v[14:17], v153 offset:1024
	ds_read_b128 v[20:23], v153 offset:2048
	ds_read_b128 v[24:27], v153 offset:3072
	ds_read_b128 v[204:207], v154
	ds_read_b128 v[208:211], v154 offset:1024
	ds_read_b128 v[212:215], v154 offset:2048
	ds_read_b128 v[216:219], v154 offset:3072
	ds_read_b128 v[28:31], v152 offset:32768
	ds_read_b128 v[62:65], v152 offset:33792
	ds_read_b128 v[220:223], v152 offset:34816
	ds_read_b128 v[224:227], v152 offset:35840
	ds_read_b128 v[228:231], v152 offset:36864
	ds_read_b128 v[232:235], v152 offset:37888
	ds_read_b128 v[236:239], v152 offset:38912
	ds_read_b128 v[240:243], v152 offset:39936
	s_add_u32 s22, s16, 0x160100
	s_addc_u32 s23, s17, 0
	s_mov_b32 m0, s40
	s_nop 0
	global_load_lds_dwordx4 v144, s[22:23] offset:0
	s_nop 0
	s_mov_b32 m0, s41
	s_nop 0
	global_load_lds_dwordx4 v146, s[22:23] offset:0
	s_waitcnt vmcnt(8)
	s_waitcnt lgkmcnt(0)
	s_barrier
	s_setprio 1
	v_mfma_f32_16x16x32_bf16 v[66:69], v[10:13], v[28:31], v[66:69]
	v_mfma_f32_16x16x32_bf16 v[128:131], v[14:17], v[62:65], v[66:69]
	v_mfma_f32_16x16x32_bf16 v[66:69], v[20:23], v[28:31], v[70:73]
	v_mfma_f32_16x16x32_bf16 v[124:127], v[24:27], v[62:65], v[66:69]
	v_mfma_f32_16x16x32_bf16 v[66:69], v[10:13], v[220:223], v[74:77]
	v_mfma_f32_16x16x32_bf16 v[112:115], v[14:17], v[224:227], v[66:69]
	v_mfma_f32_16x16x32_bf16 v[66:69], v[20:23], v[220:223], v[78:81]
	v_mfma_f32_16x16x32_bf16 v[108:111], v[24:27], v[224:227], v[66:69]
	v_mfma_f32_16x16x32_bf16 v[66:69], v[10:13], v[228:231], v[82:85]
	v_mfma_f32_16x16x32_bf16 v[96:99], v[14:17], v[232:235], v[66:69]
	v_mfma_f32_16x16x32_bf16 v[66:69], v[20:23], v[228:231], v[86:89]
	v_mfma_f32_16x16x32_bf16 v[92:95], v[24:27], v[232:235], v[66:69]
	v_mfma_f32_16x16x32_bf16 v[66:69], v[10:13], v[236:239], v[100:103]
	v_mfma_f32_16x16x32_bf16 v[80:83], v[14:17], v[240:243], v[66:69]
	v_mfma_f32_16x16x32_bf16 v[66:69], v[20:23], v[236:239], v[104:107]
	v_mfma_f32_16x16x32_bf16 v[76:79], v[24:27], v[240:243], v[66:69]
	v_mfma_f32_16x16x32_bf16 v[66:69], v[204:207], v[28:31], v[116:119]
	v_mfma_f32_16x16x32_bf16 v[28:31], v[212:215], v[28:31], v[34:37]
	v_mfma_f32_16x16x32_bf16 v[116:119], v[216:219], v[62:65], v[28:31]
	v_mfma_f32_16x16x32_bf16 v[28:31], v[204:207], v[220:223], v[38:41]
	v_mfma_f32_16x16x32_bf16 v[104:107], v[208:211], v[224:227], v[28:31]
	v_mfma_f32_16x16x32_bf16 v[28:31], v[212:215], v[220:223], v[42:45]
	v_mfma_f32_16x16x32_bf16 v[100:103], v[216:219], v[224:227], v[28:31]
	v_mfma_f32_16x16x32_bf16 v[28:31], v[204:207], v[228:231], v[46:49]
	v_mfma_f32_16x16x32_bf16 v[88:91], v[208:211], v[232:235], v[28:31]
	v_mfma_f32_16x16x32_bf16 v[28:31], v[212:215], v[228:231], v[50:53]
	v_mfma_f32_16x16x32_bf16 v[84:87], v[216:219], v[232:235], v[28:31]
	v_mfma_f32_16x16x32_bf16 v[28:31], v[204:207], v[236:239], v[54:57]
	v_mfma_f32_16x16x32_bf16 v[72:75], v[208:211], v[240:243], v[28:31]
	v_mfma_f32_16x16x32_bf16 v[28:31], v[212:215], v[236:239], v[58:61]
	v_mfma_f32_16x16x32_bf16 v[120:123], v[208:211], v[62:65], v[66:69]
	v_mfma_f32_16x16x32_bf16 v[68:71], v[216:219], v[240:243], v[28:31]
	s_barrier
	s_setprio 0
	ds_read_b128 v[36:39], v152 offset:49152
	ds_read_b128 v[40:43], v152 offset:50176
	ds_read_b128 v[220:223], v152 offset:51200
	ds_read_b128 v[224:227], v152 offset:52224
	ds_read_b128 v[228:231], v152 offset:53248
	ds_read_b128 v[232:235], v152 offset:54272
	ds_read_b128 v[236:239], v152 offset:55296
	ds_read_b128 v[240:243], v152 offset:56320
	s_add_u32 s22, s18, 0x180
	s_addc_u32 s23, s19, 0
	s_mov_b32 m0, s42
	s_nop 0
	global_load_lds_dwordx4 v145, s[22:23] offset:0
	s_nop 0
	s_mov_b32 m0, s43
	s_nop 0
	global_load_lds_dwordx4 v147, s[22:23] offset:0
	s_add_u32 s22, s18, 0x160180
	s_addc_u32 s23, s19, 0
	s_mov_b32 m0, s46
	s_nop 0
	global_load_lds_dwordx4 v145, s[22:23] offset:0
	s_nop 0
	s_mov_b32 m0, s47
	s_nop 0
	global_load_lds_dwordx4 v147, s[22:23] offset:0
	s_nop 0
	s_mov_b32 m0, s44
	s_nop 0
	global_load_lds_dwordx4 v144, s[20:21] offset:0
	s_nop 0
	s_mov_b32 m0, s45
	s_nop 0
	global_load_lds_dwordx4 v146, s[20:21] offset:0
	s_waitcnt vmcnt(8)
	s_waitcnt lgkmcnt(0)
	s_barrier
	s_setprio 1
	v_mfma_f32_16x16x32_bf16 v[28:31], v[10:13], v[36:39], v[132:135]
	v_mfma_f32_16x16x32_bf16 v[64:67], v[14:17], v[40:43], v[28:31]
	v_mfma_f32_16x16x32_bf16 v[28:31], v[20:23], v[36:39], v[140:143]
	v_mfma_f32_16x16x32_bf16 v[60:63], v[24:27], v[40:43], v[28:31]
	v_mfma_f32_16x16x32_bf16 v[28:31], v[10:13], v[220:223], v[156:159]
	v_mfma_f32_16x16x32_bf16 v[48:51], v[14:17], v[224:227], v[28:31]
	v_mfma_f32_16x16x32_bf16 v[28:31], v[20:23], v[220:223], v[160:163]
	v_mfma_f32_16x16x32_bf16 v[44:47], v[24:27], v[224:227], v[28:31]
	v_mfma_f32_16x16x32_bf16 v[28:31], v[10:13], v[228:231], v[164:167]
	v_mfma_f32_16x16x32_bf16 v[2:5], v[10:13], v[236:239], v[2:5]
	v_mfma_f32_16x16x32_bf16 v[32:35], v[14:17], v[232:235], v[28:31]
	v_mfma_f32_16x16x32_bf16 v[28:31], v[20:23], v[228:231], v[168:171]
	v_mfma_f32_16x16x32_bf16 v[16:19], v[14:17], v[240:243], v[2:5]
	v_mfma_f32_16x16x32_bf16 v[2:5], v[20:23], v[236:239], v[6:9]
	v_mfma_f32_16x16x32_bf16 v[28:31], v[24:27], v[232:235], v[28:31]
	v_mfma_f32_16x16x32_bf16 v[12:15], v[24:27], v[240:243], v[2:5]
	v_mfma_f32_16x16x32_bf16 v[2:5], v[204:207], v[36:39], v[172:175]
	v_mfma_f32_16x16x32_bf16 v[56:59], v[208:211], v[40:43], v[2:5]
	v_mfma_f32_16x16x32_bf16 v[2:5], v[212:215], v[36:39], v[176:179]
	v_mfma_f32_16x16x32_bf16 v[52:55], v[216:219], v[40:43], v[2:5]
	v_mfma_f32_16x16x32_bf16 v[2:5], v[204:207], v[220:223], v[180:183]
	v_mfma_f32_16x16x32_bf16 v[40:43], v[208:211], v[224:227], v[2:5]
	v_mfma_f32_16x16x32_bf16 v[2:5], v[212:215], v[220:223], v[184:187]
	v_mfma_f32_16x16x32_bf16 v[36:39], v[216:219], v[224:227], v[2:5]
	v_mfma_f32_16x16x32_bf16 v[2:5], v[204:207], v[228:231], v[188:191]
	v_mfma_f32_16x16x32_bf16 v[24:27], v[208:211], v[232:235], v[2:5]
	v_mfma_f32_16x16x32_bf16 v[2:5], v[212:215], v[228:231], v[192:195]
	v_mfma_f32_16x16x32_bf16 v[20:23], v[216:219], v[232:235], v[2:5]
	v_mfma_f32_16x16x32_bf16 v[2:5], v[204:207], v[236:239], v[196:199]
	v_mfma_f32_16x16x32_bf16 v[8:11], v[208:211], v[240:243], v[2:5]
	v_mfma_f32_16x16x32_bf16 v[2:5], v[212:215], v[236:239], v[200:203]
	v_mfma_f32_16x16x32_bf16 v[4:7], v[216:219], v[240:243], v[2:5]
	s_barrier
	s_setprio 0
	s_mov_b32 s20, 2
	s_branch .LBB0_3700

.LBB0_3701:
	ds_read_b128 v[132:135], v150
	ds_read_b128 v[140:143], v150 offset:1024
	ds_read_b128 v[156:159], v150 offset:2048
	ds_read_b128 v[160:163], v150 offset:3072
	ds_read_b128 v[164:167], v151
	ds_read_b128 v[168:171], v151 offset:1024
	ds_read_b128 v[172:175], v151 offset:2048
	ds_read_b128 v[176:179], v151 offset:3072
	s_cmpk_eq_i32 s22, 0x54
	s_cselect_b32 s20, s4, s57
	s_cselect_b32 s21, s5, s58
	s_cselect_b32 s18, s14, s23
	s_cselect_b32 s19, s15, s56
	s_add_u32 s16, s20, 0x80
	s_addc_u32 s17, s21, 0
	ds_read_b128 v[180:183], v152
	ds_read_b128 v[184:187], v152 offset:1024
	ds_read_b128 v[188:191], v152 offset:2048
	ds_read_b128 v[192:195], v152 offset:3072
	ds_read_b128 v[196:199], v152 offset:4096
	ds_read_b128 v[200:203], v152 offset:5120
	ds_read_b128 v[204:207], v152 offset:6144
	ds_read_b128 v[208:211], v152 offset:7168
	s_add_u32 s30, s57, 0x15ff80
	s_addc_u32 s31, s58, 0
	s_mov_b32 m0, s48
	s_nop 0
	global_load_lds_dwordx4 v144, s[30:31] offset:0
	s_nop 0
	s_mov_b32 m0, s49
	s_nop 0
	global_load_lds_dwordx4 v146, s[30:31] offset:0
	s_waitcnt vmcnt(8)
	s_waitcnt lgkmcnt(0)
	s_barrier
	s_setprio 1
	v_mfma_f32_16x16x32_bf16 v[128:131], v[132:135], v[180:183], v[128:131]
	v_mfma_f32_16x16x32_bf16 v[128:131], v[140:143], v[184:187], v[128:131]
	v_mfma_f32_16x16x32_bf16 v[124:127], v[156:159], v[180:183], v[124:127]
	v_mfma_f32_16x16x32_bf16 v[124:127], v[160:163], v[184:187], v[124:127]
	v_mfma_f32_16x16x32_bf16 v[112:115], v[132:135], v[188:191], v[112:115]
	v_mfma_f32_16x16x32_bf16 v[112:115], v[140:143], v[192:195], v[112:115]
	v_mfma_f32_16x16x32_bf16 v[108:111], v[156:159], v[188:191], v[108:111]
	v_mfma_f32_16x16x32_bf16 v[108:111], v[160:163], v[192:195], v[108:111]
	v_mfma_f32_16x16x32_bf16 v[96:99], v[132:135], v[196:199], v[96:99]
	v_mfma_f32_16x16x32_bf16 v[96:99], v[140:143], v[200:203], v[96:99]
	v_mfma_f32_16x16x32_bf16 v[92:95], v[156:159], v[196:199], v[92:95]
	v_mfma_f32_16x16x32_bf16 v[92:95], v[160:163], v[200:203], v[92:95]
	v_mfma_f32_16x16x32_bf16 v[80:83], v[132:135], v[204:207], v[80:83]
	v_mfma_f32_16x16x32_bf16 v[80:83], v[140:143], v[208:211], v[80:83]
	v_mfma_f32_16x16x32_bf16 v[76:79], v[156:159], v[204:207], v[76:79]
	v_mfma_f32_16x16x32_bf16 v[76:79], v[160:163], v[208:211], v[76:79]
	v_mfma_f32_16x16x32_bf16 v[120:123], v[164:167], v[180:183], v[120:123]
	v_mfma_f32_16x16x32_bf16 v[120:123], v[168:171], v[184:187], v[120:123]
	v_mfma_f32_16x16x32_bf16 v[116:119], v[172:175], v[180:183], v[116:119]
	v_mfma_f32_16x16x32_bf16 v[116:119], v[176:179], v[184:187], v[116:119]
	v_mfma_f32_16x16x32_bf16 v[104:107], v[164:167], v[188:191], v[104:107]
	v_mfma_f32_16x16x32_bf16 v[104:107], v[168:171], v[192:195], v[104:107]
	v_mfma_f32_16x16x32_bf16 v[100:103], v[172:175], v[188:191], v[100:103]
	v_mfma_f32_16x16x32_bf16 v[100:103], v[176:179], v[192:195], v[100:103]
	v_mfma_f32_16x16x32_bf16 v[88:91], v[164:167], v[196:199], v[88:91]
	v_mfma_f32_16x16x32_bf16 v[88:91], v[168:171], v[200:203], v[88:91]
	v_mfma_f32_16x16x32_bf16 v[84:87], v[172:175], v[196:199], v[84:87]
	v_mfma_f32_16x16x32_bf16 v[84:87], v[176:179], v[200:203], v[84:87]
	v_mfma_f32_16x16x32_bf16 v[72:75], v[164:167], v[204:207], v[72:75]
	v_mfma_f32_16x16x32_bf16 v[72:75], v[168:171], v[208:211], v[72:75]
	v_mfma_f32_16x16x32_bf16 v[68:71], v[172:175], v[204:207], v[68:71]
	v_mfma_f32_16x16x32_bf16 v[68:71], v[176:179], v[208:211], v[68:71]
	s_barrier
	s_setprio 0
	ds_read_b128 v[180:183], v152 offset:16384
	ds_read_b128 v[184:187], v152 offset:17408
	ds_read_b128 v[188:191], v152 offset:18432
	ds_read_b128 v[192:195], v152 offset:19456
	ds_read_b128 v[196:199], v152 offset:20480
	ds_read_b128 v[200:203], v152 offset:21504
	ds_read_b128 v[204:207], v152 offset:22528
	ds_read_b128 v[208:211], v152 offset:23552
	s_mov_b32 m0, s34
	s_nop 0
	global_load_lds_dwordx4 v145, s[18:19] offset:0
	s_add_u32 s30, s18, 0x160000
	s_mov_b32 m0, s36
	s_nop 0
	global_load_lds_dwordx4 v147, s[18:19] offset:0
	s_addc_u32 s31, s19, 0
	s_mov_b32 m0, s37
	s_nop 0
	global_load_lds_dwordx4 v145, s[30:31] offset:0
	s_nop 0
	s_mov_b32 m0, s38
	s_nop 0
	global_load_lds_dwordx4 v147, s[30:31] offset:0
	s_nop 0
	s_mov_b32 m0, s28
	s_nop 0
	global_load_lds_dwordx4 v144, s[20:21] offset:0
	s_nop 0
	s_mov_b32 m0, s39
	s_nop 0
	global_load_lds_dwordx4 v146, s[20:21] offset:0
	s_waitcnt vmcnt(8)
	s_waitcnt lgkmcnt(0)
	s_barrier
	s_setprio 1
	v_mfma_f32_16x16x32_bf16 v[64:67], v[132:135], v[180:183], v[64:67]
	v_mfma_f32_16x16x32_bf16 v[64:67], v[140:143], v[184:187], v[64:67]
	v_mfma_f32_16x16x32_bf16 v[60:63], v[156:159], v[180:183], v[60:63]
	v_mfma_f32_16x16x32_bf16 v[60:63], v[160:163], v[184:187], v[60:63]
	v_mfma_f32_16x16x32_bf16 v[48:51], v[132:135], v[188:191], v[48:51]
	v_mfma_f32_16x16x32_bf16 v[48:51], v[140:143], v[192:195], v[48:51]
	v_mfma_f32_16x16x32_bf16 v[44:47], v[156:159], v[188:191], v[44:47]
	v_mfma_f32_16x16x32_bf16 v[44:47], v[160:163], v[192:195], v[44:47]
	v_mfma_f32_16x16x32_bf16 v[32:35], v[132:135], v[196:199], v[32:35]
	v_mfma_f32_16x16x32_bf16 v[32:35], v[140:143], v[200:203], v[32:35]
	v_mfma_f32_16x16x32_bf16 v[28:31], v[156:159], v[196:199], v[28:31]
	v_mfma_f32_16x16x32_bf16 v[28:31], v[160:163], v[200:203], v[28:31]
	v_mfma_f32_16x16x32_bf16 v[16:19], v[132:135], v[204:207], v[16:19]
	v_mfma_f32_16x16x32_bf16 v[16:19], v[140:143], v[208:211], v[16:19]
	v_mfma_f32_16x16x32_bf16 v[12:15], v[156:159], v[204:207], v[12:15]
	v_mfma_f32_16x16x32_bf16 v[12:15], v[160:163], v[208:211], v[12:15]
	v_mfma_f32_16x16x32_bf16 v[56:59], v[164:167], v[180:183], v[56:59]
	v_mfma_f32_16x16x32_bf16 v[52:55], v[172:175], v[180:183], v[52:55]
	v_mfma_f32_16x16x32_bf16 v[40:43], v[164:167], v[188:191], v[40:43]
	v_mfma_f32_16x16x32_bf16 v[36:39], v[172:175], v[188:191], v[36:39]
	v_mfma_f32_16x16x32_bf16 v[24:27], v[164:167], v[196:199], v[24:27]
	v_mfma_f32_16x16x32_bf16 v[20:23], v[172:175], v[196:199], v[20:23]
	v_mfma_f32_16x16x32_bf16 v[8:11], v[164:167], v[204:207], v[8:11]
	v_mfma_f32_16x16x32_bf16 v[2:5], v[172:175], v[204:207], v[4:7]
	v_mfma_f32_16x16x32_bf16 v[56:59], v[168:171], v[184:187], v[56:59]
	v_mfma_f32_16x16x32_bf16 v[52:55], v[176:179], v[184:187], v[52:55]
	v_mfma_f32_16x16x32_bf16 v[40:43], v[168:171], v[192:195], v[40:43]
	v_mfma_f32_16x16x32_bf16 v[36:39], v[176:179], v[192:195], v[36:39]
	v_mfma_f32_16x16x32_bf16 v[24:27], v[168:171], v[200:203], v[24:27]
	v_mfma_f32_16x16x32_bf16 v[20:23], v[176:179], v[200:203], v[20:23]
	v_mfma_f32_16x16x32_bf16 v[8:11], v[168:171], v[208:211], v[8:11]
	v_mfma_f32_16x16x32_bf16 v[2:5], v[176:179], v[208:211], v[2:5]
	s_barrier
	s_setprio 0
	ds_read_b128 v[132:135], v153
	ds_read_b128 v[140:143], v153 offset:1024
	ds_read_b128 v[156:159], v153 offset:2048
	ds_read_b128 v[160:163], v153 offset:3072
	ds_read_b128 v[164:167], v154
	ds_read_b128 v[168:171], v154 offset:1024
	ds_read_b128 v[172:175], v154 offset:2048
	ds_read_b128 v[176:179], v154 offset:3072
	ds_read_b128 v[180:183], v152 offset:32768
	ds_read_b128 v[184:187], v152 offset:33792
	ds_read_b128 v[188:191], v152 offset:34816
	ds_read_b128 v[192:195], v152 offset:35840
	ds_read_b128 v[196:199], v152 offset:36864
	ds_read_b128 v[200:203], v152 offset:37888
	ds_read_b128 v[204:207], v152 offset:38912
	ds_read_b128 v[208:211], v152 offset:39936
	s_add_u32 s20, s20, 0x160000
	s_addc_u32 s21, s21, 0
	s_mov_b32 m0, s40
	s_nop 0
	global_load_lds_dwordx4 v144, s[20:21] offset:0
	s_nop 0
	s_mov_b32 m0, s41
	s_nop 0
	global_load_lds_dwordx4 v146, s[20:21] offset:0
	s_waitcnt vmcnt(8)
	s_waitcnt lgkmcnt(0)
	s_barrier
	s_setprio 1
	v_mfma_f32_16x16x32_bf16 v[128:131], v[132:135], v[180:183], v[128:131]
	v_mfma_f32_16x16x32_bf16 v[128:131], v[140:143], v[184:187], v[128:131]
	v_mfma_f32_16x16x32_bf16 v[124:127], v[156:159], v[180:183], v[124:127]
	v_mfma_f32_16x16x32_bf16 v[124:127], v[160:163], v[184:187], v[124:127]
	v_mfma_f32_16x16x32_bf16 v[112:115], v[132:135], v[188:191], v[112:115]
	v_mfma_f32_16x16x32_bf16 v[112:115], v[140:143], v[192:195], v[112:115]
	v_mfma_f32_16x16x32_bf16 v[108:111], v[156:159], v[188:191], v[108:111]
	v_mfma_f32_16x16x32_bf16 v[108:111], v[160:163], v[192:195], v[108:111]
	v_mfma_f32_16x16x32_bf16 v[96:99], v[132:135], v[196:199], v[96:99]
	v_mfma_f32_16x16x32_bf16 v[96:99], v[140:143], v[200:203], v[96:99]
	v_mfma_f32_16x16x32_bf16 v[92:95], v[156:159], v[196:199], v[92:95]
	v_mfma_f32_16x16x32_bf16 v[92:95], v[160:163], v[200:203], v[92:95]
	v_mfma_f32_16x16x32_bf16 v[80:83], v[132:135], v[204:207], v[80:83]
	v_mfma_f32_16x16x32_bf16 v[80:83], v[140:143], v[208:211], v[80:83]
	v_mfma_f32_16x16x32_bf16 v[76:79], v[156:159], v[204:207], v[76:79]
	v_mfma_f32_16x16x32_bf16 v[76:79], v[160:163], v[208:211], v[76:79]
	v_mfma_f32_16x16x32_bf16 v[120:123], v[164:167], v[180:183], v[120:123]
	v_mfma_f32_16x16x32_bf16 v[120:123], v[168:171], v[184:187], v[120:123]
	v_mfma_f32_16x16x32_bf16 v[116:119], v[172:175], v[180:183], v[116:119]
	v_mfma_f32_16x16x32_bf16 v[116:119], v[176:179], v[184:187], v[116:119]
	v_mfma_f32_16x16x32_bf16 v[104:107], v[164:167], v[188:191], v[104:107]
	v_mfma_f32_16x16x32_bf16 v[104:107], v[168:171], v[192:195], v[104:107]
	v_mfma_f32_16x16x32_bf16 v[100:103], v[172:175], v[188:191], v[100:103]
	v_mfma_f32_16x16x32_bf16 v[100:103], v[176:179], v[192:195], v[100:103]
	v_mfma_f32_16x16x32_bf16 v[88:91], v[164:167], v[196:199], v[88:91]
	v_mfma_f32_16x16x32_bf16 v[88:91], v[168:171], v[200:203], v[88:91]
	v_mfma_f32_16x16x32_bf16 v[84:87], v[172:175], v[196:199], v[84:87]
	v_mfma_f32_16x16x32_bf16 v[84:87], v[176:179], v[200:203], v[84:87]
	v_mfma_f32_16x16x32_bf16 v[72:75], v[164:167], v[204:207], v[72:75]
	v_mfma_f32_16x16x32_bf16 v[72:75], v[168:171], v[208:211], v[72:75]
	v_mfma_f32_16x16x32_bf16 v[68:71], v[172:175], v[204:207], v[68:71]
	v_mfma_f32_16x16x32_bf16 v[68:71], v[176:179], v[208:211], v[68:71]
	s_barrier
	s_setprio 0
	ds_read_b128 v[180:183], v152 offset:49152
	ds_read_b128 v[184:187], v152 offset:50176
	ds_read_b128 v[188:191], v152 offset:51200
	ds_read_b128 v[192:195], v152 offset:52224
	ds_read_b128 v[196:199], v152 offset:53248
	ds_read_b128 v[200:203], v152 offset:54272
	ds_read_b128 v[204:207], v152 offset:55296
	ds_read_b128 v[208:211], v152 offset:56320
	s_add_u32 s20, s18, 0x80
	s_addc_u32 s21, s19, 0
	s_mov_b32 m0, s42
	s_nop 0
	global_load_lds_dwordx4 v145, s[20:21] offset:0
	s_add_u32 s18, s18, 0x160080
	s_mov_b32 m0, s43
	s_nop 0
	global_load_lds_dwordx4 v147, s[20:21] offset:0
	s_addc_u32 s19, s19, 0
	s_mov_b32 m0, s46
	s_nop 0
	global_load_lds_dwordx4 v145, s[18:19] offset:0
	s_nop 0
	s_mov_b32 m0, s47
	s_nop 0
	global_load_lds_dwordx4 v147, s[18:19] offset:0
	s_nop 0
	s_mov_b32 m0, s44
	s_nop 0
	global_load_lds_dwordx4 v144, s[16:17] offset:0
	s_nop 0
	s_mov_b32 m0, s45
	s_nop 0
	global_load_lds_dwordx4 v146, s[16:17] offset:0
	s_waitcnt vmcnt(8)
	s_waitcnt lgkmcnt(0)
	s_barrier
	s_setprio 1
	v_mfma_f32_16x16x32_bf16 v[64:67], v[132:135], v[180:183], v[64:67]
	v_mfma_f32_16x16x32_bf16 v[64:67], v[140:143], v[184:187], v[64:67]
	v_mfma_f32_16x16x32_bf16 v[60:63], v[156:159], v[180:183], v[60:63]
	v_mfma_f32_16x16x32_bf16 v[60:63], v[160:163], v[184:187], v[60:63]
	v_mfma_f32_16x16x32_bf16 v[48:51], v[132:135], v[188:191], v[48:51]
	v_mfma_f32_16x16x32_bf16 v[48:51], v[140:143], v[192:195], v[48:51]
	v_mfma_f32_16x16x32_bf16 v[44:47], v[156:159], v[188:191], v[44:47]
	v_mfma_f32_16x16x32_bf16 v[44:47], v[160:163], v[192:195], v[44:47]
	v_mfma_f32_16x16x32_bf16 v[32:35], v[132:135], v[196:199], v[32:35]
	v_mfma_f32_16x16x32_bf16 v[32:35], v[140:143], v[200:203], v[32:35]
	v_mfma_f32_16x16x32_bf16 v[28:31], v[156:159], v[196:199], v[28:31]
	v_mfma_f32_16x16x32_bf16 v[28:31], v[160:163], v[200:203], v[28:31]
	v_mfma_f32_16x16x32_bf16 v[16:19], v[132:135], v[204:207], v[16:19]
	v_mfma_f32_16x16x32_bf16 v[16:19], v[140:143], v[208:211], v[16:19]
	v_mfma_f32_16x16x32_bf16 v[12:15], v[156:159], v[204:207], v[12:15]
	v_mfma_f32_16x16x32_bf16 v[12:15], v[160:163], v[208:211], v[12:15]
	v_mfma_f32_16x16x32_bf16 v[56:59], v[164:167], v[180:183], v[56:59]
	v_mfma_f32_16x16x32_bf16 v[52:55], v[172:175], v[180:183], v[52:55]
	v_mfma_f32_16x16x32_bf16 v[40:43], v[164:167], v[188:191], v[40:43]
	v_mfma_f32_16x16x32_bf16 v[36:39], v[172:175], v[188:191], v[36:39]
	v_mfma_f32_16x16x32_bf16 v[24:27], v[164:167], v[196:199], v[24:27]
	v_mfma_f32_16x16x32_bf16 v[20:23], v[172:175], v[196:199], v[20:23]
	v_mfma_f32_16x16x32_bf16 v[6:9], v[164:167], v[204:207], v[8:11]
	v_mfma_f32_16x16x32_bf16 v[2:5], v[172:175], v[204:207], v[2:5]
	v_mfma_f32_16x16x32_bf16 v[56:59], v[168:171], v[184:187], v[56:59]
	v_mfma_f32_16x16x32_bf16 v[52:55], v[176:179], v[184:187], v[52:55]
	v_mfma_f32_16x16x32_bf16 v[40:43], v[168:171], v[192:195], v[40:43]
	v_mfma_f32_16x16x32_bf16 v[36:39], v[176:179], v[192:195], v[36:39]
	v_mfma_f32_16x16x32_bf16 v[24:27], v[168:171], v[200:203], v[24:27]
	v_mfma_f32_16x16x32_bf16 v[20:23], v[176:179], v[200:203], v[20:23]
	v_mfma_f32_16x16x32_bf16 v[8:11], v[168:171], v[208:211], v[6:9]
	v_mfma_f32_16x16x32_bf16 v[4:7], v[176:179], v[208:211], v[2:5]
	s_barrier
	s_setprio 0
	s_add_i32 s22, s22, 2
	s_add_u32 s23, s23, 0x100
	s_addc_u32 s56, s56, 0
	s_add_u32 s57, s57, 0x100
	s_addc_u32 s58, s58, 0
	s_cmpk_gt_u32 s22, 0x55
	s_cbranch_scc0 .LBB0_3701
	s_and_b64 vcc, exec, s[12:13]
	s_cbranch_vccz .LBB0_3704
	s_barrier
